# K-loop: 4 workgroup barriers per trip (lead wave group keeps post-MMA barriers, lag group pre-MMA; stagger + epilogue re-align barriers dropped; older waves multiply first) + merge/rope epilogue batch
# baseline (speedup 1.0000x reference)
_Z10fwd_kernel4Args:
	v_readfirstlane_b32 s100, v0
	s_nop 3
	s_lshr_b32 s100, s100, 8
	s_xor_b32 s100, s100, 1
	s_mov_b32 s78, s2
	s_add_u32 s2, s0, 0xd8
	s_addc_u32 s3, s1, 0
	v_lshl_add_u32 v1, v0, 2, 0
	v_writelane_b32 v249, s2, 0
	v_add_u32_e32 v1, 0x20000, v1
	v_mov_b32_e32 v2, 0
	v_writelane_b32 v249, s3, 1
	s_load_dword s2, s[0:1], 0xd8
	v_readfirstlane_b32 s64, v0
	ds_write2st64_b32 v1, v2, v2 offset1:8
	ds_write2st64_b32 v1, v2, v2 offset0:16 offset1:24
	v_or_b32_e32 v1, 0x800, v0
	s_waitcnt lgkmcnt(0)
	v_writelane_b32 v249, s2, 2
	s_mov_b64 s[2:3], -1
	s_and_saveexec_b64 s[4:5], s[2:3]
	v_lshl_add_u32 v3, v1, 2, 0
	v_add_u32_e32 v3, 0x20000, v3
	ds_write_b32 v3, v2
	s_or_b64 exec, exec, s[4:5]
	s_and_saveexec_b64 s[4:5], s[2:3]
	s_add_i32 s2, 0, 0x20000
	v_lshl_add_u32 v1, v1, 2, s2
	v_mov_b32_e32 v2, 0
	ds_write_b32 v1, v2 offset:2048
	s_or_b64 exec, exec, s[4:5]
	s_load_dwordx4 s[68:71], s[0:1], 0xc0
	v_or_b32_e32 v0, 0xc00, v0
	v_cmp_gt_u32_e64 s[2:3], 7, 6
	v_cmp_gt_u32_e64 s[6:7], 7, 5
	s_and_saveexec_b64 s[4:5], s[6:7]
	v_lshl_add_u32 v1, v0, 2, 0
	v_add_u32_e32 v1, 0x20000, v1
	v_mov_b32_e32 v2, 0
	ds_write_b32 v1, v2
	s_or_b64 exec, exec, s[4:5]
	s_and_saveexec_b64 s[4:5], s[2:3]
	s_add_i32 s2, 0, 0x20000
	v_lshl_add_u32 v0, v0, 2, s2
	v_mov_b32_e32 v1, 0
	ds_write_b32 v0, v1 offset:2048
	s_or_b64 exec, exec, s[4:5]
	s_waitcnt lgkmcnt(0)
	s_add_u32 s96, s68, 0x4000
	s_addc_u32 s97, s69, 0
	s_sub_i32 s4, s71, s70
	s_cmp_gt_i32 s4, 1
	s_cselect_b64 s[2:3], -1, 0
	s_cmp_lt_i32 s4, 2
	s_mov_b32 s65, 0
	s_barrier
	s_cbranch_scc1 .LBB0_14
	s_getreg_b32 s4, hwreg(HW_REG_XCC_ID, 0, 4)
	s_and_b32 s65, s4, 15
	v_mov_b32_e32 v0, 0
	s_cmp_gt_u32 s64, 63
	s_cbranch_scc1 .LBB0_14
	v_mbcnt_lo_u32_b32 v0, -1, v0
	v_mbcnt_hi_u32_b32 v0, -1, v0
	v_cmp_eq_u32_e32 vcc, 0, v0
	s_and_saveexec_b64 s[4:5], vcc
	s_cbranch_execz .LBB0_13
	s_mov_b64 s[6:7], exec
	v_mbcnt_lo_u32_b32 v0, s6, 0
	v_mbcnt_hi_u32_b32 v0, s7, v0
	v_cmp_eq_u32_e32 vcc, 0, v0
	s_and_b64 s[8:9], exec, vcc
	s_mov_b64 exec, s[8:9]
	s_cbranch_execz .LBB0_13
	s_lshl_b32 s8, s65, 8
	s_bcnt1_i32_b64 s6, s[6:7]
	v_mov_b32_e32 v0, s8
	v_mov_b32_e32 v1, s6
	global_atomic_add v0, v1, s[96:97] offset:1024

.LBB0_376:
	v_readlane_b32 s0, v250, 5
	v_readlane_b32 s1, v250, 6
	v_mov_b32_e32 v0, v1
	s_andn2_b64 vcc, exec, s[0:1]
	s_cbranch_vccnz .LBB0_454
	v_mbcnt_lo_u32_b32 v0, -1, v0
	v_mbcnt_hi_u32_b32 v10, -1, v0
	v_readlane_b32 s0, v249, 60
	v_readlane_b32 s2, v254, 49
	v_readlane_b32 s3, v254, 50
	v_add_u32_e32 v0, s0, v10
	v_bfe_i32 v4, v0, 27, 1
	v_lshlrev_b32_e32 v2, 4, v0
	v_lshrrev_b32_e32 v4, 22, v4
	v_add_u32_e32 v4, v2, v4
	v_and_b32_e32 v4, 0xfffffc00, v4
	v_sub_u32_e32 v4, v2, v4
	v_ashrrev_i32_e32 v3, 31, v0
	s_waitcnt lgkmcnt(0)
	v_lshrrev_b32_e32 v5, 4, v4
	v_lshrrev_b32_e32 v3, 26, v3
	v_bitop3_b32 v4, v5, v4, 32 bitop3:0x6c
	v_add_u32_e32 v3, v0, v3
	v_ashrrev_i32_e32 v6, 31, v4
	v_ashrrev_i32_e32 v3, 6, v3
	v_lshrrev_b32_e32 v6, 26, v6
	v_lshlrev_b32_e32 v5, 3, v3
	v_add_u32_e32 v6, v4, v6
	v_and_b32_e32 v5, -16, v5
	v_ashrrev_i32_e32 v7, 6, v6
	v_and_b32_e32 v6, 0xc0, v6
	v_add_u32_e32 v5, v7, v5
	v_sub_u32_e32 v4, v4, v6
	v_lshlrev_b32_e32 v3, 5, v3
	v_ashrrev_i16_sdwa v4, v226, sext(v4) dst_sel:DWORD dst_unused:UNUSED_PAD src0_sel:DWORD src1_sel:BYTE_0
	v_lshlrev_b32_e32 v6, 1, v5
	v_lshrrev_b32_e32 v8, 2, v5
	v_and_b32_e32 v7, 3, v7
	s_mov_b32 s0, 0x1fffe0
	v_and_b32_e32 v3, 32, v3
	v_bfe_i32 v4, v4, 0, 16
	v_and_b32_e32 v6, 24, v6
	v_and_b32_e32 v8, 4, v8
	v_and_or_b32 v7, v5, s0, v7
	v_or3_b32 v6, v7, v8, v6
	v_add_lshl_u32 v3, v3, v4, 1
	v_add_u32_e32 v2, 0x2000, v2
	v_lshl_add_u32 v144, v5, 11, v3
	v_lshl_add_u32 v145, v6, 11, v3
	v_ashrrev_i32_e32 v3, 31, v2
	v_lshrrev_b32_e32 v3, 22, v3
	v_add_u32_e32 v3, v2, v3
	v_ashrrev_i32_e32 v3, 10, v3
	v_mul_i32_i24_e32 v4, 0x400, v3
	v_sub_u32_e32 v2, v2, v4
	v_lshrrev_b32_e32 v4, 4, v2
	v_bitop3_b32 v2, v4, v2, 32 bitop3:0x6c
	v_ashrrev_i32_e32 v5, 31, v2
	v_lshrrev_b32_e32 v5, 26, v5
	v_lshlrev_b32_e32 v4, 3, v3
	v_add_u32_e32 v5, v2, v5
	v_and_b32_e32 v4, -16, v4
	v_ashrrev_i32_e32 v6, 6, v5
	v_add_u32_e32 v4, v6, v4
	v_and_b32_e32 v6, 3, v6
	v_and_or_b32 v6, v4, s0, v6
	s_mov_b64 s[8:9], s[2:3]
	s_mov_b64 s[0:1], s[2:3]
	v_and_b32_e32 v5, 0xc0, v5
	v_readlane_b32 s2, v254, 47
	v_sub_u32_e32 v2, v2, v5
	v_readlane_b32 s3, v254, 48
	v_lshlrev_b32_e32 v3, 5, v3
	v_ashrrev_i16_sdwa v2, v226, sext(v2) dst_sel:DWORD dst_unused:UNUSED_PAD src0_sel:DWORD src1_sel:BYTE_0
	v_lshlrev_b32_e32 v5, 1, v4
	v_lshrrev_b32_e32 v7, 2, v4
	s_mov_b64 s[76:77], s[2:3]
	s_mov_b64 s[0:1], s[2:3]
	v_and_b32_e32 v3, 32, v3
	v_bfe_i32 v2, v2, 0, 16
	v_and_b32_e32 v5, 24, v5
	v_and_b32_e32 v7, 4, v7
	v_or3_b32 v5, v6, v7, v5
	v_add_lshl_u32 v2, v3, v2, 1
	v_ashrrev_i32_e32 v11, 1, v0
	v_readlane_b32 s0, v253, 39
	v_lshl_add_u32 v146, v4, 11, v2
	v_lshl_add_u32 v147, v5, 11, v2
	v_add_u32_e32 v2, s0, v11
	v_ashrrev_i32_e32 v3, 31, v2
	v_readlane_b32 s0, v254, 51
	v_lshlrev_b64 v[2:3], 6, v[2:3]
	v_readlane_b32 s1, v254, 52
	v_and_b32_e32 v12, 1, v10
	v_lshlrev_b32_e32 v0, 5, v12
	v_lshl_add_u64 v[2:3], s[0:1], 0, v[2:3]
	s_mov_b32 m0, s92
	s_and_b32 s77, s77, 0xffff
	v_lshl_add_u64 v[6:7], v[2:3], 0, v[0:1]
	v_readlane_b32 s0, v253, 45
	global_load_dwordx4 v[2:5], v[6:7], off offset:16
	s_nop 0
	global_load_dwordx4 v[6:9], v[6:7], off
	s_and_b32 s9, s9, 0xffff
	s_mov_b32 s10, s78
	buffer_load_dwordx4 v145, s[76:79], s0 offen lds
	s_mov_b32 m0, s93
	s_mov_b32 s11, s79
	buffer_load_dwordx4 v147, s[76:79], s0 offen lds
	s_mov_b32 m0, s94
	v_readlane_b32 s0, v253, 40
	s_nop 4
	buffer_load_dwordx4 v145, s[76:79], s0 offen lds
	s_mov_b32 m0, s95
	s_nop 0
	buffer_load_dwordx4 v147, s[76:79], s0 offen lds
	s_mov_b32 m0, s44
	v_readlane_b32 s0, v253, 43
	s_nop 4
	buffer_load_dwordx4 v144, s[8:11], s0 offen lds
	s_mov_b32 m0, s36
	s_nop 0
	buffer_load_dwordx4 v146, s[8:11], s0 offen lds
	s_mov_b32 m0, s37
	v_readlane_b32 s0, v253, 41
	s_nop 4
	buffer_load_dwordx4 v144, s[8:11], s0 offen lds
	s_mov_b32 m0, s38
	s_nop 0
	buffer_load_dwordx4 v146, s[8:11], s0 offen lds
	v_readlane_b32 s0, v250, 9
	v_readlane_b32 s1, v250, 10
	s_andn2_b64 vcc, exec, s[0:1]
	s_nop 0
	v_cndmask_b32_e64 v0, 0, 1, s[0:1]
	v_cmp_ne_u32_e64 s[50:51], 1, v0
	s_cbranch_vccnz .LBB0_379
.LBB0_379:
	s_waitcnt vmcnt(8)
	v_add_f32_e32 v0, v6, v7
	v_add_f32_e32 v6, v8, v9
	v_add_f32_e32 v2, v2, v3
	v_add_f32_e32 v3, v4, v5
	s_waitcnt vmcnt(2)
	v_add_f32_e32 v0, v0, v6
	v_add_f32_e32 v2, v2, v3
	v_add_f32_e32 v0, v0, v2
	v_mov_b32_e32 v2, v1
	v_cmp_eq_u32_e32 vcc, 0, v12
	s_barrier
	v_mov_b32_dpp v2, v0 quad_perm:[1,0,3,2] row_mask:0xf bank_mask:0xf
	s_and_saveexec_b64 s[0:1], vcc
	s_cbranch_execz .LBB0_381
	v_add_f32_e32 v0, v0, v2
	v_mov_b32_e32 v2, 0x358637bd
	v_fmamk_f32 v0, v0, 0x3a800000, v2
	v_rsq_f32_e32 v0, v0
	v_lshl_add_u32 v2, v11, 2, 0
	v_add_u32_e32 v2, 0x21000, v2
	ds_write_b32 v2, v0

.LBB0_382:
	ds_read_b128 v[2:5], v150
	ds_read_b128 v[6:9], v150 offset:1024
	ds_read_b128 v[10:13], v150 offset:2048
	ds_read_b128 v[14:17], v150 offset:3072
	ds_read_b128 v[18:21], v151
	ds_read_b128 v[22:25], v151 offset:1024
	ds_read_b128 v[26:29], v151 offset:2048
	ds_read_b128 v[30:33], v151 offset:3072
	s_or_b32 s9, s68, 0x100
	s_or_b32 s8, s68, 0x180
	s_or_b32 s10, s69, 0x100
	s_or_b32 s11, s68, 0x40080
	s_mov_b32 m0, s45
	ds_read_b128 v[34:37], v149
	ds_read_b128 v[38:41], v149 offset:1024
	ds_read_b128 v[42:45], v149 offset:2048
	ds_read_b128 v[46:49], v149 offset:3072
	ds_read_b128 v[50:53], v149 offset:4096
	ds_read_b128 v[54:57], v149 offset:5120
	ds_read_b128 v[58:61], v149 offset:6144
	ds_read_b128 v[62:65], v149 offset:7168
	buffer_load_dwordx4 v144, s[0:3], s11 offen lds
	s_mov_b32 m0, s46
	s_nop 0
	buffer_load_dwordx4 v146, s[0:3], s11 offen lds
	s_waitcnt vmcnt(24)
	s_waitcnt lgkmcnt(0)
	s_cmp_eq_u32 s100, 0
	s_cbranch_scc1 .Lhb_0
	s_barrier
.Lhb_0:
	s_setprio 1
	s_waitcnt lgkmcnt(3)
	v_mfma_f32_16x16x32_bf16 v[86:89], v[10:13], v[50:53], 0
	s_waitcnt lgkmcnt(2)
	v_mfma_f32_16x16x32_bf16 v[92:95], v[14:17], v[54:57], v[86:89]
	s_waitcnt lgkmcnt(1)
	v_mfma_f32_16x16x32_bf16 v[86:89], v[2:5], v[58:61], 0
	v_mfma_f32_16x16x32_bf16 v[66:69], v[2:5], v[34:37], 0
	v_mfma_f32_16x16x32_bf16 v[70:73], v[10:13], v[34:37], 0
	v_mfma_f32_16x16x32_bf16 v[74:77], v[2:5], v[42:45], 0
	v_mfma_f32_16x16x32_bf16 v[78:81], v[10:13], v[42:45], 0
	v_mfma_f32_16x16x32_bf16 v[82:85], v[2:5], v[50:53], 0
	s_waitcnt lgkmcnt(0)
	v_mfma_f32_16x16x32_bf16 v[96:99], v[6:9], v[62:65], v[86:89]
	v_mfma_f32_16x16x32_bf16 v[86:89], v[10:13], v[58:61], 0
	v_mfma_f32_16x16x32_bf16 v[66:69], v[6:9], v[38:41], v[66:69]
	v_mfma_f32_16x16x32_bf16 v[70:73], v[14:17], v[38:41], v[70:73]
	v_mfma_f32_16x16x32_bf16 v[74:77], v[6:9], v[46:49], v[74:77]
	v_mfma_f32_16x16x32_bf16 v[78:81], v[14:17], v[46:49], v[78:81]
	v_mfma_f32_16x16x32_bf16 v[82:85], v[6:9], v[54:57], v[82:85]
	v_mfma_f32_16x16x32_bf16 v[104:107], v[14:17], v[62:65], v[86:89]
	s_setprio 0
	s_setprio 1
	v_mfma_f32_16x16x32_bf16 v[86:89], v[18:21], v[34:37], 0
	v_mfma_f32_16x16x32_bf16 v[34:37], v[26:29], v[34:37], 0
	v_mfma_f32_16x16x32_bf16 v[116:119], v[30:33], v[38:41], v[34:37]
	v_mfma_f32_16x16x32_bf16 v[34:37], v[18:21], v[42:45], 0
	v_mfma_f32_16x16x32_bf16 v[132:135], v[22:25], v[46:49], v[34:37]
	v_mfma_f32_16x16x32_bf16 v[34:37], v[26:29], v[42:45], 0
	v_mfma_f32_16x16x32_bf16 v[108:111], v[22:25], v[38:41], v[86:89]
	v_mfma_f32_16x16x32_bf16 v[40:43], v[30:33], v[46:49], v[34:37]
	v_mfma_f32_16x16x32_bf16 v[34:37], v[18:21], v[50:53], 0
	v_mfma_f32_16x16x32_bf16 v[44:47], v[22:25], v[54:57], v[34:37]
	v_mfma_f32_16x16x32_bf16 v[34:37], v[26:29], v[50:53], 0
	v_mfma_f32_16x16x32_bf16 v[48:51], v[30:33], v[54:57], v[34:37]
	v_mfma_f32_16x16x32_bf16 v[34:37], v[18:21], v[58:61], 0
	v_mfma_f32_16x16x32_bf16 v[52:55], v[22:25], v[62:65], v[34:37]
	v_mfma_f32_16x16x32_bf16 v[34:37], v[26:29], v[58:61], 0
	v_mfma_f32_16x16x32_bf16 v[60:63], v[30:33], v[62:65], v[34:37]
	s_setprio 0
	s_cmp_lg_u32 s100, 0
	s_cbranch_scc1 .Lhb_4
	s_barrier
.Lhb_4:
	s_mov_b32 m0, s92
	s_nop 3
	ds_read_b128 v[34:37], v149 offset:16384
	ds_read_b128 v[56:59], v149 offset:17408
	ds_read_b128 v[86:89], v149 offset:18432
	ds_read_b128 v[100:103], v149 offset:19456
	ds_read_b128 v[112:115], v149 offset:20480
	ds_read_b128 v[120:123], v149 offset:21504
	ds_read_b128 v[124:127], v149 offset:22528
	ds_read_b128 v[128:131], v149 offset:23552
	buffer_load_dwordx4 v145, s[4:7], s10 offen lds
	s_mov_b32 m0, s93
	s_nop 0
	buffer_load_dwordx4 v147, s[4:7], s10 offen lds
	s_or_b32 s10, s69, 0x40100
	s_mov_b32 m0, s94
	s_nop 0
	buffer_load_dwordx4 v145, s[4:7], s10 offen lds
	s_mov_b32 m0, s95
	s_nop 0
	buffer_load_dwordx4 v147, s[4:7], s10 offen lds
	s_mov_b32 m0, s44
	s_nop 0
	buffer_load_dwordx4 v144, s[0:3], s9 offen lds
	s_mov_b32 m0, s36
	s_nop 0
	buffer_load_dwordx4 v146, s[0:3], s9 offen lds
	s_waitcnt vmcnt(24)
	s_waitcnt lgkmcnt(0)
	s_cmp_eq_u32 s100, 0
	s_cbranch_scc1 .Lhb_1
	s_barrier
.Lhb_1:
	s_setprio 1
	s_waitcnt lgkmcnt(7)
	v_mfma_f32_16x16x32_bf16 v[136:139], v[2:5], v[34:37], 0
	s_waitcnt lgkmcnt(5)
	v_mfma_f32_16x16x32_bf16 v[154:157], v[2:5], v[86:89], 0
	s_waitcnt lgkmcnt(3)
	v_mfma_f32_16x16x32_bf16 v[162:165], v[2:5], v[112:115], 0
	s_waitcnt lgkmcnt(1)
	v_mfma_f32_16x16x32_bf16 v[2:5], v[2:5], v[124:127], 0
	v_mfma_f32_16x16x32_bf16 v[136:139], v[6:9], v[56:59], v[136:139]
	v_mfma_f32_16x16x32_bf16 v[140:143], v[10:13], v[34:37], 0
	v_mfma_f32_16x16x32_bf16 v[154:157], v[6:9], v[100:103], v[154:157]
	v_mfma_f32_16x16x32_bf16 v[158:161], v[10:13], v[86:89], 0
	v_mfma_f32_16x16x32_bf16 v[162:165], v[6:9], v[120:123], v[162:165]
	v_mfma_f32_16x16x32_bf16 v[166:169], v[10:13], v[112:115], 0
	s_waitcnt lgkmcnt(0)
	v_mfma_f32_16x16x32_bf16 v[2:5], v[6:9], v[128:131], v[2:5]
	v_mfma_f32_16x16x32_bf16 v[6:9], v[10:13], v[124:127], 0
	v_mfma_f32_16x16x32_bf16 v[140:143], v[14:17], v[56:59], v[140:143]
	v_mfma_f32_16x16x32_bf16 v[158:161], v[14:17], v[100:103], v[158:161]
	v_mfma_f32_16x16x32_bf16 v[166:169], v[14:17], v[120:123], v[166:169]
	v_mfma_f32_16x16x32_bf16 v[170:173], v[14:17], v[128:131], v[6:9]
	s_setprio 0
	s_setprio 1
	v_mfma_f32_16x16x32_bf16 v[6:9], v[18:21], v[34:37], 0
	v_mfma_f32_16x16x32_bf16 v[174:177], v[22:25], v[56:59], v[6:9]
	v_mfma_f32_16x16x32_bf16 v[6:9], v[26:29], v[34:37], 0
	v_mfma_f32_16x16x32_bf16 v[178:181], v[30:33], v[56:59], v[6:9]
	v_mfma_f32_16x16x32_bf16 v[6:9], v[18:21], v[86:89], 0
	v_mfma_f32_16x16x32_bf16 v[182:185], v[22:25], v[100:103], v[6:9]
	v_mfma_f32_16x16x32_bf16 v[6:9], v[26:29], v[86:89], 0
	v_mfma_f32_16x16x32_bf16 v[186:189], v[30:33], v[100:103], v[6:9]
	v_mfma_f32_16x16x32_bf16 v[6:9], v[18:21], v[112:115], 0
	v_mfma_f32_16x16x32_bf16 v[190:193], v[22:25], v[120:123], v[6:9]
	v_mfma_f32_16x16x32_bf16 v[6:9], v[26:29], v[112:115], 0
	v_mfma_f32_16x16x32_bf16 v[212:215], v[30:33], v[120:123], v[6:9]
	v_mfma_f32_16x16x32_bf16 v[6:9], v[18:21], v[124:127], 0
	v_mfma_f32_16x16x32_bf16 v[20:23], v[22:25], v[128:131], v[6:9]
	v_mfma_f32_16x16x32_bf16 v[6:9], v[26:29], v[124:127], 0
	v_mfma_f32_16x16x32_bf16 v[216:219], v[30:33], v[128:131], v[6:9]
	s_setprio 0
	s_cmp_lg_u32 s100, 0
	s_cbranch_scc1 .Lhb_5
	s_barrier
.Lhb_5:
	s_nop 4
	ds_read_b128 v[6:9], v152
	ds_read_b128 v[24:27], v152 offset:1024
	ds_read_b128 v[228:231], v152 offset:2048
	ds_read_b128 v[232:235], v152 offset:3072
	ds_read_b128 v[236:239], v153
	ds_read_b128 v[240:243], v153 offset:1024
	ds_read_b128 v[244:247], v153 offset:2048
	ds_read_b128 v[150:153], v153 offset:3072
	s_or_b32 s9, s68, 0x40100
	s_mov_b32 m0, s37
	ds_read_b128 v[10:13], v149 offset:32768
	ds_read_b128 v[14:17], v149 offset:33792
	ds_read_b128 v[32:35], v149 offset:34816
	ds_read_b128 v[194:197], v149 offset:35840
	ds_read_b128 v[208:211], v149 offset:36864
	ds_read_b128 v[200:203], v149 offset:37888
	ds_read_b128 v[204:207], v149 offset:38912
	ds_read_b128 v[220:223], v149 offset:39936
	buffer_load_dwordx4 v144, s[0:3], s9 offen lds
	s_mov_b32 m0, s38
	s_nop 0
	buffer_load_dwordx4 v146, s[0:3], s9 offen lds
	s_waitcnt vmcnt(8)
	s_waitcnt lgkmcnt(0)
	s_cmp_eq_u32 s100, 0
	s_cbranch_scc1 .Lhb_2
	s_barrier
.Lhb_2:
	s_setprio 1
	s_waitcnt lgkmcnt(7)
	v_mfma_f32_16x16x32_bf16 v[28:31], v[6:9], v[10:13], v[66:69]
	s_waitcnt lgkmcnt(6)
	v_mfma_f32_16x16x32_bf16 v[120:123], v[24:27], v[14:17], v[28:31]
	v_mfma_f32_16x16x32_bf16 v[28:31], v[228:231], v[10:13], v[70:73]
	v_mfma_f32_16x16x32_bf16 v[112:115], v[232:235], v[14:17], v[28:31]
	s_waitcnt lgkmcnt(5)
	v_mfma_f32_16x16x32_bf16 v[28:31], v[6:9], v[32:35], v[74:77]
	s_waitcnt lgkmcnt(4)
	v_mfma_f32_16x16x32_bf16 v[100:103], v[24:27], v[194:197], v[28:31]
	v_mfma_f32_16x16x32_bf16 v[28:31], v[228:231], v[32:35], v[78:81]
	v_mfma_f32_16x16x32_bf16 v[88:91], v[232:235], v[194:197], v[28:31]
	s_waitcnt lgkmcnt(3)
	v_mfma_f32_16x16x32_bf16 v[28:31], v[6:9], v[208:211], v[82:85]
	s_waitcnt lgkmcnt(2)
	v_mfma_f32_16x16x32_bf16 v[68:71], v[24:27], v[200:203], v[28:31]
	v_mfma_f32_16x16x32_bf16 v[28:31], v[228:231], v[208:211], v[92:95]
	v_mfma_f32_16x16x32_bf16 v[56:59], v[232:235], v[200:203], v[28:31]
	s_waitcnt lgkmcnt(1)
	v_mfma_f32_16x16x32_bf16 v[28:31], v[6:9], v[204:207], v[96:99]
	s_waitcnt lgkmcnt(0)
	v_mfma_f32_16x16x32_bf16 v[36:39], v[24:27], v[220:223], v[28:31]
	v_mfma_f32_16x16x32_bf16 v[28:31], v[228:231], v[204:207], v[104:107]
	v_mfma_f32_16x16x32_bf16 v[28:31], v[232:235], v[220:223], v[28:31]
	s_setprio 0
	s_setprio 1
	v_mfma_f32_16x16x32_bf16 v[64:67], v[236:239], v[10:13], v[108:111]
	v_mfma_f32_16x16x32_bf16 v[10:13], v[244:247], v[10:13], v[116:119]
	v_mfma_f32_16x16x32_bf16 v[124:127], v[150:153], v[14:17], v[10:13]
	v_mfma_f32_16x16x32_bf16 v[10:13], v[236:239], v[32:35], v[132:135]
	v_mfma_f32_16x16x32_bf16 v[116:119], v[240:243], v[194:197], v[10:13]
	v_mfma_f32_16x16x32_bf16 v[10:13], v[244:247], v[32:35], v[40:43]
	v_mfma_f32_16x16x32_bf16 v[108:111], v[150:153], v[194:197], v[10:13]
	v_mfma_f32_16x16x32_bf16 v[10:13], v[236:239], v[208:211], v[44:47]
	v_mfma_f32_16x16x32_bf16 v[92:95], v[240:243], v[200:203], v[10:13]
	v_mfma_f32_16x16x32_bf16 v[10:13], v[244:247], v[208:211], v[48:51]
	v_mfma_f32_16x16x32_bf16 v[80:83], v[150:153], v[200:203], v[10:13]
	v_mfma_f32_16x16x32_bf16 v[10:13], v[236:239], v[204:207], v[52:55]
	v_mfma_f32_16x16x32_bf16 v[128:131], v[240:243], v[14:17], v[64:67]
	v_mfma_f32_16x16x32_bf16 v[64:67], v[240:243], v[220:223], v[10:13]
	v_mfma_f32_16x16x32_bf16 v[10:13], v[244:247], v[204:207], v[60:63]
	v_mfma_f32_16x16x32_bf16 v[48:51], v[150:153], v[220:223], v[10:13]
	s_setprio 0
	s_cmp_lg_u32 s100, 0
	s_cbranch_scc1 .Lhb_6
	s_barrier
.Lhb_6:
	s_mov_b32 m0, s39
	s_or_b32 s9, s69, 0x180
	ds_read_b128 v[44:47], v149 offset:49152
	ds_read_b128 v[52:55], v149 offset:50176
	ds_read_b128 v[76:79], v149 offset:51200
	ds_read_b128 v[132:135], v149 offset:52224
	ds_read_b128 v[194:197], v149 offset:53248
	ds_read_b128 v[200:203], v149 offset:54272
	ds_read_b128 v[204:207], v149 offset:55296
	ds_read_b128 v[208:211], v149 offset:56320
	buffer_load_dwordx4 v145, s[4:7], s9 offen lds
	s_mov_b32 m0, s40
	s_nop 0
	buffer_load_dwordx4 v147, s[4:7], s9 offen lds
	s_or_b32 s9, s69, 0x40180
	s_mov_b32 m0, s43
	s_nop 0
	buffer_load_dwordx4 v145, s[4:7], s9 offen lds
	s_mov_b32 m0, s42
	s_nop 0
	buffer_load_dwordx4 v147, s[4:7], s9 offen lds
	s_mov_b32 m0, s41
	s_nop 0
	buffer_load_dwordx4 v144, s[0:3], s8 offen lds
	s_mov_b32 m0, s33
	s_nop 0
	buffer_load_dwordx4 v146, s[0:3], s8 offen lds
	s_waitcnt vmcnt(8)
	s_waitcnt lgkmcnt(0)
	s_cmp_eq_u32 s100, 0
	s_cbranch_scc1 .Lhb_3
	s_barrier
.Lhb_3:
	s_setprio 1
	s_waitcnt lgkmcnt(7)
	v_mfma_f32_16x16x32_bf16 v[10:13], v[6:9], v[44:47], v[136:139]
	s_waitcnt lgkmcnt(6)
	v_mfma_f32_16x16x32_bf16 v[72:75], v[24:27], v[52:55], v[10:13]
	v_mfma_f32_16x16x32_bf16 v[10:13], v[228:231], v[44:47], v[140:143]
	v_mfma_f32_16x16x32_bf16 v[60:63], v[232:235], v[52:55], v[10:13]
	s_waitcnt lgkmcnt(5)
	v_mfma_f32_16x16x32_bf16 v[10:13], v[6:9], v[76:79], v[154:157]
	s_waitcnt lgkmcnt(4)
	v_mfma_f32_16x16x32_bf16 v[40:43], v[24:27], v[132:135], v[10:13]
	v_mfma_f32_16x16x32_bf16 v[10:13], v[228:231], v[76:79], v[158:161]
	v_mfma_f32_16x16x32_bf16 v[32:35], v[232:235], v[132:135], v[10:13]
	s_waitcnt lgkmcnt(3)
	v_mfma_f32_16x16x32_bf16 v[10:13], v[6:9], v[194:197], v[162:165]
	s_waitcnt lgkmcnt(2)
	v_mfma_f32_16x16x32_bf16 v[16:19], v[24:27], v[200:203], v[10:13]
	v_mfma_f32_16x16x32_bf16 v[10:13], v[228:231], v[194:197], v[166:169]
	s_waitcnt lgkmcnt(1)
	v_mfma_f32_16x16x32_bf16 v[2:5], v[6:9], v[204:207], v[2:5]
	v_mfma_f32_16x16x32_bf16 v[12:15], v[232:235], v[200:203], v[10:13]
	s_waitcnt lgkmcnt(0)
	v_mfma_f32_16x16x32_bf16 v[8:11], v[24:27], v[208:211], v[2:5]
	v_mfma_f32_16x16x32_bf16 v[2:5], v[228:231], v[204:207], v[170:173]
	v_mfma_f32_16x16x32_bf16 v[4:7], v[232:235], v[208:211], v[2:5]
	s_setprio 0
	s_setprio 1
	v_mfma_f32_16x16x32_bf16 v[24:27], v[236:239], v[44:47], v[174:177]
	v_mfma_f32_16x16x32_bf16 v[96:99], v[240:243], v[52:55], v[24:27]
	v_mfma_f32_16x16x32_bf16 v[24:27], v[244:247], v[44:47], v[178:181]
	v_mfma_f32_16x16x32_bf16 v[104:107], v[150:153], v[52:55], v[24:27]
	v_mfma_f32_16x16x32_bf16 v[24:27], v[236:239], v[76:79], v[182:185]
	v_mfma_f32_16x16x32_bf16 v[84:87], v[240:243], v[132:135], v[24:27]
	v_mfma_f32_16x16x32_bf16 v[24:27], v[244:247], v[76:79], v[186:189]
	v_mfma_f32_16x16x32_bf16 v[76:79], v[150:153], v[132:135], v[24:27]
	v_mfma_f32_16x16x32_bf16 v[24:27], v[236:239], v[194:197], v[190:193]
	v_mfma_f32_16x16x32_bf16 v[52:55], v[240:243], v[200:203], v[24:27]
	v_mfma_f32_16x16x32_bf16 v[24:27], v[244:247], v[194:197], v[212:215]
	v_mfma_f32_16x16x32_bf16 v[20:23], v[236:239], v[204:207], v[20:23]
	v_mfma_f32_16x16x32_bf16 v[44:47], v[150:153], v[200:203], v[24:27]
	v_mfma_f32_16x16x32_bf16 v[24:27], v[240:243], v[208:211], v[20:23]
	v_mfma_f32_16x16x32_bf16 v[20:23], v[244:247], v[204:207], v[216:219]
	v_mfma_f32_16x16x32_bf16 v[20:23], v[150:153], v[208:211], v[20:23]
	s_setprio 0
	s_cmp_lg_u32 s100, 0
	s_cbranch_scc1 .Lhb_7
	s_barrier
.Lhb_7:
	s_mov_b64 s[8:9], 0
	v_mov_b64_e32 v[234:235], v[198:199]
	v_mov_b64_e32 v[236:237], v[226:227]
	v_mov_b32_e32 v198, v0
	v_mov_b32_e32 v226, v225
	v_mov_b64_e32 v[244:245], 0x100
	v_mov_b64_e32 v[246:247], 0xff

.LBB0_391:
	v_add_u32_e32 v150, 0x10000, v148
	v_add_u32_e32 v151, 0x14000, v148
	ds_read_b128 v[132:135], v150
	ds_read_b128 v[136:139], v150 offset:1024
	ds_read_b128 v[140:143], v150 offset:2048
	ds_read_b128 v[152:155], v150 offset:3072
	ds_read_b128 v[156:159], v151
	ds_read_b128 v[160:163], v151 offset:1024
	ds_read_b128 v[164:167], v151 offset:2048
	ds_read_b128 v[168:171], v151 offset:3072
	s_add_i32 s12, s56, 0xfffc0080
	s_cmp_eq_u32 s29, 12
	s_cselect_b32 s60, s68, s12
	s_cselect_b32 s13, s5, s77
	s_cselect_b32 s12, s4, s76
	s_cselect_b32 s15, s7, s55
	s_cselect_b32 s14, s6, s54
	s_cselect_b32 s58, s69, s57
	s_cselect_b32 s16, s0, s8
	s_cselect_b32 s17, s1, s9
	s_cselect_b32 s18, s2, s10
	s_cselect_b32 s19, s3, s11
	s_or_b32 s59, s60, 0x80
	s_mov_b32 m0, s45
	ds_read_b128 v[172:175], v149
	ds_read_b128 v[176:179], v149 offset:1024
	ds_read_b128 v[180:183], v149 offset:2048
	ds_read_b128 v[184:187], v149 offset:3072
	ds_read_b128 v[188:191], v149 offset:4096
	ds_read_b128 v[212:215], v149 offset:5120
	ds_read_b128 v[216:219], v149 offset:6144
	ds_read_b128 v[228:231], v149 offset:7168
	buffer_load_dwordx4 v144, s[8:11], s56 offen lds
	s_mov_b32 m0, s46
	s_nop 0
	buffer_load_dwordx4 v146, s[8:11], s56 offen lds
	s_waitcnt vmcnt(8)
	s_waitcnt lgkmcnt(0)
	s_cmp_eq_u32 s100, 0
	s_cbranch_scc1 .Lhb_8
	s_barrier
.Lhb_8:
	s_setprio 1
	s_waitcnt lgkmcnt(7)
	v_mfma_f32_16x16x32_bf16 v[120:123], v[132:135], v[172:175], v[120:123]
	v_mfma_f32_16x16x32_bf16 v[112:115], v[140:143], v[172:175], v[112:115]
	s_waitcnt lgkmcnt(5)
	v_mfma_f32_16x16x32_bf16 v[100:103], v[132:135], v[180:183], v[100:103]
	v_mfma_f32_16x16x32_bf16 v[88:91], v[140:143], v[180:183], v[88:91]
	s_waitcnt lgkmcnt(3)
	v_mfma_f32_16x16x32_bf16 v[68:71], v[132:135], v[188:191], v[68:71]
	v_mfma_f32_16x16x32_bf16 v[56:59], v[140:143], v[188:191], v[56:59]
	s_waitcnt lgkmcnt(1)
	v_mfma_f32_16x16x32_bf16 v[36:39], v[132:135], v[216:219], v[36:39]
	v_mfma_f32_16x16x32_bf16 v[28:31], v[140:143], v[216:219], v[28:31]
	v_mfma_f32_16x16x32_bf16 v[120:123], v[136:139], v[176:179], v[120:123]
	v_mfma_f32_16x16x32_bf16 v[112:115], v[152:155], v[176:179], v[112:115]
	v_mfma_f32_16x16x32_bf16 v[100:103], v[136:139], v[184:187], v[100:103]
	v_mfma_f32_16x16x32_bf16 v[88:91], v[152:155], v[184:187], v[88:91]
	v_mfma_f32_16x16x32_bf16 v[68:71], v[136:139], v[212:215], v[68:71]
	v_mfma_f32_16x16x32_bf16 v[56:59], v[152:155], v[212:215], v[56:59]
	s_waitcnt lgkmcnt(0)
	v_mfma_f32_16x16x32_bf16 v[36:39], v[136:139], v[228:231], v[36:39]
	v_mfma_f32_16x16x32_bf16 v[28:31], v[152:155], v[228:231], v[28:31]
	s_setprio 0
	s_setprio 1
	v_mfma_f32_16x16x32_bf16 v[128:131], v[156:159], v[172:175], v[128:131]
	v_mfma_f32_16x16x32_bf16 v[124:127], v[164:167], v[172:175], v[124:127]
	v_mfma_f32_16x16x32_bf16 v[116:119], v[156:159], v[180:183], v[116:119]
	v_mfma_f32_16x16x32_bf16 v[108:111], v[164:167], v[180:183], v[108:111]
	v_mfma_f32_16x16x32_bf16 v[92:95], v[156:159], v[188:191], v[92:95]
	v_mfma_f32_16x16x32_bf16 v[80:83], v[164:167], v[188:191], v[80:83]
	v_mfma_f32_16x16x32_bf16 v[64:67], v[156:159], v[216:219], v[64:67]
	v_mfma_f32_16x16x32_bf16 v[48:51], v[164:167], v[216:219], v[48:51]
	v_mfma_f32_16x16x32_bf16 v[128:131], v[160:163], v[176:179], v[128:131]
	v_mfma_f32_16x16x32_bf16 v[124:127], v[168:171], v[176:179], v[124:127]
	v_mfma_f32_16x16x32_bf16 v[116:119], v[160:163], v[184:187], v[116:119]
	v_mfma_f32_16x16x32_bf16 v[108:111], v[168:171], v[184:187], v[108:111]
	v_mfma_f32_16x16x32_bf16 v[92:95], v[160:163], v[212:215], v[92:95]
	v_mfma_f32_16x16x32_bf16 v[80:83], v[168:171], v[212:215], v[80:83]
	v_mfma_f32_16x16x32_bf16 v[64:67], v[160:163], v[228:231], v[64:67]
	v_mfma_f32_16x16x32_bf16 v[48:51], v[168:171], v[228:231], v[48:51]
	s_setprio 0
	s_cmp_lg_u32 s100, 0
	s_cbranch_scc1 .Lhb_12
	s_barrier
.Lhb_12:
	s_mov_b32 m0, s92
	ds_read_b128 v[172:175], v149 offset:16384
	ds_read_b128 v[176:179], v149 offset:17408
	ds_read_b128 v[180:183], v149 offset:18432
	ds_read_b128 v[184:187], v149 offset:19456
	ds_read_b128 v[188:191], v149 offset:20480
	ds_read_b128 v[212:215], v149 offset:21504
	ds_read_b128 v[216:219], v149 offset:22528
	ds_read_b128 v[228:231], v149 offset:23552
	buffer_load_dwordx4 v145, s[12:15], s58 offen lds
	s_mov_b32 m0, s93
	s_add_i32 s61, s58, 0x40000
	buffer_load_dwordx4 v147, s[12:15], s58 offen lds
	s_mov_b32 m0, s94
	s_nop 0
	buffer_load_dwordx4 v145, s[12:15], s61 offen lds
	s_mov_b32 m0, s95
	s_nop 0
	buffer_load_dwordx4 v147, s[12:15], s61 offen lds
	s_mov_b32 m0, s44
	s_nop 0
	buffer_load_dwordx4 v144, s[16:19], s60 offen lds
	s_mov_b32 m0, s36
	s_nop 0
	buffer_load_dwordx4 v146, s[16:19], s60 offen lds
	s_waitcnt vmcnt(8)
	s_waitcnt lgkmcnt(0)
	s_cmp_eq_u32 s100, 0
	s_cbranch_scc1 .Lhb_9
	s_barrier
.Lhb_9:
	s_setprio 1
	s_waitcnt lgkmcnt(7)
	v_mfma_f32_16x16x32_bf16 v[72:75], v[132:135], v[172:175], v[72:75]
	v_mfma_f32_16x16x32_bf16 v[60:63], v[140:143], v[172:175], v[60:63]
	s_waitcnt lgkmcnt(5)
	v_mfma_f32_16x16x32_bf16 v[40:43], v[132:135], v[180:183], v[40:43]
	v_mfma_f32_16x16x32_bf16 v[32:35], v[140:143], v[180:183], v[32:35]
	s_waitcnt lgkmcnt(3)
	v_mfma_f32_16x16x32_bf16 v[16:19], v[132:135], v[188:191], v[16:19]
	v_mfma_f32_16x16x32_bf16 v[12:15], v[140:143], v[188:191], v[12:15]
	s_waitcnt lgkmcnt(1)
	v_mfma_f32_16x16x32_bf16 v[8:11], v[132:135], v[216:219], v[8:11]
	v_mfma_f32_16x16x32_bf16 v[2:5], v[140:143], v[216:219], v[4:7]
	v_mfma_f32_16x16x32_bf16 v[72:75], v[136:139], v[176:179], v[72:75]
	v_mfma_f32_16x16x32_bf16 v[60:63], v[152:155], v[176:179], v[60:63]
	v_mfma_f32_16x16x32_bf16 v[40:43], v[136:139], v[184:187], v[40:43]
	v_mfma_f32_16x16x32_bf16 v[32:35], v[152:155], v[184:187], v[32:35]
	v_mfma_f32_16x16x32_bf16 v[16:19], v[136:139], v[212:215], v[16:19]
	v_mfma_f32_16x16x32_bf16 v[12:15], v[152:155], v[212:215], v[12:15]
	s_waitcnt lgkmcnt(0)
	v_mfma_f32_16x16x32_bf16 v[8:11], v[136:139], v[228:231], v[8:11]
	v_mfma_f32_16x16x32_bf16 v[2:5], v[152:155], v[228:231], v[2:5]
	s_setprio 0
	s_setprio 1
	v_mfma_f32_16x16x32_bf16 v[96:99], v[156:159], v[172:175], v[96:99]
	v_mfma_f32_16x16x32_bf16 v[104:107], v[164:167], v[172:175], v[104:107]
	v_mfma_f32_16x16x32_bf16 v[84:87], v[156:159], v[180:183], v[84:87]
	v_mfma_f32_16x16x32_bf16 v[76:79], v[164:167], v[180:183], v[76:79]
	v_mfma_f32_16x16x32_bf16 v[52:55], v[156:159], v[188:191], v[52:55]
	v_mfma_f32_16x16x32_bf16 v[44:47], v[164:167], v[188:191], v[44:47]
	v_mfma_f32_16x16x32_bf16 v[24:27], v[156:159], v[216:219], v[24:27]
	v_mfma_f32_16x16x32_bf16 v[20:23], v[164:167], v[216:219], v[20:23]
	v_mfma_f32_16x16x32_bf16 v[96:99], v[160:163], v[176:179], v[96:99]
	v_mfma_f32_16x16x32_bf16 v[104:107], v[168:171], v[176:179], v[104:107]
	v_mfma_f32_16x16x32_bf16 v[84:87], v[160:163], v[184:187], v[84:87]
	v_mfma_f32_16x16x32_bf16 v[76:79], v[168:171], v[184:187], v[76:79]
	v_mfma_f32_16x16x32_bf16 v[52:55], v[160:163], v[212:215], v[52:55]
	v_mfma_f32_16x16x32_bf16 v[44:47], v[168:171], v[212:215], v[44:47]
	v_mfma_f32_16x16x32_bf16 v[24:27], v[160:163], v[228:231], v[24:27]
	v_mfma_f32_16x16x32_bf16 v[20:23], v[168:171], v[228:231], v[20:23]
	s_setprio 0
	s_cmp_lg_u32 s100, 0
	s_cbranch_scc1 .Lhb_13
	s_barrier
.Lhb_13:
	v_add_u32_e32 v152, 0x18000, v148
	v_add_u32_e32 v153, 0x1c000, v148
	ds_read_b128 v[132:135], v152
	ds_read_b128 v[136:139], v152 offset:1024
	ds_read_b128 v[140:143], v152 offset:2048
	ds_read_b128 v[154:157], v152 offset:3072
	ds_read_b128 v[158:161], v153
	ds_read_b128 v[162:165], v153 offset:1024
	ds_read_b128 v[166:169], v153 offset:2048
	ds_read_b128 v[170:173], v153 offset:3072
	s_add_i32 s60, s60, 0x40000
	s_mov_b32 m0, s37
	ds_read_b128 v[174:177], v149 offset:32768
	ds_read_b128 v[178:181], v149 offset:33792
	ds_read_b128 v[182:185], v149 offset:34816
	ds_read_b128 v[186:189], v149 offset:35840
	ds_read_b128 v[190:193], v149 offset:36864
	ds_read_b128 v[212:215], v149 offset:37888
	ds_read_b128 v[216:219], v149 offset:38912
	ds_read_b128 v[228:231], v149 offset:39936
	buffer_load_dwordx4 v144, s[16:19], s60 offen lds
	s_mov_b32 m0, s38
	s_nop 0
	buffer_load_dwordx4 v146, s[16:19], s60 offen lds
	s_waitcnt vmcnt(8)
	s_waitcnt lgkmcnt(0)
	s_cmp_eq_u32 s100, 0
	s_cbranch_scc1 .Lhb_10
	s_barrier
.Lhb_10:
	s_setprio 1
	s_waitcnt lgkmcnt(7)
	v_mfma_f32_16x16x32_bf16 v[120:123], v[132:135], v[174:177], v[120:123]
	v_mfma_f32_16x16x32_bf16 v[112:115], v[140:143], v[174:177], v[112:115]
	s_waitcnt lgkmcnt(5)
	v_mfma_f32_16x16x32_bf16 v[100:103], v[132:135], v[182:185], v[100:103]
	v_mfma_f32_16x16x32_bf16 v[88:91], v[140:143], v[182:185], v[88:91]
	s_waitcnt lgkmcnt(3)
	v_mfma_f32_16x16x32_bf16 v[68:71], v[132:135], v[190:193], v[68:71]
	v_mfma_f32_16x16x32_bf16 v[56:59], v[140:143], v[190:193], v[56:59]
	s_waitcnt lgkmcnt(1)
	v_mfma_f32_16x16x32_bf16 v[36:39], v[132:135], v[216:219], v[36:39]
	v_mfma_f32_16x16x32_bf16 v[28:31], v[140:143], v[216:219], v[28:31]
	v_mfma_f32_16x16x32_bf16 v[120:123], v[136:139], v[178:181], v[120:123]
	v_mfma_f32_16x16x32_bf16 v[112:115], v[154:157], v[178:181], v[112:115]
	v_mfma_f32_16x16x32_bf16 v[100:103], v[136:139], v[186:189], v[100:103]
	v_mfma_f32_16x16x32_bf16 v[88:91], v[154:157], v[186:189], v[88:91]
	v_mfma_f32_16x16x32_bf16 v[68:71], v[136:139], v[212:215], v[68:71]
	v_mfma_f32_16x16x32_bf16 v[56:59], v[154:157], v[212:215], v[56:59]
	s_waitcnt lgkmcnt(0)
	v_mfma_f32_16x16x32_bf16 v[36:39], v[136:139], v[228:231], v[36:39]
	v_mfma_f32_16x16x32_bf16 v[28:31], v[154:157], v[228:231], v[28:31]
	s_setprio 0
	s_setprio 1
	v_mfma_f32_16x16x32_bf16 v[128:131], v[158:161], v[174:177], v[128:131]
	v_mfma_f32_16x16x32_bf16 v[124:127], v[166:169], v[174:177], v[124:127]
	v_mfma_f32_16x16x32_bf16 v[116:119], v[158:161], v[182:185], v[116:119]
	v_mfma_f32_16x16x32_bf16 v[108:111], v[166:169], v[182:185], v[108:111]
	v_mfma_f32_16x16x32_bf16 v[92:95], v[158:161], v[190:193], v[92:95]
	v_mfma_f32_16x16x32_bf16 v[80:83], v[166:169], v[190:193], v[80:83]
	v_mfma_f32_16x16x32_bf16 v[64:67], v[158:161], v[216:219], v[64:67]
	v_mfma_f32_16x16x32_bf16 v[48:51], v[166:169], v[216:219], v[48:51]
	v_mfma_f32_16x16x32_bf16 v[128:131], v[162:165], v[178:181], v[128:131]
	v_mfma_f32_16x16x32_bf16 v[124:127], v[170:173], v[178:181], v[124:127]
	v_mfma_f32_16x16x32_bf16 v[116:119], v[162:165], v[186:189], v[116:119]
	v_mfma_f32_16x16x32_bf16 v[108:111], v[170:173], v[186:189], v[108:111]
	v_mfma_f32_16x16x32_bf16 v[92:95], v[162:165], v[212:215], v[92:95]
	v_mfma_f32_16x16x32_bf16 v[80:83], v[170:173], v[212:215], v[80:83]
	v_mfma_f32_16x16x32_bf16 v[64:67], v[162:165], v[228:231], v[64:67]
	v_mfma_f32_16x16x32_bf16 v[48:51], v[170:173], v[228:231], v[48:51]
	s_setprio 0
	s_cmp_lg_u32 s100, 0
	s_cbranch_scc1 .Lhb_14
	s_barrier
.Lhb_14:
	s_mov_b32 m0, s39
	s_or_b32 s60, s58, 0x80
	ds_read_b128 v[174:177], v149 offset:49152
	ds_read_b128 v[178:181], v149 offset:50176
	ds_read_b128 v[182:185], v149 offset:51200
	ds_read_b128 v[186:189], v149 offset:52224
	ds_read_b128 v[190:193], v149 offset:53248
	ds_read_b128 v[212:215], v149 offset:54272
	ds_read_b128 v[216:219], v149 offset:55296
	ds_read_b128 v[228:231], v149 offset:56320
	buffer_load_dwordx4 v145, s[12:15], s60 offen lds
	s_mov_b32 m0, s40
	s_add_i32 s58, s58, 0x40080
	buffer_load_dwordx4 v147, s[12:15], s60 offen lds
	s_mov_b32 m0, s43
	s_nop 0
	buffer_load_dwordx4 v145, s[12:15], s58 offen lds
	s_mov_b32 m0, s42
	s_nop 0
	buffer_load_dwordx4 v147, s[12:15], s58 offen lds
	s_mov_b32 m0, s41
	s_nop 0
	buffer_load_dwordx4 v144, s[16:19], s59 offen lds
	s_mov_b32 m0, s33
	s_nop 0
	buffer_load_dwordx4 v146, s[16:19], s59 offen lds
	s_waitcnt vmcnt(8)
	s_waitcnt lgkmcnt(0)
	s_cmp_eq_u32 s100, 0
	s_cbranch_scc1 .Lhb_11
	s_barrier
.Lhb_11:
	s_setprio 1
	s_waitcnt lgkmcnt(7)
	v_mfma_f32_16x16x32_bf16 v[72:75], v[132:135], v[174:177], v[72:75]
	v_mfma_f32_16x16x32_bf16 v[60:63], v[140:143], v[174:177], v[60:63]
	s_waitcnt lgkmcnt(5)
	v_mfma_f32_16x16x32_bf16 v[40:43], v[132:135], v[182:185], v[40:43]
	v_mfma_f32_16x16x32_bf16 v[32:35], v[140:143], v[182:185], v[32:35]
	s_waitcnt lgkmcnt(3)
	v_mfma_f32_16x16x32_bf16 v[16:19], v[132:135], v[190:193], v[16:19]
	v_mfma_f32_16x16x32_bf16 v[12:15], v[140:143], v[190:193], v[12:15]
	s_waitcnt lgkmcnt(1)
	v_mfma_f32_16x16x32_bf16 v[6:9], v[132:135], v[216:219], v[8:11]
	v_mfma_f32_16x16x32_bf16 v[2:5], v[140:143], v[216:219], v[2:5]
	v_mfma_f32_16x16x32_bf16 v[72:75], v[136:139], v[178:181], v[72:75]
	v_mfma_f32_16x16x32_bf16 v[60:63], v[154:157], v[178:181], v[60:63]
	v_mfma_f32_16x16x32_bf16 v[40:43], v[136:139], v[186:189], v[40:43]
	v_mfma_f32_16x16x32_bf16 v[32:35], v[154:157], v[186:189], v[32:35]
	v_mfma_f32_16x16x32_bf16 v[16:19], v[136:139], v[212:215], v[16:19]
	v_mfma_f32_16x16x32_bf16 v[12:15], v[154:157], v[212:215], v[12:15]
	s_waitcnt lgkmcnt(0)
	v_mfma_f32_16x16x32_bf16 v[8:11], v[136:139], v[228:231], v[6:9]
	v_mfma_f32_16x16x32_bf16 v[4:7], v[154:157], v[228:231], v[2:5]
	s_setprio 0
	s_setprio 1
	v_mfma_f32_16x16x32_bf16 v[96:99], v[158:161], v[174:177], v[96:99]
	v_mfma_f32_16x16x32_bf16 v[104:107], v[166:169], v[174:177], v[104:107]
	v_mfma_f32_16x16x32_bf16 v[84:87], v[158:161], v[182:185], v[84:87]
	v_mfma_f32_16x16x32_bf16 v[76:79], v[166:169], v[182:185], v[76:79]
	v_mfma_f32_16x16x32_bf16 v[52:55], v[158:161], v[190:193], v[52:55]
	v_mfma_f32_16x16x32_bf16 v[44:47], v[166:169], v[190:193], v[44:47]
	v_mfma_f32_16x16x32_bf16 v[24:27], v[158:161], v[216:219], v[24:27]
	v_mfma_f32_16x16x32_bf16 v[20:23], v[166:169], v[216:219], v[20:23]
	v_mfma_f32_16x16x32_bf16 v[96:99], v[162:165], v[178:181], v[96:99]
	v_mfma_f32_16x16x32_bf16 v[104:107], v[170:173], v[178:181], v[104:107]
	v_mfma_f32_16x16x32_bf16 v[84:87], v[162:165], v[186:189], v[84:87]
	v_mfma_f32_16x16x32_bf16 v[76:79], v[170:173], v[186:189], v[76:79]
	v_mfma_f32_16x16x32_bf16 v[52:55], v[162:165], v[212:215], v[52:55]
	v_mfma_f32_16x16x32_bf16 v[44:47], v[170:173], v[212:215], v[44:47]
	v_mfma_f32_16x16x32_bf16 v[24:27], v[162:165], v[228:231], v[24:27]
	v_mfma_f32_16x16x32_bf16 v[20:23], v[170:173], v[228:231], v[20:23]
	s_setprio 0
	s_cmp_lg_u32 s100, 0
	s_cbranch_scc1 .Lhb_15
	s_barrier
.Lhb_15:
	s_add_i32 s29, s29, 2
	s_addk_i32 s56, 0x100
	s_addk_i32 s57, 0x100
	s_cmp_gt_u32 s29, 13
	s_cbranch_scc0 .LBB0_391
	v_readlane_b32 s8, v251, 45
	v_readlane_b32 s9, v251, 46
	s_and_b64 vcc, exec, s[8:9]
	s_cbranch_vccz .LBB0_394

.LBB0_429:
	s_and_b64 vcc, exec, s[52:53]
	s_mov_b64 s[8:9], -1
	s_cbranch_vccnz .LBB0_383
	v_mov_b32_e32 v225, 1
	v_mov_b32_e32 v0, v198
	v_mov_b64_e32 v[226:227], 0x5bf
	v_mov_b64_e32 v[198:199], 0x5c0
	s_and_b64 vcc, exec, s[50:51]
	s_cbranch_vccnz .LBB0_382
	s_branch .LBB0_382

.LBB0_684:
	s_andn2_b64 vcc, exec, s[0:1]
	s_cbranch_vccnz .LBB0_761
	v_readlane_b32 s0, v253, 5
	v_readlane_b32 s1, v253, 6
	v_mov_b32_e32 v0, v1
	s_andn2_b64 vcc, exec, s[0:1]
	s_cbranch_vccnz .LBB0_709
	v_mbcnt_lo_u32_b32 v0, -1, v0
	v_mbcnt_hi_u32_b32 v2, -1, v0
	v_readlane_b32 s0, v250, 8
	s_mov_b64 s[8:9], s[22:23]
	s_mov_b64 s[2:3], s[22:23]
	v_lshl_add_u32 v3, v2, 4, s0
	v_ashrrev_i32_e32 v0, 31, v3
	v_lshrrev_b32_e32 v0, 22, v0
	v_add_u32_e32 v0, v3, v0
	v_ashrrev_i32_e32 v0, 10, v0
	v_mul_i32_i24_e32 v4, 0x400, v0
	v_sub_u32_e32 v4, v3, v4
	s_waitcnt lgkmcnt(0)
	v_lshrrev_b32_e32 v5, 4, v4
	v_bitop3_b32 v4, v5, v4, 32 bitop3:0x6c
	v_ashrrev_i32_e32 v6, 31, v4
	v_lshrrev_b32_e32 v6, 26, v6
	v_lshlrev_b32_e32 v5, 3, v0
	v_add_u32_e32 v6, v4, v6
	v_and_b32_e32 v5, -16, v5
	v_ashrrev_i32_e32 v7, 6, v6
	v_and_b32_e32 v6, 0xc0, v6
	v_add_u32_e32 v5, v7, v5
	v_sub_u32_e32 v4, v4, v6
	v_lshlrev_b32_e32 v0, 5, v0
	v_ashrrev_i16_sdwa v4, v226, sext(v4) dst_sel:DWORD dst_unused:UNUSED_PAD src0_sel:DWORD src1_sel:BYTE_0
	v_lshlrev_b32_e32 v6, 1, v5
	v_lshrrev_b32_e32 v8, 2, v5
	v_and_b32_e32 v7, 3, v7
	s_mov_b32 s0, 0x3fffe0
	v_and_b32_e32 v0, 32, v0
	v_bfe_i32 v4, v4, 0, 16
	v_and_b32_e32 v6, 24, v6
	v_and_b32_e32 v8, 4, v8
	v_and_or_b32 v7, v5, s0, v7
	v_or3_b32 v6, v7, v8, v6
	v_add_lshl_u32 v4, v0, v4, 1
	v_add_u32_e32 v3, 0x2000, v3
	v_lshl_add_u32 v0, v5, 10, v4
	v_lshl_add_u32 v199, v6, 10, v4
	v_ashrrev_i32_e32 v4, 31, v3
	v_lshrrev_b32_e32 v4, 22, v4
	v_add_u32_e32 v4, v3, v4
	v_ashrrev_i32_e32 v4, 10, v4
	v_mul_i32_i24_e32 v5, 0x400, v4
	v_sub_u32_e32 v3, v3, v5
	v_lshrrev_b32_e32 v5, 4, v3
	v_bitop3_b32 v3, v5, v3, 32 bitop3:0x6c
	v_ashrrev_i32_e32 v6, 31, v3
	v_lshrrev_b32_e32 v6, 26, v6
	v_lshlrev_b32_e32 v5, 3, v4
	v_add_u32_e32 v6, v3, v6
	v_and_b32_e32 v5, -16, v5
	v_ashrrev_i32_e32 v7, 6, v6
	v_add_u32_e32 v5, v7, v5
	v_and_b32_e32 v6, 0xffc0, v6
	v_and_b32_e32 v7, 3, v7
	v_sub_u32_e32 v3, v3, v6
	v_and_or_b32 v7, v5, s0, v7
	v_readlane_b32 s0, v254, 47
	v_lshrrev_b16_e32 v6, 7, v3
	v_readlane_b32 s1, v254, 48
	s_add_u32 s6, s0, 0xd80000
	v_and_b32_e32 v6, 1, v6
	s_addc_u32 s7, s1, 0
	s_mov_b64 s[0:1], s[22:23]
	v_add_u16_e32 v3, v3, v6
	v_lshlrev_b32_e32 v4, 5, v4
	v_ashrrev_i16_sdwa v3, v226, sext(v3) dst_sel:DWORD dst_unused:UNUSED_PAD src0_sel:DWORD src1_sel:BYTE_0
	v_lshlrev_b32_e32 v6, 1, v5
	v_lshrrev_b32_e32 v8, 2, v5
	s_mov_b64 s[76:77], s[6:7]
	s_mov_b64 s[0:1], s[6:7]
	s_mov_b64 s[2:3], s[6:7]
	v_and_b32_e32 v4, 32, v4
	v_bfe_i32 v3, v3, 0, 16
	v_and_b32_e32 v6, 24, v6
	v_and_b32_e32 v8, 4, v8
	s_mov_b32 m0, s92
	v_or3_b32 v6, v7, v8, v6
	v_add_lshl_u32 v3, v4, v3, 1
	s_and_b32 s77, s77, 0xffff
	v_readlane_b32 s0, v253, 35
	v_lshl_add_u32 v215, v6, 10, v3
	s_and_b32 s9, s9, 0xffff
	s_mov_b32 s10, s78
	s_mov_b32 s11, s79
	v_lshl_add_u32 v214, v5, 10, v3
	buffer_load_dwordx4 v199, s[76:79], s0 offen lds
	s_mov_b32 m0, s93
	v_readlane_b32 s2, v250, 9
	buffer_load_dwordx4 v215, s[76:79], s0 offen lds
	s_mov_b32 m0, s94
	v_readlane_b32 s0, v253, 30
	v_readlane_b32 s3, v250, 10
	s_andn2_b64 vcc, exec, s[2:3]
	s_nop 0
	v_cndmask_b32_e64 v3, 0, 1, s[2:3]
	s_nop 0
	buffer_load_dwordx4 v199, s[76:79], s0 offen lds
	s_mov_b32 m0, s95
	s_nop 0
	buffer_load_dwordx4 v215, s[76:79], s0 offen lds
	s_mov_b32 m0, s44
	v_readlane_b32 s0, v253, 33
	s_nop 4
	buffer_load_dwordx4 v0, s[8:11], s0 offen lds
	s_mov_b32 m0, s36
	s_nop 0
	buffer_load_dwordx4 v214, s[8:11], s0 offen lds
	s_mov_b32 m0, s37
	v_readlane_b32 s0, v253, 31
	s_nop 4
	buffer_load_dwordx4 v0, s[8:11], s0 offen lds
	s_mov_b32 m0, s38
	s_nop 0
	buffer_load_dwordx4 v214, s[8:11], s0 offen lds
	v_cmp_ne_u32_e64 s[0:1], 1, v3
	s_cbranch_vccnz .LBB0_688
.LBB0_688:
	s_mov_b32 m0, s39
	v_readlane_b32 s2, v253, 32
	s_waitcnt vmcnt(2)
	s_barrier
	s_mov_b32 s10, s78
	s_mov_b32 s11, s79
	v_and_b32_e32 v3, 15, v2
	s_nop 0
	buffer_load_dwordx4 v199, s[76:79], s2 offen lds
	s_mov_b32 m0, s40
	v_and_b32_e32 v5, 48, v2
	buffer_load_dwordx4 v215, s[76:79], s2 offen lds
	s_mov_b32 m0, s41
	v_readlane_b32 s2, v253, 34
	v_lshlrev_b32_e32 v2, 2, v2
	v_and_b32_e32 v2, 32, v2
	s_mov_b32 s50, 0
	v_readlane_b32 s20, v253, 29
	v_readlane_b32 s21, v253, 28
	buffer_load_dwordx4 v0, s[8:11], s2 offen lds
	s_mov_b32 m0, s33
	s_mov_b64 s[34:35], s[78:79]
	buffer_load_dwordx4 v214, s[8:11], s2 offen lds
	s_mov_b32 m0, s43
	v_readlane_b32 s2, v253, 36
	v_readlane_b32 s12, v253, 35
	s_mov_b64 s[10:11], s[78:79]
	v_readlane_b32 s13, v253, 33
	s_nop 1
	buffer_load_dwordx4 v199, s[76:79], s2 offen lds
	s_mov_b32 m0, s42
	s_nop 0
	buffer_load_dwordx4 v215, s[76:79], s2 offen lds
	v_readlane_b32 s2, v250, 1
	s_waitcnt vmcnt(6)
	s_barrier
	s_nop 0
	v_or_b32_e32 v4, s2, v3
	v_lshlrev_b32_e32 v6, 6, v4
	s_movk_i32 s2, 0x3c0
	v_lshlrev_b32_e32 v4, 2, v4
	v_and_or_b32 v6, v6, s2, v5
	v_and_b32_e32 v4, 32, v4
	v_readlane_b32 s2, v250, 2
	v_lshl_or_b32 v3, v3, 6, v5
	s_nop 0
	v_bitop3_b32 v4, v6, s2, v4 bitop3:0xde
	v_readlane_b32 s2, v253, 4
	v_add_u32_e32 v217, 0, v4
	s_nop 0
	v_bitop3_b32 v2, v3, s2, v2 bitop3:0xde
	v_add_u32_e32 v216, 0, v2
	s_branch .LBB0_691

.LBB0_702:
	v_add_u32_e32 v70, 0x10000, v216
	v_add_u32_e32 v118, 0x14000, v216
	ds_read_b128 v[34:37], v70
	ds_read_b128 v[46:49], v70 offset:1024
	ds_read_b128 v[58:61], v70 offset:2048
	ds_read_b128 v[70:73], v70 offset:3072
	ds_read_b128 v[82:85], v118
	ds_read_b128 v[94:97], v118 offset:1024
	ds_read_b128 v[106:109], v118 offset:2048
	ds_read_b128 v[118:121], v118 offset:3072
	s_add_i32 s12, s55, 0xfffe0080
	s_cmp_eq_u32 s57, 4
	s_cselect_b32 s60, s53, s12
	s_cselect_b32 s13, s29, s77
	s_cselect_b32 s12, s28, s76
	s_cselect_b32 s15, s31, s35
	s_cselect_b32 s14, s30, s34
	s_cselect_b32 s58, s54, s56
	s_cselect_b32 s16, s2, s8
	s_cselect_b32 s17, s3, s9
	s_cselect_b32 s18, s26, s10
	s_cselect_b32 s19, s27, s11
	s_or_b32 s59, s60, 0x80
	s_mov_b32 m0, s45
	s_waitcnt vmcnt(14)
	ds_read_b128 v[130:133], v217
	ds_read_b128 v[142:145], v217 offset:1024
	ds_read_b128 v[154:157], v217 offset:2048
	ds_read_b128 v[166:169], v217 offset:3072
	ds_read_b128 v[174:177], v217 offset:4096
	ds_read_b128 v[182:185], v217 offset:5120
	ds_read_b128 v[186:189], v217 offset:6144
	ds_read_b128 v[190:193], v217 offset:7168
	buffer_load_dwordx4 v0, s[8:11], s55 offen lds
	s_mov_b32 m0, s46
	s_nop 0
	buffer_load_dwordx4 v214, s[8:11], s55 offen lds
	s_waitcnt vmcnt(8)
	s_waitcnt lgkmcnt(0)
	s_cmp_eq_u32 s100, 0
	s_cbranch_scc1 .Lhb_16
	s_barrier
.Lhb_16:
	s_setprio 1
	s_waitcnt lgkmcnt(7)
	v_mfma_f32_16x16x32_bf16 v[178:181], v[34:37], v[130:133], v[178:181]
	v_mfma_f32_16x16x32_bf16 v[170:173], v[58:61], v[130:133], v[170:173]
	s_waitcnt lgkmcnt(5)
	v_mfma_f32_16x16x32_bf16 v[150:153], v[34:37], v[154:157], v[150:153]
	v_mfma_f32_16x16x32_bf16 v[146:149], v[58:61], v[154:157], v[146:149]
	s_waitcnt lgkmcnt(3)
	v_mfma_f32_16x16x32_bf16 v[126:129], v[34:37], v[174:177], v[126:129]
	v_mfma_f32_16x16x32_bf16 v[122:125], v[58:61], v[174:177], v[122:125]
	s_waitcnt lgkmcnt(1)
	v_mfma_f32_16x16x32_bf16 v[102:105], v[34:37], v[186:189], v[102:105]
	v_mfma_f32_16x16x32_bf16 v[98:101], v[58:61], v[186:189], v[98:101]
	v_mfma_f32_16x16x32_bf16 v[178:181], v[46:49], v[142:145], v[178:181]
	v_mfma_f32_16x16x32_bf16 v[170:173], v[70:73], v[142:145], v[170:173]
	v_mfma_f32_16x16x32_bf16 v[150:153], v[46:49], v[166:169], v[150:153]
	v_mfma_f32_16x16x32_bf16 v[146:149], v[70:73], v[166:169], v[146:149]
	v_mfma_f32_16x16x32_bf16 v[126:129], v[46:49], v[182:185], v[126:129]
	v_mfma_f32_16x16x32_bf16 v[122:125], v[70:73], v[182:185], v[122:125]
	s_waitcnt lgkmcnt(0)
	v_mfma_f32_16x16x32_bf16 v[102:105], v[46:49], v[190:193], v[102:105]
	v_mfma_f32_16x16x32_bf16 v[98:101], v[70:73], v[190:193], v[98:101]
	s_setprio 0
	s_setprio 1
	v_mfma_f32_16x16x32_bf16 v[162:165], v[82:85], v[130:133], v[162:165]
	v_mfma_f32_16x16x32_bf16 v[138:141], v[82:85], v[154:157], v[138:141]
	v_mfma_f32_16x16x32_bf16 v[134:137], v[106:109], v[154:157], v[134:137]
	v_mfma_f32_16x16x32_bf16 v[114:117], v[82:85], v[174:177], v[114:117]
	v_mfma_f32_16x16x32_bf16 v[110:113], v[106:109], v[174:177], v[110:113]
	v_mfma_f32_16x16x32_bf16 v[90:93], v[82:85], v[186:189], v[90:93]
	v_mfma_f32_16x16x32_bf16 v[86:89], v[106:109], v[186:189], v[86:89]
	v_mfma_f32_16x16x32_bf16 v[162:165], v[94:97], v[142:145], v[162:165]
	v_mfma_f32_16x16x32_bf16 v[130:133], v[106:109], v[130:133], v[158:161]
	v_mfma_f32_16x16x32_bf16 v[138:141], v[94:97], v[166:169], v[138:141]
	v_mfma_f32_16x16x32_bf16 v[134:137], v[118:121], v[166:169], v[134:137]
	v_mfma_f32_16x16x32_bf16 v[114:117], v[94:97], v[182:185], v[114:117]
	v_mfma_f32_16x16x32_bf16 v[110:113], v[118:121], v[182:185], v[110:113]
	v_mfma_f32_16x16x32_bf16 v[90:93], v[94:97], v[190:193], v[90:93]
	v_mfma_f32_16x16x32_bf16 v[86:89], v[118:121], v[190:193], v[86:89]
	v_mfma_f32_16x16x32_bf16 v[130:133], v[118:121], v[142:145], v[130:133]
	s_setprio 0
	s_cmp_lg_u32 s100, 0
	s_cbranch_scc1 .Lhb_20
	s_barrier
.Lhb_20:
	s_mov_b32 m0, s92
	ds_read_b128 v[142:145], v217 offset:16384
	ds_read_b128 v[154:157], v217 offset:17408
	ds_read_b128 v[158:161], v217 offset:18432
	ds_read_b128 v[166:169], v217 offset:19456
	ds_read_b128 v[174:177], v217 offset:20480
	ds_read_b128 v[182:185], v217 offset:21504
	ds_read_b128 v[186:189], v217 offset:22528
	ds_read_b128 v[190:193], v217 offset:23552
	buffer_load_dwordx4 v199, s[12:15], s58 offen lds
	s_mov_b32 m0, s93
	s_add_i32 s61, s58, 0x20000
	buffer_load_dwordx4 v215, s[12:15], s58 offen lds
	s_mov_b32 m0, s94
	s_nop 0
	buffer_load_dwordx4 v199, s[12:15], s61 offen lds
	s_mov_b32 m0, s95
	s_nop 0
	buffer_load_dwordx4 v215, s[12:15], s61 offen lds
	s_mov_b32 m0, s44
	s_nop 0
	buffer_load_dwordx4 v0, s[16:19], s60 offen lds
	s_mov_b32 m0, s36
	s_nop 0
	buffer_load_dwordx4 v214, s[16:19], s60 offen lds
	s_waitcnt vmcnt(8)
	s_waitcnt lgkmcnt(0)
	s_cmp_eq_u32 s100, 0
	s_cbranch_scc1 .Lhb_17
	s_barrier
.Lhb_17:
	s_setprio 1
	s_waitcnt lgkmcnt(7)
	v_mfma_f32_16x16x32_bf16 v[78:81], v[34:37], v[142:145], v[78:81]
	v_mfma_f32_16x16x32_bf16 v[74:77], v[58:61], v[142:145], v[74:77]
	s_waitcnt lgkmcnt(5)
	v_mfma_f32_16x16x32_bf16 v[54:57], v[34:37], v[158:161], v[54:57]
	v_mfma_f32_16x16x32_bf16 v[50:53], v[58:61], v[158:161], v[50:53]
	s_waitcnt lgkmcnt(3)
	v_mfma_f32_16x16x32_bf16 v[30:33], v[34:37], v[174:177], v[30:33]
	v_mfma_f32_16x16x32_bf16 v[26:29], v[58:61], v[174:177], v[26:29]
	s_waitcnt lgkmcnt(1)
	v_mfma_f32_16x16x32_bf16 v[14:17], v[34:37], v[186:189], v[14:17]
	v_mfma_f32_16x16x32_bf16 v[10:13], v[58:61], v[186:189], v[10:13]
	v_mfma_f32_16x16x32_bf16 v[78:81], v[46:49], v[154:157], v[78:81]
	v_mfma_f32_16x16x32_bf16 v[74:77], v[70:73], v[154:157], v[74:77]
	v_mfma_f32_16x16x32_bf16 v[54:57], v[46:49], v[166:169], v[54:57]
	v_mfma_f32_16x16x32_bf16 v[50:53], v[70:73], v[166:169], v[50:53]
	v_mfma_f32_16x16x32_bf16 v[30:33], v[46:49], v[182:185], v[30:33]
	v_mfma_f32_16x16x32_bf16 v[26:29], v[70:73], v[182:185], v[26:29]
	s_waitcnt lgkmcnt(0)
	v_mfma_f32_16x16x32_bf16 v[14:17], v[46:49], v[190:193], v[14:17]
	v_mfma_f32_16x16x32_bf16 v[10:13], v[70:73], v[190:193], v[10:13]
	s_setprio 0
	s_setprio 1
	v_mfma_f32_16x16x32_bf16 v[42:45], v[82:85], v[158:161], v[42:45]
	v_mfma_f32_16x16x32_bf16 v[38:41], v[106:109], v[158:161], v[38:41]
	v_mfma_f32_16x16x32_bf16 v[22:25], v[82:85], v[174:177], v[22:25]
	v_mfma_f32_16x16x32_bf16 v[18:21], v[106:109], v[174:177], v[18:21]
	v_mfma_f32_16x16x32_bf16 v[6:9], v[82:85], v[186:189], v[6:9]
	v_mfma_f32_16x16x32_bf16 v[2:5], v[106:109], v[186:189], v[2:5]
	v_mfma_f32_16x16x32_bf16 v[34:37], v[82:85], v[142:145], v[66:69]
	v_mfma_f32_16x16x32_bf16 v[46:49], v[106:109], v[142:145], v[62:65]
	v_mfma_f32_16x16x32_bf16 v[42:45], v[94:97], v[166:169], v[42:45]
	v_mfma_f32_16x16x32_bf16 v[38:41], v[118:121], v[166:169], v[38:41]
	v_mfma_f32_16x16x32_bf16 v[22:25], v[94:97], v[182:185], v[22:25]
	v_mfma_f32_16x16x32_bf16 v[18:21], v[118:121], v[182:185], v[18:21]
	v_mfma_f32_16x16x32_bf16 v[6:9], v[94:97], v[190:193], v[6:9]
	v_mfma_f32_16x16x32_bf16 v[2:5], v[118:121], v[190:193], v[2:5]
	v_mfma_f32_16x16x32_bf16 v[34:37], v[94:97], v[154:157], v[34:37]
	v_mfma_f32_16x16x32_bf16 v[46:49], v[118:121], v[154:157], v[46:49]
	s_setprio 0
	s_cmp_lg_u32 s100, 0
	s_cbranch_scc1 .Lhb_21
	s_barrier
.Lhb_21:
	v_add_u32_e32 v70, 0x18000, v216
	v_add_u32_e32 v118, 0x1c000, v216
	ds_read_b128 v[58:61], v70
	ds_read_b128 v[62:65], v70 offset:1024
	ds_read_b128 v[66:69], v70 offset:2048
	ds_read_b128 v[70:73], v70 offset:3072
	ds_read_b128 v[82:85], v118
	ds_read_b128 v[94:97], v118 offset:1024
	ds_read_b128 v[106:109], v118 offset:2048
	ds_read_b128 v[118:121], v118 offset:3072
	s_add_i32 s60, s60, 0x20000
	s_mov_b32 m0, s37
	ds_read_b128 v[142:145], v217 offset:32768
	ds_read_b128 v[154:157], v217 offset:33792
	ds_read_b128 v[166:169], v217 offset:34816
	ds_read_b128 v[174:177], v217 offset:35840
	ds_read_b128 v[182:185], v217 offset:36864
	ds_read_b128 v[186:189], v217 offset:37888
	ds_read_b128 v[190:193], v217 offset:38912
	ds_read_b128 v[194:197], v217 offset:39936
	buffer_load_dwordx4 v0, s[16:19], s60 offen lds
	s_mov_b32 m0, s38
	s_nop 0
	buffer_load_dwordx4 v214, s[16:19], s60 offen lds
	s_waitcnt vmcnt(8)
	s_waitcnt lgkmcnt(0)
	s_cmp_eq_u32 s100, 0
	s_cbranch_scc1 .Lhb_18
	s_barrier
.Lhb_18:
	s_setprio 1
	s_waitcnt lgkmcnt(7)
	v_mfma_f32_16x16x32_bf16 v[158:161], v[58:61], v[142:145], v[178:181]
	s_waitcnt lgkmcnt(6)
	v_mfma_f32_16x16x32_bf16 v[178:181], v[62:65], v[154:157], v[158:161]
	v_mfma_f32_16x16x32_bf16 v[158:161], v[66:69], v[142:145], v[170:173]
	s_waitcnt lgkmcnt(5)
	v_mfma_f32_16x16x32_bf16 v[150:153], v[58:61], v[166:169], v[150:153]
	v_mfma_f32_16x16x32_bf16 v[146:149], v[66:69], v[166:169], v[146:149]
	s_waitcnt lgkmcnt(3)
	v_mfma_f32_16x16x32_bf16 v[126:129], v[58:61], v[182:185], v[126:129]
	v_mfma_f32_16x16x32_bf16 v[122:125], v[66:69], v[182:185], v[122:125]
	s_waitcnt lgkmcnt(1)
	v_mfma_f32_16x16x32_bf16 v[102:105], v[58:61], v[190:193], v[102:105]
	v_mfma_f32_16x16x32_bf16 v[98:101], v[66:69], v[190:193], v[98:101]
	v_mfma_f32_16x16x32_bf16 v[170:173], v[70:73], v[154:157], v[158:161]
	v_mfma_f32_16x16x32_bf16 v[150:153], v[62:65], v[174:177], v[150:153]
	v_mfma_f32_16x16x32_bf16 v[146:149], v[70:73], v[174:177], v[146:149]
	v_mfma_f32_16x16x32_bf16 v[126:129], v[62:65], v[186:189], v[126:129]
	v_mfma_f32_16x16x32_bf16 v[122:125], v[70:73], v[186:189], v[122:125]
	s_waitcnt lgkmcnt(0)
	v_mfma_f32_16x16x32_bf16 v[102:105], v[62:65], v[194:197], v[102:105]
	v_mfma_f32_16x16x32_bf16 v[98:101], v[70:73], v[194:197], v[98:101]
	s_setprio 0
	s_setprio 1
	v_mfma_f32_16x16x32_bf16 v[158:161], v[82:85], v[142:145], v[162:165]
	v_mfma_f32_16x16x32_bf16 v[130:133], v[106:109], v[142:145], v[130:133]
	v_mfma_f32_16x16x32_bf16 v[162:165], v[94:97], v[154:157], v[158:161]
	v_mfma_f32_16x16x32_bf16 v[158:161], v[118:121], v[154:157], v[130:133]
	v_mfma_f32_16x16x32_bf16 v[130:133], v[82:85], v[166:169], v[138:141]
	v_mfma_f32_16x16x32_bf16 v[138:141], v[94:97], v[174:177], v[130:133]
	v_mfma_f32_16x16x32_bf16 v[130:133], v[106:109], v[166:169], v[134:137]
	v_mfma_f32_16x16x32_bf16 v[114:117], v[82:85], v[182:185], v[114:117]
	v_mfma_f32_16x16x32_bf16 v[110:113], v[106:109], v[182:185], v[110:113]
	v_mfma_f32_16x16x32_bf16 v[90:93], v[82:85], v[190:193], v[90:93]
	v_mfma_f32_16x16x32_bf16 v[86:89], v[106:109], v[190:193], v[86:89]
	v_mfma_f32_16x16x32_bf16 v[134:137], v[118:121], v[174:177], v[130:133]
	v_mfma_f32_16x16x32_bf16 v[114:117], v[94:97], v[186:189], v[114:117]
	v_mfma_f32_16x16x32_bf16 v[110:113], v[118:121], v[186:189], v[110:113]
	v_mfma_f32_16x16x32_bf16 v[90:93], v[94:97], v[194:197], v[90:93]
	v_mfma_f32_16x16x32_bf16 v[86:89], v[118:121], v[194:197], v[86:89]
	s_setprio 0
	s_cmp_lg_u32 s100, 0
	s_cbranch_scc1 .Lhb_22
	s_barrier
; #define LAS __attribute__((address_space(3)))
; __device__ __forceinline__ void unpack8(const u32x4 w, float (&v)[8]) { v[0] = bflo(w.x); v[1] = bfhi(w.x); v[2] = bflo(w.y); v[3] = bfhi(w.y); v[4] = bflo(w.z); v[5] = bfhi(w.z); v[6] = bflo(w.w); v[7] = bfhi(w.w); }
;     __device__ __forceinline__ bool operator()(Acc& acc, const Unit& u, int wr, int wc, int fr, int fq, const LAS float*) const {
;         const size_t o0 = (size_t)(u.pm * BM + wr * 64 + fr) * 512 + u.pn * BM + wc * 32 + 8 * fq; const bf16_t* yp = YS + o0; bf16_t* zp = Z + o0;
;         u32x4 yv[2][4][2];
; #pragma unroll
;         for (int ai = 0; ai < 2; ++ai)
; #pragma unroll
;             for (int m = 0; m < 4; ++m)
; #pragma unroll
;                 for (int bj = 0; bj < 2; ++bj) yv[ai][m][bj] = gld<u32x4>(yp + (ai * HALF + m * 16) * 512 + bj * HALF);
; #pragma unroll
;         for (int ai = 0; ai < 2; ++ai) {
; #pragma unroll
;             for (int m = 0; m < 4; ++m)
; #pragma unroll
;                 for (int bj = 0; bj < 2; ++bj) {
;                     float y[8]; unpack8(yv[ai][m][bj], y);
.Lhb_22:
	s_mov_b32 m0, s39
	s_or_b32 s60, s58, 0x80
	ds_read_b128 v[130:133], v217 offset:49152
	ds_read_b128 v[142:145], v217 offset:50176
	ds_read_b128 v[154:157], v217 offset:51200
	ds_read_b128 v[166:169], v217 offset:52224
	ds_read_b128 v[174:177], v217 offset:53248
	ds_read_b128 v[182:185], v217 offset:54272
	ds_read_b128 v[186:189], v217 offset:55296
	ds_read_b128 v[190:193], v217 offset:56320
	buffer_load_dwordx4 v199, s[12:15], s60 offen lds
	s_mov_b32 m0, s40
	s_add_i32 s58, s58, 0x20080
	buffer_load_dwordx4 v215, s[12:15], s60 offen lds
	s_mov_b32 m0, s43
	s_nop 0
	buffer_load_dwordx4 v199, s[12:15], s58 offen lds
	s_mov_b32 m0, s42
	s_nop 0
	buffer_load_dwordx4 v215, s[12:15], s58 offen lds
	s_mov_b32 m0, s41
	s_nop 0
	buffer_load_dwordx4 v0, s[16:19], s59 offen lds
	s_mov_b32 m0, s33
	s_nop 0
	buffer_load_dwordx4 v214, s[16:19], s59 offen lds
	s_waitcnt vmcnt(8)
	s_waitcnt lgkmcnt(0)
	s_cmp_eq_u32 s100, 0
	s_cbranch_scc1 .Lhb_19
	s_barrier
.Lhb_19:
	s_setprio 1
	s_waitcnt lgkmcnt(7)
	v_mfma_f32_16x16x32_bf16 v[78:81], v[58:61], v[130:133], v[78:81]
	v_mfma_f32_16x16x32_bf16 v[74:77], v[66:69], v[130:133], v[74:77]
	s_waitcnt lgkmcnt(5)
	v_mfma_f32_16x16x32_bf16 v[54:57], v[58:61], v[154:157], v[54:57]
	v_mfma_f32_16x16x32_bf16 v[50:53], v[66:69], v[154:157], v[50:53]
	s_waitcnt lgkmcnt(3)
	v_mfma_f32_16x16x32_bf16 v[30:33], v[58:61], v[174:177], v[30:33]
	v_mfma_f32_16x16x32_bf16 v[26:29], v[66:69], v[174:177], v[26:29]
	s_waitcnt lgkmcnt(1)
	v_mfma_f32_16x16x32_bf16 v[14:17], v[58:61], v[186:189], v[14:17]
	v_mfma_f32_16x16x32_bf16 v[10:13], v[66:69], v[186:189], v[10:13]
	v_mfma_f32_16x16x32_bf16 v[78:81], v[62:65], v[142:145], v[78:81]
	v_mfma_f32_16x16x32_bf16 v[74:77], v[70:73], v[142:145], v[74:77]
	v_mfma_f32_16x16x32_bf16 v[54:57], v[62:65], v[166:169], v[54:57]
	v_mfma_f32_16x16x32_bf16 v[50:53], v[70:73], v[166:169], v[50:53]
	v_mfma_f32_16x16x32_bf16 v[30:33], v[62:65], v[182:185], v[30:33]
	v_mfma_f32_16x16x32_bf16 v[26:29], v[70:73], v[182:185], v[26:29]
	s_waitcnt lgkmcnt(0)
	v_mfma_f32_16x16x32_bf16 v[14:17], v[62:65], v[190:193], v[14:17]
	v_mfma_f32_16x16x32_bf16 v[10:13], v[70:73], v[190:193], v[10:13]
	s_setprio 0
	s_setprio 1
	v_mfma_f32_16x16x32_bf16 v[34:37], v[82:85], v[130:133], v[34:37]
	v_mfma_f32_16x16x32_bf16 v[66:69], v[94:97], v[142:145], v[34:37]
	v_mfma_f32_16x16x32_bf16 v[34:37], v[106:109], v[130:133], v[46:49]
	v_mfma_f32_16x16x32_bf16 v[62:65], v[118:121], v[142:145], v[34:37]
	v_mfma_f32_16x16x32_bf16 v[34:37], v[82:85], v[154:157], v[42:45]
	v_mfma_f32_16x16x32_bf16 v[42:45], v[94:97], v[166:169], v[34:37]
	v_mfma_f32_16x16x32_bf16 v[34:37], v[106:109], v[154:157], v[38:41]
	v_mfma_f32_16x16x32_bf16 v[22:25], v[82:85], v[174:177], v[22:25]
	v_mfma_f32_16x16x32_bf16 v[18:21], v[106:109], v[174:177], v[18:21]
	v_mfma_f32_16x16x32_bf16 v[6:9], v[82:85], v[186:189], v[6:9]
	v_mfma_f32_16x16x32_bf16 v[2:5], v[106:109], v[186:189], v[2:5]
	v_mfma_f32_16x16x32_bf16 v[38:41], v[118:121], v[166:169], v[34:37]
	v_mfma_f32_16x16x32_bf16 v[22:25], v[94:97], v[182:185], v[22:25]
	v_mfma_f32_16x16x32_bf16 v[18:21], v[118:121], v[182:185], v[18:21]
	v_mfma_f32_16x16x32_bf16 v[6:9], v[94:97], v[190:193], v[6:9]
	v_mfma_f32_16x16x32_bf16 v[2:5], v[118:121], v[190:193], v[2:5]
	s_setprio 0
	s_cmp_lg_u32 s100, 0
	s_cbranch_scc1 .Lhb_23
	s_barrier
.Lhb_23:
	s_add_i32 s57, s57, 2
	s_addk_i32 s55, 0x100
	s_addk_i32 s56, 0x100
	s_cmp_gt_u32 s57, 5
	s_cbranch_scc0 .LBB0_702
	v_readlane_b32 s8, v251, 45
	v_readlane_b32 s9, v251, 46
	s_and_b64 vcc, exec, s[8:9]
	s_cbranch_vccz .LBB0_705
.LBB0_705:
	v_mov_b32_e32 v34, v1
	s_lshl_b32 s8, s21, 8
	v_mbcnt_lo_u32_b32 v34, -1, v34
	v_readlane_b32 s9, v250, 1
	v_mbcnt_hi_u32_b32 v36, -1, v34
	s_add_i32 s8, s8, s9
	v_and_or_b32 v34, v36, 15, s8
	v_ashrrev_i32_e32 v35, 31, v34
	s_lshl_b32 s8, s20, 8
	v_lshlrev_b64 v[34:35], 9, v[34:35]
	s_ashr_i32 s9, s8, 31
	v_lshl_add_u64 v[34:35], v[34:35], 0, s[8:9]
	v_lshrrev_b32_e32 v36, 1, v36
	v_and_or_b32 v34, v36, 24, v34
	v_readlane_b32 s8, v254, 32
	v_mul_f32_e32 v178, 0xbfb8aa3b, v178
	v_mul_f32_e32 v179, 0xbfb8aa3b, v179
	v_or_b32_e32 v34, s8, v34
	v_lshlrev_b64 v[194:195], 1, v[34:35]
	v_lshl_add_u64 v[34:35], s[22:23], 0, v[194:195]
	global_load_dwordx4 v[190:193], v[34:35], off
	global_load_dwordx4 v[186:189], v[34:35], off offset:256
	s_movk_i32 s8, 0x4000
	v_add_co_u32_e32 v36, vcc, s8, v34
	v_exp_f32_e32 v178, v178
	s_nop 0
	v_addc_co_u32_e32 v37, vcc, 0, v35, vcc
	global_load_dwordx4 v[182:185], v[36:37], off
	global_load_dwordx4 v[174:177], v[36:37], off offset:256
	v_mul_f32_e32 v170, 0xbfb8aa3b, v170
	v_exp_f32_e32 v179, v179
	v_mul_f32_e32 v171, 0xbfb8aa3b, v171
	v_mul_f32_e32 v180, 0xbfb8aa3b, v180
	v_mul_f32_e32 v181, 0xbfb8aa3b, v181
	v_exp_f32_e32 v170, v170
	v_exp_f32_e32 v171, v171
	v_exp_f32_e32 v180, v180
	v_exp_f32_e32 v181, v181
	v_mul_f32_e32 v162, 0xbfb8aa3b, v162
	v_mul_f32_e32 v163, 0xbfb8aa3b, v163
	v_exp_f32_e32 v162, v162
	v_mul_f32_e32 v158, 0xbfb8aa3b, v158
	v_exp_f32_e32 v163, v163
	v_mul_f32_e32 v159, 0xbfb8aa3b, v159
	v_add_f32_e32 v178, 1.0, v178
	v_add_f32_e32 v179, 1.0, v179
	v_exp_f32_e32 v158, v158
	v_exp_f32_e32 v159, v159
	v_rcp_f32_e32 v178, v178
	v_add_f32_e32 v170, 1.0, v170
	v_rcp_f32_e32 v179, v179
	v_add_f32_e32 v171, 1.0, v171
	v_add_f32_e32 v180, 1.0, v180
	v_add_f32_e32 v181, 1.0, v181
	v_readlane_b32 s14, v254, 55
	v_rcp_f32_e32 v170, v170
	v_rcp_f32_e32 v171, v171
	v_rcp_f32_e32 v180, v180
	v_rcp_f32_e32 v181, v181
	v_readlane_b32 s15, v254, 56
	v_add_f32_e32 v162, 1.0, v162
	v_add_f32_e32 v163, 1.0, v163
	v_lshl_add_u64 v[212:213], s[14:15], 0, v[194:195]
	v_rcp_f32_e32 v162, v162
	v_add_f32_e32 v158, 1.0, v158
	v_rcp_f32_e32 v163, v163
	v_add_f32_e32 v159, 1.0, v159
	v_rcp_f32_e32 v158, v158
	v_rcp_f32_e32 v159, v159
	s_mov_b32 s9, 0x8000
	v_add_co_u32_e32 v36, vcc, s9, v34
	v_mul_f32_e32 v172, 0xbfb8aa3b, v172
	s_nop 0
	v_addc_co_u32_e32 v37, vcc, 0, v35, vcc
	global_load_dwordx4 v[166:169], v[36:37], off
	global_load_dwordx4 v[154:157], v[36:37], off offset:256
	v_mul_f32_e32 v173, 0xbfb8aa3b, v173
	v_exp_f32_e32 v172, v172
	v_exp_f32_e32 v173, v173
	s_mov_b32 s10, 0xc000
	v_add_co_u32_e32 v36, vcc, s10, v34
	v_mul_f32_e32 v150, 0xbfb8aa3b, v150
	s_nop 0
	v_addc_co_u32_e32 v37, vcc, 0, v35, vcc
	v_mul_f32_e32 v151, 0xbfb8aa3b, v151
	global_load_dwordx4 v[142:145], v[36:37], off
	global_load_dwordx4 v[130:133], v[36:37], off offset:256
	v_add_co_u32_e32 v36, vcc, s79, v34
	v_add_f32_e32 v172, 1.0, v172
	v_add_f32_e32 v173, 1.0, v173
	v_exp_f32_e32 v150, v150
	v_mul_f32_e32 v146, 0xbfb8aa3b, v146
	v_exp_f32_e32 v151, v151
	v_mul_f32_e32 v147, 0xbfb8aa3b, v147
	v_addc_co_u32_e32 v37, vcc, 0, v35, vcc
	s_mov_b32 s11, 0x24000
	v_rcp_f32_e32 v172, v172
	v_rcp_f32_e32 v173, v173
	s_waitcnt vmcnt(7)
; __device__ __forceinline__ void unpack8(const u32x4 w, float (&v)[8]) { v[0] = bflo(w.x); v[1] = bfhi(w.x); v[2] = bflo(w.y); v[3] = bfhi(w.y); v[4] = bflo(w.z); v[5] = bfhi(w.z); v[6] = bflo(w.w); v[7] = bfhi(w.w); }
; __device__ __forceinline__ u32x4 pack8(const float (&v)[8]) { u32x4 w; w.x = pk2(v[0], v[1]); w.y = pk2(v[2], v[3]); w.z = pk2(v[4], v[5]); w.w = pk2(v[6], v[7]); return w; }
; __device__ __forceinline__ float sigmoidf_(float x) { return __builtin_amdgcn_rcpf(1.0f + __builtin_amdgcn_exp2f(-LOG2E * x)); }
;     __device__ __forceinline__ bool operator()(Acc& acc, const Unit& u, int wr, int wc, int fr, int fq, const LAS float*) const {
;     ...
; #pragma unroll
;         for (int ai = 0; ai < 2; ++ai) {
; #pragma unroll
;             for (int m = 0; m < 4; ++m)
; #pragma unroll
;                 for (int bj = 0; bj < 2; ++bj) {
;                     float y[8]; unpack8(yv[ai][m][bj], y);
;                     float v[8];
; #pragma unroll
;                     for (int e = 0; e < 4; ++e) { v[e] = y[e] * sigmoidf_(acc[ai][bj][m][0][e]); v[4 + e] = y[4 + e] * sigmoidf_(acc[ai][bj][m][1][e]); }
;                     gst<u32x4>(zp + (ai * HALF + m * 16) * 512 + bj * HALF, pack8(v));
;                 }
;             asm volatile("" ::: "memory");
	v_lshlrev_b32_e32 v194, 16, v190
	v_and_b32_e32 v195, 0xffff0000, v190
	v_pk_mul_f32 v[178:179], v[178:179], v[194:195]
	v_lshlrev_b32_e32 v194, 16, v192
	v_and_b32_e32 v195, 0xffff0000, v192
	v_lshlrev_b32_e32 v190, 16, v191
	v_and_b32_e32 v191, 0xffff0000, v191
	v_pk_mul_f32 v[170:171], v[170:171], v[194:195]
	v_pk_mul_f32 v[180:181], v[180:181], v[190:191]
	v_cvt_pk_bf16_f32 v178, v178, v179
	v_cvt_pk_bf16_f32 v179, v180, v181
	v_cvt_pk_bf16_f32 v180, v170, v171
	s_waitcnt vmcnt(6)
	v_lshlrev_b32_e32 v170, 16, v186
	v_and_b32_e32 v171, 0xffff0000, v186
	v_pk_mul_f32 v[162:163], v[162:163], v[170:171]
	v_lshlrev_b32_e32 v170, 16, v188
	v_and_b32_e32 v171, 0xffff0000, v188
	v_pk_mul_f32 v[170:171], v[158:159], v[170:171]
	v_mul_f32_e32 v159, 0xbfb8aa3b, v160
	v_exp_f32_e32 v159, v159
	v_mul_f32_e32 v158, 0xbfb8aa3b, v164
	v_exp_f32_e32 v158, v158
	v_lshlrev_b32_e32 v164, 16, v187
	v_add_f32_e32 v159, 1.0, v159
	v_rcp_f32_e32 v160, v159
	v_mul_f32_e32 v159, 0xbfb8aa3b, v165
	v_exp_f32_e32 v159, v159
	v_add_f32_e32 v158, 1.0, v158
	v_rcp_f32_e32 v158, v158
	v_and_b32_e32 v165, 0xffff0000, v187
	v_add_f32_e32 v159, 1.0, v159
	v_rcp_f32_e32 v159, v159
	v_exp_f32_e32 v146, v146
	v_exp_f32_e32 v147, v147
	global_load_dwordx4 v[118:121], v[36:37], off
	global_load_dwordx4 v[106:109], v[36:37], off offset:256
	v_pk_mul_f32 v[164:165], v[158:159], v[164:165]
	v_mul_f32_e32 v158, 0xbfb8aa3b, v161
	v_exp_f32_e32 v158, v158
	v_add_co_u32_e32 v36, vcc, s11, v34
	s_mov_b32 s12, 0x28000
	v_add_f32_e32 v158, 1.0, v158
	v_rcp_f32_e32 v161, v158
	v_addc_co_u32_e32 v37, vcc, 0, v35, vcc
	global_load_dwordx4 v[94:97], v[36:37], off
	global_load_dwordx4 v[82:85], v[36:37], off offset:256
	v_add_co_u32_e32 v36, vcc, s12, v34
	v_lshlrev_b32_e32 v190, 16, v193
	v_and_b32_e32 v191, 0xffff0000, v193
	v_add_f32_e32 v150, 1.0, v150
	v_add_f32_e32 v151, 1.0, v151
	v_addc_co_u32_e32 v37, vcc, 0, v35, vcc
	s_mov_b32 s13, 0x2c000
	v_pk_mul_f32 v[172:173], v[172:173], v[190:191]
	v_lshlrev_b32_e32 v158, 16, v189
	v_and_b32_e32 v159, 0xffff0000, v189
	v_rcp_f32_e32 v150, v150
	v_add_f32_e32 v146, 1.0, v146
	v_rcp_f32_e32 v151, v151
	v_add_f32_e32 v147, 1.0, v147
	v_add_co_u32_e32 v34, vcc, s13, v34
	v_cvt_pk_bf16_f32 v181, v172, v173
	v_pk_mul_f32 v[172:173], v[160:161], v[158:159]
	v_rcp_f32_e32 v146, v146
	v_rcp_f32_e32 v147, v147
	v_addc_co_u32_e32 v35, vcc, 0, v35, vcc
	v_cvt_pk_bf16_f32 v158, v162, v163
	v_cvt_pk_bf16_f32 v159, v164, v165
	v_cvt_pk_bf16_f32 v160, v170, v171
	v_cvt_pk_bf16_f32 v161, v172, v173
	global_load_dwordx4 v[70:73], v[36:37], off
	global_load_dwordx4 v[58:61], v[36:37], off offset:256
	global_load_dwordx4 v[46:49], v[34:35], off
	s_nop 0
	global_load_dwordx4 v[34:37], v[34:35], off offset:256
	v_mul_f32_e32 v138, 0xbfb8aa3b, v138
	global_store_dwordx4 v[212:213], v[158:161], off offset:256
	v_mul_f32_e32 v139, 0xbfb8aa3b, v139
	v_exp_f32_e32 v138, v138
	s_waitcnt vmcnt(14)
	v_lshlrev_b32_e32 v158, 16, v182
	v_and_b32_e32 v159, 0xffff0000, v182
	v_pk_mul_f32 v[150:151], v[150:151], v[158:159]
	v_lshlrev_b32_e32 v158, 16, v184
	v_and_b32_e32 v159, 0xffff0000, v184
	v_pk_mul_f32 v[158:159], v[146:147], v[158:159]
	v_mul_f32_e32 v147, 0xbfb8aa3b, v148
	v_exp_f32_e32 v147, v147
	v_mul_f32_e32 v146, 0xbfb8aa3b, v152
	v_exp_f32_e32 v146, v146
	v_lshlrev_b32_e32 v152, 16, v183
	v_add_f32_e32 v147, 1.0, v147
	v_rcp_f32_e32 v148, v147
	v_mul_f32_e32 v147, 0xbfb8aa3b, v153
	v_exp_f32_e32 v147, v147
	v_add_f32_e32 v146, 1.0, v146
	v_rcp_f32_e32 v146, v146
	v_and_b32_e32 v153, 0xffff0000, v183
	v_add_f32_e32 v147, 1.0, v147
	v_rcp_f32_e32 v147, v147
	v_mul_f32_e32 v134, 0xbfb8aa3b, v134
	v_exp_f32_e32 v139, v139
	v_mul_f32_e32 v135, 0xbfb8aa3b, v135
	v_pk_mul_f32 v[152:153], v[146:147], v[152:153]
	v_mul_f32_e32 v146, 0xbfb8aa3b, v149
	v_exp_f32_e32 v146, v146
	v_exp_f32_e32 v134, v134
	v_exp_f32_e32 v135, v135
	v_add_f32_e32 v138, 1.0, v138
	v_add_f32_e32 v146, 1.0, v146
	v_rcp_f32_e32 v149, v146
	v_add_f32_e32 v139, 1.0, v139
	v_lshlrev_b32_e32 v146, 16, v185
	v_and_b32_e32 v147, 0xffff0000, v185
	v_rcp_f32_e32 v138, v138
	v_add_f32_e32 v134, 1.0, v134
	v_rcp_f32_e32 v139, v139
	v_add_f32_e32 v135, 1.0, v135
	v_pk_mul_f32 v[160:161], v[148:149], v[146:147]
	v_cvt_pk_bf16_f32 v146, v150, v151
	v_add_co_u32_e32 v150, vcc, s8, v212
	v_rcp_f32_e32 v134, v134
	v_rcp_f32_e32 v135, v135
	v_cvt_pk_bf16_f32 v147, v152, v153
	v_cvt_pk_bf16_f32 v148, v158, v159
	v_cvt_pk_bf16_f32 v149, v160, v161
	v_addc_co_u32_e32 v151, vcc, 0, v213, vcc
	global_store_dwordx4 v[150:151], v[146:149], off
	v_mul_f32_e32 v126, 0xbfb8aa3b, v126
	v_mul_f32_e32 v127, 0xbfb8aa3b, v127
	s_waitcnt vmcnt(14)
	v_lshlrev_b32_e32 v146, 16, v174
	v_and_b32_e32 v147, 0xffff0000, v174
	v_pk_mul_f32 v[138:139], v[138:139], v[146:147]
	v_lshlrev_b32_e32 v146, 16, v176
	v_and_b32_e32 v147, 0xffff0000, v176
	v_pk_mul_f32 v[146:147], v[134:135], v[146:147]
	v_mul_f32_e32 v135, 0xbfb8aa3b, v136
	v_exp_f32_e32 v135, v135
	v_mul_f32_e32 v134, 0xbfb8aa3b, v140
	v_exp_f32_e32 v134, v134
	v_lshlrev_b32_e32 v140, 16, v175
	v_add_f32_e32 v135, 1.0, v135
	v_rcp_f32_e32 v136, v135
	v_mul_f32_e32 v135, 0xbfb8aa3b, v141
	v_exp_f32_e32 v135, v135
	v_add_f32_e32 v134, 1.0, v134
	v_rcp_f32_e32 v134, v134
	v_and_b32_e32 v141, 0xffff0000, v175
	v_add_f32_e32 v135, 1.0, v135
	v_rcp_f32_e32 v135, v135
	v_exp_f32_e32 v126, v126
	v_mul_f32_e32 v122, 0xbfb8aa3b, v122
	v_exp_f32_e32 v127, v127
	v_pk_mul_f32 v[140:141], v[134:135], v[140:141]
	v_mul_f32_e32 v134, 0xbfb8aa3b, v137
	v_exp_f32_e32 v134, v134
	v_mul_f32_e32 v123, 0xbfb8aa3b, v123
	v_exp_f32_e32 v122, v122
	v_exp_f32_e32 v123, v123
	v_add_f32_e32 v134, 1.0, v134
	v_rcp_f32_e32 v137, v134
	v_add_f32_e32 v126, 1.0, v126
	v_add_f32_e32 v127, 1.0, v127
	v_lshlrev_b32_e32 v134, 16, v177
	v_and_b32_e32 v135, 0xffff0000, v177
	v_rcp_f32_e32 v126, v126
	v_add_f32_e32 v122, 1.0, v122
	v_rcp_f32_e32 v127, v127
	v_add_f32_e32 v123, 1.0, v123
	v_pk_mul_f32 v[148:149], v[136:137], v[134:135]
	v_rcp_f32_e32 v122, v122
	v_rcp_f32_e32 v123, v123
	v_cvt_pk_bf16_f32 v134, v138, v139
	v_cvt_pk_bf16_f32 v135, v140, v141
	v_cvt_pk_bf16_f32 v136, v146, v147
	v_cvt_pk_bf16_f32 v137, v148, v149
	global_store_dwordx4 v[150:151], v[134:137], off offset:256
	v_mul_f32_e32 v114, 0xbfb8aa3b, v114
	v_mul_f32_e32 v115, 0xbfb8aa3b, v115
	s_waitcnt vmcnt(14)
; __device__ __forceinline__ void unpack8(const u32x4 w, float (&v)[8]) { v[0] = bflo(w.x); v[1] = bfhi(w.x); v[2] = bflo(w.y); v[3] = bfhi(w.y); v[4] = bflo(w.z); v[5] = bfhi(w.z); v[6] = bflo(w.w); v[7] = bfhi(w.w); }
; __device__ __forceinline__ u32x4 pack8(const float (&v)[8]) { u32x4 w; w.x = pk2(v[0], v[1]); w.y = pk2(v[2], v[3]); w.z = pk2(v[4], v[5]); w.w = pk2(v[6], v[7]); return w; }
; __device__ __forceinline__ float sigmoidf_(float x) { return __builtin_amdgcn_rcpf(1.0f + __builtin_amdgcn_exp2f(-LOG2E * x)); }
;     __device__ __forceinline__ bool operator()(Acc& acc, const Unit& u, int wr, int wc, int fr, int fq, const LAS float*) const {
;     ...
; #pragma unroll
;         for (int ai = 0; ai < 2; ++ai) {
; #pragma unroll
;             for (int m = 0; m < 4; ++m)
; #pragma unroll
;                 for (int bj = 0; bj < 2; ++bj) {
;                     float y[8]; unpack8(yv[ai][m][bj], y);
;                     float v[8];
; #pragma unroll
;                     for (int e = 0; e < 4; ++e) { v[e] = y[e] * sigmoidf_(acc[ai][bj][m][0][e]); v[4 + e] = y[4 + e] * sigmoidf_(acc[ai][bj][m][1][e]); }
;                     gst<u32x4>(zp + (ai * HALF + m * 16) * 512 + bj * HALF, pack8(v));
;                 }
;             asm volatile("" ::: "memory");
	v_lshlrev_b32_e32 v134, 16, v166
	v_and_b32_e32 v135, 0xffff0000, v166
	v_pk_mul_f32 v[126:127], v[126:127], v[134:135]
	v_lshlrev_b32_e32 v134, 16, v168
	v_and_b32_e32 v135, 0xffff0000, v168
	v_pk_mul_f32 v[134:135], v[122:123], v[134:135]
	v_mul_f32_e32 v123, 0xbfb8aa3b, v124
	v_exp_f32_e32 v123, v123
	v_mul_f32_e32 v122, 0xbfb8aa3b, v128
	v_exp_f32_e32 v122, v122
	v_lshlrev_b32_e32 v128, 16, v167
	v_add_f32_e32 v123, 1.0, v123
	v_rcp_f32_e32 v124, v123
	v_mul_f32_e32 v123, 0xbfb8aa3b, v129
	v_exp_f32_e32 v123, v123
	v_add_f32_e32 v122, 1.0, v122
	v_rcp_f32_e32 v122, v122
	v_and_b32_e32 v129, 0xffff0000, v167
	v_add_f32_e32 v123, 1.0, v123
	v_rcp_f32_e32 v123, v123
	v_exp_f32_e32 v114, v114
	v_mul_f32_e32 v110, 0xbfb8aa3b, v110
	v_exp_f32_e32 v115, v115
	v_pk_mul_f32 v[128:129], v[122:123], v[128:129]
	v_mul_f32_e32 v122, 0xbfb8aa3b, v125
	v_exp_f32_e32 v122, v122
	v_mul_f32_e32 v111, 0xbfb8aa3b, v111
	v_exp_f32_e32 v110, v110
	v_exp_f32_e32 v111, v111
	v_add_f32_e32 v122, 1.0, v122
	v_rcp_f32_e32 v125, v122
	v_add_f32_e32 v114, 1.0, v114
	v_add_f32_e32 v115, 1.0, v115
	v_lshlrev_b32_e32 v122, 16, v169
	v_and_b32_e32 v123, 0xffff0000, v169
	v_rcp_f32_e32 v114, v114
	v_add_f32_e32 v110, 1.0, v110
	v_rcp_f32_e32 v115, v115
	v_add_f32_e32 v111, 1.0, v111
	v_pk_mul_f32 v[136:137], v[124:125], v[122:123]
	v_cvt_pk_bf16_f32 v122, v126, v127
	v_add_co_u32_e32 v126, vcc, s9, v212
	v_rcp_f32_e32 v110, v110
	v_rcp_f32_e32 v111, v111
	v_cvt_pk_bf16_f32 v123, v128, v129
	v_cvt_pk_bf16_f32 v124, v134, v135
	v_cvt_pk_bf16_f32 v125, v136, v137
	v_addc_co_u32_e32 v127, vcc, 0, v213, vcc
	global_store_dwordx4 v[126:127], v[122:125], off
	v_mul_f32_e32 v102, 0xbfb8aa3b, v102
	v_mul_f32_e32 v103, 0xbfb8aa3b, v103
	s_waitcnt vmcnt(14)
	v_lshlrev_b32_e32 v122, 16, v154
	v_and_b32_e32 v123, 0xffff0000, v154
	v_pk_mul_f32 v[114:115], v[114:115], v[122:123]
	v_lshlrev_b32_e32 v122, 16, v156
	v_and_b32_e32 v123, 0xffff0000, v156
	v_pk_mul_f32 v[122:123], v[110:111], v[122:123]
	v_mul_f32_e32 v111, 0xbfb8aa3b, v112
	v_exp_f32_e32 v111, v111
	v_mul_f32_e32 v110, 0xbfb8aa3b, v116
	v_exp_f32_e32 v110, v110
	v_lshlrev_b32_e32 v116, 16, v155
	v_add_f32_e32 v111, 1.0, v111
	v_rcp_f32_e32 v112, v111
	v_mul_f32_e32 v111, 0xbfb8aa3b, v117
	v_exp_f32_e32 v111, v111
	v_add_f32_e32 v110, 1.0, v110
	v_rcp_f32_e32 v110, v110
	v_and_b32_e32 v117, 0xffff0000, v155
	v_add_f32_e32 v111, 1.0, v111
	v_rcp_f32_e32 v111, v111
	v_exp_f32_e32 v102, v102
	v_mul_f32_e32 v98, 0xbfb8aa3b, v98
	v_exp_f32_e32 v103, v103
	v_pk_mul_f32 v[116:117], v[110:111], v[116:117]
	v_mul_f32_e32 v110, 0xbfb8aa3b, v113
	v_exp_f32_e32 v110, v110
	v_mul_f32_e32 v99, 0xbfb8aa3b, v99
	v_exp_f32_e32 v98, v98
	v_exp_f32_e32 v99, v99
	v_add_f32_e32 v110, 1.0, v110
	v_rcp_f32_e32 v113, v110
	v_add_f32_e32 v102, 1.0, v102
	v_add_f32_e32 v103, 1.0, v103
	v_lshlrev_b32_e32 v110, 16, v157
	v_and_b32_e32 v111, 0xffff0000, v157
	v_rcp_f32_e32 v102, v102
	v_add_f32_e32 v98, 1.0, v98
	v_rcp_f32_e32 v103, v103
	v_add_f32_e32 v99, 1.0, v99
	v_pk_mul_f32 v[124:125], v[112:113], v[110:111]
	v_rcp_f32_e32 v98, v98
	v_rcp_f32_e32 v99, v99
	v_cvt_pk_bf16_f32 v110, v114, v115
	v_cvt_pk_bf16_f32 v111, v116, v117
	v_cvt_pk_bf16_f32 v112, v122, v123
	v_cvt_pk_bf16_f32 v113, v124, v125
	global_store_dwordx4 v[126:127], v[110:113], off offset:256
	v_mul_f32_e32 v90, 0xbfb8aa3b, v90
	v_mul_f32_e32 v91, 0xbfb8aa3b, v91
	s_waitcnt vmcnt(14)
	v_lshlrev_b32_e32 v110, 16, v142
	v_and_b32_e32 v111, 0xffff0000, v142
	v_pk_mul_f32 v[102:103], v[102:103], v[110:111]
	v_lshlrev_b32_e32 v110, 16, v144
	v_and_b32_e32 v111, 0xffff0000, v144
	v_pk_mul_f32 v[110:111], v[98:99], v[110:111]
	v_mul_f32_e32 v99, 0xbfb8aa3b, v100
	v_exp_f32_e32 v99, v99
	v_mul_f32_e32 v98, 0xbfb8aa3b, v104
	v_exp_f32_e32 v98, v98
	v_lshlrev_b32_e32 v104, 16, v143
	v_add_f32_e32 v99, 1.0, v99
	v_rcp_f32_e32 v100, v99
	v_mul_f32_e32 v99, 0xbfb8aa3b, v105
	v_exp_f32_e32 v99, v99
	v_add_f32_e32 v98, 1.0, v98
	v_rcp_f32_e32 v98, v98
	v_and_b32_e32 v105, 0xffff0000, v143
	v_add_f32_e32 v99, 1.0, v99
	v_rcp_f32_e32 v99, v99
	v_exp_f32_e32 v90, v90
	v_mul_f32_e32 v86, 0xbfb8aa3b, v86
	v_exp_f32_e32 v91, v91
	v_pk_mul_f32 v[104:105], v[98:99], v[104:105]
	v_mul_f32_e32 v98, 0xbfb8aa3b, v101
	v_exp_f32_e32 v98, v98
	v_mul_f32_e32 v87, 0xbfb8aa3b, v87
	v_exp_f32_e32 v86, v86
	v_exp_f32_e32 v87, v87
	v_add_f32_e32 v98, 1.0, v98
	v_rcp_f32_e32 v101, v98
	v_add_f32_e32 v90, 1.0, v90
	v_add_f32_e32 v91, 1.0, v91
	v_lshlrev_b32_e32 v98, 16, v145
	v_and_b32_e32 v99, 0xffff0000, v145
	v_rcp_f32_e32 v90, v90
	v_add_f32_e32 v86, 1.0, v86
	v_rcp_f32_e32 v91, v91
	v_add_f32_e32 v87, 1.0, v87
	v_pk_mul_f32 v[112:113], v[100:101], v[98:99]
	v_cvt_pk_bf16_f32 v98, v102, v103
	v_add_co_u32_e32 v102, vcc, s10, v212
	v_rcp_f32_e32 v86, v86
	v_rcp_f32_e32 v87, v87
	v_cvt_pk_bf16_f32 v99, v104, v105
	v_cvt_pk_bf16_f32 v100, v110, v111
	v_cvt_pk_bf16_f32 v101, v112, v113
	v_addc_co_u32_e32 v103, vcc, 0, v213, vcc
	global_store_dwordx4 v[102:103], v[98:101], off
	v_mul_f32_e32 v78, 0xbfb8aa3b, v78
	v_mul_f32_e32 v79, 0xbfb8aa3b, v79
	s_waitcnt vmcnt(14)
; __device__ __forceinline__ void unpack8(const u32x4 w, float (&v)[8]) { v[0] = bflo(w.x); v[1] = bfhi(w.x); v[2] = bflo(w.y); v[3] = bfhi(w.y); v[4] = bflo(w.z); v[5] = bfhi(w.z); v[6] = bflo(w.w); v[7] = bfhi(w.w); }
; __device__ __forceinline__ u32x4 pack8(const float (&v)[8]) { u32x4 w; w.x = pk2(v[0], v[1]); w.y = pk2(v[2], v[3]); w.z = pk2(v[4], v[5]); w.w = pk2(v[6], v[7]); return w; }
; __device__ __forceinline__ float sigmoidf_(float x) { return __builtin_amdgcn_rcpf(1.0f + __builtin_amdgcn_exp2f(-LOG2E * x)); }
;     __device__ __forceinline__ bool operator()(Acc& acc, const Unit& u, int wr, int wc, int fr, int fq, const LAS float*) const {
;     ...
; #pragma unroll
;         for (int ai = 0; ai < 2; ++ai) {
; #pragma unroll
;             for (int m = 0; m < 4; ++m)
; #pragma unroll
;                 for (int bj = 0; bj < 2; ++bj) {
;                     float y[8]; unpack8(yv[ai][m][bj], y);
;                     float v[8];
; #pragma unroll
;                     for (int e = 0; e < 4; ++e) { v[e] = y[e] * sigmoidf_(acc[ai][bj][m][0][e]); v[4 + e] = y[4 + e] * sigmoidf_(acc[ai][bj][m][1][e]); }
;                     gst<u32x4>(zp + (ai * HALF + m * 16) * 512 + bj * HALF, pack8(v));
;                 }
;             asm volatile("" ::: "memory");
	v_lshlrev_b32_e32 v98, 16, v130
	v_and_b32_e32 v99, 0xffff0000, v130
	v_pk_mul_f32 v[90:91], v[90:91], v[98:99]
	v_lshlrev_b32_e32 v98, 16, v132
	v_and_b32_e32 v99, 0xffff0000, v132
	v_pk_mul_f32 v[98:99], v[86:87], v[98:99]
	v_mul_f32_e32 v87, 0xbfb8aa3b, v88
	v_exp_f32_e32 v87, v87
	v_mul_f32_e32 v86, 0xbfb8aa3b, v92
	v_exp_f32_e32 v86, v86
	v_lshlrev_b32_e32 v92, 16, v131
	v_add_f32_e32 v87, 1.0, v87
	v_rcp_f32_e32 v88, v87
	v_mul_f32_e32 v87, 0xbfb8aa3b, v93
	v_exp_f32_e32 v87, v87
	v_add_f32_e32 v86, 1.0, v86
	v_rcp_f32_e32 v86, v86
	v_and_b32_e32 v93, 0xffff0000, v131
	v_add_f32_e32 v87, 1.0, v87
	v_rcp_f32_e32 v87, v87
	v_exp_f32_e32 v78, v78
	v_mul_f32_e32 v74, 0xbfb8aa3b, v74
	v_exp_f32_e32 v79, v79
	v_pk_mul_f32 v[92:93], v[86:87], v[92:93]
	v_mul_f32_e32 v86, 0xbfb8aa3b, v89
	v_exp_f32_e32 v86, v86
	v_mul_f32_e32 v75, 0xbfb8aa3b, v75
	v_exp_f32_e32 v74, v74
	v_exp_f32_e32 v75, v75
	v_add_f32_e32 v86, 1.0, v86
	v_rcp_f32_e32 v89, v86
	v_add_f32_e32 v78, 1.0, v78
	v_add_f32_e32 v79, 1.0, v79
	v_lshlrev_b32_e32 v86, 16, v133
	v_and_b32_e32 v87, 0xffff0000, v133
	v_rcp_f32_e32 v78, v78
	v_add_f32_e32 v74, 1.0, v74
	v_rcp_f32_e32 v79, v79
	v_add_f32_e32 v75, 1.0, v75
	v_pk_mul_f32 v[100:101], v[88:89], v[86:87]
	v_rcp_f32_e32 v74, v74
	v_rcp_f32_e32 v75, v75
	v_cvt_pk_bf16_f32 v86, v90, v91
	v_cvt_pk_bf16_f32 v87, v92, v93
	v_cvt_pk_bf16_f32 v88, v98, v99
	v_cvt_pk_bf16_f32 v89, v100, v101
	global_store_dwordx4 v[102:103], v[86:89], off offset:256
	v_mul_f32_e32 v66, 0xbfb8aa3b, v66
	v_mul_f32_e32 v67, 0xbfb8aa3b, v67
	s_waitcnt vmcnt(14)
	v_lshlrev_b32_e32 v86, 16, v118
	v_and_b32_e32 v87, 0xffff0000, v118
	v_pk_mul_f32 v[78:79], v[78:79], v[86:87]
	v_lshlrev_b32_e32 v86, 16, v120
	v_and_b32_e32 v87, 0xffff0000, v120
	v_pk_mul_f32 v[86:87], v[74:75], v[86:87]
	v_mul_f32_e32 v75, 0xbfb8aa3b, v76
	v_exp_f32_e32 v75, v75
	v_mul_f32_e32 v74, 0xbfb8aa3b, v80
	v_exp_f32_e32 v74, v74
	v_lshlrev_b32_e32 v80, 16, v119
	v_add_f32_e32 v75, 1.0, v75
	v_rcp_f32_e32 v76, v75
	v_mul_f32_e32 v75, 0xbfb8aa3b, v81
	v_exp_f32_e32 v75, v75
	v_add_f32_e32 v74, 1.0, v74
	v_rcp_f32_e32 v74, v74
	v_and_b32_e32 v81, 0xffff0000, v119
	v_add_f32_e32 v75, 1.0, v75
	v_rcp_f32_e32 v75, v75
	v_exp_f32_e32 v66, v66
	v_mul_f32_e32 v62, 0xbfb8aa3b, v62
	v_exp_f32_e32 v67, v67
	v_pk_mul_f32 v[80:81], v[74:75], v[80:81]
	v_mul_f32_e32 v74, 0xbfb8aa3b, v77
	v_exp_f32_e32 v74, v74
	v_mul_f32_e32 v63, 0xbfb8aa3b, v63
	v_exp_f32_e32 v62, v62
	v_exp_f32_e32 v63, v63
	v_add_f32_e32 v74, 1.0, v74
	v_rcp_f32_e32 v77, v74
	v_add_f32_e32 v66, 1.0, v66
	v_add_f32_e32 v67, 1.0, v67
	v_lshlrev_b32_e32 v74, 16, v121
	v_and_b32_e32 v75, 0xffff0000, v121
	v_rcp_f32_e32 v66, v66
	v_add_f32_e32 v62, 1.0, v62
	v_rcp_f32_e32 v67, v67
	v_add_f32_e32 v63, 1.0, v63
	v_pk_mul_f32 v[88:89], v[76:77], v[74:75]
	v_cvt_pk_bf16_f32 v74, v78, v79
	v_add_co_u32_e32 v78, vcc, s79, v212
	v_rcp_f32_e32 v62, v62
	v_rcp_f32_e32 v63, v63
	global_store_dwordx4 v[212:213], v[178:181], off
	v_cvt_pk_bf16_f32 v75, v80, v81
	v_cvt_pk_bf16_f32 v76, v86, v87
	v_cvt_pk_bf16_f32 v77, v88, v89
	v_addc_co_u32_e32 v79, vcc, 0, v213, vcc
	global_store_dwordx4 v[78:79], v[74:77], off
	v_mul_f32_e32 v54, 0xbfb8aa3b, v54
	v_mul_f32_e32 v55, 0xbfb8aa3b, v55
	s_waitcnt vmcnt(15)
	v_lshlrev_b32_e32 v74, 16, v106
	v_and_b32_e32 v75, 0xffff0000, v106
	v_pk_mul_f32 v[66:67], v[66:67], v[74:75]
	v_lshlrev_b32_e32 v74, 16, v108
	v_and_b32_e32 v75, 0xffff0000, v108
	v_pk_mul_f32 v[74:75], v[62:63], v[74:75]
	v_mul_f32_e32 v63, 0xbfb8aa3b, v64
	v_exp_f32_e32 v63, v63
	v_mul_f32_e32 v62, 0xbfb8aa3b, v68
	v_exp_f32_e32 v62, v62
	v_lshlrev_b32_e32 v68, 16, v107
	v_add_f32_e32 v63, 1.0, v63
	v_rcp_f32_e32 v64, v63
	v_mul_f32_e32 v63, 0xbfb8aa3b, v69
	v_exp_f32_e32 v63, v63
	v_add_f32_e32 v62, 1.0, v62
	v_rcp_f32_e32 v62, v62
	v_and_b32_e32 v69, 0xffff0000, v107
	v_add_f32_e32 v63, 1.0, v63
	v_rcp_f32_e32 v63, v63
	v_exp_f32_e32 v54, v54
	v_mul_f32_e32 v50, 0xbfb8aa3b, v50
	v_exp_f32_e32 v55, v55
	v_pk_mul_f32 v[68:69], v[62:63], v[68:69]
	v_mul_f32_e32 v62, 0xbfb8aa3b, v65
	v_exp_f32_e32 v62, v62
	v_mul_f32_e32 v51, 0xbfb8aa3b, v51
	v_exp_f32_e32 v50, v50
	v_exp_f32_e32 v51, v51
	v_add_f32_e32 v62, 1.0, v62
	v_rcp_f32_e32 v65, v62
	v_add_f32_e32 v54, 1.0, v54
	v_add_f32_e32 v55, 1.0, v55
	v_lshlrev_b32_e32 v62, 16, v109
	v_and_b32_e32 v63, 0xffff0000, v109
	v_rcp_f32_e32 v54, v54
	v_add_f32_e32 v50, 1.0, v50
	v_rcp_f32_e32 v55, v55
	v_add_f32_e32 v51, 1.0, v51
	v_pk_mul_f32 v[76:77], v[64:65], v[62:63]
	v_rcp_f32_e32 v50, v50
	v_rcp_f32_e32 v51, v51
	v_cvt_pk_bf16_f32 v62, v66, v67
	v_cvt_pk_bf16_f32 v63, v68, v69
	v_cvt_pk_bf16_f32 v64, v74, v75
	v_cvt_pk_bf16_f32 v65, v76, v77
	global_store_dwordx4 v[78:79], v[62:65], off offset:256
	v_mul_f32_e32 v42, 0xbfb8aa3b, v42
	v_mul_f32_e32 v43, 0xbfb8aa3b, v43
	s_waitcnt vmcnt(15)
	v_lshlrev_b32_e32 v62, 16, v94
	v_and_b32_e32 v63, 0xffff0000, v94
	v_pk_mul_f32 v[54:55], v[54:55], v[62:63]
	v_lshlrev_b32_e32 v62, 16, v96
	v_and_b32_e32 v63, 0xffff0000, v96
	v_pk_mul_f32 v[62:63], v[50:51], v[62:63]
	v_mul_f32_e32 v51, 0xbfb8aa3b, v52
	v_exp_f32_e32 v51, v51
	v_mul_f32_e32 v50, 0xbfb8aa3b, v56
	v_exp_f32_e32 v50, v50
	v_lshlrev_b32_e32 v56, 16, v95
	v_add_f32_e32 v51, 1.0, v51
	v_rcp_f32_e32 v52, v51
	v_mul_f32_e32 v51, 0xbfb8aa3b, v57
	v_exp_f32_e32 v51, v51
	v_add_f32_e32 v50, 1.0, v50
	v_rcp_f32_e32 v50, v50
	v_and_b32_e32 v57, 0xffff0000, v95
	v_add_f32_e32 v51, 1.0, v51
	v_rcp_f32_e32 v51, v51
	v_exp_f32_e32 v42, v42
	v_mul_f32_e32 v38, 0xbfb8aa3b, v38
	v_exp_f32_e32 v43, v43
	v_pk_mul_f32 v[56:57], v[50:51], v[56:57]
	v_mul_f32_e32 v50, 0xbfb8aa3b, v53
	v_exp_f32_e32 v50, v50
	v_mul_f32_e32 v39, 0xbfb8aa3b, v39
	v_exp_f32_e32 v38, v38
	v_exp_f32_e32 v39, v39
	v_add_f32_e32 v50, 1.0, v50
	v_rcp_f32_e32 v53, v50
	v_add_f32_e32 v42, 1.0, v42
	v_add_f32_e32 v43, 1.0, v43
	v_lshlrev_b32_e32 v50, 16, v97
	v_and_b32_e32 v51, 0xffff0000, v97
	v_rcp_f32_e32 v42, v42
	v_add_f32_e32 v38, 1.0, v38
	v_rcp_f32_e32 v43, v43
	v_add_f32_e32 v39, 1.0, v39
	v_pk_mul_f32 v[64:65], v[52:53], v[50:51]
	v_cvt_pk_bf16_f32 v50, v54, v55
	v_add_co_u32_e32 v54, vcc, s11, v212
	v_rcp_f32_e32 v38, v38
	v_rcp_f32_e32 v39, v39
	v_cvt_pk_bf16_f32 v51, v56, v57
	v_cvt_pk_bf16_f32 v52, v62, v63
	v_cvt_pk_bf16_f32 v53, v64, v65
	v_addc_co_u32_e32 v55, vcc, 0, v213, vcc
	global_store_dwordx4 v[54:55], v[50:53], off
	v_mul_f32_e32 v30, 0xbfb8aa3b, v30
	v_mul_f32_e32 v31, 0xbfb8aa3b, v31
	s_waitcnt vmcnt(15)
; __device__ __forceinline__ void unpack8(const u32x4 w, float (&v)[8]) { v[0] = bflo(w.x); v[1] = bfhi(w.x); v[2] = bflo(w.y); v[3] = bfhi(w.y); v[4] = bflo(w.z); v[5] = bfhi(w.z); v[6] = bflo(w.w); v[7] = bfhi(w.w); }
; __device__ __forceinline__ u32x4 pack8(const float (&v)[8]) { u32x4 w; w.x = pk2(v[0], v[1]); w.y = pk2(v[2], v[3]); w.z = pk2(v[4], v[5]); w.w = pk2(v[6], v[7]); return w; }
; __device__ __forceinline__ float sigmoidf_(float x) { return __builtin_amdgcn_rcpf(1.0f + __builtin_amdgcn_exp2f(-LOG2E * x)); }
;     __device__ __forceinline__ bool operator()(Acc& acc, const Unit& u, int wr, int wc, int fr, int fq, const LAS float*) const {
;     ...
; #pragma unroll
;         for (int ai = 0; ai < 2; ++ai) {
; #pragma unroll
;             for (int m = 0; m < 4; ++m)
; #pragma unroll
;                 for (int bj = 0; bj < 2; ++bj) {
;                     float y[8]; unpack8(yv[ai][m][bj], y);
;                     float v[8];
; #pragma unroll
;                     for (int e = 0; e < 4; ++e) { v[e] = y[e] * sigmoidf_(acc[ai][bj][m][0][e]); v[4 + e] = y[4 + e] * sigmoidf_(acc[ai][bj][m][1][e]); }
;                     gst<u32x4>(zp + (ai * HALF + m * 16) * 512 + bj * HALF, pack8(v));
;                 }
;             asm volatile("" ::: "memory");
	v_lshlrev_b32_e32 v50, 16, v82
	v_and_b32_e32 v51, 0xffff0000, v82
	v_pk_mul_f32 v[42:43], v[42:43], v[50:51]
	v_lshlrev_b32_e32 v50, 16, v84
	v_and_b32_e32 v51, 0xffff0000, v84
	v_pk_mul_f32 v[50:51], v[38:39], v[50:51]
	v_mul_f32_e32 v39, 0xbfb8aa3b, v40
	v_exp_f32_e32 v39, v39
	v_mul_f32_e32 v38, 0xbfb8aa3b, v44
	v_exp_f32_e32 v38, v38
	v_lshlrev_b32_e32 v44, 16, v83
	v_add_f32_e32 v39, 1.0, v39
	v_rcp_f32_e32 v40, v39
	v_mul_f32_e32 v39, 0xbfb8aa3b, v45
	v_exp_f32_e32 v39, v39
	v_add_f32_e32 v38, 1.0, v38
	v_rcp_f32_e32 v38, v38
	v_and_b32_e32 v45, 0xffff0000, v83
	v_add_f32_e32 v39, 1.0, v39
	v_rcp_f32_e32 v39, v39
	v_exp_f32_e32 v30, v30
	v_mul_f32_e32 v26, 0xbfb8aa3b, v26
	v_exp_f32_e32 v31, v31
	v_pk_mul_f32 v[44:45], v[38:39], v[44:45]
	v_mul_f32_e32 v38, 0xbfb8aa3b, v41
	v_exp_f32_e32 v38, v38
	v_mul_f32_e32 v27, 0xbfb8aa3b, v27
	v_exp_f32_e32 v26, v26
	v_exp_f32_e32 v27, v27
	v_add_f32_e32 v38, 1.0, v38
	v_rcp_f32_e32 v41, v38
	v_add_f32_e32 v30, 1.0, v30
	v_add_f32_e32 v31, 1.0, v31
	v_lshlrev_b32_e32 v38, 16, v85
	v_and_b32_e32 v39, 0xffff0000, v85
	v_rcp_f32_e32 v30, v30
	v_add_f32_e32 v26, 1.0, v26
	v_rcp_f32_e32 v31, v31
	v_add_f32_e32 v27, 1.0, v27
	v_pk_mul_f32 v[52:53], v[40:41], v[38:39]
	v_rcp_f32_e32 v26, v26
	v_rcp_f32_e32 v27, v27
	v_cvt_pk_bf16_f32 v38, v42, v43
	v_cvt_pk_bf16_f32 v39, v44, v45
	v_cvt_pk_bf16_f32 v40, v50, v51
	v_cvt_pk_bf16_f32 v41, v52, v53
	global_store_dwordx4 v[54:55], v[38:41], off offset:256
	v_mul_f32_e32 v22, 0xbfb8aa3b, v22
	v_mul_f32_e32 v23, 0xbfb8aa3b, v23
	s_waitcnt vmcnt(15)
	v_lshlrev_b32_e32 v38, 16, v70
	v_and_b32_e32 v39, 0xffff0000, v70
	v_pk_mul_f32 v[30:31], v[30:31], v[38:39]
	v_lshlrev_b32_e32 v38, 16, v72
	v_and_b32_e32 v39, 0xffff0000, v72
	v_pk_mul_f32 v[38:39], v[26:27], v[38:39]
	v_mul_f32_e32 v27, 0xbfb8aa3b, v28
	v_exp_f32_e32 v27, v27
	v_mul_f32_e32 v26, 0xbfb8aa3b, v32
	v_exp_f32_e32 v26, v26
	v_lshlrev_b32_e32 v32, 16, v71
	v_add_f32_e32 v27, 1.0, v27
	v_rcp_f32_e32 v28, v27
	v_mul_f32_e32 v27, 0xbfb8aa3b, v33
	v_exp_f32_e32 v27, v27
	v_add_f32_e32 v26, 1.0, v26
	v_rcp_f32_e32 v26, v26
	v_and_b32_e32 v33, 0xffff0000, v71
	v_add_f32_e32 v27, 1.0, v27
	v_rcp_f32_e32 v27, v27
	v_exp_f32_e32 v22, v22
	v_mul_f32_e32 v18, 0xbfb8aa3b, v18
	v_exp_f32_e32 v23, v23
	v_pk_mul_f32 v[32:33], v[26:27], v[32:33]
	v_mul_f32_e32 v26, 0xbfb8aa3b, v29
	v_exp_f32_e32 v26, v26
	v_mul_f32_e32 v19, 0xbfb8aa3b, v19
	v_exp_f32_e32 v18, v18
	v_exp_f32_e32 v19, v19
	v_add_f32_e32 v26, 1.0, v26
	v_rcp_f32_e32 v29, v26
	v_add_f32_e32 v22, 1.0, v22
	v_add_f32_e32 v23, 1.0, v23
	v_lshlrev_b32_e32 v26, 16, v73
	v_and_b32_e32 v27, 0xffff0000, v73
	v_rcp_f32_e32 v22, v22
	v_add_f32_e32 v18, 1.0, v18
	v_rcp_f32_e32 v23, v23
	v_add_f32_e32 v19, 1.0, v19
	v_pk_mul_f32 v[40:41], v[28:29], v[26:27]
	v_cvt_pk_bf16_f32 v26, v30, v31
	v_add_co_u32_e32 v30, vcc, s12, v212
	v_rcp_f32_e32 v18, v18
	v_rcp_f32_e32 v19, v19
	v_cvt_pk_bf16_f32 v27, v32, v33
	v_cvt_pk_bf16_f32 v28, v38, v39
	v_cvt_pk_bf16_f32 v29, v40, v41
	v_addc_co_u32_e32 v31, vcc, 0, v213, vcc
	global_store_dwordx4 v[30:31], v[26:29], off
	v_mul_f32_e32 v14, 0xbfb8aa3b, v14
	v_mul_f32_e32 v15, 0xbfb8aa3b, v15
	s_waitcnt vmcnt(15)
; __device__ __forceinline__ void unpack8(const u32x4 w, float (&v)[8]) { v[0] = bflo(w.x); v[1] = bfhi(w.x); v[2] = bflo(w.y); v[3] = bfhi(w.y); v[4] = bflo(w.z); v[5] = bfhi(w.z); v[6] = bflo(w.w); v[7] = bfhi(w.w); }
; __device__ __forceinline__ u32x4 pack8(const float (&v)[8]) { u32x4 w; w.x = pk2(v[0], v[1]); w.y = pk2(v[2], v[3]); w.z = pk2(v[4], v[5]); w.w = pk2(v[6], v[7]); return w; }
; __device__ __forceinline__ float sigmoidf_(float x) { return __builtin_amdgcn_rcpf(1.0f + __builtin_amdgcn_exp2f(-LOG2E * x)); }
; #define PG8_BAR __builtin_amdgcn_s_barrier()
;     __device__ __forceinline__ bool operator()(Acc& acc, const Unit& u, int wr, int wc, int fr, int fq, const LAS float*) const {
;     ...
;         for (int ai = 0; ai < 2; ++ai) {
; #pragma unroll
;             for (int m = 0; m < 4; ++m)
; #pragma unroll
;                 for (int bj = 0; bj < 2; ++bj) {
;                     float y[8]; unpack8(yv[ai][m][bj], y);
;                     float v[8];
; #pragma unroll
;                     for (int e = 0; e < 4; ++e) { v[e] = y[e] * sigmoidf_(acc[ai][bj][m][0][e]); v[4 + e] = y[4 + e] * sigmoidf_(acc[ai][bj][m][1][e]); }
;                     gst<u32x4>(zp + (ai * HALF + m * 16) * 512 + bj * HALF, pack8(v));
;                 }
;             asm volatile("" ::: "memory");
; template <class Epi, bool ALIGN_EPI, bool SP2, class Hook>
; __device__ __forceinline__ void gemm_phase(LAS unsigned char* lds, const Gemm g, const StaticOrder& S, const Epi& E, Acc& acc, const bool fresh, const Hook& H, const int wave_id) {
;     ...
;         if (!has_next) break;
;         if (reset) {
; #pragma unroll
;             for (int a = 0; a < 2; ++a)
; #pragma unroll
;                 for (int b = 0; b < 2; ++b)
; #pragma unroll
;                     for (int m = 0; m < 4; ++m)
; #pragma unroll
;                         for (int n = 0; n < 2; ++n) acc[a][b][m][n] = (f32x4){0.f, 0.f, 0.f, 0.f};
;         }
;         cur = nxt; cA = nA; cB = nB; ++ui;
;         if constexpr (ALIGN_EPI) { if (wr == 1) PG8_BAR; }
	v_lshlrev_b32_e32 v26, 16, v58
	v_and_b32_e32 v27, 0xffff0000, v58
	v_pk_mul_f32 v[22:23], v[22:23], v[26:27]
	v_lshlrev_b32_e32 v26, 16, v60
	v_and_b32_e32 v27, 0xffff0000, v60
	v_pk_mul_f32 v[26:27], v[18:19], v[26:27]
	v_mul_f32_e32 v19, 0xbfb8aa3b, v20
	v_exp_f32_e32 v19, v19
	v_mul_f32_e32 v18, 0xbfb8aa3b, v24
	v_exp_f32_e32 v18, v18
	v_lshlrev_b32_e32 v24, 16, v59
	v_add_f32_e32 v19, 1.0, v19
	v_rcp_f32_e32 v20, v19
	v_mul_f32_e32 v19, 0xbfb8aa3b, v25
	v_exp_f32_e32 v19, v19
	v_add_f32_e32 v18, 1.0, v18
	v_rcp_f32_e32 v18, v18
	v_and_b32_e32 v25, 0xffff0000, v59
	v_add_f32_e32 v19, 1.0, v19
	v_rcp_f32_e32 v19, v19
	v_exp_f32_e32 v14, v14
	v_mul_f32_e32 v10, 0xbfb8aa3b, v10
	v_exp_f32_e32 v15, v15
	v_pk_mul_f32 v[24:25], v[18:19], v[24:25]
	v_mul_f32_e32 v18, 0xbfb8aa3b, v21
	v_exp_f32_e32 v18, v18
	v_mul_f32_e32 v11, 0xbfb8aa3b, v11
	v_exp_f32_e32 v10, v10
	v_exp_f32_e32 v11, v11
	v_add_f32_e32 v18, 1.0, v18
	v_rcp_f32_e32 v21, v18
	v_add_f32_e32 v14, 1.0, v14
	v_add_f32_e32 v15, 1.0, v15
	v_lshlrev_b32_e32 v18, 16, v61
	v_and_b32_e32 v19, 0xffff0000, v61
	v_rcp_f32_e32 v14, v14
	v_add_f32_e32 v10, 1.0, v10
	v_rcp_f32_e32 v15, v15
	v_add_f32_e32 v11, 1.0, v11
	v_pk_mul_f32 v[28:29], v[20:21], v[18:19]
	v_rcp_f32_e32 v10, v10
	v_rcp_f32_e32 v11, v11
	v_cvt_pk_bf16_f32 v18, v22, v23
	v_cvt_pk_bf16_f32 v19, v24, v25
	v_cvt_pk_bf16_f32 v20, v26, v27
	v_cvt_pk_bf16_f32 v21, v28, v29
	global_store_dwordx4 v[30:31], v[18:21], off offset:256
	v_mul_f32_e32 v6, 0xbfb8aa3b, v6
	v_mul_f32_e32 v7, 0xbfb8aa3b, v7
	s_waitcnt vmcnt(15)
	v_lshlrev_b32_e32 v18, 16, v46
	v_and_b32_e32 v19, 0xffff0000, v46
	v_pk_mul_f32 v[14:15], v[14:15], v[18:19]
	v_lshlrev_b32_e32 v18, 16, v48
	v_and_b32_e32 v19, 0xffff0000, v48
	v_pk_mul_f32 v[18:19], v[10:11], v[18:19]
	v_mul_f32_e32 v11, 0xbfb8aa3b, v12
	v_exp_f32_e32 v11, v11
	v_mul_f32_e32 v10, 0xbfb8aa3b, v16
	v_exp_f32_e32 v10, v10
	v_lshlrev_b32_e32 v16, 16, v47
	v_add_f32_e32 v11, 1.0, v11
	v_rcp_f32_e32 v12, v11
	v_mul_f32_e32 v11, 0xbfb8aa3b, v17
	v_exp_f32_e32 v11, v11
	v_add_f32_e32 v10, 1.0, v10
	v_rcp_f32_e32 v10, v10
	v_and_b32_e32 v17, 0xffff0000, v47
	v_add_f32_e32 v11, 1.0, v11
	v_rcp_f32_e32 v11, v11
	v_exp_f32_e32 v6, v6
	v_mul_f32_e32 v2, 0xbfb8aa3b, v2
	v_exp_f32_e32 v7, v7
	v_pk_mul_f32 v[16:17], v[10:11], v[16:17]
	v_mul_f32_e32 v10, 0xbfb8aa3b, v13
	v_exp_f32_e32 v10, v10
	v_mul_f32_e32 v3, 0xbfb8aa3b, v3
	v_exp_f32_e32 v2, v2
	v_exp_f32_e32 v3, v3
	v_add_f32_e32 v10, 1.0, v10
	v_rcp_f32_e32 v13, v10
	v_add_f32_e32 v6, 1.0, v6
	v_add_f32_e32 v7, 1.0, v7
	v_lshlrev_b32_e32 v10, 16, v49
	v_and_b32_e32 v11, 0xffff0000, v49
	v_rcp_f32_e32 v6, v6
	v_add_f32_e32 v2, 1.0, v2
	v_rcp_f32_e32 v7, v7
	v_add_f32_e32 v3, 1.0, v3
	v_pk_mul_f32 v[20:21], v[12:13], v[10:11]
	v_cvt_pk_bf16_f32 v10, v14, v15
	v_add_co_u32_e32 v14, vcc, s13, v212
	v_rcp_f32_e32 v2, v2
	v_rcp_f32_e32 v3, v3
	v_cvt_pk_bf16_f32 v11, v16, v17
	v_cvt_pk_bf16_f32 v12, v18, v19
	v_cvt_pk_bf16_f32 v13, v20, v21
	v_addc_co_u32_e32 v15, vcc, 0, v213, vcc
	global_store_dwordx4 v[14:15], v[10:13], off
	s_mov_b64 s[8:9], -1
	s_and_b64 vcc, exec, s[4:5]
	s_waitcnt vmcnt(15)
	v_lshlrev_b32_e32 v10, 16, v34
	v_and_b32_e32 v11, 0xffff0000, v34
	v_pk_mul_f32 v[6:7], v[6:7], v[10:11]
	v_lshlrev_b32_e32 v10, 16, v36
	v_and_b32_e32 v11, 0xffff0000, v36
	v_pk_mul_f32 v[10:11], v[2:3], v[10:11]
	v_mul_f32_e32 v3, 0xbfb8aa3b, v4
	v_exp_f32_e32 v3, v3
	v_mul_f32_e32 v2, 0xbfb8aa3b, v8
	v_exp_f32_e32 v2, v2
	v_lshlrev_b32_e32 v8, 16, v35
	v_add_f32_e32 v3, 1.0, v3
	v_rcp_f32_e32 v4, v3
	v_mul_f32_e32 v3, 0xbfb8aa3b, v9
	v_exp_f32_e32 v3, v3
	v_add_f32_e32 v2, 1.0, v2
	v_rcp_f32_e32 v2, v2
	v_and_b32_e32 v9, 0xffff0000, v35
	v_add_f32_e32 v3, 1.0, v3
	v_rcp_f32_e32 v3, v3
	s_nop 0
	v_pk_mul_f32 v[8:9], v[2:3], v[8:9]
	v_mul_f32_e32 v2, 0xbfb8aa3b, v5
	v_exp_f32_e32 v2, v2
	v_and_b32_e32 v3, 0xffff0000, v37
	v_add_f32_e32 v2, 1.0, v2
	v_rcp_f32_e32 v5, v2
	v_lshlrev_b32_e32 v2, 16, v37
	v_pk_mul_f32 v[12:13], v[4:5], v[2:3]
	v_cvt_pk_bf16_f32 v2, v6, v7
	v_cvt_pk_bf16_f32 v3, v8, v9
	v_cvt_pk_bf16_f32 v4, v10, v11
	v_cvt_pk_bf16_f32 v5, v12, v13
	global_store_dwordx4 v[14:15], v[2:5], off offset:256
	s_cbranch_vccnz .LBB0_690
	s_and_b64 vcc, exec, s[0:1]
	s_cbranch_vccnz .LBB0_689
	s_branch .LBB0_689

; #define GAS __attribute__((address_space(1)))
; __device__ __forceinline__ const bf16_t* selA(const Gemm& g, int s) { return sel3(g.A0, g.A1, g.A2, s); }
; __device__ __forceinline__ const bf16_t* selB(const Gemm& g, int s) { return sel3(g.B0, g.B1, g.B2, s); }
; __device__ __forceinline__ Src make_src(const bf16_t* p, size_t off) { Src s_; s_.r = __builtin_amdgcn_make_buffer_rsrc((void*)p, (short)0, 0x7fffffff, 0x00020000); s_.o = (unsigned)off; return s_; }
; #define PG8_BAR __builtin_amdgcn_s_barrier()
; template <class Epi, bool ALIGN_EPI, bool SP2, class Hook>
; __device__ __forceinline__ void gemm_phase(LAS unsigned char* lds, const Gemm g, const StaticOrder& S, const Epi& E, Acc& acc, const bool fresh, const Hook& H, const int wave_id) {
;     ...
;     for (int i = 0; i < 2; ++i) { int R, C; stage_rc(tid * 16 + i * 8192, R, C); const int Rb = (R & ~31) + perm32(R & 31);
;         voffA[i] = (unsigned)(R * lda + C) * 2u; voffB[i] = (unsigned)(Rb * K + C) * 2u; }
;     const size_t kstep = (size_t)(BK * 2);
;     const size_t hstep = (size_t)HALF * K * 2, hstepA = (size_t)HALF * lda * 2;
;     const size_t tstep = 2 * hstep, tstepA = 2 * hstepA;
;     const unsigned ldsw = (unsigned)wid * 1024u;
;     const int aoff = lds_byte(wr * 64 + fr, fq * 8), boff = lds_byte(wc * 32 + fr, fq * 8);
;     ...
;     Unit cur, nxt; int ui = 0, rs_pm = -1, t0 = 0;
;     if (!S.next(0, cur)) return;
;     if (fresh) {
; #pragma unroll
;         for (int a = 0; a < 2; ++a)
; #pragma unroll
;             for (int b = 0; b < 2; ++b)
; #pragma unroll
;                 for (int m = 0; m < 4; ++m)
; #pragma unroll
;                     for (int n = 0; n < 2; ++n) acc[a][b][m][n] = (f32x4){0.f, 0.f, 0.f, 0.f};
;     }
;     bf16x8 At[4][2], B0[2][2], B1[2][2];
;     Src cA = make_src(selA(g, cur.seg), (size_t)cur.pm * tstepA), cB = make_src(selB(g, cur.seg), (size_t)cur.pn * tstep);
;     if constexpr (SP2) {
;         f32x4 rpa = {0.f, 0.f, 0.f, 0.f}, rpb = rpa;
;         float rsum = 0.f;
;         if constexpr (Epi::NEEDS_RS) { const GAS f32x4* p = (const GAS f32x4*)(E.rowss + (size_t)(cur.pm * BM + (tid >> 1)) * 16) + (tid & 1) * 2; rpa = p[0]; rpb = p[1]; }
;         PG8_STAGE(PG8_SB(0, 0), cB, voffB); PG8_STAGE(PG8_SB(0, 1), cB + hstep, voffB); PG8_STAGE(PG8_SA(0, 0), cA, voffA); PG8_STAGE(PG8_SA(0, 1), cA + hstepA, voffA);
;         if (wr == 1) PG8_BAR;
.LBB0_761:
	v_readlane_b32 s0, v249, 54
	v_readlane_b32 s2, v249, 56
	v_readlane_b32 s1, v249, 55
	v_readlane_b32 s3, v249, 57
	s_cmp_le_i32 s2, s16
	s_cselect_b64 s[0:1], -1, 0
	s_cmp_lt_i32 s16, s3
	s_cselect_b64 s[2:3], -1, 0
	s_and_b64 s[0:1], s[0:1], s[2:3]
	s_andn2_b64 vcc, exec, s[0:1]
	s_cbranch_vccnz .LBB0_884
	v_readlane_b32 s0, v251, 40
	v_readlane_b32 s1, v251, 41
	v_mov_b32_e32 v0, v1
	s_andn2_b64 vcc, exec, s[0:1]
	s_cbranch_vccnz .LBB0_884
	v_mbcnt_lo_u32_b32 v0, -1, v0
	v_mbcnt_hi_u32_b32 v0, -1, v0
	v_readlane_b32 s0, v250, 8
	v_readlane_b32 s2, v254, 53
	v_readlane_b32 s3, v254, 54
	v_lshl_add_u32 v2, v0, 4, s0
	v_ashrrev_i32_e32 v3, 31, v2
	v_lshrrev_b32_e32 v3, 22, v3
	v_add_u32_e32 v3, v2, v3
	v_ashrrev_i32_e32 v3, 10, v3
	v_mul_i32_i24_e32 v4, 0x400, v3
	v_sub_u32_e32 v4, v2, v4
	s_waitcnt lgkmcnt(0)
	v_lshrrev_b32_e32 v5, 4, v4
	v_bitop3_b32 v4, v5, v4, 32 bitop3:0x6c
	v_ashrrev_i32_e32 v6, 31, v4
	v_lshrrev_b32_e32 v6, 26, v6
	v_lshlrev_b32_e32 v5, 3, v3
	v_add_u32_e32 v6, v4, v6
	v_and_b32_e32 v5, -16, v5
	v_ashrrev_i32_e32 v7, 6, v6
	v_and_b32_e32 v6, 0xc0, v6
	v_add_u32_e32 v5, v7, v5
	v_sub_u32_e32 v4, v4, v6
	v_lshlrev_b32_e32 v3, 5, v3
	v_ashrrev_i16_sdwa v4, v226, sext(v4) dst_sel:DWORD dst_unused:UNUSED_PAD src0_sel:DWORD src1_sel:BYTE_0
	v_lshlrev_b32_e32 v6, 1, v5
	v_lshrrev_b32_e32 v8, 2, v5
	v_and_b32_e32 v7, 3, v7
	s_mov_b32 s0, 0x3fffe0
	v_and_b32_e32 v3, 32, v3
	v_bfe_i32 v4, v4, 0, 16
	v_and_b32_e32 v6, 24, v6
	v_and_b32_e32 v8, 4, v8
	v_and_or_b32 v7, v5, s0, v7
	v_or3_b32 v6, v7, v8, v6
	v_add_lshl_u32 v3, v3, v4, 1
	v_add_u32_e32 v2, 0x2000, v2
	v_lshl_add_u32 v199, v5, 10, v3
	v_lshl_add_u32 v227, v6, 10, v3
	v_ashrrev_i32_e32 v3, 31, v2
	v_lshrrev_b32_e32 v3, 22, v3
	v_add_u32_e32 v3, v2, v3
	v_ashrrev_i32_e32 v3, 10, v3
	v_mul_i32_i24_e32 v4, 0x400, v3
	v_sub_u32_e32 v2, v2, v4
	v_lshrrev_b32_e32 v4, 4, v2
	v_bitop3_b32 v2, v4, v2, 32 bitop3:0x6c
	v_ashrrev_i32_e32 v5, 31, v2
	v_lshrrev_b32_e32 v5, 26, v5
	v_lshlrev_b32_e32 v4, 3, v3
	v_add_u32_e32 v5, v2, v5
	v_and_b32_e32 v4, -16, v4
	v_ashrrev_i32_e32 v6, 6, v5
	v_add_u32_e32 v4, v6, v4
	v_and_b32_e32 v6, 3, v6
	v_and_or_b32 v6, v4, s0, v6
	v_readlane_b32 s0, v254, 47
	v_readlane_b32 s1, v254, 48
	s_add_u32 s26, s0, 0xe00000
	s_addc_u32 s27, s1, 0
	s_add_u32 s28, s0, 0xc80000
	v_and_b32_e32 v5, 0xffc0, v5
	s_addc_u32 s29, s1, 0
	v_sub_u32_e32 v2, v2, v5
	s_add_u32 s30, s0, 0xb80000
	v_lshrrev_b16_e32 v5, 7, v2
	s_addc_u32 s31, s1, 0
	v_readlane_b32 s0, v254, 59
	s_mov_b64 s[8:9], s[2:3]
	v_readlane_b32 s2, v254, 55
	v_and_b32_e32 v5, 1, v5
	v_readlane_b32 s1, v254, 60
	v_readlane_b32 s3, v254, 56
	v_add_u16_e32 v2, v2, v5
	v_lshlrev_b32_e32 v3, 5, v3
	v_ashrrev_i16_sdwa v2, v226, sext(v2) dst_sel:DWORD dst_unused:UNUSED_PAD src0_sel:DWORD src1_sel:BYTE_0
	v_lshlrev_b32_e32 v5, 1, v4
	v_lshrrev_b32_e32 v7, 2, v4
	s_mov_b64 s[76:77], s[30:31]
	s_mov_b64 s[0:1], s[26:27]
	s_mov_b64 s[2:3], s[28:29]
	v_and_b32_e32 v3, 32, v3
	v_bfe_i32 v2, v2, 0, 16
	v_and_b32_e32 v5, 24, v5
	v_and_b32_e32 v7, 4, v7
	s_mov_b32 m0, s92
	v_or3_b32 v5, v6, v7, v5
	v_add_lshl_u32 v2, v3, v2, 1
	s_and_b32 s77, s77, 0xffff
	v_readlane_b32 s0, v253, 52
	v_lshl_add_u32 v229, v5, 10, v2
	s_and_b32 s9, s9, 0xffff
	s_mov_b32 s10, s78
	s_mov_b32 s11, s79
	v_lshl_add_u32 v228, v4, 10, v2
	buffer_load_dwordx4 v227, s[76:79], s0 offen lds
	s_mov_b32 m0, s93
	v_readlane_b32 s2, v250, 9
	buffer_load_dwordx4 v229, s[76:79], s0 offen lds
	s_mov_b32 m0, s94
	v_readlane_b32 s0, v253, 47
	v_readlane_b32 s3, v250, 10
	s_andn2_b64 vcc, exec, s[2:3]
	s_nop 0
	v_cndmask_b32_e64 v2, 0, 1, s[2:3]
	s_nop 0
	buffer_load_dwordx4 v227, s[76:79], s0 offen lds
	s_mov_b32 m0, s95
	s_nop 0
	buffer_load_dwordx4 v229, s[76:79], s0 offen lds
	s_mov_b32 m0, s44
	v_readlane_b32 s0, v253, 50
	s_nop 4
	buffer_load_dwordx4 v199, s[8:11], s0 offen lds
	s_mov_b32 m0, s36
	s_nop 0
	buffer_load_dwordx4 v228, s[8:11], s0 offen lds
	s_mov_b32 m0, s37
	v_readlane_b32 s0, v253, 48
	s_nop 4
	buffer_load_dwordx4 v199, s[8:11], s0 offen lds
	s_mov_b32 m0, s38
	s_nop 0
	buffer_load_dwordx4 v228, s[8:11], s0 offen lds
	v_cmp_ne_u32_e64 s[0:1], 1, v2
	s_cbranch_vccnz .LBB0_765
; #define LAS __attribute__((address_space(3)))
; #define GAS __attribute__((address_space(1)))
; __device__ __forceinline__ const bf16_t* selA(const Gemm& g, int s) { return sel3(g.A0, g.A1, g.A2, s); }
; __device__ __forceinline__ const bf16_t* selB(const Gemm& g, int s) { return sel3(g.B0, g.B1, g.B2, s); }
; #define PG8_WAIT_V(n) asm volatile("s_waitcnt vmcnt(" #n ")" ::: "memory")
; #define PG8_BAR __builtin_amdgcn_s_barrier()
; template <class Epi, bool ALIGN_EPI, bool SP2, class Hook>
; __device__ __forceinline__ void gemm_phase(LAS unsigned char* lds, const Gemm g, const StaticOrder& S, const Epi& E, Acc& acc, const bool fresh, const Hook& H, const int wave_id) {
;     ...
;     if (fresh) {
; #pragma unroll
;         for (int a = 0; a < 2; ++a)
; #pragma unroll
;             for (int b = 0; b < 2; ++b)
; #pragma unroll
;                 for (int m = 0; m < 4; ++m)
; #pragma unroll
;                     for (int n = 0; n < 2; ++n) acc[a][b][m][n] = (f32x4){0.f, 0.f, 0.f, 0.f};
;     }
;     bf16x8 At[4][2], B0[2][2], B1[2][2];
;     Src cA = make_src(selA(g, cur.seg), (size_t)cur.pm * tstepA), cB = make_src(selB(g, cur.seg), (size_t)cur.pn * tstep);
;     if constexpr (SP2) {
;         f32x4 rpa = {0.f, 0.f, 0.f, 0.f}, rpb = rpa;
;         float rsum = 0.f;
;         if constexpr (Epi::NEEDS_RS) { const GAS f32x4* p = (const GAS f32x4*)(E.rowss + (size_t)(cur.pm * BM + (tid >> 1)) * 16) + (tid & 1) * 2; rpa = p[0]; rpb = p[1]; }
;         PG8_STAGE(PG8_SB(0, 0), cB, voffB); PG8_STAGE(PG8_SB(0, 1), cB + hstep, voffB); PG8_STAGE(PG8_SA(0, 0), cA, voffA); PG8_STAGE(PG8_SA(0, 1), cA + hstepA, voffA);
;         if (wr == 1) PG8_BAR;
;         PG8_WAIT_V(2); PG8_BAR;
;         if constexpr (Epi::NEEDS_RS) {
;             rsum = ((rpa[0] + rpa[1]) + (rpa[2] + rpa[3])) + ((rpb[0] + rpb[1]) + (rpb[2] + rpb[3]));
;             const float t2 = __builtin_bit_cast(float, __builtin_amdgcn_update_dpp(0, __builtin_bit_cast(int, rsum), 0xB1  , 0xf, 0xf, false)); rsum = (tid & 1) ? (t2 + rsum) : (rsum + t2);
;             if ((tid & 1) == 0) ((LAS float*)(lds + RSTAB_OFF))[tid >> 1] = __builtin_amdgcn_rsqf(rsum * (1.0f / DM) + NORM_EPS);
;             rs_pm = cur.pm;
;         }
;         PG8_STAGE(PG8_SB(1, 0), cB + kstep, voffB); PG8_STAGE(PG8_SA(1, 0), cA + kstep, voffA); PG8_STAGE(PG8_SB(1, 1), cB + hstep + kstep, voffB);
;         PG8_WAIT_V(6); PG8_BAR;
.LBB0_765:
	v_and_b32_e32 v2, 15, v0
	v_readlane_b32 s2, v250, 1
	v_and_b32_e32 v4, 48, v0
	v_lshlrev_b32_e32 v0, 2, v0
	v_or_b32_e32 v3, s2, v2
	v_lshlrev_b32_e32 v5, 6, v3
	s_movk_i32 s2, 0x3c0
	v_lshlrev_b32_e32 v3, 2, v3
	v_and_or_b32 v5, v5, s2, v4
	v_and_b32_e32 v3, 32, v3
	v_readlane_b32 s2, v250, 2
	v_lshl_or_b32 v2, v2, 6, v4
	v_and_b32_e32 v0, 32, v0
	v_bitop3_b32 v3, v5, s2, v3 bitop3:0xde
	v_readlane_b32 s2, v253, 4
	s_mov_b32 m0, s39
	s_waitcnt vmcnt(2)
	s_barrier
	v_bitop3_b32 v0, v2, s2, v0 bitop3:0xde
	v_readlane_b32 s2, v253, 49
	s_mov_b32 s10, s78
	s_mov_b32 s11, s79
	v_mov_b32_e32 v2, 0
	s_mov_b32 s62, 0
	v_add_u32_e32 v230, 0, v0
	buffer_load_dwordx4 v227, s[76:79], s2 offen lds
	s_mov_b32 m0, s40
	v_add_u32_e32 v231, 0, v3
	buffer_load_dwordx4 v229, s[76:79], s2 offen lds
	s_mov_b32 m0, s41
	v_readlane_b32 s2, v253, 51
	v_readlane_b32 s20, v254, 7
	v_readlane_b32 s21, v254, 9
	s_mov_b64 s[6:7], s[78:79]
	v_readlane_b32 s12, v253, 52
	v_readlane_b32 s13, v253, 50
	buffer_load_dwordx4 v199, s[8:11], s2 offen lds
	s_mov_b32 m0, s33
	s_mov_b32 s56, 0
	buffer_load_dwordx4 v228, s[8:11], s2 offen lds
	s_mov_b32 m0, s43
	v_readlane_b32 s2, v253, 53
	s_mov_b64 s[10:11], s[78:79]
	v_mov_b32_e32 v3, v2
	v_mov_b32_e32 v4, v2
	v_mov_b32_e32 v5, v2
	v_mov_b32_e32 v6, v2
	buffer_load_dwordx4 v227, s[76:79], s2 offen lds
	s_mov_b32 m0, s42
	v_mov_b32_e32 v7, v2
	buffer_load_dwordx4 v229, s[76:79], s2 offen lds
	s_waitcnt vmcnt(6)
	v_mov_b32_e32 v8, v2
	v_mov_b32_e32 v9, v2
	v_mov_b32_e32 v10, v2
	v_mov_b32_e32 v11, v2
	v_mov_b32_e32 v12, v2
	v_mov_b32_e32 v13, v2
	v_mov_b32_e32 v14, v2
	v_mov_b32_e32 v15, v2
	v_mov_b32_e32 v16, v2
	v_mov_b32_e32 v17, v2
	v_mov_b32_e32 v18, v2
	v_mov_b32_e32 v19, v2
	v_mov_b32_e32 v20, v2
	v_mov_b32_e32 v21, v2
	v_mov_b32_e32 v22, v2
	v_mov_b32_e32 v23, v2
	v_mov_b32_e32 v24, v2
	v_mov_b32_e32 v25, v2
	v_mov_b32_e32 v26, v2
	v_mov_b32_e32 v27, v2
	v_mov_b32_e32 v28, v2
	v_mov_b32_e32 v29, v2
	v_mov_b32_e32 v30, v2
	v_mov_b32_e32 v31, v2
	v_mov_b32_e32 v32, v2
	v_mov_b32_e32 v33, v2
	v_mov_b32_e32 v34, v2
	v_mov_b32_e32 v35, v2
	v_mov_b32_e32 v36, v2
	v_mov_b32_e32 v37, v2
	v_mov_b32_e32 v38, v2
	v_mov_b32_e32 v39, v2
	v_mov_b32_e32 v40, v2
	v_mov_b32_e32 v41, v2
	v_mov_b32_e32 v42, v2
	v_mov_b32_e32 v43, v2
	v_mov_b32_e32 v44, v2
	v_mov_b32_e32 v45, v2
	v_mov_b32_e32 v46, v2
	v_mov_b32_e32 v47, v2
	v_mov_b32_e32 v48, v2
	v_mov_b32_e32 v49, v2
	v_mov_b32_e32 v50, v2
	v_mov_b32_e32 v51, v2
	v_mov_b32_e32 v52, v2
	v_mov_b32_e32 v53, v2
	v_mov_b32_e32 v54, v2
	v_mov_b32_e32 v55, v2
	v_mov_b32_e32 v56, v2
	v_mov_b32_e32 v57, v2
	v_mov_b32_e32 v58, v2
	v_mov_b32_e32 v59, v2
	v_mov_b32_e32 v60, v2
	v_mov_b32_e32 v61, v2
	v_mov_b32_e32 v62, v2
	v_mov_b32_e32 v63, v2
	v_mov_b32_e32 v64, v2
	v_mov_b32_e32 v65, v2
	v_mov_b32_e32 v66, v2
	v_mov_b32_e32 v67, v2
	v_mov_b32_e32 v68, v2
	v_mov_b32_e32 v69, v2
	v_mov_b32_e32 v70, v2
	v_mov_b32_e32 v71, v2
	v_mov_b32_e32 v72, v2
	v_mov_b32_e32 v73, v2
	v_mov_b32_e32 v74, v2
	v_mov_b32_e32 v75, v2
	v_mov_b32_e32 v76, v2
	v_mov_b32_e32 v77, v2
	v_mov_b32_e32 v78, v2
	v_mov_b32_e32 v79, v2
	v_mov_b32_e32 v80, v2
	v_mov_b32_e32 v81, v2
	v_mov_b32_e32 v82, v2
	v_mov_b32_e32 v83, v2
	v_mov_b32_e32 v84, v2
	v_mov_b32_e32 v85, v2
	v_mov_b32_e32 v86, v2
	v_mov_b32_e32 v87, v2
	v_mov_b32_e32 v88, v2
	v_mov_b32_e32 v89, v2
	v_mov_b32_e32 v90, v2
	v_mov_b32_e32 v91, v2
	v_mov_b32_e32 v92, v2
	v_mov_b32_e32 v93, v2
	v_mov_b32_e32 v94, v2
	v_mov_b32_e32 v95, v2
	v_mov_b32_e32 v96, v2
	v_mov_b32_e32 v97, v2
	v_mov_b32_e32 v98, v2
	v_mov_b32_e32 v99, v2
	v_mov_b32_e32 v100, v2
	v_mov_b32_e32 v101, v2
	v_mov_b32_e32 v102, v2
	v_mov_b32_e32 v103, v2
	v_mov_b32_e32 v104, v2
	v_mov_b32_e32 v105, v2
	v_mov_b32_e32 v106, v2
	v_mov_b32_e32 v107, v2
	v_mov_b32_e32 v108, v2
	v_mov_b32_e32 v109, v2
	v_mov_b32_e32 v110, v2
	v_mov_b32_e32 v111, v2
	v_mov_b32_e32 v112, v2
	v_mov_b32_e32 v113, v2
	v_mov_b32_e32 v114, v2
	v_mov_b32_e32 v115, v2
	v_mov_b32_e32 v116, v2
	v_mov_b32_e32 v117, v2
	v_mov_b32_e32 v118, v2
	v_mov_b32_e32 v119, v2
	v_mov_b32_e32 v120, v2
	v_mov_b32_e32 v121, v2
	v_mov_b32_e32 v122, v2
	v_mov_b32_e32 v123, v2
	v_mov_b32_e32 v124, v2
	v_mov_b32_e32 v125, v2
	v_mov_b32_e32 v126, v2
	v_mov_b32_e32 v127, v2
	v_mov_b32_e32 v128, v2
	v_mov_b32_e32 v129, v2
	s_barrier
	s_branch .LBB0_768

; template <class Epi, bool ALIGN_EPI, bool SP2, class Hook>
; __device__ __forceinline__ void gemm_phase(LAS unsigned char* lds, const Gemm g, const StaticOrder& S, const Epi& E, Acc& acc, const bool fresh, const Hook& H, const int wave_id) {
;     ...
;             const bool last = (t == nt - 2);
;             const Src a1 = cA + (size_t)(t + 1) * kstep;
;             const Src a2 = last ? nA : cA + (size_t)(t + 2) * kstep, b2 = last ? nB : cB + (size_t)(t + 2) * kstep;
;             const Src a3 = a2 + kstep, b3 = b2 + kstep;
.LBB0_779:
	v_add_u32_e32 v0, 0x10000, v230
	s_waitcnt vmcnt(0)
	ds_read_b128 v[130:133], v0
	ds_read_b128 v[134:137], v0 offset:1024
	ds_read_b128 v[138:141], v0 offset:2048
	ds_read_b128 v[142:145], v0 offset:3072
	v_add_u32_e32 v0, 0x14000, v230
	ds_read_b128 v[146:149], v0
	ds_read_b128 v[150:153], v0 offset:1024
	ds_read_b128 v[154:157], v0 offset:2048
	ds_read_b128 v[158:161], v0 offset:3072
	s_add_i32 s12, s2, 0xfffe0080
	s_cmp_eq_u32 s63, 4
	s_cselect_b32 s66, s60, s12
	s_cselect_b32 s13, s53, s77
	s_cselect_b32 s12, s52, s76
	s_cselect_b32 s15, s55, s7
	s_cselect_b32 s14, s54, s6
	s_cselect_b32 s64, s61, s3
	s_cselect_b32 s16, s34, s8
	s_cselect_b32 s17, s35, s9
	s_cselect_b32 s18, s50, s10
	s_cselect_b32 s19, s51, s11
	s_or_b32 s65, s66, 0x80
	s_mov_b32 m0, s45
	ds_read_b128 v[162:165], v231
	ds_read_b128 v[166:169], v231 offset:1024
	ds_read_b128 v[170:173], v231 offset:2048
	ds_read_b128 v[174:177], v231 offset:3072
	ds_read_b128 v[178:181], v231 offset:4096
	ds_read_b128 v[182:185], v231 offset:5120
	ds_read_b128 v[186:189], v231 offset:6144
	ds_read_b128 v[190:193], v231 offset:7168
	buffer_load_dwordx4 v199, s[8:11], s2 offen lds
	s_mov_b32 m0, s46
	s_nop 0
	buffer_load_dwordx4 v228, s[8:11], s2 offen lds
	s_waitcnt vmcnt(8)
	s_waitcnt lgkmcnt(0)
	s_cmp_eq_u32 s100, 0
	s_cbranch_scc1 .Lhb_24
	s_barrier
.Lhb_24:
	s_setprio 1
	s_waitcnt lgkmcnt(7)
	v_mfma_f32_16x16x32_bf16 v[126:129], v[130:133], v[162:165], v[126:129]
	v_mfma_f32_16x16x32_bf16 v[122:125], v[138:141], v[162:165], v[122:125]
	s_waitcnt lgkmcnt(5)
	v_mfma_f32_16x16x32_bf16 v[118:121], v[130:133], v[170:173], v[118:121]
	v_mfma_f32_16x16x32_bf16 v[114:117], v[138:141], v[170:173], v[114:117]
	s_waitcnt lgkmcnt(3)
	v_mfma_f32_16x16x32_bf16 v[110:113], v[130:133], v[178:181], v[110:113]
	v_mfma_f32_16x16x32_bf16 v[106:109], v[138:141], v[178:181], v[106:109]
	s_waitcnt lgkmcnt(1)
	v_mfma_f32_16x16x32_bf16 v[102:105], v[130:133], v[186:189], v[102:105]
	v_mfma_f32_16x16x32_bf16 v[98:101], v[138:141], v[186:189], v[98:101]
	v_mfma_f32_16x16x32_bf16 v[126:129], v[134:137], v[166:169], v[126:129]
	v_mfma_f32_16x16x32_bf16 v[122:125], v[142:145], v[166:169], v[122:125]
	v_mfma_f32_16x16x32_bf16 v[118:121], v[134:137], v[174:177], v[118:121]
	v_mfma_f32_16x16x32_bf16 v[114:117], v[142:145], v[174:177], v[114:117]
	v_mfma_f32_16x16x32_bf16 v[110:113], v[134:137], v[182:185], v[110:113]
	v_mfma_f32_16x16x32_bf16 v[106:109], v[142:145], v[182:185], v[106:109]
	s_waitcnt lgkmcnt(0)
	v_mfma_f32_16x16x32_bf16 v[102:105], v[134:137], v[190:193], v[102:105]
	v_mfma_f32_16x16x32_bf16 v[98:101], v[142:145], v[190:193], v[98:101]
	s_setprio 0
	s_setprio 1
	v_mfma_f32_16x16x32_bf16 v[94:97], v[146:149], v[162:165], v[94:97]
	v_mfma_f32_16x16x32_bf16 v[90:93], v[154:157], v[162:165], v[90:93]
	v_mfma_f32_16x16x32_bf16 v[86:89], v[146:149], v[170:173], v[86:89]
	v_mfma_f32_16x16x32_bf16 v[82:85], v[154:157], v[170:173], v[82:85]
	v_mfma_f32_16x16x32_bf16 v[78:81], v[146:149], v[178:181], v[78:81]
	v_mfma_f32_16x16x32_bf16 v[74:77], v[154:157], v[178:181], v[74:77]
	v_mfma_f32_16x16x32_bf16 v[70:73], v[146:149], v[186:189], v[70:73]
	v_mfma_f32_16x16x32_bf16 v[66:69], v[154:157], v[186:189], v[66:69]
	v_mfma_f32_16x16x32_bf16 v[94:97], v[150:153], v[166:169], v[94:97]
	v_mfma_f32_16x16x32_bf16 v[90:93], v[158:161], v[166:169], v[90:93]
	v_mfma_f32_16x16x32_bf16 v[86:89], v[150:153], v[174:177], v[86:89]
	v_mfma_f32_16x16x32_bf16 v[82:85], v[158:161], v[174:177], v[82:85]
	v_mfma_f32_16x16x32_bf16 v[78:81], v[150:153], v[182:185], v[78:81]
	v_mfma_f32_16x16x32_bf16 v[74:77], v[158:161], v[182:185], v[74:77]
	v_mfma_f32_16x16x32_bf16 v[70:73], v[150:153], v[190:193], v[70:73]
	v_mfma_f32_16x16x32_bf16 v[66:69], v[158:161], v[190:193], v[66:69]
	s_setprio 0
	s_cmp_lg_u32 s100, 0
	s_cbranch_scc1 .Lhb_28
	s_barrier
.Lhb_28:
	s_mov_b32 m0, s92
	ds_read_b128 v[162:165], v231 offset:16384
	ds_read_b128 v[166:169], v231 offset:17408
	ds_read_b128 v[170:173], v231 offset:18432
	ds_read_b128 v[174:177], v231 offset:19456
	ds_read_b128 v[178:181], v231 offset:20480
	ds_read_b128 v[182:185], v231 offset:21504
	ds_read_b128 v[186:189], v231 offset:22528
	ds_read_b128 v[190:193], v231 offset:23552
	buffer_load_dwordx4 v227, s[12:15], s64 offen lds
	s_mov_b32 m0, s93
	s_add_i32 s67, s64, 0x20000
	buffer_load_dwordx4 v229, s[12:15], s64 offen lds
	s_mov_b32 m0, s94
	s_nop 0
	buffer_load_dwordx4 v227, s[12:15], s67 offen lds
	s_mov_b32 m0, s95
	s_nop 0
	buffer_load_dwordx4 v229, s[12:15], s67 offen lds
	s_mov_b32 m0, s44
	s_nop 0
	buffer_load_dwordx4 v199, s[16:19], s66 offen lds
	s_mov_b32 m0, s36
	s_nop 0
	buffer_load_dwordx4 v228, s[16:19], s66 offen lds
	s_waitcnt vmcnt(8)
	s_waitcnt lgkmcnt(0)
	s_cmp_eq_u32 s100, 0
	s_cbranch_scc1 .Lhb_25
	s_barrier
.Lhb_25:
	s_setprio 1
	s_waitcnt lgkmcnt(7)
	v_mfma_f32_16x16x32_bf16 v[62:65], v[130:133], v[162:165], v[62:65]
	v_mfma_f32_16x16x32_bf16 v[58:61], v[138:141], v[162:165], v[58:61]
	s_waitcnt lgkmcnt(5)
	v_mfma_f32_16x16x32_bf16 v[54:57], v[130:133], v[170:173], v[54:57]
	v_mfma_f32_16x16x32_bf16 v[50:53], v[138:141], v[170:173], v[50:53]
	s_waitcnt lgkmcnt(3)
	v_mfma_f32_16x16x32_bf16 v[46:49], v[130:133], v[178:181], v[46:49]
	v_mfma_f32_16x16x32_bf16 v[42:45], v[138:141], v[178:181], v[42:45]
	s_waitcnt lgkmcnt(1)
	v_mfma_f32_16x16x32_bf16 v[38:41], v[130:133], v[186:189], v[38:41]
	v_mfma_f32_16x16x32_bf16 v[34:37], v[138:141], v[186:189], v[34:37]
	v_mfma_f32_16x16x32_bf16 v[62:65], v[134:137], v[166:169], v[62:65]
	v_mfma_f32_16x16x32_bf16 v[58:61], v[142:145], v[166:169], v[58:61]
	v_mfma_f32_16x16x32_bf16 v[54:57], v[134:137], v[174:177], v[54:57]
	v_mfma_f32_16x16x32_bf16 v[50:53], v[142:145], v[174:177], v[50:53]
	v_mfma_f32_16x16x32_bf16 v[46:49], v[134:137], v[182:185], v[46:49]
	v_mfma_f32_16x16x32_bf16 v[42:45], v[142:145], v[182:185], v[42:45]
	s_waitcnt lgkmcnt(0)
	v_mfma_f32_16x16x32_bf16 v[38:41], v[134:137], v[190:193], v[38:41]
	v_mfma_f32_16x16x32_bf16 v[34:37], v[142:145], v[190:193], v[34:37]
	s_setprio 0
	s_setprio 1
	v_mfma_f32_16x16x32_bf16 v[30:33], v[146:149], v[162:165], v[30:33]
	v_mfma_f32_16x16x32_bf16 v[26:29], v[154:157], v[162:165], v[26:29]
	v_mfma_f32_16x16x32_bf16 v[22:25], v[146:149], v[170:173], v[22:25]
	v_mfma_f32_16x16x32_bf16 v[18:21], v[154:157], v[170:173], v[18:21]
	v_mfma_f32_16x16x32_bf16 v[14:17], v[146:149], v[178:181], v[14:17]
	v_mfma_f32_16x16x32_bf16 v[10:13], v[154:157], v[178:181], v[10:13]
	v_mfma_f32_16x16x32_bf16 v[6:9], v[146:149], v[186:189], v[6:9]
	v_mfma_f32_16x16x32_bf16 v[2:5], v[154:157], v[186:189], v[2:5]
	v_mfma_f32_16x16x32_bf16 v[30:33], v[150:153], v[166:169], v[30:33]
	v_mfma_f32_16x16x32_bf16 v[26:29], v[158:161], v[166:169], v[26:29]
	v_mfma_f32_16x16x32_bf16 v[22:25], v[150:153], v[174:177], v[22:25]
	v_mfma_f32_16x16x32_bf16 v[18:21], v[158:161], v[174:177], v[18:21]
	v_mfma_f32_16x16x32_bf16 v[14:17], v[150:153], v[182:185], v[14:17]
	v_mfma_f32_16x16x32_bf16 v[10:13], v[158:161], v[182:185], v[10:13]
	v_mfma_f32_16x16x32_bf16 v[6:9], v[150:153], v[190:193], v[6:9]
	v_mfma_f32_16x16x32_bf16 v[2:5], v[158:161], v[190:193], v[2:5]
	s_setprio 0
	s_cmp_lg_u32 s100, 0
	s_cbranch_scc1 .Lhb_29
	s_barrier
.Lhb_29:
	v_add_u32_e32 v0, 0x18000, v230
	ds_read_b128 v[130:133], v0
	ds_read_b128 v[134:137], v0 offset:1024
	ds_read_b128 v[138:141], v0 offset:2048
	ds_read_b128 v[142:145], v0 offset:3072
	v_add_u32_e32 v0, 0x1c000, v230
	ds_read_b128 v[146:149], v0
	ds_read_b128 v[150:153], v0 offset:1024
	ds_read_b128 v[154:157], v0 offset:2048
	ds_read_b128 v[158:161], v0 offset:3072
	s_add_i32 s66, s66, 0x20000
	s_mov_b32 m0, s37
	ds_read_b128 v[162:165], v231 offset:32768
	ds_read_b128 v[166:169], v231 offset:33792
	ds_read_b128 v[170:173], v231 offset:34816
	ds_read_b128 v[174:177], v231 offset:35840
	ds_read_b128 v[178:181], v231 offset:36864
	ds_read_b128 v[182:185], v231 offset:37888
	ds_read_b128 v[186:189], v231 offset:38912
	ds_read_b128 v[190:193], v231 offset:39936
	buffer_load_dwordx4 v199, s[16:19], s66 offen lds
	s_mov_b32 m0, s38
	s_nop 0
	buffer_load_dwordx4 v228, s[16:19], s66 offen lds
	s_waitcnt vmcnt(8)
	s_waitcnt lgkmcnt(0)
	s_cmp_eq_u32 s100, 0
	s_cbranch_scc1 .Lhb_26
	s_barrier

.Lhb_30:
	s_mov_b32 m0, s39
	s_or_b32 s66, s64, 0x80
	ds_read_b128 v[162:165], v231 offset:49152
	ds_read_b128 v[166:169], v231 offset:50176
	ds_read_b128 v[170:173], v231 offset:51200
	ds_read_b128 v[174:177], v231 offset:52224
	ds_read_b128 v[178:181], v231 offset:53248
	ds_read_b128 v[182:185], v231 offset:54272
	ds_read_b128 v[186:189], v231 offset:55296
	ds_read_b128 v[190:193], v231 offset:56320
	buffer_load_dwordx4 v227, s[12:15], s66 offen lds
	s_mov_b32 m0, s40
	s_add_i32 s64, s64, 0x20080
	buffer_load_dwordx4 v229, s[12:15], s66 offen lds
	s_mov_b32 m0, s43
	s_nop 0
	buffer_load_dwordx4 v227, s[12:15], s64 offen lds
	s_mov_b32 m0, s42
	s_nop 0
	buffer_load_dwordx4 v229, s[12:15], s64 offen lds
	s_mov_b32 m0, s41
	s_nop 0
	buffer_load_dwordx4 v199, s[16:19], s65 offen lds
	s_mov_b32 m0, s33
	s_nop 0
	buffer_load_dwordx4 v228, s[16:19], s65 offen lds
	s_waitcnt vmcnt(8)
	s_waitcnt lgkmcnt(0)
	s_cmp_eq_u32 s100, 0
	s_cbranch_scc1 .Lhb_27
	s_barrier

; #define PG8_STAGE(bufoff, gbase, voff) do { const Src _g = (gbase); _Pragma("unroll") for (int _i = 0; _i < 2; ++_i) \
;         __builtin_amdgcn_raw_ptr_buffer_load_lds(_g.r, (LAS unsigned*)(lds + (bufoff) + ldsw + _i * 8192), 16, (voff)[_i], _g.o, 0, 0); } while (0)
; #define PG8_WAIT_V(n) asm volatile("s_waitcnt vmcnt(" #n ")" ::: "memory")
; template <class Epi, bool ALIGN_EPI, bool SP2, class Hook>
; __device__ __forceinline__ void gemm_phase(LAS unsigned char* lds, const Gemm g, const StaticOrder& S, const Epi& E, Acc& acc, const bool fresh, const Hook& H, const int wave_id) {
;     ...
;         for (int t = t0; t < nt; t += 2) {
;             const bool last = (t == nt - 2);
;             const Src a1 = cA + (size_t)(t + 1) * kstep;
;             const Src a2 = last ? nA : cA + (size_t)(t + 2) * kstep, b2 = last ? nB : cB + (size_t)(t + 2) * kstep;
;             const Src a3 = a2 + kstep, b3 = b2 + kstep;
;             if (last && has_next) H(nxt);
;             if constexpr (SP2) {
;             PG8_TRIP_SP2(PG8_WAIT_V(8));
;             } else {
;             PG8_LDB(B0, 0, 0); PG8_SCHED; PG8_LDA(At, 0, 0); PG8_STAGE(PG8_SA(1, 1), a1 + hstepA, voffA);
;             PG8_WAIT_L(8); PG8_BAR; PG8_WAIT_L(0); PG8_MMA(0, 0, At, B0); PG8_BAR; PG8_SCHED;
;             PG8_LDB(B1, 0, 1); PG8_STAGE(PG8_SB(0, 0), b2, voffB);
;             PG8_BAR; PG8_WAIT_L(0); PG8_MMA(0, 1, At, B1); PG8_BAR;
;             PG8_LDA(At, 0, 1); PG8_STAGE(PG8_SA(0, 0), a2, voffA);
;             PG8_BAR; PG8_WAIT_L(0); PG8_MMA(1, 0, At, B0); PG8_BAR; PG8_SCHED;
;             PG8_STAGE(PG8_SB(0, 1), b2 + hstep, voffB);
;             PG8_WAIT_V(6); PG8_BAR; PG8_MMA(1, 1, At, B1); PG8_BAR;
;             PG8_LDB(B0, 1, 0); PG8_SCHED; PG8_LDA(At, 1, 0); PG8_STAGE(PG8_SA(0, 1), a2 + hstepA, voffA);
;             PG8_WAIT_L(8); PG8_BAR; PG8_WAIT_L(0); PG8_MMA(0, 0, At, B0); PG8_BAR; PG8_SCHED;
;             PG8_LDB(B1, 1, 1); PG8_STAGE(PG8_SB(1, 0), b3, voffB);
;             PG8_BAR; PG8_WAIT_L(0); PG8_MMA(0, 1, At, B1); PG8_BAR;
;             PG8_LDA(At, 1, 1); PG8_STAGE(PG8_SA(1, 0), a3, voffA);
;             PG8_BAR; PG8_WAIT_L(0); PG8_MMA(1, 0, At, B0); PG8_BAR; PG8_SCHED;
;             PG8_STAGE(PG8_SB(1, 1), b3 + hstep, voffB);
;             PG8_WAIT_V(6); PG8_BAR; PG8_MMA(1, 1, At, B1); PG8_BAR;
;             }
;         }
;         if constexpr (ALIGN_EPI) { if (wr == 0) PG8_BAR; }
.Lhb_31:
	s_add_i32 s63, s63, 2
	s_addk_i32 s2, 0x100
	s_addk_i32 s3, 0x100
	s_cmp_gt_u32 s63, 5
	s_cbranch_scc0 .LBB0_779
	v_readlane_b32 s2, v251, 45
	v_readlane_b32 s3, v251, 46
	s_and_b64 vcc, exec, s[2:3]
	s_cbranch_vccz .LBB0_782

; #define PG8_BAR __builtin_amdgcn_s_barrier()
; template <class Epi, bool ALIGN_EPI, bool SP2, class Hook>
; __device__ __forceinline__ void gemm_phase(LAS unsigned char* lds, const Gemm g, const StaticOrder& S, const Epi& E, Acc& acc, const bool fresh, const Hook& H, const int wave_id) {
;     ...
;         if (reset) {
; #pragma unroll
;             for (int a = 0; a < 2; ++a)
; #pragma unroll
;                 for (int b = 0; b < 2; ++b)
; #pragma unroll
;                     for (int m = 0; m < 4; ++m)
; #pragma unroll
;                         for (int n = 0; n < 2; ++n) acc[a][b][m][n] = (f32x4){0.f, 0.f, 0.f, 0.f};
;         }
;         cur = nxt; cA = nA; cB = nB; ++ui;
;         if constexpr (ALIGN_EPI) { if (wr == 1) PG8_BAR; }
.LBB0_881:
	s_and_b64 vcc, exec, s[0:1]
	s_cbranch_vccnz .LBB0_766
	s_branch .LBB0_766

; template <class Epi, bool ALIGN_EPI, bool SP2, class Hook>
; __device__ __forceinline__ void gemm_phase(LAS unsigned char* lds, const Gemm g, const StaticOrder& S, const Epi& E, Acc& acc, const bool fresh, const Hook& H, const int wave_id) {
;     ...
;     for (int i = 0; i < 2; ++i) { int R, C; stage_rc(tid * 16 + i * 8192, R, C); const int Rb = (R & ~31) + perm32(R & 31);
;         voffA[i] = (unsigned)(R * lda + C) * 2u; voffB[i] = (unsigned)(Rb * K + C) * 2u; }
;     const size_t kstep = (size_t)(BK * 2);
;     const size_t hstep = (size_t)HALF * K * 2, hstepA = (size_t)HALF * lda * 2;
;     const size_t tstep = 2 * hstep, tstepA = 2 * hstepA;
;     const unsigned ldsw = (unsigned)wid * 1024u;
;     const int aoff = lds_byte(wr * 64 + fr, fq * 8), boff = lds_byte(wc * 32 + fr, fq * 8);
;     ...
;     Unit cur, nxt; int ui = 0, rs_pm = -1, t0 = 0;
;     if (!S.next(0, cur)) return;
;     if (fresh) {
; #pragma unroll
;         for (int a = 0; a < 2; ++a)
; #pragma unroll
;             for (int b = 0; b < 2; ++b)
; #pragma unroll
;                 for (int m = 0; m < 4; ++m)
; #pragma unroll
;                     for (int n = 0; n < 2; ++n) acc[a][b][m][n] = (f32x4){0.f, 0.f, 0.f, 0.f};
;     }
;     bf16x8 At[4][2], B0[2][2], B1[2][2];
;     Src cA = make_src(selA(g, cur.seg), (size_t)cur.pm * tstepA), cB = make_src(selB(g, cur.seg), (size_t)cur.pn * tstep);
;     if constexpr (SP2) {
;         f32x4 rpa = {0.f, 0.f, 0.f, 0.f}, rpb = rpa;
;         float rsum = 0.f;
;         if constexpr (Epi::NEEDS_RS) { const GAS f32x4* p = (const GAS f32x4*)(E.rowss + (size_t)(cur.pm * BM + (tid >> 1)) * 16) + (tid & 1) * 2; rpa = p[0]; rpb = p[1]; }
;         PG8_STAGE(PG8_SB(0, 0), cB, voffB); PG8_STAGE(PG8_SB(0, 1), cB + hstep, voffB); PG8_STAGE(PG8_SA(0, 0), cA, voffA); PG8_STAGE(PG8_SA(0, 1), cA + hstepA, voffA);
;         if (wr == 1) PG8_BAR;
;         PG8_WAIT_V(2); PG8_BAR;
;         if constexpr (Epi::NEEDS_RS) {
;             rsum = ((rpa[0] + rpa[1]) + (rpa[2] + rpa[3])) + ((rpb[0] + rpb[1]) + (rpb[2] + rpb[3]));
;             const float t2 = __builtin_bit_cast(float, __builtin_amdgcn_update_dpp(0, __builtin_bit_cast(int, rsum), 0xB1  , 0xf, 0xf, false)); rsum = (tid & 1) ? (t2 + rsum) : (rsum + t2);
;             if ((tid & 1) == 0) ((LAS float*)(lds + RSTAB_OFF))[tid >> 1] = __builtin_amdgcn_rsqf(rsum * (1.0f / DM) + NORM_EPS);
;             rs_pm = cur.pm;
.LBB0_885:
	s_and_b64 vcc, exec, s[0:1]
	s_cbranch_vccz .LBB0_1136
	v_readlane_b32 s0, v253, 5
	v_readlane_b32 s1, v253, 6
	v_mov_b32_e32 v0, v1
	s_andn2_b64 vcc, exec, s[0:1]
	s_cbranch_vccnz .LBB0_910
	v_readlane_b32 s0, v254, 47
	v_mbcnt_lo_u32_b32 v0, -1, v0
	s_add_u32 s6, s0, 0xd80000
	v_mbcnt_hi_u32_b32 v2, -1, v0
	v_readlane_b32 s0, v250, 8
	v_readlane_b32 s1, v254, 48
	s_addc_u32 s7, s1, 0
	v_lshl_add_u32 v3, v2, 4, s0
	v_ashrrev_i32_e32 v0, 31, v3
	v_lshrrev_b32_e32 v0, 22, v0
	v_add_u32_e32 v0, v3, v0
	v_ashrrev_i32_e32 v0, 10, v0
	v_mul_i32_i24_e32 v4, 0x400, v0
	v_sub_u32_e32 v4, v3, v4
	s_waitcnt lgkmcnt(0)
	v_lshrrev_b32_e32 v5, 4, v4
	v_bitop3_b32 v4, v5, v4, 32 bitop3:0x6c
	v_ashrrev_i32_e32 v6, 31, v4
	v_lshrrev_b32_e32 v6, 26, v6
	v_lshlrev_b32_e32 v5, 3, v0
	v_add_u32_e32 v6, v4, v6
	v_and_b32_e32 v5, -16, v5
	v_ashrrev_i32_e32 v7, 6, v6
	v_and_b32_e32 v6, 0xc0, v6
	v_add_u32_e32 v5, v7, v5
	v_sub_u32_e32 v4, v4, v6
	v_lshlrev_b32_e32 v0, 5, v0
	v_ashrrev_i16_sdwa v4, v226, sext(v4) dst_sel:DWORD dst_unused:UNUSED_PAD src0_sel:DWORD src1_sel:BYTE_0
	v_lshlrev_b32_e32 v6, 1, v5
	v_lshrrev_b32_e32 v8, 2, v5
	v_and_b32_e32 v7, 3, v7
	s_mov_b32 s0, 0x3fffe0
	v_and_b32_e32 v0, 32, v0
	v_bfe_i32 v4, v4, 0, 16
	v_and_b32_e32 v6, 24, v6
	v_and_b32_e32 v8, 4, v8
	v_and_or_b32 v7, v5, s0, v7
	v_or3_b32 v6, v7, v8, v6
	v_add_lshl_u32 v4, v0, v4, 1
	v_add_u32_e32 v3, 0x2000, v3
	v_lshl_add_u32 v0, v5, 10, v4
	v_lshl_add_u32 v199, v6, 10, v4
	v_ashrrev_i32_e32 v4, 31, v3
	v_lshrrev_b32_e32 v4, 22, v4
	v_add_u32_e32 v4, v3, v4
	v_ashrrev_i32_e32 v4, 10, v4
	v_mul_i32_i24_e32 v5, 0x400, v4
	v_sub_u32_e32 v3, v3, v5
	v_lshrrev_b32_e32 v5, 4, v3
	v_bitop3_b32 v3, v5, v3, 32 bitop3:0x6c
	v_ashrrev_i32_e32 v6, 31, v3
	v_lshrrev_b32_e32 v6, 26, v6
	v_add_u32_e32 v6, v3, v6
	v_lshlrev_b32_e32 v5, 3, v4
	v_ashrrev_i32_e32 v7, 6, v6
	v_and_b32_e32 v6, 0xffc0, v6
	v_and_b32_e32 v5, -16, v5
	v_sub_u32_e32 v3, v3, v6
	v_add_u32_e32 v5, v7, v5
	v_lshrrev_b16_e32 v6, 7, v3
	v_and_b32_e32 v7, 3, v7
	v_and_b32_e32 v6, 1, v6
	v_and_or_b32 v7, v5, s0, v7
	s_mov_b64 s[8:9], s[22:23]
	s_mov_b64 s[0:1], s[22:23]
	s_mov_b64 s[2:3], s[22:23]
	v_add_u16_e32 v3, v3, v6
	v_lshlrev_b32_e32 v4, 5, v4
	v_ashrrev_i16_sdwa v3, v226, sext(v3) dst_sel:DWORD dst_unused:UNUSED_PAD src0_sel:DWORD src1_sel:BYTE_0
	v_lshlrev_b32_e32 v6, 1, v5
	v_lshrrev_b32_e32 v8, 2, v5
	s_mov_b64 s[76:77], s[6:7]
	s_mov_b64 s[0:1], s[6:7]
	s_mov_b64 s[2:3], s[6:7]
	v_and_b32_e32 v4, 32, v4
	v_bfe_i32 v3, v3, 0, 16
	v_and_b32_e32 v6, 24, v6
	v_and_b32_e32 v8, 4, v8
	s_mov_b32 m0, s92
	v_or3_b32 v6, v7, v8, v6
	v_add_lshl_u32 v3, v4, v3, 1
	s_and_b32 s77, s77, 0xffff
	v_readlane_b32 s0, v253, 35
	v_lshl_add_u32 v215, v6, 10, v3
	s_and_b32 s9, s9, 0xffff
	s_mov_b32 s10, s78
	s_mov_b32 s11, s79
	v_lshl_add_u32 v214, v5, 10, v3
	buffer_load_dwordx4 v199, s[76:79], s0 offen lds
	s_mov_b32 m0, s93
	v_readlane_b32 s2, v250, 9
	buffer_load_dwordx4 v215, s[76:79], s0 offen lds
	s_mov_b32 m0, s94
	v_readlane_b32 s0, v253, 30
	v_readlane_b32 s3, v250, 10
	s_andn2_b64 vcc, exec, s[2:3]
	s_nop 0
	v_cndmask_b32_e64 v3, 0, 1, s[2:3]
	s_nop 0
	buffer_load_dwordx4 v199, s[76:79], s0 offen lds
	s_mov_b32 m0, s95
	s_nop 0
	buffer_load_dwordx4 v215, s[76:79], s0 offen lds
	s_mov_b32 m0, s44
	v_readlane_b32 s0, v253, 33
	s_nop 4
	buffer_load_dwordx4 v0, s[8:11], s0 offen lds
	s_mov_b32 m0, s36
	s_nop 0
	buffer_load_dwordx4 v214, s[8:11], s0 offen lds
	s_mov_b32 m0, s37
	v_readlane_b32 s0, v253, 31
	s_nop 4
	buffer_load_dwordx4 v0, s[8:11], s0 offen lds
	s_mov_b32 m0, s38
	s_nop 0
	buffer_load_dwordx4 v214, s[8:11], s0 offen lds
	v_cmp_ne_u32_e64 s[0:1], 1, v3
	s_cbranch_vccnz .LBB0_889
.LBB0_889:
	s_mov_b32 m0, s39
	v_readlane_b32 s2, v253, 32
	s_waitcnt vmcnt(2)
	s_barrier
	s_mov_b32 s10, s78
	s_mov_b32 s11, s79
	v_and_b32_e32 v3, 15, v2
	s_nop 0
	buffer_load_dwordx4 v199, s[76:79], s2 offen lds
	s_mov_b32 m0, s40
	v_and_b32_e32 v5, 48, v2
	buffer_load_dwordx4 v215, s[76:79], s2 offen lds
	s_mov_b32 m0, s41
	v_readlane_b32 s2, v253, 34
	v_lshlrev_b32_e32 v2, 2, v2
	v_and_b32_e32 v2, 32, v2
	s_mov_b32 s50, 0
	v_readlane_b32 s20, v253, 29
	v_readlane_b32 s21, v253, 28
	buffer_load_dwordx4 v0, s[8:11], s2 offen lds
	s_mov_b32 m0, s33
	s_mov_b64 s[34:35], s[78:79]
	buffer_load_dwordx4 v214, s[8:11], s2 offen lds
	s_mov_b32 m0, s43
	v_readlane_b32 s2, v253, 36
	v_readlane_b32 s12, v253, 35
	s_mov_b64 s[10:11], s[78:79]
	v_readlane_b32 s13, v253, 33
	s_nop 1
	buffer_load_dwordx4 v199, s[76:79], s2 offen lds
	s_mov_b32 m0, s42
	s_nop 0
	buffer_load_dwordx4 v215, s[76:79], s2 offen lds
	v_readlane_b32 s2, v250, 1
	s_waitcnt vmcnt(6)
	s_barrier
	s_nop 0
	v_or_b32_e32 v4, s2, v3
	v_lshlrev_b32_e32 v6, 6, v4
	s_movk_i32 s2, 0x3c0
	v_lshlrev_b32_e32 v4, 2, v4
	v_and_or_b32 v6, v6, s2, v5
	v_and_b32_e32 v4, 32, v4
	v_readlane_b32 s2, v250, 2
	v_lshl_or_b32 v3, v3, 6, v5
	s_nop 0
	v_bitop3_b32 v4, v6, s2, v4 bitop3:0xde
	v_readlane_b32 s2, v253, 4
	v_add_u32_e32 v217, 0, v4
	s_nop 0
	v_bitop3_b32 v2, v3, s2, v2 bitop3:0xde
	v_add_u32_e32 v216, 0, v2
	s_branch .LBB0_892

; template <class Epi, bool ALIGN_EPI, bool SP2, class Hook>
; __device__ __forceinline__ void gemm_phase(LAS unsigned char* lds, const Gemm g, const StaticOrder& S, const Epi& E, Acc& acc, const bool fresh, const Hook& H, const int wave_id) {
;     ...
;             const bool last = (t == nt - 2);
;             const Src a1 = cA + (size_t)(t + 1) * kstep;
;             const Src a2 = last ? nA : cA + (size_t)(t + 2) * kstep, b2 = last ? nB : cB + (size_t)(t + 2) * kstep;
;             const Src a3 = a2 + kstep, b3 = b2 + kstep;
.LBB0_903:
	v_add_u32_e32 v70, 0x10000, v216
	v_add_u32_e32 v118, 0x14000, v216
	ds_read_b128 v[34:37], v70
	ds_read_b128 v[46:49], v70 offset:1024
	ds_read_b128 v[58:61], v70 offset:2048
	ds_read_b128 v[70:73], v70 offset:3072
	ds_read_b128 v[82:85], v118
	ds_read_b128 v[94:97], v118 offset:1024
	ds_read_b128 v[106:109], v118 offset:2048
	ds_read_b128 v[118:121], v118 offset:3072
	s_add_i32 s12, s55, 0xfffe0080
	s_cmp_eq_u32 s57, 4
	s_cselect_b32 s60, s53, s12
	s_cselect_b32 s13, s29, s77
	s_cselect_b32 s12, s28, s76
	s_cselect_b32 s15, s31, s35
	s_cselect_b32 s14, s30, s34
	s_cselect_b32 s58, s54, s56
	s_cselect_b32 s16, s2, s8
	s_cselect_b32 s17, s3, s9
	s_cselect_b32 s18, s26, s10
	s_cselect_b32 s19, s27, s11
	s_or_b32 s59, s60, 0x80
	s_mov_b32 m0, s45
	ds_read_b128 v[130:133], v217
	ds_read_b128 v[142:145], v217 offset:1024
	ds_read_b128 v[154:157], v217 offset:2048
	ds_read_b128 v[166:169], v217 offset:3072
	ds_read_b128 v[174:177], v217 offset:4096
	ds_read_b128 v[182:185], v217 offset:5120
	ds_read_b128 v[186:189], v217 offset:6144
	ds_read_b128 v[190:193], v217 offset:7168
	buffer_load_dwordx4 v0, s[8:11], s55 offen lds
	s_mov_b32 m0, s46
	s_nop 0
	buffer_load_dwordx4 v214, s[8:11], s55 offen lds
	s_waitcnt vmcnt(8)
	s_waitcnt lgkmcnt(0)
	s_cmp_eq_u32 s100, 0
	s_cbranch_scc1 .Lhb_32
	s_barrier

; #define GAS __attribute__((address_space(1)))
; __device__ __forceinline__ const bf16_t* selA(const Gemm& g, int s) { return sel3(g.A0, g.A1, g.A2, s); }
; __device__ __forceinline__ const bf16_t* selB(const Gemm& g, int s) { return sel3(g.B0, g.B1, g.B2, s); }
; __device__ __forceinline__ Src make_src(const bf16_t* p, size_t off) { Src s_; s_.r = __builtin_amdgcn_make_buffer_rsrc((void*)p, (short)0, 0x7fffffff, 0x00020000); s_.o = (unsigned)off; return s_; }
; #define PG8_BAR __builtin_amdgcn_s_barrier()
; template <class Epi, bool ALIGN_EPI, bool SP2, class Hook>
; __device__ __forceinline__ void gemm_phase(LAS unsigned char* lds, const Gemm g, const StaticOrder& S, const Epi& E, Acc& acc, const bool fresh, const Hook& H, const int wave_id) {
;     ...
;     for (int i = 0; i < 2; ++i) { int R, C; stage_rc(tid * 16 + i * 8192, R, C); const int Rb = (R & ~31) + perm32(R & 31);
;         voffA[i] = (unsigned)(R * lda + C) * 2u; voffB[i] = (unsigned)(Rb * K + C) * 2u; }
;     const size_t kstep = (size_t)(BK * 2);
;     const size_t hstep = (size_t)HALF * K * 2, hstepA = (size_t)HALF * lda * 2;
;     const size_t tstep = 2 * hstep, tstepA = 2 * hstepA;
;     const unsigned ldsw = (unsigned)wid * 1024u;
;     const int aoff = lds_byte(wr * 64 + fr, fq * 8), boff = lds_byte(wc * 32 + fr, fq * 8);
;     ...
;     Unit cur, nxt; int ui = 0, rs_pm = -1, t0 = 0;
;     if (!S.next(0, cur)) return;
;     if (fresh) {
; #pragma unroll
;         for (int a = 0; a < 2; ++a)
; #pragma unroll
;             for (int b = 0; b < 2; ++b)
; #pragma unroll
;                 for (int m = 0; m < 4; ++m)
; #pragma unroll
;                     for (int n = 0; n < 2; ++n) acc[a][b][m][n] = (f32x4){0.f, 0.f, 0.f, 0.f};
;     }
;     bf16x8 At[4][2], B0[2][2], B1[2][2];
;     Src cA = make_src(selA(g, cur.seg), (size_t)cur.pm * tstepA), cB = make_src(selB(g, cur.seg), (size_t)cur.pn * tstep);
;     if constexpr (SP2) {
;         f32x4 rpa = {0.f, 0.f, 0.f, 0.f}, rpb = rpa;
;         float rsum = 0.f;
;         if constexpr (Epi::NEEDS_RS) { const GAS f32x4* p = (const GAS f32x4*)(E.rowss + (size_t)(cur.pm * BM + (tid >> 1)) * 16) + (tid & 1) * 2; rpa = p[0]; rpb = p[1]; }
;         PG8_STAGE(PG8_SB(0, 0), cB, voffB); PG8_STAGE(PG8_SB(0, 1), cB + hstep, voffB); PG8_STAGE(PG8_SA(0, 0), cA, voffA); PG8_STAGE(PG8_SA(0, 1), cA + hstepA, voffA);
;         if (wr == 1) PG8_BAR;
.LBB0_934:
	v_readlane_b32 s0, v251, 40
	v_readlane_b32 s1, v251, 41
	v_mov_b32_e32 v0, v1
	s_andn2_b64 vcc, exec, s[0:1]
	s_cbranch_vccnz .LBB0_1136
	v_mbcnt_lo_u32_b32 v0, -1, v0
	v_mbcnt_hi_u32_b32 v0, -1, v0
	v_readlane_b32 s0, v250, 8
	v_readlane_b32 s2, v254, 59
	v_readlane_b32 s3, v254, 60
	v_lshl_add_u32 v2, v0, 4, s0
	v_ashrrev_i32_e32 v3, 31, v2
	v_lshrrev_b32_e32 v3, 22, v3
	v_add_u32_e32 v3, v2, v3
	v_ashrrev_i32_e32 v3, 10, v3
	v_mul_i32_i24_e32 v4, 0x400, v3
	v_sub_u32_e32 v4, v2, v4
	s_waitcnt lgkmcnt(0)
	v_lshrrev_b32_e32 v5, 4, v4
	v_bitop3_b32 v4, v5, v4, 32 bitop3:0x6c
	v_ashrrev_i32_e32 v6, 31, v4
	v_lshrrev_b32_e32 v6, 26, v6
	v_lshlrev_b32_e32 v5, 3, v3
	v_add_u32_e32 v6, v4, v6
	v_and_b32_e32 v5, -16, v5
	v_ashrrev_i32_e32 v7, 6, v6
	v_and_b32_e32 v6, 0xc0, v6
	v_add_u32_e32 v5, v7, v5
	v_sub_u32_e32 v4, v4, v6
	v_lshlrev_b32_e32 v3, 5, v3
	v_ashrrev_i16_sdwa v4, v226, sext(v4) dst_sel:DWORD dst_unused:UNUSED_PAD src0_sel:DWORD src1_sel:BYTE_0
	v_lshlrev_b32_e32 v6, 1, v5
	v_lshrrev_b32_e32 v8, 2, v5
	v_and_b32_e32 v7, 3, v7
	s_mov_b32 s0, 0x3fffe0
	v_and_b32_e32 v3, 32, v3
	v_bfe_i32 v4, v4, 0, 16
	v_and_b32_e32 v6, 24, v6
	v_and_b32_e32 v8, 4, v8
	v_and_or_b32 v7, v5, s0, v7
	v_or3_b32 v6, v7, v8, v6
	v_add_lshl_u32 v3, v3, v4, 1
	v_add_u32_e32 v2, 0x2000, v2
	v_lshl_add_u32 v199, v5, 10, v3
	v_lshl_add_u32 v227, v6, 10, v3
	v_ashrrev_i32_e32 v3, 31, v2
	v_lshrrev_b32_e32 v3, 22, v3
	v_add_u32_e32 v3, v2, v3
	v_ashrrev_i32_e32 v3, 10, v3
	v_mul_i32_i24_e32 v4, 0x400, v3
	v_sub_u32_e32 v2, v2, v4
	v_lshrrev_b32_e32 v4, 4, v2
	v_bitop3_b32 v2, v4, v2, 32 bitop3:0x6c
	v_ashrrev_i32_e32 v5, 31, v2
	v_lshrrev_b32_e32 v5, 26, v5
	v_lshlrev_b32_e32 v4, 3, v3
	v_add_u32_e32 v5, v2, v5
	v_and_b32_e32 v4, -16, v4
	v_ashrrev_i32_e32 v6, 6, v5
	v_add_u32_e32 v4, v6, v4
	v_and_b32_e32 v6, 3, v6
	v_and_or_b32 v6, v4, s0, v6
	v_readlane_b32 s0, v254, 47
	v_readlane_b32 s1, v254, 48
	s_add_u32 s4, s0, 0xb80000
	s_addc_u32 s5, s1, 0
	s_add_u32 s26, s0, 0xc80000
	s_addc_u32 s27, s1, 0
	s_add_u32 s28, s0, 0xe00000
	v_and_b32_e32 v5, 0xffc0, v5
	s_addc_u32 s29, s1, 0
	v_readlane_b32 s0, v254, 53
	v_sub_u32_e32 v2, v2, v5
	v_readlane_b32 s1, v254, 54
	v_lshrrev_b16_e32 v5, 7, v2
	s_mov_b64 s[8:9], s[0:1]
	v_readlane_b32 s0, v254, 55
	v_and_b32_e32 v5, 1, v5
	v_readlane_b32 s1, v254, 56
	v_add_u16_e32 v2, v2, v5
	v_lshlrev_b32_e32 v3, 5, v3
	v_ashrrev_i16_sdwa v2, v226, sext(v2) dst_sel:DWORD dst_unused:UNUSED_PAD src0_sel:DWORD src1_sel:BYTE_0
	v_lshlrev_b32_e32 v5, 1, v4
	v_lshrrev_b32_e32 v7, 2, v4
	s_mov_b64 s[0:1], s[26:27]
	v_writelane_b32 v254, s4, 45
	s_mov_b64 s[76:77], s[4:5]
	s_mov_b64 s[2:3], s[28:29]
	v_and_b32_e32 v3, 32, v3
	v_bfe_i32 v2, v2, 0, 16
	v_and_b32_e32 v5, 24, v5
	v_and_b32_e32 v7, 4, v7
	s_mov_b32 m0, s92
	v_or3_b32 v5, v6, v7, v5
	v_add_lshl_u32 v2, v3, v2, 1
	s_and_b32 s77, s77, 0xffff
	v_readlane_b32 s0, v253, 52
	v_lshl_add_u32 v229, v5, 10, v2
	s_and_b32 s9, s9, 0xffff
	s_mov_b32 s10, s78
	s_mov_b32 s11, s79
	v_lshl_add_u32 v228, v4, 10, v2
	buffer_load_dwordx4 v227, s[76:79], s0 offen lds
	s_mov_b32 m0, s93
	v_readlane_b32 s2, v250, 9
	buffer_load_dwordx4 v229, s[76:79], s0 offen lds
	s_mov_b32 m0, s94
	v_readlane_b32 s0, v253, 47
	v_readlane_b32 s3, v250, 10
	s_mov_b32 s23, s73
	v_writelane_b32 v254, s5, 46
	v_cndmask_b32_e64 v2, 0, 1, s[2:3]
	s_andn2_b64 vcc, exec, s[2:3]
	buffer_load_dwordx4 v227, s[76:79], s0 offen lds
	s_mov_b32 m0, s95
	s_nop 0
	buffer_load_dwordx4 v229, s[76:79], s0 offen lds
	s_mov_b32 m0, s44
	v_readlane_b32 s0, v253, 50
	s_nop 4
	buffer_load_dwordx4 v199, s[8:11], s0 offen lds
	s_mov_b32 m0, s36
	s_nop 0
	buffer_load_dwordx4 v228, s[8:11], s0 offen lds
	s_mov_b32 m0, s37
	v_readlane_b32 s0, v253, 48
	s_nop 4
	buffer_load_dwordx4 v199, s[8:11], s0 offen lds
	s_mov_b32 m0, s38
	s_nop 0
	buffer_load_dwordx4 v228, s[8:11], s0 offen lds
	v_cmp_ne_u32_e64 s[0:1], 1, v2
	s_cbranch_vccnz .LBB0_937
; #define LAS __attribute__((address_space(3)))
; #define GAS __attribute__((address_space(1)))
; __device__ __forceinline__ const bf16_t* selA(const Gemm& g, int s) { return sel3(g.A0, g.A1, g.A2, s); }
; __device__ __forceinline__ const bf16_t* selB(const Gemm& g, int s) { return sel3(g.B0, g.B1, g.B2, s); }
; #define PG8_WAIT_V(n) asm volatile("s_waitcnt vmcnt(" #n ")" ::: "memory")
; #define PG8_BAR __builtin_amdgcn_s_barrier()
; template <class Epi, bool ALIGN_EPI, bool SP2, class Hook>
; __device__ __forceinline__ void gemm_phase(LAS unsigned char* lds, const Gemm g, const StaticOrder& S, const Epi& E, Acc& acc, const bool fresh, const Hook& H, const int wave_id) {
;     ...
;     if (fresh) {
; #pragma unroll
;         for (int a = 0; a < 2; ++a)
; #pragma unroll
;             for (int b = 0; b < 2; ++b)
; #pragma unroll
;                 for (int m = 0; m < 4; ++m)
; #pragma unroll
;                     for (int n = 0; n < 2; ++n) acc[a][b][m][n] = (f32x4){0.f, 0.f, 0.f, 0.f};
;     }
;     bf16x8 At[4][2], B0[2][2], B1[2][2];
;     Src cA = make_src(selA(g, cur.seg), (size_t)cur.pm * tstepA), cB = make_src(selB(g, cur.seg), (size_t)cur.pn * tstep);
;     if constexpr (SP2) {
;         f32x4 rpa = {0.f, 0.f, 0.f, 0.f}, rpb = rpa;
;         float rsum = 0.f;
;         if constexpr (Epi::NEEDS_RS) { const GAS f32x4* p = (const GAS f32x4*)(E.rowss + (size_t)(cur.pm * BM + (tid >> 1)) * 16) + (tid & 1) * 2; rpa = p[0]; rpb = p[1]; }
;         PG8_STAGE(PG8_SB(0, 0), cB, voffB); PG8_STAGE(PG8_SB(0, 1), cB + hstep, voffB); PG8_STAGE(PG8_SA(0, 0), cA, voffA); PG8_STAGE(PG8_SA(0, 1), cA + hstepA, voffA);
;         if (wr == 1) PG8_BAR;
;         PG8_WAIT_V(2); PG8_BAR;
;         if constexpr (Epi::NEEDS_RS) {
;             rsum = ((rpa[0] + rpa[1]) + (rpa[2] + rpa[3])) + ((rpb[0] + rpb[1]) + (rpb[2] + rpb[3]));
;             const float t2 = __builtin_bit_cast(float, __builtin_amdgcn_update_dpp(0, __builtin_bit_cast(int, rsum), 0xB1  , 0xf, 0xf, false)); rsum = (tid & 1) ? (t2 + rsum) : (rsum + t2);
;             if ((tid & 1) == 0) ((LAS float*)(lds + RSTAB_OFF))[tid >> 1] = __builtin_amdgcn_rsqf(rsum * (1.0f / DM) + NORM_EPS);
;             rs_pm = cur.pm;
;         }
;         PG8_STAGE(PG8_SB(1, 0), cB + kstep, voffB); PG8_STAGE(PG8_SA(1, 0), cA + kstep, voffA); PG8_STAGE(PG8_SB(1, 1), cB + hstep + kstep, voffB);
;         PG8_WAIT_V(6); PG8_BAR;
.LBB0_937:
	v_and_b32_e32 v2, 15, v0
	v_readlane_b32 s2, v250, 1
	v_and_b32_e32 v4, 48, v0
	v_lshlrev_b32_e32 v0, 2, v0
	v_or_b32_e32 v3, s2, v2
	v_lshlrev_b32_e32 v5, 6, v3
	s_movk_i32 s2, 0x3c0
	v_lshlrev_b32_e32 v3, 2, v3
	v_and_or_b32 v5, v5, s2, v4
	v_and_b32_e32 v3, 32, v3
	v_readlane_b32 s2, v250, 2
	v_lshl_or_b32 v2, v2, 6, v4
	v_and_b32_e32 v0, 32, v0
	v_bitop3_b32 v3, v5, s2, v3 bitop3:0xde
	v_readlane_b32 s2, v253, 4
	s_mov_b32 m0, s39
	s_waitcnt vmcnt(2)
	s_barrier
	v_bitop3_b32 v0, v2, s2, v0 bitop3:0xde
	v_readlane_b32 s2, v253, 49
	s_mov_b32 s10, s78
	s_mov_b32 s11, s79
	v_mov_b32_e32 v2, 0
	s_mov_b32 s70, 0
	v_add_u32_e32 v230, 0, v0
	buffer_load_dwordx4 v227, s[76:79], s2 offen lds
	s_mov_b32 m0, s40
	v_add_u32_e32 v231, 0, v3
	buffer_load_dwordx4 v229, s[76:79], s2 offen lds
	s_mov_b32 m0, s41
	v_readlane_b32 s2, v253, 51
	v_readlane_b32 s71, v254, 7
	v_readlane_b32 s72, v254, 9
	s_mov_b64 s[6:7], s[78:79]
	v_readlane_b32 s12, v253, 52
	v_readlane_b32 s13, v253, 50
	buffer_load_dwordx4 v199, s[8:11], s2 offen lds
	s_mov_b32 m0, s33
	s_mov_b32 s64, 0
	buffer_load_dwordx4 v228, s[8:11], s2 offen lds
	s_mov_b32 m0, s43
	v_readlane_b32 s2, v253, 53
	s_mov_b64 s[10:11], s[78:79]
	v_mov_b32_e32 v3, v2
	v_mov_b32_e32 v4, v2
	v_mov_b32_e32 v5, v2
	v_mov_b32_e32 v6, v2
	buffer_load_dwordx4 v227, s[76:79], s2 offen lds
	s_mov_b32 m0, s42
	v_mov_b32_e32 v7, v2
	buffer_load_dwordx4 v229, s[76:79], s2 offen lds
	s_waitcnt vmcnt(6)
	v_mov_b32_e32 v8, v2
	v_mov_b32_e32 v9, v2
	v_mov_b32_e32 v10, v2
	v_mov_b32_e32 v11, v2
	v_mov_b32_e32 v12, v2
	v_mov_b32_e32 v13, v2
	v_mov_b32_e32 v14, v2
	v_mov_b32_e32 v15, v2
	v_mov_b32_e32 v16, v2
	v_mov_b32_e32 v17, v2
	v_mov_b32_e32 v18, v2
	v_mov_b32_e32 v19, v2
	v_mov_b32_e32 v20, v2
	v_mov_b32_e32 v21, v2
	v_mov_b32_e32 v22, v2
	v_mov_b32_e32 v23, v2
	v_mov_b32_e32 v24, v2
	v_mov_b32_e32 v25, v2
	v_mov_b32_e32 v26, v2
	v_mov_b32_e32 v27, v2
	v_mov_b32_e32 v28, v2
	v_mov_b32_e32 v29, v2
	v_mov_b32_e32 v30, v2
	v_mov_b32_e32 v31, v2
	v_mov_b32_e32 v32, v2
	v_mov_b32_e32 v33, v2
	v_mov_b32_e32 v34, v2
	v_mov_b32_e32 v35, v2
	v_mov_b32_e32 v36, v2
	v_mov_b32_e32 v37, v2
	v_mov_b32_e32 v38, v2
	v_mov_b32_e32 v39, v2
	v_mov_b32_e32 v40, v2
	v_mov_b32_e32 v41, v2
	v_mov_b32_e32 v42, v2
	v_mov_b32_e32 v43, v2
	v_mov_b32_e32 v44, v2
	v_mov_b32_e32 v45, v2
	v_mov_b32_e32 v46, v2
	v_mov_b32_e32 v47, v2
	v_mov_b32_e32 v48, v2
	v_mov_b32_e32 v49, v2
	v_mov_b32_e32 v50, v2
	v_mov_b32_e32 v51, v2
	v_mov_b32_e32 v52, v2
	v_mov_b32_e32 v53, v2
	v_mov_b32_e32 v54, v2
	v_mov_b32_e32 v55, v2
	v_mov_b32_e32 v56, v2
	v_mov_b32_e32 v57, v2
	v_mov_b32_e32 v58, v2
	v_mov_b32_e32 v59, v2
	v_mov_b32_e32 v60, v2
	v_mov_b32_e32 v61, v2
	v_mov_b32_e32 v62, v2
	v_mov_b32_e32 v63, v2
	v_mov_b32_e32 v64, v2
	v_mov_b32_e32 v65, v2
	v_mov_b32_e32 v66, v2
	v_mov_b32_e32 v67, v2
	v_mov_b32_e32 v68, v2
	v_mov_b32_e32 v69, v2
	v_mov_b32_e32 v70, v2
	v_mov_b32_e32 v71, v2
	v_mov_b32_e32 v72, v2
	v_mov_b32_e32 v73, v2
	v_mov_b32_e32 v74, v2
	v_mov_b32_e32 v75, v2
	v_mov_b32_e32 v76, v2
	v_mov_b32_e32 v77, v2
	v_mov_b32_e32 v78, v2
	v_mov_b32_e32 v79, v2
	v_mov_b32_e32 v80, v2
	v_mov_b32_e32 v81, v2
	v_mov_b32_e32 v82, v2
	v_mov_b32_e32 v83, v2
	v_mov_b32_e32 v84, v2
	v_mov_b32_e32 v85, v2
	v_mov_b32_e32 v86, v2
	v_mov_b32_e32 v87, v2
	v_mov_b32_e32 v88, v2
	v_mov_b32_e32 v89, v2
	v_mov_b32_e32 v90, v2
	v_mov_b32_e32 v91, v2
	v_mov_b32_e32 v92, v2
	v_mov_b32_e32 v93, v2
	v_mov_b32_e32 v94, v2
	v_mov_b32_e32 v95, v2
	v_mov_b32_e32 v96, v2
	v_mov_b32_e32 v97, v2
	v_mov_b32_e32 v98, v2
	v_mov_b32_e32 v99, v2
	v_mov_b32_e32 v100, v2
	v_mov_b32_e32 v101, v2
	v_mov_b32_e32 v102, v2
	v_mov_b32_e32 v103, v2
	v_mov_b32_e32 v104, v2
	v_mov_b32_e32 v105, v2
	v_mov_b32_e32 v106, v2
	v_mov_b32_e32 v107, v2
	v_mov_b32_e32 v108, v2
	v_mov_b32_e32 v109, v2
	v_mov_b32_e32 v110, v2
	v_mov_b32_e32 v111, v2
	v_mov_b32_e32 v112, v2
	v_mov_b32_e32 v113, v2
	v_mov_b32_e32 v114, v2
	v_mov_b32_e32 v115, v2
	v_mov_b32_e32 v116, v2
	v_mov_b32_e32 v117, v2
	v_mov_b32_e32 v118, v2
	v_mov_b32_e32 v119, v2
	v_mov_b32_e32 v120, v2
	v_mov_b32_e32 v121, v2
	v_mov_b32_e32 v122, v2
	v_mov_b32_e32 v123, v2
	v_mov_b32_e32 v124, v2
	v_mov_b32_e32 v125, v2
	v_mov_b32_e32 v126, v2
	v_mov_b32_e32 v127, v2
	v_mov_b32_e32 v128, v2
	v_mov_b32_e32 v129, v2
	s_barrier
	s_branch .LBB0_940

; template <class Epi, bool ALIGN_EPI, bool SP2, class Hook>
; __device__ __forceinline__ void gemm_phase(LAS unsigned char* lds, const Gemm g, const StaticOrder& S, const Epi& E, Acc& acc, const bool fresh, const Hook& H, const int wave_id) {
;     ...
;             const bool last = (t == nt - 2);
;             const Src a1 = cA + (size_t)(t + 1) * kstep;
;             const Src a2 = last ? nA : cA + (size_t)(t + 2) * kstep, b2 = last ? nB : cB + (size_t)(t + 2) * kstep;
;             const Src a3 = a2 + kstep, b3 = b2 + kstep;
.LBB0_1029:
.LBB0_1030:
	v_add_u32_e32 v0, 0x10000, v230
	s_waitcnt vmcnt(0)
	ds_read_b128 v[130:133], v0
	ds_read_b128 v[134:137], v0 offset:1024
	ds_read_b128 v[138:141], v0 offset:2048
	ds_read_b128 v[142:145], v0 offset:3072
	v_add_u32_e32 v0, 0x14000, v230
	ds_read_b128 v[146:149], v0
	ds_read_b128 v[150:153], v0 offset:1024
	ds_read_b128 v[154:157], v0 offset:2048
	ds_read_b128 v[158:161], v0 offset:3072
	s_lshl_b32 s55, s20, 7
	s_add_i32 s18, s73, s55
	s_and_b64 s[12:13], s[16:17], exec
	s_cselect_b32 s13, s31, s9
	s_cselect_b32 s12, s30, s8
	s_cselect_b32 s15, s35, s11
	s_cselect_b32 s14, s34, s10
	s_cselect_b32 s56, s68, s18
	s_add_i32 s21, s74, s55
	s_and_b64 s[16:17], s[16:17], exec
	s_cselect_b32 s54, s69, s21
	s_cselect_b32 s17, s51, s77
	s_cselect_b32 s16, s50, s76
	s_cselect_b32 s19, s53, s7
	s_cselect_b32 s18, s52, s6
	s_or_b32 s21, s56, 0x80
	s_or_b32 s57, s54, 0x80
	s_add_i32 s55, s55, s75
	s_mov_b32 m0, s45
	ds_read_b128 v[162:165], v231
	ds_read_b128 v[166:169], v231 offset:1024
	ds_read_b128 v[170:173], v231 offset:2048
	ds_read_b128 v[174:177], v231 offset:3072
	ds_read_b128 v[178:181], v231 offset:4096
	ds_read_b128 v[182:185], v231 offset:5120
	ds_read_b128 v[186:189], v231 offset:6144
	ds_read_b128 v[190:193], v231 offset:7168
	buffer_load_dwordx4 v199, s[8:11], s55 offen lds
	s_mov_b32 m0, s46
	s_nop 0
	buffer_load_dwordx4 v228, s[8:11], s55 offen lds
	s_waitcnt vmcnt(8)
	s_waitcnt lgkmcnt(0)
	s_cmp_eq_u32 s100, 0
	s_cbranch_scc1 .Lhb_40
	s_barrier

.Lhb_44:
	s_mov_b32 m0, s92
	ds_read_b128 v[162:165], v231 offset:16384
	ds_read_b128 v[166:169], v231 offset:17408
	ds_read_b128 v[170:173], v231 offset:18432
	ds_read_b128 v[174:177], v231 offset:19456
	ds_read_b128 v[178:181], v231 offset:20480
	ds_read_b128 v[182:185], v231 offset:21504
	ds_read_b128 v[186:189], v231 offset:22528
	ds_read_b128 v[190:193], v231 offset:23552
	buffer_load_dwordx4 v227, s[16:19], s54 offen lds
	s_mov_b32 m0, s93
	s_add_i32 s55, s54, 0x20000
	buffer_load_dwordx4 v229, s[16:19], s54 offen lds
	s_mov_b32 m0, s94
	s_nop 0
	buffer_load_dwordx4 v227, s[16:19], s55 offen lds
	s_mov_b32 m0, s95
	s_nop 0
	buffer_load_dwordx4 v229, s[16:19], s55 offen lds
	s_mov_b32 m0, s44
	s_nop 0
	buffer_load_dwordx4 v199, s[12:15], s56 offen lds
	s_mov_b32 m0, s36
	s_nop 0
	buffer_load_dwordx4 v228, s[12:15], s56 offen lds
	s_waitcnt vmcnt(8)
	s_waitcnt lgkmcnt(0)
	s_cmp_eq_u32 s100, 0
	s_cbranch_scc1 .Lhb_41
	s_barrier

.Lhb_45:
	v_add_u32_e32 v0, 0x18000, v230
	ds_read_b128 v[130:133], v0
	ds_read_b128 v[134:137], v0 offset:1024
	ds_read_b128 v[138:141], v0 offset:2048
	ds_read_b128 v[142:145], v0 offset:3072
	v_add_u32_e32 v0, 0x1c000, v230
	ds_read_b128 v[146:149], v0
	ds_read_b128 v[150:153], v0 offset:1024
	ds_read_b128 v[154:157], v0 offset:2048
	ds_read_b128 v[158:161], v0 offset:3072
	s_add_i32 s56, s56, 0x20000
	s_mov_b32 m0, s37
	ds_read_b128 v[162:165], v231 offset:32768
	ds_read_b128 v[166:169], v231 offset:33792
	ds_read_b128 v[170:173], v231 offset:34816
	ds_read_b128 v[174:177], v231 offset:35840
	ds_read_b128 v[178:181], v231 offset:36864
	ds_read_b128 v[182:185], v231 offset:37888
	ds_read_b128 v[186:189], v231 offset:38912
	ds_read_b128 v[190:193], v231 offset:39936
	buffer_load_dwordx4 v199, s[12:15], s56 offen lds
	s_mov_b32 m0, s38
	s_nop 0
	buffer_load_dwordx4 v228, s[12:15], s56 offen lds
	s_waitcnt vmcnt(8)
	s_waitcnt lgkmcnt(0)
	s_cmp_eq_u32 s100, 0
	s_cbranch_scc1 .Lhb_42
	s_barrier

.Lhb_46:
	s_mov_b32 m0, s39
	ds_read_b128 v[162:165], v231 offset:49152
	ds_read_b128 v[166:169], v231 offset:50176
	ds_read_b128 v[170:173], v231 offset:51200
	ds_read_b128 v[174:177], v231 offset:52224
	ds_read_b128 v[178:181], v231 offset:53248
	ds_read_b128 v[182:185], v231 offset:54272
	ds_read_b128 v[186:189], v231 offset:55296
	ds_read_b128 v[190:193], v231 offset:56320
	buffer_load_dwordx4 v227, s[16:19], s57 offen lds
	s_mov_b32 m0, s40
	s_add_i32 s54, s54, 0x20080
	buffer_load_dwordx4 v229, s[16:19], s57 offen lds
	s_mov_b32 m0, s43
	s_nop 0
	buffer_load_dwordx4 v227, s[16:19], s54 offen lds
	s_mov_b32 m0, s42
	s_nop 0
	buffer_load_dwordx4 v229, s[16:19], s54 offen lds
	s_mov_b32 m0, s41
	s_nop 0
	buffer_load_dwordx4 v199, s[12:15], s21 offen lds
	s_mov_b32 m0, s33
	s_nop 0
	buffer_load_dwordx4 v228, s[12:15], s21 offen lds
	s_waitcnt vmcnt(8)
	s_waitcnt lgkmcnt(0)
	s_cmp_eq_u32 s100, 0
	s_cbranch_scc1 .Lhb_43
	s_barrier

; #define LAS __attribute__((address_space(3)))
;     __device__ __forceinline__ bool operator()(Acc& acc, const Unit& u, int wr, int wc, int fr, int fq, const LAS float*) const {
;         const int s = u.seg + seg_base;
;         const bf16_t* gp = Gt + (size_t)(u.pm * BM + wr * 64 + fr) * 3072 + u.pn * BM + wc * 32 + 8 * fq;
; template <class Epi, bool ALIGN_EPI, bool SP2, class Hook>
; __device__ __forceinline__ void gemm_phase(LAS unsigned char* lds, const Gemm g, const StaticOrder& S, const Epi& E, Acc& acc, const bool fresh, const Hook& H, const int wave_id) {
;     ...
;         for (int t = t0; t < nt; t += 2) {
;             const bool last = (t == nt - 2);
;             const Src a1 = cA + (size_t)(t + 1) * kstep;
;             const Src a2 = last ? nA : cA + (size_t)(t + 2) * kstep, b2 = last ? nB : cB + (size_t)(t + 2) * kstep;
;             const Src a3 = a2 + kstep, b3 = b2 + kstep;
;             if (last && has_next) H(nxt);
;             if constexpr (SP2) {
;             PG8_TRIP_SP2(PG8_WAIT_V(8));
;             } else {
;             PG8_LDB(B0, 0, 0); PG8_SCHED; PG8_LDA(At, 0, 0); PG8_STAGE(PG8_SA(1, 1), a1 + hstepA, voffA);
;             PG8_WAIT_L(8); PG8_BAR; PG8_WAIT_L(0); PG8_MMA(0, 0, At, B0); PG8_BAR; PG8_SCHED;
;             PG8_LDB(B1, 0, 1); PG8_STAGE(PG8_SB(0, 0), b2, voffB);
;             PG8_BAR; PG8_WAIT_L(0); PG8_MMA(0, 1, At, B1); PG8_BAR;
;             PG8_LDA(At, 0, 1); PG8_STAGE(PG8_SA(0, 0), a2, voffA);
;             PG8_BAR; PG8_WAIT_L(0); PG8_MMA(1, 0, At, B0); PG8_BAR; PG8_SCHED;
;             PG8_STAGE(PG8_SB(0, 1), b2 + hstep, voffB);
;             PG8_WAIT_V(6); PG8_BAR; PG8_MMA(1, 1, At, B1); PG8_BAR;
;             PG8_LDB(B0, 1, 0); PG8_SCHED; PG8_LDA(At, 1, 0); PG8_STAGE(PG8_SA(0, 1), a2 + hstepA, voffA);
;             PG8_WAIT_L(8); PG8_BAR; PG8_WAIT_L(0); PG8_MMA(0, 0, At, B0); PG8_BAR; PG8_SCHED;
;             PG8_LDB(B1, 1, 1); PG8_STAGE(PG8_SB(1, 0), b3, voffB);
;             PG8_BAR; PG8_WAIT_L(0); PG8_MMA(0, 1, At, B1); PG8_BAR;
;             PG8_LDA(At, 1, 1); PG8_STAGE(PG8_SA(1, 0), a3, voffA);
;             PG8_BAR; PG8_WAIT_L(0); PG8_MMA(1, 0, At, B0); PG8_BAR; PG8_SCHED;
;             PG8_STAGE(PG8_SB(1, 1), b3 + hstep, voffB);
;             PG8_WAIT_V(6); PG8_BAR; PG8_MMA(1, 1, At, B1); PG8_BAR;
;             }
;         }
;         if constexpr (ALIGN_EPI) { if (wr == 0) PG8_BAR; }
.Lhb_47:
	s_add_i32 s12, s20, 2
	s_cmp_gt_u32 s20, 5
	s_cbranch_scc1 .LBB0_1032
	s_mov_b32 s20, s12
	s_branch .LBB0_951
.LBB0_1032:
	v_readlane_b32 s2, v251, 45
	v_readlane_b32 s3, v251, 46
	s_and_b64 vcc, exec, s[2:3]
	s_cbranch_vccz .LBB0_1034
.LBB0_1034:
	v_mov_b32_e32 v0, v1
	s_lshl_b32 s2, s72, 8
	v_mbcnt_lo_u32_b32 v0, -1, v0
	v_readlane_b32 s3, v250, 1
	v_mbcnt_hi_u32_b32 v0, -1, v0
	s_add_i32 s2, s2, s3
	v_and_or_b32 v212, v0, 15, s2
	v_readlane_b32 s2, v254, 57
	v_readlane_b32 s3, v254, 58
	s_lshl_b32 s6, s71, 8
	s_ashr_i32 s7, s6, 31
	v_mov_b64_e32 v[130:131], s[2:3]
	s_movk_i32 s2, 0x1800
	v_mad_i64_i32 v[130:131], s[2:3], v212, s2, v[130:131]
	v_readlane_b32 s12, v254, 33
	v_readlane_b32 s13, v254, 34
	v_lshrrev_b32_e32 v0, 1, v0
	s_cmp_eq_u32 s70, 1
	s_movk_i32 s2, 0x800
	v_lshl_add_u64 v[130:131], s[6:7], 1, v[130:131]
	s_mov_b32 s13, s23
	v_and_b32_e32 v0, 24, v0
	s_cselect_b32 s2, 0x400, s2
	s_cmp_eq_u32 s70, 0
	v_lshl_add_u64 v[130:131], v[130:131], 0, s[12:13]
	v_lshlrev_b32_e32 v0, 1, v0
	s_movk_i32 s3, 0x1000
	s_cselect_b32 s2, 0, s2
	v_lshl_add_u64 v[130:131], v[130:131], 0, v[0:1]
	s_cselect_b32 s22, 0x800, s3
	s_lshl_b32 s2, s2, 1
	s_mov_b32 s3, s23
	v_lshl_add_u64 v[216:217], v[130:131], 0, s[2:3]
	global_load_dwordx4 v[190:193], v[216:217], off
	s_cmp_lt_i32 s70, 2
	s_cselect_b64 s[10:11], -1, 0
	s_cmp_gt_i32 s70, 1
	s_cselect_b64 s[8:9], -1, 0
	v_lshl_add_u64 v[214:215], v[130:131], 0, s[22:23]
	s_and_b64 vcc, exec, s[8:9]
	s_cbranch_vccnz .LBB0_1036
	global_load_dwordx4 v[186:189], v[214:215], off

; template <class Epi, bool ALIGN_EPI, bool SP2, class Hook>
; __device__ __forceinline__ void gemm_phase(LAS unsigned char* lds, const Gemm g, const StaticOrder& S, const Epi& E, Acc& acc, const bool fresh, const Hook& H, const int wave_id) {
;     ...
;     for (int i = 0; i < 2; ++i) { int R, C; stage_rc(tid * 16 + i * 8192, R, C); const int Rb = (R & ~31) + perm32(R & 31);
;         voffA[i] = (unsigned)(R * lda + C) * 2u; voffB[i] = (unsigned)(Rb * K + C) * 2u; }
;     const size_t kstep = (size_t)(BK * 2);
;     const size_t hstep = (size_t)HALF * K * 2, hstepA = (size_t)HALF * lda * 2;
;     const size_t tstep = 2 * hstep, tstepA = 2 * hstepA;
;     const unsigned ldsw = (unsigned)wid * 1024u;
;     const int aoff = lds_byte(wr * 64 + fr, fq * 8), boff = lds_byte(wc * 32 + fr, fq * 8);
;     ...
;     Unit cur, nxt; int ui = 0, rs_pm = -1, t0 = 0;
;     if (!S.next(0, cur)) return;
;     if (fresh) {
; #pragma unroll
;         for (int a = 0; a < 2; ++a)
; #pragma unroll
;             for (int b = 0; b < 2; ++b)
; #pragma unroll
;                 for (int m = 0; m < 4; ++m)
; #pragma unroll
;                     for (int n = 0; n < 2; ++n) acc[a][b][m][n] = (f32x4){0.f, 0.f, 0.f, 0.f};
;     }
;     bf16x8 At[4][2], B0[2][2], B1[2][2];
;     Src cA = make_src(selA(g, cur.seg), (size_t)cur.pm * tstepA), cB = make_src(selB(g, cur.seg), (size_t)cur.pn * tstep);
;     if constexpr (SP2) {
;         f32x4 rpa = {0.f, 0.f, 0.f, 0.f}, rpb = rpa;
;         float rsum = 0.f;
;         if constexpr (Epi::NEEDS_RS) { const GAS f32x4* p = (const GAS f32x4*)(E.rowss + (size_t)(cur.pm * BM + (tid >> 1)) * 16) + (tid & 1) * 2; rpa = p[0]; rpb = p[1]; }
;         PG8_STAGE(PG8_SB(0, 0), cB, voffB); PG8_STAGE(PG8_SB(0, 1), cB + hstep, voffB); PG8_STAGE(PG8_SA(0, 0), cA, voffA); PG8_STAGE(PG8_SA(0, 1), cA + hstepA, voffA);
;         if (wr == 1) PG8_BAR;
;         PG8_WAIT_V(2); PG8_BAR;
;         if constexpr (Epi::NEEDS_RS) {
;             rsum = ((rpa[0] + rpa[1]) + (rpa[2] + rpa[3])) + ((rpb[0] + rpb[1]) + (rpb[2] + rpb[3]));
;             const float t2 = __builtin_bit_cast(float, __builtin_amdgcn_update_dpp(0, __builtin_bit_cast(int, rsum), 0xB1  , 0xf, 0xf, false)); rsum = (tid & 1) ? (t2 + rsum) : (rsum + t2);
;             if ((tid & 1) == 0) ((LAS float*)(lds + RSTAB_OFF))[tid >> 1] = __builtin_amdgcn_rsqf(rsum * (1.0f / DM) + NORM_EPS);
;             rs_pm = cur.pm;
.LBB0_1217:
	s_andn2_b64 vcc, exec, s[0:1]
	s_cbranch_vccnz .LBB0_1337
	v_readlane_b32 s0, v251, 40
	v_readlane_b32 s1, v251, 41
	v_mov_b32_e32 v0, v1
	s_andn2_b64 vcc, exec, s[0:1]
	s_cbranch_vccnz .LBB0_1258
	v_readlane_b32 s0, v254, 47
	v_mbcnt_lo_u32_b32 v0, -1, v0
	s_add_u32 s6, s0, 0xf00000
	v_mbcnt_hi_u32_b32 v2, -1, v0
	v_readlane_b32 s0, v250, 8
	v_readlane_b32 s1, v254, 48
	s_addc_u32 s7, s1, 0
	v_lshl_add_u32 v3, v2, 4, s0
	v_ashrrev_i32_e32 v0, 31, v3
	v_lshrrev_b32_e32 v0, 22, v0
	v_add_u32_e32 v0, v3, v0
	v_ashrrev_i32_e32 v0, 10, v0
	v_mul_i32_i24_e32 v4, 0x400, v0
	v_sub_u32_e32 v4, v3, v4
	s_waitcnt lgkmcnt(0)
	v_lshrrev_b32_e32 v5, 4, v4
	v_bitop3_b32 v4, v5, v4, 32 bitop3:0x6c
	v_ashrrev_i32_e32 v6, 31, v4
	v_lshrrev_b32_e32 v6, 26, v6
	v_lshlrev_b32_e32 v5, 3, v0
	v_add_u32_e32 v6, v4, v6
	v_and_b32_e32 v5, -16, v5
	v_ashrrev_i32_e32 v7, 6, v6
	v_and_b32_e32 v6, 0xc0, v6
	v_add_u32_e32 v5, v7, v5
	v_sub_u32_e32 v4, v4, v6
	v_lshlrev_b32_e32 v0, 5, v0
	v_ashrrev_i16_sdwa v4, v226, sext(v4) dst_sel:DWORD dst_unused:UNUSED_PAD src0_sel:DWORD src1_sel:BYTE_0
	v_lshlrev_b32_e32 v6, 1, v5
	v_lshrrev_b32_e32 v8, 2, v5
	v_and_b32_e32 v7, 3, v7
	s_mov_b32 s0, 0x1fffe0
	v_and_b32_e32 v0, 32, v0
	v_bfe_i32 v4, v4, 0, 16
	v_and_b32_e32 v6, 24, v6
	v_and_b32_e32 v8, 4, v8
	v_and_or_b32 v7, v5, s0, v7
	v_or3_b32 v6, v7, v8, v6
	v_add_lshl_u32 v4, v0, v4, 1
	v_add_u32_e32 v3, 0x2000, v3
	v_lshl_add_u32 v0, v5, 11, v4
	v_lshl_add_u32 v158, v6, 11, v4
	v_ashrrev_i32_e32 v4, 31, v3
	v_lshrrev_b32_e32 v4, 22, v4
	v_add_u32_e32 v4, v3, v4
	v_ashrrev_i32_e32 v4, 10, v4
	v_mul_i32_i24_e32 v5, 0x400, v4
	v_sub_u32_e32 v3, v3, v5
	v_lshrrev_b32_e32 v5, 4, v3
	v_bitop3_b32 v3, v5, v3, 32 bitop3:0x6c
	v_ashrrev_i32_e32 v6, 31, v3
	v_lshrrev_b32_e32 v6, 26, v6
	v_add_u32_e32 v6, v3, v6
	v_lshlrev_b32_e32 v5, 3, v4
	v_ashrrev_i32_e32 v7, 6, v6
	v_and_b32_e32 v6, 0xffc0, v6
	v_and_b32_e32 v5, -16, v5
	v_sub_u32_e32 v3, v3, v6
	v_add_u32_e32 v5, v7, v5
	v_lshrrev_b16_e32 v6, 7, v3
	v_and_b32_e32 v7, 3, v7
	v_and_b32_e32 v6, 1, v6
	v_and_or_b32 v7, v5, s0, v7
	s_mov_b64 s[76:77], s[24:25]
	s_mov_b64 s[0:1], s[24:25]
	s_mov_b64 s[2:3], s[24:25]
	v_add_u16_e32 v3, v3, v6
	v_lshlrev_b32_e32 v4, 5, v4
	v_ashrrev_i16_sdwa v3, v226, sext(v3) dst_sel:DWORD dst_unused:UNUSED_PAD src0_sel:DWORD src1_sel:BYTE_0
	v_lshlrev_b32_e32 v6, 1, v5
	v_lshrrev_b32_e32 v8, 2, v5
	s_mov_b64 s[8:9], s[6:7]
	s_mov_b64 s[0:1], s[6:7]
	s_mov_b64 s[2:3], s[6:7]
	v_and_b32_e32 v4, 32, v4
	v_bfe_i32 v3, v3, 0, 16
	v_and_b32_e32 v6, 24, v6
	v_and_b32_e32 v8, 4, v8
	s_mov_b32 m0, s92
	v_or3_b32 v6, v7, v8, v6
	v_add_lshl_u32 v3, v4, v3, 1
	s_and_b32 s9, s9, 0xffff
	s_mov_b32 s10, s78
	s_mov_b32 s11, s79
	v_readlane_b32 s0, v253, 59
	v_lshl_add_u32 v160, v6, 11, v3
	s_and_b32 s77, s77, 0xffff
	v_lshl_add_u32 v159, v5, 11, v3
	v_readlane_b32 s2, v250, 9
	v_readlane_b32 s3, v250, 10
	buffer_load_dwordx4 v158, s[8:11], s0 offen lds
	s_mov_b32 m0, s93
	v_cndmask_b32_e64 v3, 0, 1, s[2:3]
	buffer_load_dwordx4 v160, s[8:11], s0 offen lds
	s_mov_b32 m0, s94
	v_readlane_b32 s0, v253, 54
	s_andn2_b64 vcc, exec, s[2:3]
	s_nop 3
	buffer_load_dwordx4 v158, s[8:11], s0 offen lds
	s_mov_b32 m0, s95
	s_nop 0
	buffer_load_dwordx4 v160, s[8:11], s0 offen lds
	s_mov_b32 m0, s44
	v_readlane_b32 s0, v253, 57
	s_nop 4
	buffer_load_dwordx4 v0, s[76:79], s0 offen lds
	s_mov_b32 m0, s36
	s_nop 0
	buffer_load_dwordx4 v159, s[76:79], s0 offen lds
	s_mov_b32 m0, s37
	v_readlane_b32 s0, v253, 55
	s_nop 4
	buffer_load_dwordx4 v0, s[76:79], s0 offen lds
	s_mov_b32 m0, s38
	s_nop 0
	buffer_load_dwordx4 v159, s[76:79], s0 offen lds
	v_cmp_ne_u32_e64 s[0:1], 1, v3
	s_cbranch_vccnz .LBB0_1221
.LBB0_1221:
	s_mov_b32 m0, s39
	s_mov_b32 s10, s78
	s_mov_b32 s11, s79
	v_readlane_b32 s2, v253, 56
	s_waitcnt vmcnt(2)
	s_barrier
	v_and_b32_e32 v3, 15, v2
	v_and_b32_e32 v5, 48, v2
	v_lshlrev_b32_e32 v2, 2, v2
	s_nop 0
	buffer_load_dwordx4 v158, s[8:11], s2 offen lds
	s_mov_b32 m0, s40
	v_and_b32_e32 v2, 32, v2
	buffer_load_dwordx4 v160, s[8:11], s2 offen lds
	s_mov_b32 m0, s41
	v_readlane_b32 s2, v253, 58
	s_mov_b32 s52, 0
	v_readlane_b32 s57, v254, 7
	v_readlane_b32 s58, v254, 9
	s_mov_b64 s[50:51], s[78:79]
	v_readlane_b32 s16, v253, 59
	buffer_load_dwordx4 v0, s[76:79], s2 offen lds
	s_mov_b32 m0, s33
	s_mov_b64 s[12:13], s[76:77]
	buffer_load_dwordx4 v159, s[76:79], s2 offen lds
	s_mov_b32 m0, s43
	v_readlane_b32 s2, v253, 60
	s_mov_b64 s[14:15], s[78:79]
	v_readlane_b32 s17, v253, 57
	s_nop 2
	buffer_load_dwordx4 v158, s[8:11], s2 offen lds
	s_mov_b32 m0, s42
	s_nop 0
	buffer_load_dwordx4 v160, s[8:11], s2 offen lds
	v_readlane_b32 s2, v254, 37
	s_add_u32 s10, s2, 0x600000
	v_readlane_b32 s2, v250, 1
	s_waitcnt vmcnt(6)
	v_readlane_b32 s3, v254, 38
	s_addc_u32 s11, s3, 0
	v_or_b32_e32 v4, s2, v3
	v_lshlrev_b32_e32 v6, 6, v4
	s_movk_i32 s2, 0x3c0
	v_lshlrev_b32_e32 v4, 2, v4
	v_and_or_b32 v6, v6, s2, v5
	v_and_b32_e32 v4, 32, v4
	v_readlane_b32 s2, v250, 2
	v_lshl_or_b32 v3, v3, 6, v5
	s_barrier
	v_bitop3_b32 v4, v6, s2, v4 bitop3:0xde
	v_readlane_b32 s2, v250, 4
	v_add_u32_e32 v162, 0, v4
	s_nop 0
	v_bitop3_b32 v2, v3, s2, v2 bitop3:0xde
	v_add_u32_e32 v161, 0, v2
	s_branch .LBB0_1224

; template <class Epi, bool ALIGN_EPI, bool SP2, class Hook>
; __device__ __forceinline__ void gemm_phase(LAS unsigned char* lds, const Gemm g, const StaticOrder& S, const Epi& E, Acc& acc, const bool fresh, const Hook& H, const int wave_id) {
;     ...
;             const bool last = (t == nt - 2);
;             const Src a1 = cA + (size_t)(t + 1) * kstep;
;             const Src a2 = last ? nA : cA + (size_t)(t + 2) * kstep, b2 = last ? nB : cB + (size_t)(t + 2) * kstep;
;             const Src a3 = a2 + kstep, b3 = b2 + kstep;
.LBB0_1235:
	v_add_u32_e32 v142, 0x10000, v161
	v_add_u32_e32 v163, 0x14000, v161
	ds_read_b128 v[130:133], v142
	ds_read_b128 v[134:137], v142 offset:1024
	ds_read_b128 v[138:141], v142 offset:2048
	ds_read_b128 v[142:145], v142 offset:3072
	ds_read_b128 v[146:149], v163
	ds_read_b128 v[150:153], v163 offset:1024
	ds_read_b128 v[154:157], v163 offset:2048
	ds_read_b128 v[164:167], v163 offset:3072
	s_add_i32 s16, s2, 0xfffc0080
	s_cmp_eq_u32 s59, 12
	s_cselect_b32 s62, s55, s16
	s_cselect_b32 s17, s31, s9
	s_cselect_b32 s16, s30, s8
	s_cselect_b32 s19, s35, s51
	s_cselect_b32 s18, s34, s50
	s_cselect_b32 s60, s56, s3
	s_cselect_b32 s20, s26, s12
	s_cselect_b32 s21, s27, s13
	s_cselect_b32 s22, s28, s14
	s_cselect_b32 s23, s29, s15
	s_or_b32 s61, s62, 0x80
	s_mov_b32 m0, s45
	ds_read_b128 v[168:171], v162
	ds_read_b128 v[172:175], v162 offset:1024
	ds_read_b128 v[176:179], v162 offset:2048
	ds_read_b128 v[180:183], v162 offset:3072
	ds_read_b128 v[184:187], v162 offset:4096
	ds_read_b128 v[188:191], v162 offset:5120
	ds_read_b128 v[192:195], v162 offset:6144
	ds_read_b128 v[200:203], v162 offset:7168
	buffer_load_dwordx4 v0, s[12:15], s2 offen lds
	s_mov_b32 m0, s46
	s_nop 0
	buffer_load_dwordx4 v159, s[12:15], s2 offen lds
	s_waitcnt vmcnt(8)
	s_waitcnt lgkmcnt(0)
	s_cmp_eq_u32 s100, 0
	s_cbranch_scc1 .Lhb_48
	s_barrier
.Lhb_48:
	s_setprio 1
	s_waitcnt lgkmcnt(7)
	v_mfma_f32_16x16x32_bf16 v[126:129], v[130:133], v[168:171], v[126:129]
	v_mfma_f32_16x16x32_bf16 v[122:125], v[138:141], v[168:171], v[122:125]
	s_waitcnt lgkmcnt(5)
	v_mfma_f32_16x16x32_bf16 v[110:113], v[130:133], v[176:179], v[110:113]
	v_mfma_f32_16x16x32_bf16 v[106:109], v[138:141], v[176:179], v[106:109]
	s_waitcnt lgkmcnt(3)
	v_mfma_f32_16x16x32_bf16 v[94:97], v[130:133], v[184:187], v[94:97]
	v_mfma_f32_16x16x32_bf16 v[90:93], v[138:141], v[184:187], v[90:93]
	s_waitcnt lgkmcnt(1)
	v_mfma_f32_16x16x32_bf16 v[78:81], v[130:133], v[192:195], v[78:81]
	v_mfma_f32_16x16x32_bf16 v[74:77], v[138:141], v[192:195], v[74:77]
	v_mfma_f32_16x16x32_bf16 v[126:129], v[134:137], v[172:175], v[126:129]
	v_mfma_f32_16x16x32_bf16 v[122:125], v[142:145], v[172:175], v[122:125]
	v_mfma_f32_16x16x32_bf16 v[110:113], v[134:137], v[180:183], v[110:113]
	v_mfma_f32_16x16x32_bf16 v[106:109], v[142:145], v[180:183], v[106:109]
	v_mfma_f32_16x16x32_bf16 v[94:97], v[134:137], v[188:191], v[94:97]
	v_mfma_f32_16x16x32_bf16 v[90:93], v[142:145], v[188:191], v[90:93]
	s_waitcnt lgkmcnt(0)
	v_mfma_f32_16x16x32_bf16 v[78:81], v[134:137], v[200:203], v[78:81]
	v_mfma_f32_16x16x32_bf16 v[74:77], v[142:145], v[200:203], v[74:77]
	s_setprio 0
	s_setprio 1
	v_mfma_f32_16x16x32_bf16 v[118:121], v[146:149], v[168:171], v[118:121]
	v_mfma_f32_16x16x32_bf16 v[114:117], v[154:157], v[168:171], v[114:117]
	v_mfma_f32_16x16x32_bf16 v[102:105], v[146:149], v[176:179], v[102:105]
	v_mfma_f32_16x16x32_bf16 v[98:101], v[154:157], v[176:179], v[98:101]
	v_mfma_f32_16x16x32_bf16 v[86:89], v[146:149], v[184:187], v[86:89]
	v_mfma_f32_16x16x32_bf16 v[82:85], v[154:157], v[184:187], v[82:85]
	v_mfma_f32_16x16x32_bf16 v[70:73], v[146:149], v[192:195], v[70:73]
	v_mfma_f32_16x16x32_bf16 v[66:69], v[154:157], v[192:195], v[66:69]
	v_mfma_f32_16x16x32_bf16 v[118:121], v[150:153], v[172:175], v[118:121]
	v_mfma_f32_16x16x32_bf16 v[114:117], v[164:167], v[172:175], v[114:117]
	v_mfma_f32_16x16x32_bf16 v[102:105], v[150:153], v[180:183], v[102:105]
	v_mfma_f32_16x16x32_bf16 v[98:101], v[164:167], v[180:183], v[98:101]
	v_mfma_f32_16x16x32_bf16 v[86:89], v[150:153], v[188:191], v[86:89]
	v_mfma_f32_16x16x32_bf16 v[82:85], v[164:167], v[188:191], v[82:85]
	v_mfma_f32_16x16x32_bf16 v[70:73], v[150:153], v[200:203], v[70:73]
	v_mfma_f32_16x16x32_bf16 v[66:69], v[164:167], v[200:203], v[66:69]
	s_setprio 0
	s_cmp_lg_u32 s100, 0
	s_cbranch_scc1 .Lhb_52
	s_barrier
.Lhb_52:
	s_mov_b32 m0, s92
	ds_read_b128 v[168:171], v162 offset:16384
	ds_read_b128 v[172:175], v162 offset:17408
	ds_read_b128 v[176:179], v162 offset:18432
	ds_read_b128 v[180:183], v162 offset:19456
	ds_read_b128 v[184:187], v162 offset:20480
	ds_read_b128 v[188:191], v162 offset:21504
	ds_read_b128 v[192:195], v162 offset:22528
	ds_read_b128 v[200:203], v162 offset:23552
	buffer_load_dwordx4 v158, s[16:19], s60 offen lds
	s_mov_b32 m0, s93
	s_add_i32 s63, s60, 0x40000
	buffer_load_dwordx4 v160, s[16:19], s60 offen lds
	s_mov_b32 m0, s94
	s_nop 0
	buffer_load_dwordx4 v158, s[16:19], s63 offen lds
	s_mov_b32 m0, s95
	s_nop 0
	buffer_load_dwordx4 v160, s[16:19], s63 offen lds
	s_mov_b32 m0, s44
	s_nop 0
	buffer_load_dwordx4 v0, s[20:23], s62 offen lds
	s_mov_b32 m0, s36
	s_nop 0
	buffer_load_dwordx4 v159, s[20:23], s62 offen lds
	s_waitcnt vmcnt(8)
	s_waitcnt lgkmcnt(0)
	s_cmp_eq_u32 s100, 0
	s_cbranch_scc1 .Lhb_49
	s_barrier
.Lhb_49:
	s_setprio 1
	s_waitcnt lgkmcnt(7)
	v_mfma_f32_16x16x32_bf16 v[62:65], v[130:133], v[168:171], v[62:65]
	v_mfma_f32_16x16x32_bf16 v[58:61], v[138:141], v[168:171], v[58:61]
	s_waitcnt lgkmcnt(5)
	v_mfma_f32_16x16x32_bf16 v[46:49], v[130:133], v[176:179], v[46:49]
	v_mfma_f32_16x16x32_bf16 v[42:45], v[138:141], v[176:179], v[42:45]
	s_waitcnt lgkmcnt(3)
	v_mfma_f32_16x16x32_bf16 v[30:33], v[130:133], v[184:187], v[30:33]
	v_mfma_f32_16x16x32_bf16 v[26:29], v[138:141], v[184:187], v[26:29]
	s_waitcnt lgkmcnt(1)
	v_mfma_f32_16x16x32_bf16 v[14:17], v[130:133], v[192:195], v[14:17]
	v_mfma_f32_16x16x32_bf16 v[10:13], v[138:141], v[192:195], v[10:13]
	v_mfma_f32_16x16x32_bf16 v[62:65], v[134:137], v[172:175], v[62:65]
	v_mfma_f32_16x16x32_bf16 v[58:61], v[142:145], v[172:175], v[58:61]
	v_mfma_f32_16x16x32_bf16 v[46:49], v[134:137], v[180:183], v[46:49]
	v_mfma_f32_16x16x32_bf16 v[42:45], v[142:145], v[180:183], v[42:45]
	v_mfma_f32_16x16x32_bf16 v[30:33], v[134:137], v[188:191], v[30:33]
	v_mfma_f32_16x16x32_bf16 v[26:29], v[142:145], v[188:191], v[26:29]
	s_waitcnt lgkmcnt(0)
	v_mfma_f32_16x16x32_bf16 v[14:17], v[134:137], v[200:203], v[14:17]
	v_mfma_f32_16x16x32_bf16 v[10:13], v[142:145], v[200:203], v[10:13]
	s_setprio 0
	s_setprio 1
	v_mfma_f32_16x16x32_bf16 v[54:57], v[146:149], v[168:171], v[54:57]
	v_mfma_f32_16x16x32_bf16 v[50:53], v[154:157], v[168:171], v[50:53]
	v_mfma_f32_16x16x32_bf16 v[38:41], v[146:149], v[176:179], v[38:41]
	v_mfma_f32_16x16x32_bf16 v[34:37], v[154:157], v[176:179], v[34:37]
	v_mfma_f32_16x16x32_bf16 v[22:25], v[146:149], v[184:187], v[22:25]
	v_mfma_f32_16x16x32_bf16 v[18:21], v[154:157], v[184:187], v[18:21]
	v_mfma_f32_16x16x32_bf16 v[6:9], v[146:149], v[192:195], v[6:9]
	v_mfma_f32_16x16x32_bf16 v[2:5], v[154:157], v[192:195], v[2:5]
	v_mfma_f32_16x16x32_bf16 v[54:57], v[150:153], v[172:175], v[54:57]
	v_mfma_f32_16x16x32_bf16 v[50:53], v[164:167], v[172:175], v[50:53]
	v_mfma_f32_16x16x32_bf16 v[38:41], v[150:153], v[180:183], v[38:41]
	v_mfma_f32_16x16x32_bf16 v[34:37], v[164:167], v[180:183], v[34:37]
	v_mfma_f32_16x16x32_bf16 v[22:25], v[150:153], v[188:191], v[22:25]
	v_mfma_f32_16x16x32_bf16 v[18:21], v[164:167], v[188:191], v[18:21]
	v_mfma_f32_16x16x32_bf16 v[6:9], v[150:153], v[200:203], v[6:9]
	v_mfma_f32_16x16x32_bf16 v[2:5], v[164:167], v[200:203], v[2:5]
	s_setprio 0
	s_cmp_lg_u32 s100, 0
	s_cbranch_scc1 .Lhb_53
	s_barrier
.Lhb_53:
	v_add_u32_e32 v142, 0x18000, v161
	v_add_u32_e32 v163, 0x1c000, v161
	ds_read_b128 v[130:133], v142
	ds_read_b128 v[134:137], v142 offset:1024
	ds_read_b128 v[138:141], v142 offset:2048
	ds_read_b128 v[142:145], v142 offset:3072
	ds_read_b128 v[146:149], v163
	ds_read_b128 v[150:153], v163 offset:1024
	ds_read_b128 v[154:157], v163 offset:2048
	ds_read_b128 v[164:167], v163 offset:3072
	s_add_i32 s62, s62, 0x40000
	s_mov_b32 m0, s37
	ds_read_b128 v[168:171], v162 offset:32768
	ds_read_b128 v[172:175], v162 offset:33792
	ds_read_b128 v[176:179], v162 offset:34816
	ds_read_b128 v[180:183], v162 offset:35840
	ds_read_b128 v[184:187], v162 offset:36864
	ds_read_b128 v[188:191], v162 offset:37888
	ds_read_b128 v[192:195], v162 offset:38912
	ds_read_b128 v[200:203], v162 offset:39936
	buffer_load_dwordx4 v0, s[20:23], s62 offen lds
	s_mov_b32 m0, s38
	s_nop 0
	buffer_load_dwordx4 v159, s[20:23], s62 offen lds
	s_waitcnt vmcnt(8)
	s_waitcnt lgkmcnt(0)
	s_cmp_eq_u32 s100, 0
	s_cbranch_scc1 .Lhb_50
	s_barrier

.Lhb_54:
	s_mov_b32 m0, s39
	s_or_b32 s62, s60, 0x80
	ds_read_b128 v[168:171], v162 offset:49152
	ds_read_b128 v[172:175], v162 offset:50176
	ds_read_b128 v[176:179], v162 offset:51200
	ds_read_b128 v[180:183], v162 offset:52224
	ds_read_b128 v[184:187], v162 offset:53248
	ds_read_b128 v[188:191], v162 offset:54272
	ds_read_b128 v[192:195], v162 offset:55296
	ds_read_b128 v[200:203], v162 offset:56320
	buffer_load_dwordx4 v158, s[16:19], s62 offen lds
	s_mov_b32 m0, s40
	s_add_i32 s60, s60, 0x40080
	buffer_load_dwordx4 v160, s[16:19], s62 offen lds
	s_mov_b32 m0, s43
	s_nop 0
	buffer_load_dwordx4 v158, s[16:19], s60 offen lds
	s_mov_b32 m0, s42
	s_nop 0
	buffer_load_dwordx4 v160, s[16:19], s60 offen lds
	s_mov_b32 m0, s41
	s_nop 0
	buffer_load_dwordx4 v0, s[20:23], s61 offen lds
	s_mov_b32 m0, s33
	s_nop 0
	buffer_load_dwordx4 v159, s[20:23], s61 offen lds
	s_waitcnt vmcnt(8)
	s_waitcnt lgkmcnt(0)
	s_cmp_eq_u32 s100, 0
	s_cbranch_scc1 .Lhb_51
	s_barrier

; #define PG8_STAGE(bufoff, gbase, voff) do { const Src _g = (gbase); _Pragma("unroll") for (int _i = 0; _i < 2; ++_i) \
;         __builtin_amdgcn_raw_ptr_buffer_load_lds(_g.r, (LAS unsigned*)(lds + (bufoff) + ldsw + _i * 8192), 16, (voff)[_i], _g.o, 0, 0); } while (0)
; #define PG8_WAIT_V(n) asm volatile("s_waitcnt vmcnt(" #n ")" ::: "memory")
; template <class Epi, bool ALIGN_EPI, bool SP2, class Hook>
; __device__ __forceinline__ void gemm_phase(LAS unsigned char* lds, const Gemm g, const StaticOrder& S, const Epi& E, Acc& acc, const bool fresh, const Hook& H, const int wave_id) {
;     ...
;         for (int t = t0; t < nt; t += 2) {
;             const bool last = (t == nt - 2);
;             const Src a1 = cA + (size_t)(t + 1) * kstep;
;             const Src a2 = last ? nA : cA + (size_t)(t + 2) * kstep, b2 = last ? nB : cB + (size_t)(t + 2) * kstep;
;             const Src a3 = a2 + kstep, b3 = b2 + kstep;
;             if (last && has_next) H(nxt);
;             if constexpr (SP2) {
;             PG8_TRIP_SP2(PG8_WAIT_V(8));
;             } else {
;             PG8_LDB(B0, 0, 0); PG8_SCHED; PG8_LDA(At, 0, 0); PG8_STAGE(PG8_SA(1, 1), a1 + hstepA, voffA);
;             PG8_WAIT_L(8); PG8_BAR; PG8_WAIT_L(0); PG8_MMA(0, 0, At, B0); PG8_BAR; PG8_SCHED;
;             PG8_LDB(B1, 0, 1); PG8_STAGE(PG8_SB(0, 0), b2, voffB);
;             PG8_BAR; PG8_WAIT_L(0); PG8_MMA(0, 1, At, B1); PG8_BAR;
;             PG8_LDA(At, 0, 1); PG8_STAGE(PG8_SA(0, 0), a2, voffA);
;             PG8_BAR; PG8_WAIT_L(0); PG8_MMA(1, 0, At, B0); PG8_BAR; PG8_SCHED;
;             PG8_STAGE(PG8_SB(0, 1), b2 + hstep, voffB);
;             PG8_WAIT_V(6); PG8_BAR; PG8_MMA(1, 1, At, B1); PG8_BAR;
;             PG8_LDB(B0, 1, 0); PG8_SCHED; PG8_LDA(At, 1, 0); PG8_STAGE(PG8_SA(0, 1), a2 + hstepA, voffA);
;             PG8_WAIT_L(8); PG8_BAR; PG8_WAIT_L(0); PG8_MMA(0, 0, At, B0); PG8_BAR; PG8_SCHED;
;             PG8_LDB(B1, 1, 1); PG8_STAGE(PG8_SB(1, 0), b3, voffB);
;             PG8_BAR; PG8_WAIT_L(0); PG8_MMA(0, 1, At, B1); PG8_BAR;
;             PG8_LDA(At, 1, 1); PG8_STAGE(PG8_SA(1, 0), a3, voffA);
;             PG8_BAR; PG8_WAIT_L(0); PG8_MMA(1, 0, At, B0); PG8_BAR; PG8_SCHED;
;             PG8_STAGE(PG8_SB(1, 1), b3 + hstep, voffB);
;             PG8_WAIT_V(6); PG8_BAR; PG8_MMA(1, 1, At, B1); PG8_BAR;
;             }
;         }
;         if constexpr (ALIGN_EPI) { if (wr == 0) PG8_BAR; }
.Lhb_55:
	s_add_i32 s59, s59, 2
	s_addk_i32 s2, 0x100
	s_addk_i32 s3, 0x100
	s_cmp_gt_u32 s59, 13
	s_cbranch_scc0 .LBB0_1235
	v_readlane_b32 s2, v251, 45
	v_readlane_b32 s3, v251, 46
	s_and_b64 vcc, exec, s[2:3]
	s_cbranch_vccz .LBB0_1238

; #define PG8_BAR __builtin_amdgcn_s_barrier()
; template <class Epi, bool ALIGN_EPI, bool SP2, class Hook>
; __device__ __forceinline__ void gemm_phase(LAS unsigned char* lds, const Gemm g, const StaticOrder& S, const Epi& E, Acc& acc, const bool fresh, const Hook& H, const int wave_id) {
;     ...
;         if (reset) {
; #pragma unroll
;             for (int a = 0; a < 2; ++a)
; #pragma unroll
;                 for (int b = 0; b < 2; ++b)
; #pragma unroll
;                     for (int m = 0; m < 4; ++m)
; #pragma unroll
;                         for (int n = 0; n < 2; ++n) acc[a][b][m][n] = (f32x4){0.f, 0.f, 0.f, 0.f};
;         }
;         cur = nxt; cA = nA; cB = nB; ++ui;
;         if constexpr (ALIGN_EPI) { if (wr == 1) PG8_BAR; }
.LBB0_1254:
	s_or_b64 exec, exec, s[12:13]
	s_and_b64 vcc, exec, s[4:5]
	s_mov_b64 s[2:3], -1
	s_cbranch_vccnz .LBB0_1223
	s_and_b64 vcc, exec, s[0:1]
	s_cbranch_vccnz .LBB0_1222
	s_branch .LBB0_1222

; template <class Epi, bool ALIGN_EPI, bool SP2, class Hook>
; __device__ __forceinline__ void gemm_phase(LAS unsigned char* lds, const Gemm g, const StaticOrder& S, const Epi& E, Acc& acc, const bool fresh, const Hook& H, const int wave_id) {
;     ...
;     for (int i = 0; i < 2; ++i) { int R, C; stage_rc(tid * 16 + i * 8192, R, C); const int Rb = (R & ~31) + perm32(R & 31);
;         voffA[i] = (unsigned)(R * lda + C) * 2u; voffB[i] = (unsigned)(Rb * K + C) * 2u; }
;     const size_t kstep = (size_t)(BK * 2);
;     const size_t hstep = (size_t)HALF * K * 2, hstepA = (size_t)HALF * lda * 2;
;     const size_t tstep = 2 * hstep, tstepA = 2 * hstepA;
;     const unsigned ldsw = (unsigned)wid * 1024u;
;     const int aoff = lds_byte(wr * 64 + fr, fq * 8), boff = lds_byte(wc * 32 + fr, fq * 8);
;     ...
;     Unit cur, nxt; int ui = 0, rs_pm = -1, t0 = 0;
;     if (!S.next(0, cur)) return;
;     if (fresh) {
; #pragma unroll
;         for (int a = 0; a < 2; ++a)
; #pragma unroll
;             for (int b = 0; b < 2; ++b)
; #pragma unroll
;                 for (int m = 0; m < 4; ++m)
; #pragma unroll
;                     for (int n = 0; n < 2; ++n) acc[a][b][m][n] = (f32x4){0.f, 0.f, 0.f, 0.f};
;     }
;     bf16x8 At[4][2], B0[2][2], B1[2][2];
;     Src cA = make_src(selA(g, cur.seg), (size_t)cur.pm * tstepA), cB = make_src(selB(g, cur.seg), (size_t)cur.pn * tstep);
;     if constexpr (SP2) {
;         f32x4 rpa = {0.f, 0.f, 0.f, 0.f}, rpb = rpa;
;         float rsum = 0.f;
;         if constexpr (Epi::NEEDS_RS) { const GAS f32x4* p = (const GAS f32x4*)(E.rowss + (size_t)(cur.pm * BM + (tid >> 1)) * 16) + (tid & 1) * 2; rpa = p[0]; rpb = p[1]; }
;         PG8_STAGE(PG8_SB(0, 0), cB, voffB); PG8_STAGE(PG8_SB(0, 1), cB + hstep, voffB); PG8_STAGE(PG8_SA(0, 0), cA, voffA); PG8_STAGE(PG8_SA(0, 1), cA + hstepA, voffA);
;         if (wr == 1) PG8_BAR;
;         PG8_WAIT_V(2); PG8_BAR;
;         if constexpr (Epi::NEEDS_RS) {
;             rsum = ((rpa[0] + rpa[1]) + (rpa[2] + rpa[3])) + ((rpb[0] + rpb[1]) + (rpb[2] + rpb[3]));
;             const float t2 = __builtin_bit_cast(float, __builtin_amdgcn_update_dpp(0, __builtin_bit_cast(int, rsum), 0xB1  , 0xf, 0xf, false)); rsum = (tid & 1) ? (t2 + rsum) : (rsum + t2);
;             if ((tid & 1) == 0) ((LAS float*)(lds + RSTAB_OFF))[tid >> 1] = __builtin_amdgcn_rsqf(rsum * (1.0f / DM) + NORM_EPS);
;             rs_pm = cur.pm;
.LBB0_1446:
	v_readlane_b32 s0, v253, 21
	v_readlane_b32 s1, v253, 22
	v_mov_b32_e32 v0, v1
	s_andn2_b64 vcc, exec, s[0:1]
	s_cbranch_vccnz .LBB0_1474
	v_mbcnt_lo_u32_b32 v0, -1, v0
	v_mbcnt_hi_u32_b32 v10, -1, v0
	v_readlane_b32 s0, v249, 60
	v_readlane_b32 s2, v254, 49
	v_readlane_b32 s3, v254, 50
	v_add_u32_e32 v0, s0, v10
	v_bfe_i32 v4, v0, 27, 1
	v_lshlrev_b32_e32 v2, 4, v0
	v_lshrrev_b32_e32 v4, 22, v4
	v_add_u32_e32 v4, v2, v4
	v_and_b32_e32 v4, 0xfffffc00, v4
	v_sub_u32_e32 v4, v2, v4
	v_ashrrev_i32_e32 v3, 31, v0
	s_waitcnt lgkmcnt(0)
	v_lshrrev_b32_e32 v5, 4, v4
	v_lshrrev_b32_e32 v3, 26, v3
	v_bitop3_b32 v4, v5, v4, 32 bitop3:0x6c
	v_add_u32_e32 v3, v0, v3
	v_ashrrev_i32_e32 v6, 31, v4
	v_ashrrev_i32_e32 v3, 6, v3
	v_lshrrev_b32_e32 v6, 26, v6
	v_lshlrev_b32_e32 v5, 3, v3
	v_add_u32_e32 v6, v4, v6
	v_and_b32_e32 v5, -16, v5
	v_ashrrev_i32_e32 v7, 6, v6
	v_and_b32_e32 v6, 0xc0, v6
	v_add_u32_e32 v5, v7, v5
	v_sub_u32_e32 v4, v4, v6
	v_lshlrev_b32_e32 v3, 5, v3
	v_ashrrev_i16_sdwa v4, v226, sext(v4) dst_sel:DWORD dst_unused:UNUSED_PAD src0_sel:DWORD src1_sel:BYTE_0
	v_lshlrev_b32_e32 v6, 1, v5
	v_lshrrev_b32_e32 v8, 2, v5
	v_and_b32_e32 v7, 3, v7
	s_mov_b32 s0, 0x1fffe0
	v_and_b32_e32 v3, 32, v3
	v_bfe_i32 v4, v4, 0, 16
	v_and_b32_e32 v6, 24, v6
	v_and_b32_e32 v8, 4, v8
	v_and_or_b32 v7, v5, s0, v7
	v_or3_b32 v6, v7, v8, v6
	v_add_lshl_u32 v3, v3, v4, 1
	v_add_u32_e32 v2, 0x2000, v2
	s_waitcnt vmcnt(0)
	v_lshl_add_u32 v132, v5, 11, v3
	v_lshl_add_u32 v133, v6, 11, v3
	v_ashrrev_i32_e32 v3, 31, v2
	v_lshrrev_b32_e32 v3, 22, v3
	v_add_u32_e32 v3, v2, v3
	v_ashrrev_i32_e32 v3, 10, v3
	v_mul_i32_i24_e32 v4, 0x400, v3
	v_sub_u32_e32 v2, v2, v4
	v_lshrrev_b32_e32 v4, 4, v2
	v_bitop3_b32 v2, v4, v2, 32 bitop3:0x6c
	v_ashrrev_i32_e32 v5, 31, v2
	v_lshrrev_b32_e32 v5, 26, v5
	v_lshlrev_b32_e32 v4, 3, v3
	v_add_u32_e32 v5, v2, v5
	v_and_b32_e32 v4, -16, v4
	v_ashrrev_i32_e32 v6, 6, v5
	v_add_u32_e32 v4, v6, v4
	v_and_b32_e32 v6, 3, v6
	v_and_or_b32 v6, v4, s0, v6
	v_readlane_b32 s0, v254, 47
	v_readlane_b32 s1, v254, 48
	s_add_u32 s24, s0, 0x1100000
	s_addc_u32 s25, s1, 0
	v_readlane_b32 s0, v254, 37
	v_readlane_b32 s1, v254, 38
	s_add_u32 s26, s0, 0x600000
	v_and_b32_e32 v5, 0xc0, v5
	s_addc_u32 s27, s1, 0
	s_mov_b64 s[12:13], s[2:3]
	s_mov_b64 s[0:1], s[2:3]
	v_sub_u32_e32 v2, v2, v5
	v_lshlrev_b32_e32 v3, 5, v3
	v_ashrrev_i16_sdwa v2, v226, sext(v2) dst_sel:DWORD dst_unused:UNUSED_PAD src0_sel:DWORD src1_sel:BYTE_0
	v_lshlrev_b32_e32 v5, 1, v4
	v_lshrrev_b32_e32 v7, 2, v4
	s_mov_b64 s[76:77], s[24:25]
	s_mov_b64 s[0:1], s[24:25]
	s_mov_b64 s[2:3], s[24:25]
	v_and_b32_e32 v3, 32, v3
	v_bfe_i32 v2, v2, 0, 16
	v_and_b32_e32 v5, 24, v5
	v_and_b32_e32 v7, 4, v7
	v_or3_b32 v5, v6, v7, v5
	v_add_lshl_u32 v2, v3, v2, 1
	v_ashrrev_i32_e32 v11, 1, v0
	v_readlane_b32 s0, v253, 63
	v_lshl_add_u32 v134, v4, 11, v2
	v_lshl_add_u32 v135, v5, 11, v2
	v_add_u32_e32 v2, s0, v11
	v_ashrrev_i32_e32 v3, 31, v2
	v_lshlrev_b64 v[2:3], 6, v[2:3]
	v_and_b32_e32 v12, 1, v10
	v_lshl_add_u64 v[2:3], s[26:27], 0, v[2:3]
	v_lshlrev_b32_e32 v0, 5, v12
	s_mov_b32 m0, s92
	s_and_b32 s77, s77, 0xffff
	v_lshl_add_u64 v[6:7], v[2:3], 0, v[0:1]
	v_readlane_b32 s0, v254, 5
	global_load_dwordx4 v[2:5], v[6:7], off offset:16
	s_nop 0
	global_load_dwordx4 v[6:9], v[6:7], off
	s_and_b32 s13, s13, 0xffff
	s_mov_b32 s14, s78
	buffer_load_dwordx4 v133, s[76:79], s0 offen lds
	s_mov_b32 m0, s93
	s_mov_b32 s15, s79
	buffer_load_dwordx4 v135, s[76:79], s0 offen lds
	s_mov_b32 m0, s94
	v_readlane_b32 s0, v254, 0
	v_readlane_b32 s2, v250, 9
	v_readlane_b32 s3, v250, 10
	s_andn2_b64 vcc, exec, s[2:3]
	s_nop 0
	v_cndmask_b32_e64 v0, 0, 1, s[2:3]
	buffer_load_dwordx4 v133, s[76:79], s0 offen lds
	s_mov_b32 m0, s95
	s_nop 0
	buffer_load_dwordx4 v135, s[76:79], s0 offen lds
	s_mov_b32 m0, s44
	v_readlane_b32 s0, v254, 3
	s_nop 4
	buffer_load_dwordx4 v132, s[12:15], s0 offen lds
	s_mov_b32 m0, s36
	s_nop 0
	buffer_load_dwordx4 v134, s[12:15], s0 offen lds
	s_mov_b32 m0, s37
	v_readlane_b32 s0, v254, 1
	s_nop 4
	buffer_load_dwordx4 v132, s[12:15], s0 offen lds
	s_mov_b32 m0, s38
	s_nop 0
	buffer_load_dwordx4 v134, s[12:15], s0 offen lds
	v_cmp_ne_u32_e64 s[0:1], 1, v0
	s_cbranch_vccnz .LBB0_1449
.LBB0_1449:
	s_waitcnt vmcnt(8)
	v_add_f32_e32 v0, v6, v7
	v_add_f32_e32 v6, v8, v9
	v_add_f32_e32 v2, v2, v3
	v_add_f32_e32 v3, v4, v5
	s_waitcnt vmcnt(2)
	v_add_f32_e32 v0, v0, v6
	v_add_f32_e32 v2, v2, v3
	v_add_f32_e32 v0, v0, v2
	v_mov_b32_e32 v2, v1
	v_cmp_eq_u32_e32 vcc, 0, v12
	s_barrier
	v_mov_b32_dpp v2, v0 quad_perm:[1,0,3,2] row_mask:0xf bank_mask:0xf
	s_and_saveexec_b64 s[2:3], vcc
	s_cbranch_execz .LBB0_1451
	v_add_f32_e32 v0, v0, v2
	v_mov_b32_e32 v2, 0x358637bd
	v_fmamk_f32 v0, v0, 0x3a800000, v2
	v_rsq_f32_e32 v0, v0
	v_lshl_add_u32 v2, v11, 2, 0
	v_add_u32_e32 v2, 0x21000, v2
	ds_write_b32 v2, v0

; #define PG8_WAIT_V(n) asm volatile("s_waitcnt vmcnt(" #n ")" ::: "memory")
; template <class Epi, bool ALIGN_EPI, bool SP2, class Hook>
; __device__ __forceinline__ void gemm_phase(LAS unsigned char* lds, const Gemm g, const StaticOrder& S, const Epi& E, Acc& acc, const bool fresh, const Hook& H, const int wave_id) {
;     ...
;         if constexpr (SP2 && Epi::NSTORE > 0) {
;             const Src a1 = cA + kstep, a2 = cA + 2 * kstep, b2 = cB + 2 * kstep, a3 = a2 + kstep, b3 = b2 + kstep;
;             if constexpr (Epi::NSTORE == 16) PG8_TRIP_SP2(PG8_WAIT_V(24)); else PG8_TRIP_SP2(PG8_WAIT_V(16));
.LBB0_1452:
	ds_read_b128 v[2:5], v138
	ds_read_b128 v[6:9], v138 offset:1024
	ds_read_b128 v[10:13], v138 offset:2048
	ds_read_b128 v[14:17], v138 offset:3072
	ds_read_b128 v[18:21], v139
	ds_read_b128 v[22:25], v139 offset:1024
	ds_read_b128 v[26:29], v139 offset:2048
	ds_read_b128 v[30:33], v139 offset:3072
	s_or_b32 s3, s50, 0x100
	s_or_b32 s2, s50, 0x180
	s_or_b32 s12, s51, 0x100
	s_or_b32 s13, s50, 0x40080
	s_mov_b32 m0, s45
	ds_read_b128 v[34:37], v137
	ds_read_b128 v[38:41], v137 offset:1024
	ds_read_b128 v[42:45], v137 offset:2048
	ds_read_b128 v[46:49], v137 offset:3072
	ds_read_b128 v[50:53], v137 offset:4096
	ds_read_b128 v[54:57], v137 offset:5120
	ds_read_b128 v[58:61], v137 offset:6144
	ds_read_b128 v[62:65], v137 offset:7168
	buffer_load_dwordx4 v132, s[4:7], s13 offen lds
	s_mov_b32 m0, s46
	s_nop 0
	buffer_load_dwordx4 v134, s[4:7], s13 offen lds
	s_waitcnt vmcnt(16)
	s_waitcnt lgkmcnt(0)
	s_cmp_eq_u32 s100, 0
	s_cbranch_scc1 .Lhb_56
	s_barrier
.Lhb_56:
	s_setprio 1
	s_waitcnt lgkmcnt(1)
	v_mfma_f32_16x16x32_bf16 v[90:93], v[2:5], v[58:61], 0
	v_mfma_f32_16x16x32_bf16 v[66:69], v[2:5], v[34:37], 0
	v_mfma_f32_16x16x32_bf16 v[70:73], v[10:13], v[34:37], 0
	v_mfma_f32_16x16x32_bf16 v[74:77], v[2:5], v[42:45], 0
	v_mfma_f32_16x16x32_bf16 v[78:81], v[10:13], v[42:45], 0
	v_mfma_f32_16x16x32_bf16 v[82:85], v[2:5], v[50:53], 0
	v_mfma_f32_16x16x32_bf16 v[86:89], v[10:13], v[50:53], 0
	s_waitcnt lgkmcnt(0)
	v_mfma_f32_16x16x32_bf16 v[96:99], v[6:9], v[62:65], v[90:93]
	v_mfma_f32_16x16x32_bf16 v[90:93], v[10:13], v[58:61], 0
	v_mfma_f32_16x16x32_bf16 v[66:69], v[6:9], v[38:41], v[66:69]
	v_mfma_f32_16x16x32_bf16 v[70:73], v[14:17], v[38:41], v[70:73]
	v_mfma_f32_16x16x32_bf16 v[74:77], v[6:9], v[46:49], v[74:77]
	v_mfma_f32_16x16x32_bf16 v[78:81], v[14:17], v[46:49], v[78:81]
	v_mfma_f32_16x16x32_bf16 v[82:85], v[6:9], v[54:57], v[82:85]
	v_mfma_f32_16x16x32_bf16 v[86:89], v[14:17], v[54:57], v[86:89]
	v_mfma_f32_16x16x32_bf16 v[104:107], v[14:17], v[62:65], v[90:93]
	s_setprio 0
	s_setprio 1
	v_mfma_f32_16x16x32_bf16 v[90:93], v[18:21], v[34:37], 0
	v_mfma_f32_16x16x32_bf16 v[34:37], v[26:29], v[34:37], 0
	v_mfma_f32_16x16x32_bf16 v[112:115], v[22:25], v[38:41], v[90:93]
	v_mfma_f32_16x16x32_bf16 v[34:37], v[30:33], v[38:41], v[34:37]
	v_mfma_f32_16x16x32_bf16 v[38:41], v[18:21], v[42:45], 0
	v_mfma_f32_16x16x32_bf16 v[42:45], v[26:29], v[42:45], 0
	v_mfma_f32_16x16x32_bf16 v[38:41], v[22:25], v[46:49], v[38:41]
	v_mfma_f32_16x16x32_bf16 v[42:45], v[30:33], v[46:49], v[42:45]
	v_mfma_f32_16x16x32_bf16 v[46:49], v[18:21], v[50:53], 0
	v_mfma_f32_16x16x32_bf16 v[50:53], v[26:29], v[50:53], 0
	v_mfma_f32_16x16x32_bf16 v[46:49], v[22:25], v[54:57], v[46:49]
	v_mfma_f32_16x16x32_bf16 v[50:53], v[30:33], v[54:57], v[50:53]
	v_mfma_f32_16x16x32_bf16 v[54:57], v[18:21], v[58:61], 0
	v_mfma_f32_16x16x32_bf16 v[58:61], v[26:29], v[58:61], 0
	v_mfma_f32_16x16x32_bf16 v[54:57], v[22:25], v[62:65], v[54:57]
	v_mfma_f32_16x16x32_bf16 v[58:61], v[30:33], v[62:65], v[58:61]
	s_setprio 0
	s_cmp_lg_u32 s100, 0
	s_cbranch_scc1 .Lhb_60
	s_barrier
.Lhb_60:
	s_mov_b32 m0, s92
	ds_read_b128 v[62:65], v137 offset:16384
	ds_read_b128 v[90:93], v137 offset:17408
	ds_read_b128 v[100:103], v137 offset:18432
	ds_read_b128 v[108:111], v137 offset:19456
	ds_read_b128 v[116:119], v137 offset:20480
	ds_read_b128 v[120:123], v137 offset:21504
	ds_read_b128 v[124:127], v137 offset:22528
	ds_read_b128 v[128:131], v137 offset:23552
	buffer_load_dwordx4 v133, s[8:11], s12 offen lds
	s_mov_b32 m0, s93
	s_nop 0
	buffer_load_dwordx4 v135, s[8:11], s12 offen lds
	s_or_b32 s12, s51, 0x40100
	s_mov_b32 m0, s94
	s_nop 0
	buffer_load_dwordx4 v133, s[8:11], s12 offen lds
	s_mov_b32 m0, s95
	s_nop 0
	buffer_load_dwordx4 v135, s[8:11], s12 offen lds
	s_mov_b32 m0, s44
	s_nop 0
	buffer_load_dwordx4 v132, s[4:7], s3 offen lds
	s_mov_b32 m0, s36
	s_nop 0
	buffer_load_dwordx4 v134, s[4:7], s3 offen lds
	s_waitcnt vmcnt(16)
	s_waitcnt lgkmcnt(0)
	s_cmp_eq_u32 s100, 0
	s_cbranch_scc1 .Lhb_57
	s_barrier
.Lhb_57:
	s_setprio 1
	s_waitcnt lgkmcnt(7)
	v_mfma_f32_16x16x32_bf16 v[142:145], v[2:5], v[62:65], 0
	s_waitcnt lgkmcnt(5)
	v_mfma_f32_16x16x32_bf16 v[150:153], v[2:5], v[100:103], 0
	s_waitcnt lgkmcnt(3)
	v_mfma_f32_16x16x32_bf16 v[158:161], v[2:5], v[116:119], 0
	s_waitcnt lgkmcnt(1)
	v_mfma_f32_16x16x32_bf16 v[2:5], v[2:5], v[124:127], 0
	v_mfma_f32_16x16x32_bf16 v[142:145], v[6:9], v[90:93], v[142:145]
	v_mfma_f32_16x16x32_bf16 v[150:153], v[6:9], v[108:111], v[150:153]
	v_mfma_f32_16x16x32_bf16 v[158:161], v[6:9], v[120:123], v[158:161]
	s_waitcnt lgkmcnt(0)
	v_mfma_f32_16x16x32_bf16 v[2:5], v[6:9], v[128:131], v[2:5]
	v_mfma_f32_16x16x32_bf16 v[6:9], v[10:13], v[124:127], 0
	v_mfma_f32_16x16x32_bf16 v[146:149], v[10:13], v[62:65], 0
	v_mfma_f32_16x16x32_bf16 v[154:157], v[10:13], v[100:103], 0
	v_mfma_f32_16x16x32_bf16 v[162:165], v[10:13], v[116:119], 0
	v_mfma_f32_16x16x32_bf16 v[6:9], v[14:17], v[128:131], v[6:9]
	v_mfma_f32_16x16x32_bf16 v[146:149], v[14:17], v[90:93], v[146:149]
	v_mfma_f32_16x16x32_bf16 v[154:157], v[14:17], v[108:111], v[154:157]
	v_mfma_f32_16x16x32_bf16 v[162:165], v[14:17], v[120:123], v[162:165]
	s_setprio 0
	s_setprio 1
	v_mfma_f32_16x16x32_bf16 v[10:13], v[18:21], v[62:65], 0
	v_mfma_f32_16x16x32_bf16 v[166:169], v[22:25], v[90:93], v[10:13]
	v_mfma_f32_16x16x32_bf16 v[10:13], v[26:29], v[62:65], 0
	v_mfma_f32_16x16x32_bf16 v[170:173], v[30:33], v[90:93], v[10:13]
	v_mfma_f32_16x16x32_bf16 v[10:13], v[18:21], v[100:103], 0
	v_mfma_f32_16x16x32_bf16 v[174:177], v[22:25], v[108:111], v[10:13]
	v_mfma_f32_16x16x32_bf16 v[10:13], v[26:29], v[100:103], 0
	v_mfma_f32_16x16x32_bf16 v[178:181], v[30:33], v[108:111], v[10:13]
	v_mfma_f32_16x16x32_bf16 v[10:13], v[18:21], v[116:119], 0
	v_mfma_f32_16x16x32_bf16 v[182:185], v[22:25], v[120:123], v[10:13]
	v_mfma_f32_16x16x32_bf16 v[10:13], v[26:29], v[116:119], 0
	v_mfma_f32_16x16x32_bf16 v[186:189], v[30:33], v[120:123], v[10:13]
	v_mfma_f32_16x16x32_bf16 v[10:13], v[18:21], v[124:127], 0
	v_mfma_f32_16x16x32_bf16 v[16:19], v[22:25], v[128:131], v[10:13]
	v_mfma_f32_16x16x32_bf16 v[10:13], v[26:29], v[124:127], 0
	v_mfma_f32_16x16x32_bf16 v[190:193], v[30:33], v[128:131], v[10:13]
	s_setprio 0
	s_cmp_lg_u32 s100, 0
	s_cbranch_scc1 .Lhb_61
	s_barrier
; #define PG8_WAIT_V(n) asm volatile("s_waitcnt vmcnt(" #n ")" ::: "memory")
; template <class Epi, bool ALIGN_EPI, bool SP2, class Hook>
; __device__ __forceinline__ void gemm_phase(LAS unsigned char* lds, const Gemm g, const StaticOrder& S, const Epi& E, Acc& acc, const bool fresh, const Hook& H, const int wave_id) {
;     ...
;         if constexpr (SP2 && Epi::NSTORE > 0) {
;             const Src a1 = cA + kstep, a2 = cA + 2 * kstep, b2 = cB + 2 * kstep, a3 = a2 + kstep, b3 = b2 + kstep;
;             if constexpr (Epi::NSTORE == 16) PG8_TRIP_SP2(PG8_WAIT_V(24)); else PG8_TRIP_SP2(PG8_WAIT_V(16));
;             t0 = 2;
.Lhb_61:
	s_nop 4
	ds_read_b128 v[10:13], v140
	ds_read_b128 v[24:27], v140 offset:1024
	ds_read_b128 v[194:197], v140 offset:2048
	ds_read_b128 v[200:203], v140 offset:3072
	ds_read_b128 v[204:207], v141
	ds_read_b128 v[208:211], v141 offset:1024
	ds_read_b128 v[212:215], v141 offset:2048
	ds_read_b128 v[138:141], v141 offset:3072
	s_or_b32 s3, s50, 0x40100
	s_mov_b32 m0, s37
	ds_read_b128 v[20:23], v137 offset:32768
	ds_read_b128 v[28:31], v137 offset:33792
	ds_read_b128 v[216:219], v137 offset:34816
	ds_read_b128 v[220:223], v137 offset:35840
	ds_read_b128 v[228:231], v137 offset:36864
	ds_read_b128 v[232:235], v137 offset:37888
	ds_read_b128 v[236:239], v137 offset:38912
	ds_read_b128 v[240:243], v137 offset:39936
	buffer_load_dwordx4 v132, s[4:7], s3 offen lds
	s_mov_b32 m0, s38
	s_nop 0
	buffer_load_dwordx4 v134, s[4:7], s3 offen lds
	s_waitcnt vmcnt(8)
	s_waitcnt lgkmcnt(0)
	s_cmp_eq_u32 s100, 0
	s_cbranch_scc1 .Lhb_58
	s_barrier
.Lhb_58:
	s_setprio 1
	s_waitcnt lgkmcnt(7)
	v_mfma_f32_16x16x32_bf16 v[62:65], v[10:13], v[20:23], v[66:69]
	s_waitcnt lgkmcnt(6)
	v_mfma_f32_16x16x32_bf16 v[124:127], v[24:27], v[28:31], v[62:65]
	v_mfma_f32_16x16x32_bf16 v[62:65], v[194:197], v[20:23], v[70:73]
	v_mfma_f32_16x16x32_bf16 v[116:119], v[200:203], v[28:31], v[62:65]
	s_waitcnt lgkmcnt(5)
	v_mfma_f32_16x16x32_bf16 v[62:65], v[10:13], v[216:219], v[74:77]
	s_waitcnt lgkmcnt(4)
	v_mfma_f32_16x16x32_bf16 v[108:111], v[24:27], v[220:223], v[62:65]
	v_mfma_f32_16x16x32_bf16 v[62:65], v[194:197], v[216:219], v[78:81]
	v_mfma_f32_16x16x32_bf16 v[100:103], v[200:203], v[220:223], v[62:65]
	s_waitcnt lgkmcnt(3)
	v_mfma_f32_16x16x32_bf16 v[62:65], v[10:13], v[228:231], v[82:85]
	s_waitcnt lgkmcnt(2)
	v_mfma_f32_16x16x32_bf16 v[92:95], v[24:27], v[232:235], v[62:65]
	v_mfma_f32_16x16x32_bf16 v[62:65], v[194:197], v[228:231], v[86:89]
	v_mfma_f32_16x16x32_bf16 v[84:87], v[200:203], v[232:235], v[62:65]
	s_waitcnt lgkmcnt(1)
	v_mfma_f32_16x16x32_bf16 v[62:65], v[10:13], v[236:239], v[96:99]
	s_waitcnt lgkmcnt(0)
	v_mfma_f32_16x16x32_bf16 v[76:79], v[24:27], v[240:243], v[62:65]
	v_mfma_f32_16x16x32_bf16 v[62:65], v[194:197], v[236:239], v[104:107]
	v_mfma_f32_16x16x32_bf16 v[64:67], v[200:203], v[240:243], v[62:65]
	s_setprio 0
	s_setprio 1
	v_mfma_f32_16x16x32_bf16 v[68:71], v[204:207], v[20:23], v[112:115]
	v_mfma_f32_16x16x32_bf16 v[20:23], v[212:215], v[20:23], v[34:37]
	v_mfma_f32_16x16x32_bf16 v[120:123], v[138:141], v[28:31], v[20:23]
	v_mfma_f32_16x16x32_bf16 v[20:23], v[204:207], v[216:219], v[38:41]
	v_mfma_f32_16x16x32_bf16 v[112:115], v[208:211], v[220:223], v[20:23]
	v_mfma_f32_16x16x32_bf16 v[20:23], v[212:215], v[216:219], v[42:45]
	v_mfma_f32_16x16x32_bf16 v[104:107], v[138:141], v[220:223], v[20:23]
	v_mfma_f32_16x16x32_bf16 v[20:23], v[204:207], v[228:231], v[46:49]
	v_mfma_f32_16x16x32_bf16 v[96:99], v[208:211], v[232:235], v[20:23]
	v_mfma_f32_16x16x32_bf16 v[20:23], v[212:215], v[228:231], v[50:53]
	v_mfma_f32_16x16x32_bf16 v[88:91], v[138:141], v[232:235], v[20:23]
	v_mfma_f32_16x16x32_bf16 v[20:23], v[204:207], v[236:239], v[54:57]
	v_mfma_f32_16x16x32_bf16 v[80:83], v[208:211], v[240:243], v[20:23]
	v_mfma_f32_16x16x32_bf16 v[20:23], v[212:215], v[236:239], v[58:61]
	v_mfma_f32_16x16x32_bf16 v[128:131], v[208:211], v[28:31], v[68:71]
	v_mfma_f32_16x16x32_bf16 v[68:71], v[138:141], v[240:243], v[20:23]
	s_setprio 0
	s_cmp_lg_u32 s100, 0
	s_cbranch_scc1 .Lhb_62
	s_barrier
.Lhb_62:
	s_mov_b32 m0, s39
	s_or_b32 s3, s51, 0x180
	ds_read_b128 v[32:35], v137 offset:49152
	ds_read_b128 v[40:43], v137 offset:50176
	ds_read_b128 v[216:219], v137 offset:51200
	ds_read_b128 v[220:223], v137 offset:52224
	ds_read_b128 v[228:231], v137 offset:53248
	ds_read_b128 v[232:235], v137 offset:54272
	ds_read_b128 v[236:239], v137 offset:55296
	ds_read_b128 v[240:243], v137 offset:56320
	buffer_load_dwordx4 v133, s[8:11], s3 offen lds
	s_mov_b32 m0, s40
	s_nop 0
	buffer_load_dwordx4 v135, s[8:11], s3 offen lds
	s_or_b32 s3, s51, 0x40180
	s_mov_b32 m0, s43
	s_nop 0
	buffer_load_dwordx4 v133, s[8:11], s3 offen lds
	s_mov_b32 m0, s42
	s_nop 0
	buffer_load_dwordx4 v135, s[8:11], s3 offen lds
	s_mov_b32 m0, s41
	s_nop 0
	buffer_load_dwordx4 v132, s[4:7], s2 offen lds
	s_mov_b32 m0, s33
	s_nop 0
	buffer_load_dwordx4 v134, s[4:7], s2 offen lds
	s_waitcnt vmcnt(8)
	s_waitcnt lgkmcnt(0)
	s_cmp_eq_u32 s100, 0
	s_cbranch_scc1 .Lhb_59
	s_barrier
.Lhb_59:
	s_setprio 1
	s_waitcnt lgkmcnt(7)
	v_mfma_f32_16x16x32_bf16 v[20:23], v[10:13], v[32:35], v[142:145]
	s_waitcnt lgkmcnt(6)
	v_mfma_f32_16x16x32_bf16 v[60:63], v[24:27], v[40:43], v[20:23]
	v_mfma_f32_16x16x32_bf16 v[20:23], v[194:197], v[32:35], v[146:149]
	v_mfma_f32_16x16x32_bf16 v[52:55], v[200:203], v[40:43], v[20:23]
	s_waitcnt lgkmcnt(5)
	v_mfma_f32_16x16x32_bf16 v[20:23], v[10:13], v[216:219], v[150:153]
	s_waitcnt lgkmcnt(4)
	v_mfma_f32_16x16x32_bf16 v[44:47], v[24:27], v[220:223], v[20:23]
	v_mfma_f32_16x16x32_bf16 v[20:23], v[194:197], v[216:219], v[154:157]
	v_mfma_f32_16x16x32_bf16 v[36:39], v[200:203], v[220:223], v[20:23]
	s_waitcnt lgkmcnt(3)
	v_mfma_f32_16x16x32_bf16 v[20:23], v[10:13], v[228:231], v[158:161]
	s_waitcnt lgkmcnt(1)
	v_mfma_f32_16x16x32_bf16 v[2:5], v[10:13], v[236:239], v[2:5]
	v_mfma_f32_16x16x32_bf16 v[28:31], v[24:27], v[232:235], v[20:23]
	v_mfma_f32_16x16x32_bf16 v[20:23], v[194:197], v[228:231], v[162:165]
	s_waitcnt lgkmcnt(0)
	v_mfma_f32_16x16x32_bf16 v[12:15], v[24:27], v[240:243], v[2:5]
	v_mfma_f32_16x16x32_bf16 v[2:5], v[194:197], v[236:239], v[6:9]
	v_mfma_f32_16x16x32_bf16 v[20:23], v[200:203], v[232:235], v[20:23]
	v_mfma_f32_16x16x32_bf16 v[4:7], v[200:203], v[240:243], v[2:5]
	s_setprio 0
	s_setprio 1
	v_mfma_f32_16x16x32_bf16 v[8:11], v[204:207], v[32:35], v[166:169]
	v_mfma_f32_16x16x32_bf16 v[72:75], v[208:211], v[40:43], v[8:11]
	v_mfma_f32_16x16x32_bf16 v[8:11], v[212:215], v[32:35], v[170:173]
	v_mfma_f32_16x16x32_bf16 v[56:59], v[138:141], v[40:43], v[8:11]
	v_mfma_f32_16x16x32_bf16 v[8:11], v[204:207], v[216:219], v[174:177]
	v_mfma_f32_16x16x32_bf16 v[48:51], v[208:211], v[220:223], v[8:11]
	v_mfma_f32_16x16x32_bf16 v[8:11], v[212:215], v[216:219], v[178:181]
	v_mfma_f32_16x16x32_bf16 v[40:43], v[138:141], v[220:223], v[8:11]
	v_mfma_f32_16x16x32_bf16 v[8:11], v[204:207], v[228:231], v[182:185]
	v_mfma_f32_16x16x32_bf16 v[32:35], v[208:211], v[232:235], v[8:11]
	v_mfma_f32_16x16x32_bf16 v[8:11], v[212:215], v[228:231], v[186:189]
	v_mfma_f32_16x16x32_bf16 v[24:27], v[138:141], v[232:235], v[8:11]
	v_mfma_f32_16x16x32_bf16 v[8:11], v[204:207], v[236:239], v[16:19]
	v_mfma_f32_16x16x32_bf16 v[16:19], v[208:211], v[240:243], v[8:11]
	v_mfma_f32_16x16x32_bf16 v[8:11], v[212:215], v[236:239], v[190:193]
	v_mfma_f32_16x16x32_bf16 v[8:11], v[138:141], v[240:243], v[8:11]
	s_setprio 0
	s_cmp_lg_u32 s100, 0
	s_cbranch_scc1 .Lhb_63
	s_barrier
.Lhb_63:
	s_mov_b64 s[2:3], 0
	v_mov_b64_e32 v[234:235], v[226:227]
	v_mov_b32_e32 v226, v0
	v_mov_b64_e32 v[236:237], v[198:199]
	v_mov_b32_e32 v198, v225

; template <class Epi, bool ALIGN_EPI, bool SP2, class Hook>
; __device__ __forceinline__ void gemm_phase(LAS unsigned char* lds, const Gemm g, const StaticOrder& S, const Epi& E, Acc& acc, const bool fresh, const Hook& H, const int wave_id) {
;     ...
;             const bool last = (t == nt - 2);
;             const Src a1 = cA + (size_t)(t + 1) * kstep;
;             const Src a2 = last ? nA : cA + (size_t)(t + 2) * kstep, b2 = last ? nB : cB + (size_t)(t + 2) * kstep;
;             const Src a3 = a2 + kstep, b3 = b2 + kstep;
.LBB0_1461:
	v_add_u32_e32 v138, 0x10000, v136
	v_add_u32_e32 v139, 0x14000, v136
	ds_read_b128 v[140:143], v138
	ds_read_b128 v[144:147], v138 offset:1024
	ds_read_b128 v[148:151], v138 offset:2048
	ds_read_b128 v[152:155], v138 offset:3072
	ds_read_b128 v[156:159], v139
	ds_read_b128 v[160:163], v139 offset:1024
	ds_read_b128 v[164:167], v139 offset:2048
	ds_read_b128 v[168:171], v139 offset:3072
	s_add_i32 s16, s55, 0xfffc0080
	s_cmp_eq_u32 s54, 12
	s_cselect_b32 s59, s50, s16
	s_cselect_b32 s17, s9, s77
	s_cselect_b32 s16, s8, s76
	s_cselect_b32 s19, s11, s29
	s_cselect_b32 s18, s10, s28
	s_cselect_b32 s57, s51, s56
	s_cselect_b32 s20, s4, s12
	s_cselect_b32 s21, s5, s13
	s_cselect_b32 s22, s6, s14
	s_cselect_b32 s23, s7, s15
	s_or_b32 s58, s59, 0x80
	s_mov_b32 m0, s45
	ds_read_b128 v[172:175], v137
	ds_read_b128 v[176:179], v137 offset:1024
	ds_read_b128 v[180:183], v137 offset:2048
	ds_read_b128 v[184:187], v137 offset:3072
	ds_read_b128 v[188:191], v137 offset:4096
	ds_read_b128 v[192:195], v137 offset:5120
	ds_read_b128 v[200:203], v137 offset:6144
	ds_read_b128 v[204:207], v137 offset:7168
	buffer_load_dwordx4 v132, s[12:15], s55 offen lds
	s_mov_b32 m0, s46
	s_nop 0
	buffer_load_dwordx4 v134, s[12:15], s55 offen lds
	s_waitcnt vmcnt(8)
	s_waitcnt lgkmcnt(0)
	s_cmp_eq_u32 s100, 0
	s_cbranch_scc1 .Lhb_64
	s_barrier
.Lhb_64:
	s_setprio 1
	s_waitcnt lgkmcnt(7)
	v_mfma_f32_16x16x32_bf16 v[124:127], v[140:143], v[172:175], v[124:127]
	v_mfma_f32_16x16x32_bf16 v[116:119], v[148:151], v[172:175], v[116:119]
	s_waitcnt lgkmcnt(5)
	v_mfma_f32_16x16x32_bf16 v[108:111], v[140:143], v[180:183], v[108:111]
	v_mfma_f32_16x16x32_bf16 v[100:103], v[148:151], v[180:183], v[100:103]
	s_waitcnt lgkmcnt(3)
	v_mfma_f32_16x16x32_bf16 v[92:95], v[140:143], v[188:191], v[92:95]
	v_mfma_f32_16x16x32_bf16 v[84:87], v[148:151], v[188:191], v[84:87]
	s_waitcnt lgkmcnt(1)
	v_mfma_f32_16x16x32_bf16 v[76:79], v[140:143], v[200:203], v[76:79]
	v_mfma_f32_16x16x32_bf16 v[64:67], v[148:151], v[200:203], v[64:67]
	v_mfma_f32_16x16x32_bf16 v[124:127], v[144:147], v[176:179], v[124:127]
	v_mfma_f32_16x16x32_bf16 v[116:119], v[152:155], v[176:179], v[116:119]
	v_mfma_f32_16x16x32_bf16 v[108:111], v[144:147], v[184:187], v[108:111]
	v_mfma_f32_16x16x32_bf16 v[100:103], v[152:155], v[184:187], v[100:103]
	v_mfma_f32_16x16x32_bf16 v[92:95], v[144:147], v[192:195], v[92:95]
	v_mfma_f32_16x16x32_bf16 v[84:87], v[152:155], v[192:195], v[84:87]
	s_waitcnt lgkmcnt(0)
	v_mfma_f32_16x16x32_bf16 v[76:79], v[144:147], v[204:207], v[76:79]
	v_mfma_f32_16x16x32_bf16 v[64:67], v[152:155], v[204:207], v[64:67]
	s_setprio 0
	s_setprio 1
	v_mfma_f32_16x16x32_bf16 v[128:131], v[156:159], v[172:175], v[128:131]
	v_mfma_f32_16x16x32_bf16 v[120:123], v[164:167], v[172:175], v[120:123]
	v_mfma_f32_16x16x32_bf16 v[112:115], v[156:159], v[180:183], v[112:115]
	v_mfma_f32_16x16x32_bf16 v[104:107], v[164:167], v[180:183], v[104:107]
	v_mfma_f32_16x16x32_bf16 v[96:99], v[156:159], v[188:191], v[96:99]
	v_mfma_f32_16x16x32_bf16 v[88:91], v[164:167], v[188:191], v[88:91]
	v_mfma_f32_16x16x32_bf16 v[80:83], v[156:159], v[200:203], v[80:83]
	v_mfma_f32_16x16x32_bf16 v[68:71], v[164:167], v[200:203], v[68:71]
	v_mfma_f32_16x16x32_bf16 v[128:131], v[160:163], v[176:179], v[128:131]
	v_mfma_f32_16x16x32_bf16 v[120:123], v[168:171], v[176:179], v[120:123]
	v_mfma_f32_16x16x32_bf16 v[112:115], v[160:163], v[184:187], v[112:115]
	v_mfma_f32_16x16x32_bf16 v[104:107], v[168:171], v[184:187], v[104:107]
	v_mfma_f32_16x16x32_bf16 v[96:99], v[160:163], v[192:195], v[96:99]
	v_mfma_f32_16x16x32_bf16 v[88:91], v[168:171], v[192:195], v[88:91]
	v_mfma_f32_16x16x32_bf16 v[80:83], v[160:163], v[204:207], v[80:83]
	v_mfma_f32_16x16x32_bf16 v[68:71], v[168:171], v[204:207], v[68:71]
	s_setprio 0
	s_cmp_lg_u32 s100, 0
	s_cbranch_scc1 .Lhb_68
	s_barrier
.Lhb_68:
	s_mov_b32 m0, s92
	ds_read_b128 v[172:175], v137 offset:16384
	ds_read_b128 v[176:179], v137 offset:17408
	ds_read_b128 v[180:183], v137 offset:18432
	ds_read_b128 v[184:187], v137 offset:19456
	ds_read_b128 v[188:191], v137 offset:20480
	ds_read_b128 v[192:195], v137 offset:21504
	ds_read_b128 v[200:203], v137 offset:22528
	ds_read_b128 v[204:207], v137 offset:23552
	buffer_load_dwordx4 v133, s[16:19], s57 offen lds
	s_mov_b32 m0, s93
	s_add_i32 s60, s57, 0x40000
	buffer_load_dwordx4 v135, s[16:19], s57 offen lds
	s_mov_b32 m0, s94
	s_nop 0
	buffer_load_dwordx4 v133, s[16:19], s60 offen lds
	s_mov_b32 m0, s95
	s_nop 0
	buffer_load_dwordx4 v135, s[16:19], s60 offen lds
	s_mov_b32 m0, s44
	s_nop 0
	buffer_load_dwordx4 v132, s[20:23], s59 offen lds
	s_mov_b32 m0, s36
	s_nop 0
	buffer_load_dwordx4 v134, s[20:23], s59 offen lds
	s_waitcnt vmcnt(8)
	s_waitcnt lgkmcnt(0)
	s_cmp_eq_u32 s100, 0
	s_cbranch_scc1 .Lhb_65
	s_barrier
.Lhb_65:
	s_setprio 1
	s_waitcnt lgkmcnt(7)
	v_mfma_f32_16x16x32_bf16 v[60:63], v[140:143], v[172:175], v[60:63]
	v_mfma_f32_16x16x32_bf16 v[52:55], v[148:151], v[172:175], v[52:55]
	s_waitcnt lgkmcnt(5)
	v_mfma_f32_16x16x32_bf16 v[44:47], v[140:143], v[180:183], v[44:47]
	v_mfma_f32_16x16x32_bf16 v[36:39], v[148:151], v[180:183], v[36:39]
	s_waitcnt lgkmcnt(3)
	v_mfma_f32_16x16x32_bf16 v[28:31], v[140:143], v[188:191], v[28:31]
	v_mfma_f32_16x16x32_bf16 v[20:23], v[148:151], v[188:191], v[20:23]
	s_waitcnt lgkmcnt(1)
	v_mfma_f32_16x16x32_bf16 v[12:15], v[140:143], v[200:203], v[12:15]
	v_mfma_f32_16x16x32_bf16 v[2:5], v[148:151], v[200:203], v[4:7]
	v_mfma_f32_16x16x32_bf16 v[60:63], v[144:147], v[176:179], v[60:63]
	v_mfma_f32_16x16x32_bf16 v[52:55], v[152:155], v[176:179], v[52:55]
	v_mfma_f32_16x16x32_bf16 v[44:47], v[144:147], v[184:187], v[44:47]
	v_mfma_f32_16x16x32_bf16 v[36:39], v[152:155], v[184:187], v[36:39]
	v_mfma_f32_16x16x32_bf16 v[28:31], v[144:147], v[192:195], v[28:31]
	v_mfma_f32_16x16x32_bf16 v[20:23], v[152:155], v[192:195], v[20:23]
	s_waitcnt lgkmcnt(0)
	v_mfma_f32_16x16x32_bf16 v[12:15], v[144:147], v[204:207], v[12:15]
	v_mfma_f32_16x16x32_bf16 v[2:5], v[152:155], v[204:207], v[2:5]
	s_setprio 0
	s_setprio 1
	v_mfma_f32_16x16x32_bf16 v[72:75], v[156:159], v[172:175], v[72:75]
	v_mfma_f32_16x16x32_bf16 v[56:59], v[164:167], v[172:175], v[56:59]
	v_mfma_f32_16x16x32_bf16 v[48:51], v[156:159], v[180:183], v[48:51]
	v_mfma_f32_16x16x32_bf16 v[40:43], v[164:167], v[180:183], v[40:43]
	v_mfma_f32_16x16x32_bf16 v[32:35], v[156:159], v[188:191], v[32:35]
	v_mfma_f32_16x16x32_bf16 v[24:27], v[164:167], v[188:191], v[24:27]
	v_mfma_f32_16x16x32_bf16 v[16:19], v[156:159], v[200:203], v[16:19]
	v_mfma_f32_16x16x32_bf16 v[6:9], v[164:167], v[200:203], v[8:11]
	v_mfma_f32_16x16x32_bf16 v[72:75], v[160:163], v[176:179], v[72:75]
	v_mfma_f32_16x16x32_bf16 v[56:59], v[168:171], v[176:179], v[56:59]
	v_mfma_f32_16x16x32_bf16 v[48:51], v[160:163], v[184:187], v[48:51]
	v_mfma_f32_16x16x32_bf16 v[40:43], v[168:171], v[184:187], v[40:43]
	v_mfma_f32_16x16x32_bf16 v[32:35], v[160:163], v[192:195], v[32:35]
	v_mfma_f32_16x16x32_bf16 v[24:27], v[168:171], v[192:195], v[24:27]
	v_mfma_f32_16x16x32_bf16 v[16:19], v[160:163], v[204:207], v[16:19]
	v_mfma_f32_16x16x32_bf16 v[8:11], v[168:171], v[204:207], v[6:9]
	s_setprio 0
	s_cmp_lg_u32 s100, 0
	s_cbranch_scc1 .Lhb_69
	s_barrier
.Lhb_69:
	v_add_u32_e32 v140, 0x18000, v136
	v_add_u32_e32 v141, 0x1c000, v136
	ds_read_b128 v[142:145], v140
	ds_read_b128 v[146:149], v140 offset:1024
	ds_read_b128 v[150:153], v140 offset:2048
	ds_read_b128 v[154:157], v140 offset:3072
	ds_read_b128 v[158:161], v141
	ds_read_b128 v[162:165], v141 offset:1024
	ds_read_b128 v[166:169], v141 offset:2048
	ds_read_b128 v[170:173], v141 offset:3072
	s_add_i32 s59, s59, 0x40000
	s_mov_b32 m0, s37
	ds_read_b128 v[174:177], v137 offset:32768
	ds_read_b128 v[178:181], v137 offset:33792
	ds_read_b128 v[182:185], v137 offset:34816
	ds_read_b128 v[186:189], v137 offset:35840
	ds_read_b128 v[190:193], v137 offset:36864
	ds_read_b128 v[194:197], v137 offset:37888
	ds_read_b128 v[200:203], v137 offset:38912
	ds_read_b128 v[204:207], v137 offset:39936
	buffer_load_dwordx4 v132, s[20:23], s59 offen lds
	s_mov_b32 m0, s38
	s_nop 0
	buffer_load_dwordx4 v134, s[20:23], s59 offen lds
	s_waitcnt vmcnt(8)
	s_waitcnt lgkmcnt(0)
	s_cmp_eq_u32 s100, 0
	s_cbranch_scc1 .Lhb_66
	s_barrier
.Lhb_66:
	s_setprio 1
	s_waitcnt lgkmcnt(7)
	v_mfma_f32_16x16x32_bf16 v[124:127], v[142:145], v[174:177], v[124:127]
	v_mfma_f32_16x16x32_bf16 v[116:119], v[150:153], v[174:177], v[116:119]
	s_waitcnt lgkmcnt(5)
	v_mfma_f32_16x16x32_bf16 v[108:111], v[142:145], v[182:185], v[108:111]
	v_mfma_f32_16x16x32_bf16 v[100:103], v[150:153], v[182:185], v[100:103]
	s_waitcnt lgkmcnt(3)
	v_mfma_f32_16x16x32_bf16 v[92:95], v[142:145], v[190:193], v[92:95]
	v_mfma_f32_16x16x32_bf16 v[84:87], v[150:153], v[190:193], v[84:87]
	s_waitcnt lgkmcnt(1)
	v_mfma_f32_16x16x32_bf16 v[76:79], v[142:145], v[200:203], v[76:79]
	v_mfma_f32_16x16x32_bf16 v[64:67], v[150:153], v[200:203], v[64:67]
	v_mfma_f32_16x16x32_bf16 v[124:127], v[146:149], v[178:181], v[124:127]
	v_mfma_f32_16x16x32_bf16 v[116:119], v[154:157], v[178:181], v[116:119]
	v_mfma_f32_16x16x32_bf16 v[108:111], v[146:149], v[186:189], v[108:111]
	v_mfma_f32_16x16x32_bf16 v[100:103], v[154:157], v[186:189], v[100:103]
	v_mfma_f32_16x16x32_bf16 v[92:95], v[146:149], v[194:197], v[92:95]
	v_mfma_f32_16x16x32_bf16 v[84:87], v[154:157], v[194:197], v[84:87]
	s_waitcnt lgkmcnt(0)
	v_mfma_f32_16x16x32_bf16 v[76:79], v[146:149], v[204:207], v[76:79]
	v_mfma_f32_16x16x32_bf16 v[64:67], v[154:157], v[204:207], v[64:67]
	s_setprio 0
	s_setprio 1
	v_mfma_f32_16x16x32_bf16 v[128:131], v[158:161], v[174:177], v[128:131]
	v_mfma_f32_16x16x32_bf16 v[120:123], v[166:169], v[174:177], v[120:123]
	v_mfma_f32_16x16x32_bf16 v[112:115], v[158:161], v[182:185], v[112:115]
	v_mfma_f32_16x16x32_bf16 v[104:107], v[166:169], v[182:185], v[104:107]
	v_mfma_f32_16x16x32_bf16 v[96:99], v[158:161], v[190:193], v[96:99]
	v_mfma_f32_16x16x32_bf16 v[88:91], v[166:169], v[190:193], v[88:91]
	v_mfma_f32_16x16x32_bf16 v[80:83], v[158:161], v[200:203], v[80:83]
	v_mfma_f32_16x16x32_bf16 v[68:71], v[166:169], v[200:203], v[68:71]
	v_mfma_f32_16x16x32_bf16 v[128:131], v[162:165], v[178:181], v[128:131]
	v_mfma_f32_16x16x32_bf16 v[120:123], v[170:173], v[178:181], v[120:123]
	v_mfma_f32_16x16x32_bf16 v[112:115], v[162:165], v[186:189], v[112:115]
	v_mfma_f32_16x16x32_bf16 v[104:107], v[170:173], v[186:189], v[104:107]
	v_mfma_f32_16x16x32_bf16 v[96:99], v[162:165], v[194:197], v[96:99]
	v_mfma_f32_16x16x32_bf16 v[88:91], v[170:173], v[194:197], v[88:91]
	v_mfma_f32_16x16x32_bf16 v[80:83], v[162:165], v[204:207], v[80:83]
	v_mfma_f32_16x16x32_bf16 v[68:71], v[170:173], v[204:207], v[68:71]
	s_setprio 0
	s_cmp_lg_u32 s100, 0
	s_cbranch_scc1 .Lhb_70
	s_barrier
; #define PG8_STAGE(bufoff, gbase, voff) do { const Src _g = (gbase); _Pragma("unroll") for (int _i = 0; _i < 2; ++_i) \
;         __builtin_amdgcn_raw_ptr_buffer_load_lds(_g.r, (LAS unsigned*)(lds + (bufoff) + ldsw + _i * 8192), 16, (voff)[_i], _g.o, 0, 0); } while (0)
; #define PG8_WAIT_V(n) asm volatile("s_waitcnt vmcnt(" #n ")" ::: "memory")
; template <class Epi, bool ALIGN_EPI, bool SP2, class Hook>
; __device__ __forceinline__ void gemm_phase(LAS unsigned char* lds, const Gemm g, const StaticOrder& S, const Epi& E, Acc& acc, const bool fresh, const Hook& H, const int wave_id) {
;     ...
;         for (int t = t0; t < nt; t += 2) {
;             const bool last = (t == nt - 2);
;             const Src a1 = cA + (size_t)(t + 1) * kstep;
;             const Src a2 = last ? nA : cA + (size_t)(t + 2) * kstep, b2 = last ? nB : cB + (size_t)(t + 2) * kstep;
;             const Src a3 = a2 + kstep, b3 = b2 + kstep;
;             if (last && has_next) H(nxt);
;             if constexpr (SP2) {
;             PG8_TRIP_SP2(PG8_WAIT_V(8));
;             } else {
;             PG8_LDB(B0, 0, 0); PG8_SCHED; PG8_LDA(At, 0, 0); PG8_STAGE(PG8_SA(1, 1), a1 + hstepA, voffA);
;             PG8_WAIT_L(8); PG8_BAR; PG8_WAIT_L(0); PG8_MMA(0, 0, At, B0); PG8_BAR; PG8_SCHED;
;             PG8_LDB(B1, 0, 1); PG8_STAGE(PG8_SB(0, 0), b2, voffB);
;             PG8_BAR; PG8_WAIT_L(0); PG8_MMA(0, 1, At, B1); PG8_BAR;
;             PG8_LDA(At, 0, 1); PG8_STAGE(PG8_SA(0, 0), a2, voffA);
;             PG8_BAR; PG8_WAIT_L(0); PG8_MMA(1, 0, At, B0); PG8_BAR; PG8_SCHED;
;             PG8_STAGE(PG8_SB(0, 1), b2 + hstep, voffB);
;             PG8_WAIT_V(6); PG8_BAR; PG8_MMA(1, 1, At, B1); PG8_BAR;
;             PG8_LDB(B0, 1, 0); PG8_SCHED; PG8_LDA(At, 1, 0); PG8_STAGE(PG8_SA(0, 1), a2 + hstepA, voffA);
;             PG8_WAIT_L(8); PG8_BAR; PG8_WAIT_L(0); PG8_MMA(0, 0, At, B0); PG8_BAR; PG8_SCHED;
;             PG8_LDB(B1, 1, 1); PG8_STAGE(PG8_SB(1, 0), b3, voffB);
;             PG8_BAR; PG8_WAIT_L(0); PG8_MMA(0, 1, At, B1); PG8_BAR;
;             PG8_LDA(At, 1, 1); PG8_STAGE(PG8_SA(1, 0), a3, voffA);
;             PG8_BAR; PG8_WAIT_L(0); PG8_MMA(1, 0, At, B0); PG8_BAR; PG8_SCHED;
;             PG8_STAGE(PG8_SB(1, 1), b3 + hstep, voffB);
;             PG8_WAIT_V(6); PG8_BAR; PG8_MMA(1, 1, At, B1); PG8_BAR;
;             }
;         }
;         if constexpr (ALIGN_EPI) { if (wr == 0) PG8_BAR; }
.Lhb_70:
	s_mov_b32 m0, s39
	s_or_b32 s59, s57, 0x80
	ds_read_b128 v[174:177], v137 offset:49152
	ds_read_b128 v[178:181], v137 offset:50176
	ds_read_b128 v[182:185], v137 offset:51200
	ds_read_b128 v[186:189], v137 offset:52224
	ds_read_b128 v[190:193], v137 offset:53248
	ds_read_b128 v[194:197], v137 offset:54272
	ds_read_b128 v[200:203], v137 offset:55296
	ds_read_b128 v[204:207], v137 offset:56320
	buffer_load_dwordx4 v133, s[16:19], s59 offen lds
	s_mov_b32 m0, s40
	s_add_i32 s57, s57, 0x40080
	buffer_load_dwordx4 v135, s[16:19], s59 offen lds
	s_mov_b32 m0, s43
	s_nop 0
	buffer_load_dwordx4 v133, s[16:19], s57 offen lds
	s_mov_b32 m0, s42
	s_nop 0
	buffer_load_dwordx4 v135, s[16:19], s57 offen lds
	s_mov_b32 m0, s41
	s_nop 0
	buffer_load_dwordx4 v132, s[20:23], s58 offen lds
	s_mov_b32 m0, s33
	s_nop 0
	buffer_load_dwordx4 v134, s[20:23], s58 offen lds
	s_waitcnt vmcnt(8)
	s_waitcnt lgkmcnt(0)
	s_cmp_eq_u32 s100, 0
	s_cbranch_scc1 .Lhb_67
	s_barrier
.Lhb_67:
	s_setprio 1
	s_waitcnt lgkmcnt(7)
	v_mfma_f32_16x16x32_bf16 v[60:63], v[142:145], v[174:177], v[60:63]
	v_mfma_f32_16x16x32_bf16 v[52:55], v[150:153], v[174:177], v[52:55]
	s_waitcnt lgkmcnt(5)
	v_mfma_f32_16x16x32_bf16 v[44:47], v[142:145], v[182:185], v[44:47]
	v_mfma_f32_16x16x32_bf16 v[36:39], v[150:153], v[182:185], v[36:39]
	s_waitcnt lgkmcnt(3)
	v_mfma_f32_16x16x32_bf16 v[28:31], v[142:145], v[190:193], v[28:31]
	v_mfma_f32_16x16x32_bf16 v[20:23], v[150:153], v[190:193], v[20:23]
	s_waitcnt lgkmcnt(1)
	v_mfma_f32_16x16x32_bf16 v[12:15], v[142:145], v[200:203], v[12:15]
	v_mfma_f32_16x16x32_bf16 v[2:5], v[150:153], v[200:203], v[2:5]
	v_mfma_f32_16x16x32_bf16 v[60:63], v[146:149], v[178:181], v[60:63]
	v_mfma_f32_16x16x32_bf16 v[52:55], v[154:157], v[178:181], v[52:55]
	v_mfma_f32_16x16x32_bf16 v[44:47], v[146:149], v[186:189], v[44:47]
	v_mfma_f32_16x16x32_bf16 v[36:39], v[154:157], v[186:189], v[36:39]
	v_mfma_f32_16x16x32_bf16 v[28:31], v[146:149], v[194:197], v[28:31]
	v_mfma_f32_16x16x32_bf16 v[20:23], v[154:157], v[194:197], v[20:23]
	s_waitcnt lgkmcnt(0)
	v_mfma_f32_16x16x32_bf16 v[12:15], v[146:149], v[204:207], v[12:15]
	v_mfma_f32_16x16x32_bf16 v[4:7], v[154:157], v[204:207], v[2:5]
	s_setprio 0
	s_setprio 1
	v_mfma_f32_16x16x32_bf16 v[72:75], v[158:161], v[174:177], v[72:75]
	v_mfma_f32_16x16x32_bf16 v[56:59], v[166:169], v[174:177], v[56:59]
	v_mfma_f32_16x16x32_bf16 v[48:51], v[158:161], v[182:185], v[48:51]
	v_mfma_f32_16x16x32_bf16 v[40:43], v[166:169], v[182:185], v[40:43]
	v_mfma_f32_16x16x32_bf16 v[32:35], v[158:161], v[190:193], v[32:35]
	v_mfma_f32_16x16x32_bf16 v[24:27], v[166:169], v[190:193], v[24:27]
	v_mfma_f32_16x16x32_bf16 v[16:19], v[158:161], v[200:203], v[16:19]
	v_mfma_f32_16x16x32_bf16 v[8:11], v[166:169], v[200:203], v[8:11]
	v_mfma_f32_16x16x32_bf16 v[72:75], v[162:165], v[178:181], v[72:75]
	v_mfma_f32_16x16x32_bf16 v[56:59], v[170:173], v[178:181], v[56:59]
	v_mfma_f32_16x16x32_bf16 v[48:51], v[162:165], v[186:189], v[48:51]
	v_mfma_f32_16x16x32_bf16 v[40:43], v[170:173], v[186:189], v[40:43]
	v_mfma_f32_16x16x32_bf16 v[32:35], v[162:165], v[194:197], v[32:35]
	v_mfma_f32_16x16x32_bf16 v[24:27], v[170:173], v[194:197], v[24:27]
	v_mfma_f32_16x16x32_bf16 v[16:19], v[162:165], v[204:207], v[16:19]
	v_mfma_f32_16x16x32_bf16 v[8:11], v[170:173], v[204:207], v[8:11]
	s_setprio 0
	s_cmp_lg_u32 s100, 0
	s_cbranch_scc1 .Lhb_71
	s_barrier
.Lhb_71:
	s_add_i32 s54, s54, 2
	s_addk_i32 s55, 0x100
	s_addk_i32 s56, 0x100
	s_cmp_gt_u32 s54, 13
	s_cbranch_scc0 .LBB0_1461
	v_readlane_b32 s12, v251, 45
	v_readlane_b32 s13, v251, 46
	s_and_b64 vcc, exec, s[12:13]
	s_cbranch_vccz .LBB0_1464

; #define LAS __attribute__((address_space(3)))
; __device__ __forceinline__ u32x4 pack8(const float (&v)[8]) { u32x4 w; w.x = pk2(v[0], v[1]); w.y = pk2(v[2], v[3]); w.z = pk2(v[4], v[5]); w.w = pk2(v[6], v[7]); return w; }
;     __device__ __forceinline__ bool operator()(Acc& acc, const Unit& u, int wr, int wc, int fr, int fq, const LAS float* rstab) const {
;         bf16_t* p0 = H + (size_t)(u.pm * BM + wr * 64 + fr) * HD_PITCH + u.pn * HALF + wc * 32 + 8 * fq;
;         const LAS float* rsp = rstab + wr * 64 + fr;
; #pragma unroll
;         for (int ai = 0; ai < 2; ++ai)
; #pragma unroll
;             for (int m = 0; m < 4; ++m) {
;                 const float rs = rsp[ai * HALF + m * 16], nrs = -LOG2E * rs, rs2 = rs * rs;
;                 float v[8];
; #pragma unroll
;                 for (int n = 0; n < 2; ++n)
; #pragma unroll
;                     for (int e = 0; e < 4; ++e) {
;                         const float g = acc[ai][0][m][n][e], up = acc[ai][1][m][n][e];
;                         v[4 * n + e] = (g * up * rs2) * __builtin_amdgcn_rcpf(1.0f + __builtin_amdgcn_exp2f(g * nrs));
;                     }
;                 gst<u32x4>(p0 + (ai * HALF + m * 16) * HD_PITCH, pack8(v));
;                 asm volatile("" ::: "memory");
;             }
.LBB0_1470:
	v_readlane_b32 s12, v250, 1
	v_and_b32_e32 v0, 15, v2
	s_add_i32 s12, s14, s12
	v_or_b32_e32 v3, s12, v0
	v_readlane_b32 s12, v254, 57
	v_readlane_b32 s13, v254, 58
	v_pk_mul_f32 v[130:131], v[126:127], v[130:131]
	v_pk_mul_f32 v[122:123], v[118:119], v[122:123]
	s_waitcnt lgkmcnt(0)
	v_mov_b64_e32 v[142:143], s[12:13]
	s_movk_i32 s12, 0x1800
	v_mad_i64_i32 v[142:143], s[12:13], v3, s12, v[142:143]
	s_lshl_b32 s12, s52, 7
	s_ashr_i32 s13, s12, 31
	v_lshl_add_u64 v[144:145], s[12:13], 1, v[142:143]
	v_readlane_b32 s12, v250, 11
	v_pk_mul_f32 v[114:115], v[110:111], v[114:115]
	v_pk_mul_f32 v[106:107], v[102:103], v[106:107]
	v_lshl_add_u32 v142, v0, 2, s12
	ds_read_b32 v143, v142
	v_readlane_b32 s12, v254, 33
	s_mov_b32 s14, s12
	v_lshl_add_u64 v[144:145], v[144:145], 0, s[14:15]
	v_and_b32_e32 v0, 48, v2
	s_waitcnt lgkmcnt(0)
	v_mul_f32_e32 v146, 0xbfb8aa3b, v143
	v_mul_f32_e32 v126, v126, v146
	v_mul_f32_e32 v127, v127, v146
	v_exp_f32_e32 v126, v126
	v_exp_f32_e32 v127, v127
	v_lshl_add_u64 v[2:3], v[144:145], 0, v[0:1]
	v_mul_f32_e32 v0, v124, v146
	v_exp_f32_e32 v144, v0
	v_mul_f32_e32 v0, v125, v146
	v_exp_f32_e32 v145, v0
	v_mul_f32_e32 v0, v143, v143
	v_pk_mul_f32 v[124:125], v[124:125], v[128:129]
	v_add_f32_e32 v126, 1.0, v126
	v_add_f32_e32 v127, 1.0, v127
	v_pk_mul_f32 v[128:129], v[130:131], v[0:1] op_sel_hi:[1,0]
	v_mul_f32_e32 v130, v116, v146
	v_mul_f32_e32 v131, v117, v146
	v_rcp_f32_e32 v126, v126
	v_rcp_f32_e32 v127, v127
	v_exp_f32_e32 v130, v130
	v_exp_f32_e32 v131, v131
	v_mul_f32_e32 v118, v118, v146
	v_mul_f32_e32 v119, v119, v146
	v_exp_f32_e32 v118, v118
	v_exp_f32_e32 v119, v119
	v_add_f32_e32 v143, 1.0, v144
	v_pk_mul_f32 v[126:127], v[128:129], v[126:127]
	v_add_f32_e32 v128, 1.0, v130
	v_add_f32_e32 v129, 1.0, v131
	v_rcp_f32_e32 v144, v143
	v_add_f32_e32 v143, 1.0, v145
	v_rcp_f32_e32 v128, v128
	v_rcp_f32_e32 v129, v129
	v_add_f32_e32 v118, 1.0, v118
	v_add_f32_e32 v119, 1.0, v119
	v_rcp_f32_e32 v145, v143
	v_rcp_f32_e32 v118, v118
	v_rcp_f32_e32 v119, v119
	v_pk_mul_f32 v[116:117], v[116:117], v[120:121]
	v_pk_mul_f32 v[124:125], v[124:125], v[0:1] op_sel_hi:[1,0]
	v_pk_mul_f32 v[116:117], v[116:117], v[0:1] op_sel_hi:[1,0]
	v_pk_mul_f32 v[124:125], v[124:125], v[144:145]
	v_pk_mul_f32 v[120:121], v[116:117], v[128:129]
	v_pk_mul_f32 v[116:117], v[122:123], v[0:1] op_sel_hi:[1,0]
	v_readlane_b32 s13, v254, 34
	v_pk_mul_f32 v[122:123], v[116:117], v[118:119]
	v_cvt_pk_bf16_f32 v116, v124, v125
	v_cvt_pk_bf16_f32 v117, v126, v127
	v_cvt_pk_bf16_f32 v118, v120, v121
	v_cvt_pk_bf16_f32 v119, v122, v123
	global_store_dwordx4 v[2:3], v[116:119], off
	ds_read_b32 v0, v142 offset:64
	v_writelane_b32 v254, s12, 33
	v_pk_mul_f32 v[98:99], v[94:95], v[98:99]
	v_pk_mul_f32 v[90:91], v[86:87], v[90:91]
	v_writelane_b32 v254, s13, 34
	s_waitcnt lgkmcnt(0)
	v_mul_f32_e32 v118, 0xbfb8aa3b, v0
	v_mul_f32_e32 v110, v110, v118
	v_mul_f32_e32 v111, v111, v118
	v_exp_f32_e32 v110, v110
	v_exp_f32_e32 v111, v111
	v_mul_f32_e32 v0, v0, v0
	v_mul_f32_e32 v116, v108, v118
	v_mul_f32_e32 v117, v109, v118
	v_pk_mul_f32 v[108:109], v[108:109], v[112:113]
	v_add_f32_e32 v110, 1.0, v110
	v_add_f32_e32 v111, 1.0, v111
	v_pk_mul_f32 v[112:113], v[114:115], v[0:1] op_sel_hi:[1,0]
	v_mul_f32_e32 v114, v100, v118
	v_mul_f32_e32 v115, v101, v118
	v_rcp_f32_e32 v110, v110
	v_rcp_f32_e32 v111, v111
	v_exp_f32_e32 v114, v114
	v_exp_f32_e32 v115, v115
	v_mul_f32_e32 v102, v102, v118
	v_mul_f32_e32 v103, v103, v118
	v_exp_f32_e32 v116, v116
	v_exp_f32_e32 v117, v117
	v_exp_f32_e32 v102, v102
	v_exp_f32_e32 v103, v103
	v_pk_mul_f32 v[110:111], v[112:113], v[110:111]
	v_add_f32_e32 v112, 1.0, v114
	v_add_f32_e32 v113, 1.0, v115
	v_add_f32_e32 v116, 1.0, v116
	v_add_f32_e32 v117, 1.0, v117
	v_rcp_f32_e32 v112, v112
	v_rcp_f32_e32 v113, v113
	v_add_f32_e32 v102, 1.0, v102
	v_add_f32_e32 v103, 1.0, v103
	v_rcp_f32_e32 v116, v116
	v_rcp_f32_e32 v117, v117
	v_rcp_f32_e32 v102, v102
	v_rcp_f32_e32 v103, v103
	v_pk_mul_f32 v[100:101], v[100:101], v[104:105]
	v_pk_mul_f32 v[108:109], v[108:109], v[0:1] op_sel_hi:[1,0]
	v_pk_mul_f32 v[100:101], v[100:101], v[0:1] op_sel_hi:[1,0]
	s_mov_b32 s12, 0x18000
	v_pk_mul_f32 v[104:105], v[100:101], v[112:113]
	v_pk_mul_f32 v[100:101], v[106:107], v[0:1] op_sel_hi:[1,0]
	v_pk_mul_f32 v[108:109], v[108:109], v[116:117]
	v_pk_mul_f32 v[106:107], v[100:101], v[102:103]
	v_cvt_pk_bf16_f32 v102, v104, v105
	v_add_co_u32_e32 v104, vcc, s12, v2
	v_cvt_pk_bf16_f32 v100, v108, v109
	v_cvt_pk_bf16_f32 v101, v110, v111
	v_cvt_pk_bf16_f32 v103, v106, v107
	v_addc_co_u32_e32 v105, vcc, 0, v3, vcc
	global_store_dwordx4 v[104:105], v[100:103], off
	ds_read_b32 v0, v142 offset:128
	s_mov_b32 s12, 0x30000
	v_pk_mul_f32 v[82:83], v[78:79], v[82:83]
	v_pk_mul_f32 v[70:71], v[66:67], v[70:71]
	v_pk_mul_f32 v[58:59], v[54:55], v[58:59]
	s_waitcnt lgkmcnt(0)
; #define LAS __attribute__((address_space(3)))
; __device__ __forceinline__ u32x4 pack8(const float (&v)[8]) { u32x4 w; w.x = pk2(v[0], v[1]); w.y = pk2(v[2], v[3]); w.z = pk2(v[4], v[5]); w.w = pk2(v[6], v[7]); return w; }
;     __device__ __forceinline__ bool operator()(Acc& acc, const Unit& u, int wr, int wc, int fr, int fq, const LAS float* rstab) const {
;         bf16_t* p0 = H + (size_t)(u.pm * BM + wr * 64 + fr) * HD_PITCH + u.pn * HALF + wc * 32 + 8 * fq;
;         const LAS float* rsp = rstab + wr * 64 + fr;
; #pragma unroll
;         for (int ai = 0; ai < 2; ++ai)
; #pragma unroll
;             for (int m = 0; m < 4; ++m) {
;                 const float rs = rsp[ai * HALF + m * 16], nrs = -LOG2E * rs, rs2 = rs * rs;
;                 float v[8];
; #pragma unroll
;                 for (int n = 0; n < 2; ++n)
; #pragma unroll
;                     for (int e = 0; e < 4; ++e) {
;                         const float g = acc[ai][0][m][n][e], up = acc[ai][1][m][n][e];
;                         v[4 * n + e] = (g * up * rs2) * __builtin_amdgcn_rcpf(1.0f + __builtin_amdgcn_exp2f(g * nrs));
;                     }
;                 gst<u32x4>(p0 + (ai * HALF + m * 16) * HD_PITCH, pack8(v));
;                 asm volatile("" ::: "memory");
;             }
;         return true;
;     }
	v_mul_f32_e32 v102, 0xbfb8aa3b, v0
	v_mul_f32_e32 v94, v94, v102
	v_mul_f32_e32 v95, v95, v102
	v_exp_f32_e32 v94, v94
	v_exp_f32_e32 v95, v95
	v_mul_f32_e32 v0, v0, v0
	v_mul_f32_e32 v100, v92, v102
	v_mul_f32_e32 v101, v93, v102
	v_pk_mul_f32 v[92:93], v[92:93], v[96:97]
	v_add_f32_e32 v94, 1.0, v94
	v_add_f32_e32 v95, 1.0, v95
	v_pk_mul_f32 v[96:97], v[98:99], v[0:1] op_sel_hi:[1,0]
	v_mul_f32_e32 v98, v84, v102
	v_mul_f32_e32 v99, v85, v102
	v_rcp_f32_e32 v94, v94
	v_rcp_f32_e32 v95, v95
	v_exp_f32_e32 v98, v98
	v_exp_f32_e32 v99, v99
	v_mul_f32_e32 v86, v86, v102
	v_mul_f32_e32 v87, v87, v102
	v_exp_f32_e32 v100, v100
	v_exp_f32_e32 v101, v101
	v_exp_f32_e32 v86, v86
	v_exp_f32_e32 v87, v87
	v_pk_mul_f32 v[94:95], v[96:97], v[94:95]
	v_add_f32_e32 v96, 1.0, v98
	v_add_f32_e32 v97, 1.0, v99
	v_add_f32_e32 v100, 1.0, v100
	v_add_f32_e32 v101, 1.0, v101
	v_rcp_f32_e32 v96, v96
	v_rcp_f32_e32 v97, v97
	v_add_f32_e32 v86, 1.0, v86
	v_add_f32_e32 v87, 1.0, v87
	v_rcp_f32_e32 v100, v100
	v_rcp_f32_e32 v101, v101
	v_rcp_f32_e32 v86, v86
	v_rcp_f32_e32 v87, v87
	v_pk_mul_f32 v[84:85], v[84:85], v[88:89]
	v_pk_mul_f32 v[92:93], v[92:93], v[0:1] op_sel_hi:[1,0]
	v_pk_mul_f32 v[84:85], v[84:85], v[0:1] op_sel_hi:[1,0]
	v_pk_mul_f32 v[92:93], v[92:93], v[100:101]
	v_pk_mul_f32 v[88:89], v[84:85], v[96:97]
	v_pk_mul_f32 v[84:85], v[90:91], v[0:1] op_sel_hi:[1,0]
	v_pk_mul_f32 v[50:51], v[46:47], v[50:51]
	v_pk_mul_f32 v[90:91], v[84:85], v[86:87]
	v_cvt_pk_bf16_f32 v86, v88, v89
	v_add_co_u32_e32 v88, vcc, s12, v2
	v_cvt_pk_bf16_f32 v84, v92, v93
	v_cvt_pk_bf16_f32 v85, v94, v95
	v_cvt_pk_bf16_f32 v87, v90, v91
	v_addc_co_u32_e32 v89, vcc, 0, v3, vcc
	global_store_dwordx4 v[88:89], v[84:87], off
	ds_read_b32 v0, v142 offset:192
	s_mov_b32 s12, 0x48000
	v_pk_mul_f32 v[42:43], v[38:39], v[42:43]
	v_pk_mul_f32 v[34:35], v[30:31], v[34:35]
	v_pk_mul_f32 v[26:27], v[22:23], v[26:27]
	s_waitcnt lgkmcnt(0)
	v_mul_f32_e32 v86, 0xbfb8aa3b, v0
	v_mul_f32_e32 v78, v78, v86
	v_mul_f32_e32 v79, v79, v86
	v_exp_f32_e32 v78, v78
	v_exp_f32_e32 v79, v79
	v_mul_f32_e32 v0, v0, v0
	v_mul_f32_e32 v84, v76, v86
	v_mul_f32_e32 v85, v77, v86
	v_pk_mul_f32 v[76:77], v[76:77], v[80:81]
	v_add_f32_e32 v78, 1.0, v78
	v_add_f32_e32 v79, 1.0, v79
	v_pk_mul_f32 v[80:81], v[82:83], v[0:1] op_sel_hi:[1,0]
	v_mul_f32_e32 v82, v64, v86
	v_mul_f32_e32 v83, v65, v86
	v_rcp_f32_e32 v78, v78
	v_rcp_f32_e32 v79, v79
	v_exp_f32_e32 v82, v82
	v_exp_f32_e32 v83, v83
	v_mul_f32_e32 v66, v66, v86
	v_mul_f32_e32 v67, v67, v86
	v_exp_f32_e32 v84, v84
	v_exp_f32_e32 v85, v85
	v_exp_f32_e32 v66, v66
	v_exp_f32_e32 v67, v67
	v_pk_mul_f32 v[78:79], v[80:81], v[78:79]
	v_add_f32_e32 v80, 1.0, v82
	v_add_f32_e32 v81, 1.0, v83
	v_add_f32_e32 v84, 1.0, v84
	v_add_f32_e32 v85, 1.0, v85
	v_rcp_f32_e32 v80, v80
	v_rcp_f32_e32 v81, v81
	v_add_f32_e32 v66, 1.0, v66
	v_add_f32_e32 v67, 1.0, v67
	v_rcp_f32_e32 v84, v84
	v_rcp_f32_e32 v85, v85
	v_rcp_f32_e32 v66, v66
	v_rcp_f32_e32 v67, v67
	v_pk_mul_f32 v[64:65], v[64:65], v[68:69]
	v_pk_mul_f32 v[76:77], v[76:77], v[0:1] op_sel_hi:[1,0]
	v_pk_mul_f32 v[64:65], v[64:65], v[0:1] op_sel_hi:[1,0]
	v_pk_mul_f32 v[76:77], v[76:77], v[84:85]
	v_pk_mul_f32 v[68:69], v[64:65], v[80:81]
	v_pk_mul_f32 v[64:65], v[70:71], v[0:1] op_sel_hi:[1,0]
	v_pk_mul_f32 v[18:19], v[14:15], v[18:19]
	v_pk_mul_f32 v[70:71], v[64:65], v[66:67]
	v_cvt_pk_bf16_f32 v66, v68, v69
	v_add_co_u32_e32 v68, vcc, s12, v2
	v_cvt_pk_bf16_f32 v64, v76, v77
	v_cvt_pk_bf16_f32 v65, v78, v79
	v_cvt_pk_bf16_f32 v67, v70, v71
	v_addc_co_u32_e32 v69, vcc, 0, v3, vcc
	global_store_dwordx4 v[68:69], v[64:67], off
	ds_read_b32 v0, v142 offset:512
	s_mov_b32 s12, 0xc0000
	v_pk_mul_f32 v[66:67], v[62:63], v[74:75]
	v_pk_mul_f32 v[10:11], v[6:7], v[10:11]
	s_waitcnt lgkmcnt(0)
	v_mul_f32_e32 v68, 0xbfb8aa3b, v0
	v_mul_f32_e32 v64, v60, v68
	v_mul_f32_e32 v65, v61, v68
	v_exp_f32_e32 v64, v64
	v_exp_f32_e32 v65, v65
	v_mul_f32_e32 v62, v62, v68
	v_mul_f32_e32 v63, v63, v68
	v_add_f32_e32 v64, 1.0, v64
	v_add_f32_e32 v65, 1.0, v65
	v_rcp_f32_e32 v64, v64
	v_rcp_f32_e32 v65, v65
	v_exp_f32_e32 v62, v62
	v_exp_f32_e32 v63, v63
	v_mul_f32_e32 v0, v0, v0
	v_pk_mul_f32 v[60:61], v[60:61], v[72:73]
	v_add_f32_e32 v62, 1.0, v62
	v_pk_mul_f32 v[60:61], v[60:61], v[0:1] op_sel_hi:[1,0]
	v_add_f32_e32 v63, 1.0, v63
	v_pk_mul_f32 v[60:61], v[60:61], v[64:65]
	v_pk_mul_f32 v[64:65], v[66:67], v[0:1] op_sel_hi:[1,0]
	v_mul_f32_e32 v66, v52, v68
	v_mul_f32_e32 v67, v53, v68
	v_rcp_f32_e32 v62, v62
	v_rcp_f32_e32 v63, v63
	v_exp_f32_e32 v66, v66
	v_exp_f32_e32 v67, v67
	v_mul_f32_e32 v54, v54, v68
	v_mul_f32_e32 v55, v55, v68
	v_exp_f32_e32 v54, v54
	v_exp_f32_e32 v55, v55
	v_pk_mul_f32 v[62:63], v[64:65], v[62:63]
	v_add_f32_e32 v64, 1.0, v66
	v_add_f32_e32 v65, 1.0, v67
	v_rcp_f32_e32 v64, v64
	v_rcp_f32_e32 v65, v65
	v_add_f32_e32 v54, 1.0, v54
	v_add_f32_e32 v55, 1.0, v55
	v_rcp_f32_e32 v54, v54
	v_rcp_f32_e32 v55, v55
	v_pk_mul_f32 v[52:53], v[52:53], v[56:57]
	s_nop 0
	v_pk_mul_f32 v[52:53], v[52:53], v[0:1] op_sel_hi:[1,0]
	s_nop 0
	v_pk_mul_f32 v[56:57], v[52:53], v[64:65]
	v_pk_mul_f32 v[52:53], v[58:59], v[0:1] op_sel_hi:[1,0]
	s_nop 0
	v_pk_mul_f32 v[58:59], v[52:53], v[54:55]
	v_cvt_pk_bf16_f32 v54, v56, v57
	v_add_co_u32_e32 v56, vcc, s12, v2
	v_cvt_pk_bf16_f32 v52, v60, v61
	v_cvt_pk_bf16_f32 v53, v62, v63
	v_cvt_pk_bf16_f32 v55, v58, v59
	v_addc_co_u32_e32 v57, vcc, 0, v3, vcc
	global_store_dwordx4 v[56:57], v[52:55], off
	ds_read_b32 v0, v142 offset:576
	s_mov_b32 s12, 0xd8000
	s_waitcnt lgkmcnt(0)
; __device__ __forceinline__ u32x4 pack8(const float (&v)[8]) { u32x4 w; w.x = pk2(v[0], v[1]); w.y = pk2(v[2], v[3]); w.z = pk2(v[4], v[5]); w.w = pk2(v[6], v[7]); return w; }
; #define PG8_BAR __builtin_amdgcn_s_barrier()
;     __device__ __forceinline__ bool operator()(Acc& acc, const Unit& u, int wr, int wc, int fr, int fq, const LAS float* rstab) const {
;     ...
;         for (int ai = 0; ai < 2; ++ai)
; #pragma unroll
;             for (int m = 0; m < 4; ++m) {
;                 const float rs = rsp[ai * HALF + m * 16], nrs = -LOG2E * rs, rs2 = rs * rs;
;                 float v[8];
; #pragma unroll
;                 for (int n = 0; n < 2; ++n)
; #pragma unroll
;                     for (int e = 0; e < 4; ++e) {
;                         const float g = acc[ai][0][m][n][e], up = acc[ai][1][m][n][e];
;                         v[4 * n + e] = (g * up * rs2) * __builtin_amdgcn_rcpf(1.0f + __builtin_amdgcn_exp2f(g * nrs));
;                     }
;                 gst<u32x4>(p0 + (ai * HALF + m * 16) * HD_PITCH, pack8(v));
;                 asm volatile("" ::: "memory");
;             }
; template <class Epi, bool ALIGN_EPI, bool SP2, class Hook>
; __device__ __forceinline__ void gemm_phase(LAS unsigned char* lds, const Gemm g, const StaticOrder& S, const Epi& E, Acc& acc, const bool fresh, const Hook& H, const int wave_id) {
;     ...
;         if (!has_next) break;
;         if (reset) {
; #pragma unroll
;             for (int a = 0; a < 2; ++a)
; #pragma unroll
;                 for (int b = 0; b < 2; ++b)
; #pragma unroll
;                     for (int m = 0; m < 4; ++m)
; #pragma unroll
;                         for (int n = 0; n < 2; ++n) acc[a][b][m][n] = (f32x4){0.f, 0.f, 0.f, 0.f};
;         }
;         cur = nxt; cA = nA; cB = nB; ++ui;
;         if constexpr (ALIGN_EPI) { if (wr == 1) PG8_BAR; }
	v_mul_f32_e32 v54, 0xbfb8aa3b, v0
	v_mul_f32_e32 v46, v46, v54
	v_mul_f32_e32 v47, v47, v54
	v_exp_f32_e32 v46, v46
	v_exp_f32_e32 v47, v47
	v_mul_f32_e32 v0, v0, v0
	v_mul_f32_e32 v52, v44, v54
	v_mul_f32_e32 v53, v45, v54
	v_pk_mul_f32 v[44:45], v[44:45], v[48:49]
	v_add_f32_e32 v46, 1.0, v46
	v_add_f32_e32 v47, 1.0, v47
	v_pk_mul_f32 v[48:49], v[50:51], v[0:1] op_sel_hi:[1,0]
	v_mul_f32_e32 v50, v36, v54
	v_mul_f32_e32 v51, v37, v54
	v_rcp_f32_e32 v46, v46
	v_rcp_f32_e32 v47, v47
	v_exp_f32_e32 v50, v50
	v_exp_f32_e32 v51, v51
	v_mul_f32_e32 v38, v38, v54
	v_mul_f32_e32 v39, v39, v54
	v_exp_f32_e32 v52, v52
	v_exp_f32_e32 v53, v53
	v_exp_f32_e32 v38, v38
	v_exp_f32_e32 v39, v39
	v_pk_mul_f32 v[46:47], v[48:49], v[46:47]
	v_add_f32_e32 v48, 1.0, v50
	v_add_f32_e32 v49, 1.0, v51
	v_add_f32_e32 v52, 1.0, v52
	v_add_f32_e32 v53, 1.0, v53
	v_rcp_f32_e32 v48, v48
	v_rcp_f32_e32 v49, v49
	v_add_f32_e32 v38, 1.0, v38
	v_add_f32_e32 v39, 1.0, v39
	v_rcp_f32_e32 v52, v52
	v_rcp_f32_e32 v53, v53
	v_rcp_f32_e32 v38, v38
	v_rcp_f32_e32 v39, v39
	v_pk_mul_f32 v[36:37], v[36:37], v[40:41]
	v_pk_mul_f32 v[44:45], v[44:45], v[0:1] op_sel_hi:[1,0]
	v_pk_mul_f32 v[36:37], v[36:37], v[0:1] op_sel_hi:[1,0]
	v_pk_mul_f32 v[44:45], v[44:45], v[52:53]
	v_pk_mul_f32 v[40:41], v[36:37], v[48:49]
	v_pk_mul_f32 v[36:37], v[42:43], v[0:1] op_sel_hi:[1,0]
	s_nop 0
	v_pk_mul_f32 v[42:43], v[36:37], v[38:39]
	v_cvt_pk_bf16_f32 v38, v40, v41
	v_add_co_u32_e32 v40, vcc, s12, v2
	v_cvt_pk_bf16_f32 v36, v44, v45
	v_cvt_pk_bf16_f32 v37, v46, v47
	v_cvt_pk_bf16_f32 v39, v42, v43
	v_addc_co_u32_e32 v41, vcc, 0, v3, vcc
	global_store_dwordx4 v[40:41], v[36:39], off
	ds_read_b32 v0, v142 offset:640
	s_mov_b32 s12, 0xf0000
	s_waitcnt lgkmcnt(0)
	v_mul_f32_e32 v38, 0xbfb8aa3b, v0
	v_mul_f32_e32 v30, v30, v38
	v_mul_f32_e32 v31, v31, v38
	v_exp_f32_e32 v30, v30
	v_exp_f32_e32 v31, v31
	v_mul_f32_e32 v0, v0, v0
	v_mul_f32_e32 v36, v28, v38
	v_mul_f32_e32 v37, v29, v38
	v_pk_mul_f32 v[28:29], v[28:29], v[32:33]
	v_add_f32_e32 v30, 1.0, v30
	v_add_f32_e32 v31, 1.0, v31
	v_pk_mul_f32 v[32:33], v[34:35], v[0:1] op_sel_hi:[1,0]
	v_mul_f32_e32 v34, v20, v38
	v_mul_f32_e32 v35, v21, v38
	v_rcp_f32_e32 v30, v30
	v_rcp_f32_e32 v31, v31
	v_exp_f32_e32 v34, v34
	v_exp_f32_e32 v35, v35
	v_mul_f32_e32 v22, v22, v38
	v_mul_f32_e32 v23, v23, v38
	v_exp_f32_e32 v36, v36
	v_exp_f32_e32 v37, v37
	v_exp_f32_e32 v22, v22
	v_exp_f32_e32 v23, v23
	v_pk_mul_f32 v[30:31], v[32:33], v[30:31]
	v_add_f32_e32 v32, 1.0, v34
	v_add_f32_e32 v33, 1.0, v35
	v_add_f32_e32 v36, 1.0, v36
	v_add_f32_e32 v37, 1.0, v37
	v_rcp_f32_e32 v32, v32
	v_rcp_f32_e32 v33, v33
	v_add_f32_e32 v22, 1.0, v22
	v_add_f32_e32 v23, 1.0, v23
	v_rcp_f32_e32 v36, v36
	v_rcp_f32_e32 v37, v37
	v_rcp_f32_e32 v22, v22
	v_rcp_f32_e32 v23, v23
	v_pk_mul_f32 v[20:21], v[20:21], v[24:25]
	v_pk_mul_f32 v[28:29], v[28:29], v[0:1] op_sel_hi:[1,0]
	v_pk_mul_f32 v[20:21], v[20:21], v[0:1] op_sel_hi:[1,0]
	v_pk_mul_f32 v[28:29], v[28:29], v[36:37]
	v_pk_mul_f32 v[24:25], v[20:21], v[32:33]
	v_pk_mul_f32 v[20:21], v[26:27], v[0:1] op_sel_hi:[1,0]
	s_nop 0
	v_pk_mul_f32 v[26:27], v[20:21], v[22:23]
	v_cvt_pk_bf16_f32 v22, v24, v25
	v_add_co_u32_e32 v24, vcc, s12, v2
	v_cvt_pk_bf16_f32 v20, v28, v29
	v_cvt_pk_bf16_f32 v21, v30, v31
	v_cvt_pk_bf16_f32 v23, v26, v27
	v_addc_co_u32_e32 v25, vcc, 0, v3, vcc
	global_store_dwordx4 v[24:25], v[20:23], off
	ds_read_b32 v0, v142 offset:704
	v_add_co_u32_e32 v2, vcc, 0x108000, v2
	s_waitcnt lgkmcnt(0)
	v_mul_f32_e32 v22, 0xbfb8aa3b, v0
	v_mul_f32_e32 v14, v14, v22
	v_mul_f32_e32 v15, v15, v22
	v_exp_f32_e32 v14, v14
	v_exp_f32_e32 v15, v15
	v_mul_f32_e32 v0, v0, v0
	v_mul_f32_e32 v20, v12, v22
	v_mul_f32_e32 v21, v13, v22
	v_pk_mul_f32 v[12:13], v[12:13], v[16:17]
	v_add_f32_e32 v14, 1.0, v14
	v_add_f32_e32 v15, 1.0, v15
	v_pk_mul_f32 v[16:17], v[18:19], v[0:1] op_sel_hi:[1,0]
	v_mul_f32_e32 v18, v4, v22
	v_mul_f32_e32 v19, v5, v22
	v_rcp_f32_e32 v14, v14
	v_rcp_f32_e32 v15, v15
	v_exp_f32_e32 v18, v18
	v_exp_f32_e32 v19, v19
	v_mul_f32_e32 v6, v6, v22
	v_mul_f32_e32 v7, v7, v22
	v_exp_f32_e32 v20, v20
	v_exp_f32_e32 v21, v21
	v_exp_f32_e32 v6, v6
	v_exp_f32_e32 v7, v7
	v_pk_mul_f32 v[14:15], v[16:17], v[14:15]
	v_add_f32_e32 v16, 1.0, v18
	v_add_f32_e32 v17, 1.0, v19
	v_add_f32_e32 v20, 1.0, v20
	v_add_f32_e32 v21, 1.0, v21
	v_rcp_f32_e32 v16, v16
	v_rcp_f32_e32 v17, v17
	v_add_f32_e32 v6, 1.0, v6
	v_add_f32_e32 v7, 1.0, v7
	v_rcp_f32_e32 v20, v20
	v_rcp_f32_e32 v21, v21
	v_rcp_f32_e32 v6, v6
	v_rcp_f32_e32 v7, v7
	v_pk_mul_f32 v[4:5], v[4:5], v[8:9]
	v_pk_mul_f32 v[12:13], v[12:13], v[0:1] op_sel_hi:[1,0]
	v_pk_mul_f32 v[4:5], v[4:5], v[0:1] op_sel_hi:[1,0]
	v_pk_mul_f32 v[12:13], v[12:13], v[20:21]
	v_pk_mul_f32 v[8:9], v[4:5], v[16:17]
	v_pk_mul_f32 v[4:5], v[10:11], v[0:1] op_sel_hi:[1,0]
	v_addc_co_u32_e32 v3, vcc, 0, v3, vcc
	v_pk_mul_f32 v[10:11], v[4:5], v[6:7]
	v_cvt_pk_bf16_f32 v4, v12, v13
	v_cvt_pk_bf16_f32 v5, v14, v15
	v_cvt_pk_bf16_f32 v6, v8, v9
	v_cvt_pk_bf16_f32 v7, v10, v11
	global_store_dwordx4 v[2:3], v[4:7], off
	s_and_b64 vcc, exec, s[2:3]
	s_mov_b64 s[2:3], -1
	s_cbranch_vccnz .LBB0_1453
	v_mov_b32_e32 v225, v198
	v_mov_b64_e32 v[198:199], 0x5bf
	v_mov_b32_e32 v0, 1
	v_mov_b64_e32 v[226:227], 0x5c0
	v_mov_b64_e32 v[246:247], 0xff
	v_mov_b64_e32 v[244:245], 0x100
	s_and_b64 vcc, exec, s[0:1]
	s_cbranch_vccnz .LBB0_1452
	s_branch .LBB0_1452

; #define GAS __attribute__((address_space(1)))
; #define PG8_BAR __builtin_amdgcn_s_barrier()
; template <class Epi, bool ALIGN_EPI, bool SP2, class Hook>
; __device__ __forceinline__ void gemm_phase(LAS unsigned char* lds, const Gemm g, const StaticOrder& S, const Epi& E, Acc& acc, const bool fresh, const Hook& H, const int wave_id) {
;     const int tid = opaque_tid(wave_id), wid = wave_id, lane = tid & 63, wr = wid >> 2, wc = wid & 3, fr = lane & 15, fq = lane >> 4;
;     const int K = g.K, nt = K / BK, lda = g.lda ? g.lda : K;
;     unsigned voffA[2], voffB[2];
; #pragma unroll
;     for (int i = 0; i < 2; ++i) { int R, C; stage_rc(tid * 16 + i * 8192, R, C); const int Rb = (R & ~31) + perm32(R & 31);
;         voffA[i] = (unsigned)(R * lda + C) * 2u; voffB[i] = (unsigned)(Rb * K + C) * 2u; }
;     const size_t kstep = (size_t)(BK * 2);
;     const size_t hstep = (size_t)HALF * K * 2, hstepA = (size_t)HALF * lda * 2;
;     const size_t tstep = 2 * hstep, tstepA = 2 * hstepA;
;     const unsigned ldsw = (unsigned)wid * 1024u;
;     const int aoff = lds_byte(wr * 64 + fr, fq * 8), boff = lds_byte(wc * 32 + fr, fq * 8);
;     ...
;     Unit cur, nxt; int ui = 0, rs_pm = -1, t0 = 0;
;     if (!S.next(0, cur)) return;
;     if (fresh) {
; #pragma unroll
;         for (int a = 0; a < 2; ++a)
; #pragma unroll
;             for (int b = 0; b < 2; ++b)
; #pragma unroll
;                 for (int m = 0; m < 4; ++m)
; #pragma unroll
;                     for (int n = 0; n < 2; ++n) acc[a][b][m][n] = (f32x4){0.f, 0.f, 0.f, 0.f};
;     }
;     bf16x8 At[4][2], B0[2][2], B1[2][2];
;     Src cA = make_src(selA(g, cur.seg), (size_t)cur.pm * tstepA), cB = make_src(selB(g, cur.seg), (size_t)cur.pn * tstep);
;     if constexpr (SP2) {
;         f32x4 rpa = {0.f, 0.f, 0.f, 0.f}, rpb = rpa;
;         float rsum = 0.f;
;         if constexpr (Epi::NEEDS_RS) { const GAS f32x4* p = (const GAS f32x4*)(E.rowss + (size_t)(cur.pm * BM + (tid >> 1)) * 16) + (tid & 1) * 2; rpa = p[0]; rpb = p[1]; }
;         PG8_STAGE(PG8_SB(0, 0), cB, voffB); PG8_STAGE(PG8_SB(0, 1), cB + hstep, voffB); PG8_STAGE(PG8_SA(0, 0), cA, voffA); PG8_STAGE(PG8_SA(0, 1), cA + hstepA, voffA);
;         if (wr == 1) PG8_BAR;
;         PG8_WAIT_V(2); PG8_BAR;
;         if constexpr (Epi::NEEDS_RS) {
;             rsum = ((rpa[0] + rpa[1]) + (rpa[2] + rpa[3])) + ((rpb[0] + rpb[1]) + (rpb[2] + rpb[3]));
.LBB0_1552:
.LBB0_1553:
	v_readlane_b32 s0, v254, 36
	s_cmp_eq_u32 s0, 3
	v_readlane_b32 s2, v253, 23
	s_cselect_b64 s[0:1], -1, 0
	v_readlane_b32 s3, v253, 24
	s_and_b64 s[0:1], s[0:1], s[2:3]
	v_readlane_b32 s2, v253, 25
	v_readlane_b32 s3, v253, 26
	s_and_b64 s[0:1], s[0:1], s[2:3]
	v_readlane_b32 s2, v254, 39
	v_readlane_b32 s3, v254, 40
	s_and_b64 s[6:7], s[0:1], s[2:3]
	v_readlane_b32 s0, v249, 54
	v_readlane_b32 s2, v249, 56
	s_cmp_gt_i32 s2, s16
	v_readlane_b32 s1, v249, 55
	v_readlane_b32 s3, v249, 57
	s_cselect_b64 s[24:25], -1, 0
	s_cmp_le_i32 s2, s16
	s_cselect_b64 s[0:1], -1, 0
	s_cmp_lt_i32 s16, s3
	s_cselect_b64 s[26:27], -1, 0
	s_and_b64 s[0:1], s[0:1], s[26:27]
	s_andn2_b64 vcc, exec, s[0:1]
	v_readlane_b32 s16, v254, 35
	s_cbranch_vccnz .LBB0_1716
	s_xor_b64 s[0:1], s[6:7], -1
	v_readlane_b32 s2, v254, 47
	v_readlane_b32 s3, v254, 48
	s_add_u32 s28, s2, 0x1c00000
	s_addc_u32 s29, s3, 0
	s_andn2_b64 vcc, exec, s[0:1]
	s_mov_b64 s[0:1], -1
	s_cbranch_vccnz .LBB0_1596
	v_readlane_b32 s0, v251, 40
	v_readlane_b32 s1, v251, 41
	v_mov_b32_e32 v0, v1
	s_and_b64 vcc, exec, s[0:1]
	s_cbranch_vccz .LBB0_1595
	v_mbcnt_lo_u32_b32 v0, -1, v0
	v_mbcnt_hi_u32_b32 v2, -1, v0
	v_readlane_b32 s0, v250, 8
	s_mov_b32 s1, 0xffffe0
	v_readlane_b32 s2, v254, 57
	v_lshl_add_u32 v3, v2, 4, s0
	v_ashrrev_i32_e32 v0, 31, v3
	v_lshrrev_b32_e32 v0, 22, v0
	v_add_u32_e32 v0, v3, v0
	v_ashrrev_i32_e32 v0, 10, v0
	v_mul_i32_i24_e32 v4, 0x400, v0
	v_sub_u32_e32 v4, v3, v4
	s_waitcnt lgkmcnt(0)
	v_lshrrev_b32_e32 v5, 4, v4
	v_bitop3_b32 v4, v5, v4, 32 bitop3:0x6c
	v_ashrrev_i32_e32 v6, 31, v4
	v_lshrrev_b32_e32 v6, 26, v6
	v_add_u32_e32 v6, v4, v6
	v_lshlrev_b32_e32 v5, 3, v0
	v_ashrrev_i32_e32 v7, 6, v6
	v_and_b32_e32 v6, 0xc0, v6
	v_and_b32_e32 v5, -16, v5
	v_lshlrev_b32_e32 v0, 5, v0
	v_sub_u32_e32 v4, v4, v6
	v_add_u32_e32 v5, v7, v5
	v_and_b32_e32 v0, 32, v0
	v_ashrrev_i16_sdwa v4, v226, sext(v4) dst_sel:DWORD dst_unused:UNUSED_PAD src0_sel:DWORD src1_sel:BYTE_0
	v_add_u32_sdwa v4, v0, sext(v4) dst_sel:DWORD dst_unused:UNUSED_PAD src0_sel:DWORD src1_sel:WORD_0
	v_lshlrev_b32_e32 v0, 1, v5
	v_lshrrev_b32_e32 v6, 2, v5
	v_and_b32_e32 v7, 3, v7
	v_and_b32_e32 v0, 24, v0
	v_and_b32_e32 v6, 4, v6
	v_and_or_b32 v7, v5, s1, v7
	v_or3_b32 v6, v7, v6, v0
	s_movk_i32 s0, 0xc00
	v_mul_lo_u32 v0, v5, s0
	v_mul_u32_u24_e32 v5, 0xb00, v6
	v_add_u32_e32 v3, 0x2000, v3
	v_add_lshl_u32 v0, v4, v0, 1
	v_add_lshl_u32 v158, v5, v4, 1
	v_ashrrev_i32_e32 v4, 31, v3
	v_lshrrev_b32_e32 v4, 22, v4
	v_add_u32_e32 v4, v3, v4
	v_ashrrev_i32_e32 v4, 10, v4
	v_mul_i32_i24_e32 v5, 0x400, v4
	v_sub_u32_e32 v3, v3, v5
	v_lshrrev_b32_e32 v5, 4, v3
	v_bitop3_b32 v3, v5, v3, 32 bitop3:0x6c
	v_ashrrev_i32_e32 v6, 31, v3
	v_lshrrev_b32_e32 v6, 26, v6
	v_add_u32_e32 v6, v3, v6
	v_ashrrev_i32_e32 v7, 6, v6
	v_and_b32_e32 v6, 0xffc0, v6
	v_sub_u32_e32 v3, v3, v6
	v_lshrrev_b16_e32 v6, 7, v3
	v_lshlrev_b32_e32 v5, 3, v4
	v_and_b32_e32 v6, 1, v6
	v_and_b32_e32 v5, -16, v5
	v_lshlrev_b32_e32 v4, 5, v4
	v_add_u16_e32 v3, v3, v6
	v_add_u32_e32 v5, v7, v5
	v_and_b32_e32 v4, 32, v4
	v_ashrrev_i16_sdwa v3, v226, sext(v3) dst_sel:DWORD dst_unused:UNUSED_PAD src0_sel:DWORD src1_sel:BYTE_0
	v_and_b32_e32 v7, 3, v7
	v_readlane_b32 s3, v254, 58
	v_add_u32_sdwa v3, v4, sext(v3) dst_sel:DWORD dst_unused:UNUSED_PAD src0_sel:DWORD src1_sel:WORD_0
	v_lshlrev_b32_e32 v4, 1, v5
	v_lshrrev_b32_e32 v6, 2, v5
	v_and_or_b32 v7, v5, s1, v7
	v_mul_lo_u32 v5, v5, s0
	s_mov_b64 s[76:77], s[2:3]
	s_mov_b64 s[0:1], s[2:3]
	v_and_b32_e32 v4, 24, v4
	v_and_b32_e32 v6, 4, v6
	s_mov_b64 s[8:9], s[28:29]
	s_mov_b64 s[0:1], s[28:29]
	s_mov_b64 s[2:3], s[28:29]
	v_or3_b32 v4, v7, v6, v4
	s_mov_b32 m0, s92
	v_mul_u32_u24_e32 v4, 0xb00, v4
	s_and_b32 s9, s9, 0xffff
	s_mov_b32 s10, s78
	s_mov_b32 s11, s79
	v_readlane_b32 s0, v254, 14
	v_add_lshl_u32 v160, v4, v3, 1
	s_and_b32 s77, s77, 0xffff
	v_add_lshl_u32 v159, v3, v5, 1
	v_readlane_b32 s2, v250, 9
	v_readlane_b32 s3, v250, 10
	buffer_load_dwordx4 v158, s[8:11], s0 offen lds
	s_mov_b32 m0, s93
	v_cndmask_b32_e64 v3, 0, 1, s[2:3]
	buffer_load_dwordx4 v160, s[8:11], s0 offen lds
	s_mov_b32 m0, s94
	v_readlane_b32 s0, v254, 8
	s_andn2_b64 vcc, exec, s[2:3]
	s_nop 3
	buffer_load_dwordx4 v158, s[8:11], s0 offen lds
	s_mov_b32 m0, s95
	s_nop 0
	buffer_load_dwordx4 v160, s[8:11], s0 offen lds
	s_mov_b32 m0, s44
	v_readlane_b32 s0, v254, 12
	s_nop 4
	buffer_load_dwordx4 v0, s[76:79], s0 offen lds
	s_mov_b32 m0, s36
	s_nop 0
	buffer_load_dwordx4 v159, s[76:79], s0 offen lds
	s_mov_b32 m0, s37
	v_readlane_b32 s0, v254, 10
	s_nop 4
	buffer_load_dwordx4 v0, s[76:79], s0 offen lds
	s_mov_b32 m0, s38
	s_nop 0
	buffer_load_dwordx4 v159, s[76:79], s0 offen lds
	v_cmp_ne_u32_e64 s[0:1], 1, v3
	s_cbranch_vccnz .LBB0_1558
.LBB0_1558:
	s_mov_b32 m0, s39
	s_mov_b32 s10, s78
	s_mov_b32 s11, s79
	v_readlane_b32 s2, v254, 11
	s_waitcnt vmcnt(2)
	s_barrier
	v_and_b32_e32 v3, 15, v2
	v_and_b32_e32 v5, 48, v2
	v_lshlrev_b32_e32 v2, 2, v2
	s_nop 0
	buffer_load_dwordx4 v158, s[8:11], s2 offen lds
	s_mov_b32 m0, s40
	v_and_b32_e32 v2, 32, v2
	buffer_load_dwordx4 v160, s[8:11], s2 offen lds
	s_mov_b32 m0, s41
	v_readlane_b32 s2, v254, 13
	s_mov_b32 s54, 0
	v_readlane_b32 s59, v254, 7
	v_readlane_b32 s60, v254, 9
	s_mov_b64 s[52:53], s[78:79]
	v_readlane_b32 s16, v254, 14
	buffer_load_dwordx4 v0, s[76:79], s2 offen lds
	s_mov_b32 m0, s33
	s_mov_b64 s[12:13], s[76:77]
	buffer_load_dwordx4 v159, s[76:79], s2 offen lds
	s_mov_b32 m0, s43
	v_readlane_b32 s2, v254, 15
	s_mov_b64 s[14:15], s[78:79]
	v_readlane_b32 s17, v254, 12
	s_nop 2
	buffer_load_dwordx4 v158, s[8:11], s2 offen lds
	s_mov_b32 m0, s42
	s_nop 0
	buffer_load_dwordx4 v160, s[8:11], s2 offen lds
	v_readlane_b32 s2, v250, 1
	s_waitcnt vmcnt(6)
	s_barrier
	s_nop 0
	v_or_b32_e32 v4, s2, v3
	v_lshlrev_b32_e32 v6, 6, v4
	s_movk_i32 s2, 0x3c0
	v_lshlrev_b32_e32 v4, 2, v4
	v_and_or_b32 v6, v6, s2, v5
	v_and_b32_e32 v4, 32, v4
	v_readlane_b32 s2, v250, 2
	v_lshl_or_b32 v3, v3, 6, v5
	s_nop 0
	v_bitop3_b32 v4, v6, s2, v4 bitop3:0xde
	v_readlane_b32 s2, v250, 4
	v_add_u32_e32 v162, 0, v4
	s_nop 0
	v_bitop3_b32 v2, v3, s2, v2 bitop3:0xde
	v_add_u32_e32 v161, 0, v2
	s_branch .LBB0_1561

.LBB0_1572:
	v_add_u32_e32 v142, 0x10000, v161
	v_add_u32_e32 v163, 0x14000, v161
	ds_read_b128 v[130:133], v142
	ds_read_b128 v[134:137], v142 offset:1024
	ds_read_b128 v[138:141], v142 offset:2048
	ds_read_b128 v[142:145], v142 offset:3072
	ds_read_b128 v[146:149], v163
	ds_read_b128 v[150:153], v163 offset:1024
	ds_read_b128 v[154:157], v163 offset:2048
	ds_read_b128 v[164:167], v163 offset:3072
	s_add_i32 s16, s2, 0xfff40080
	s_cmp_eq_u32 s61, 40
	s_cselect_b32 s64, s57, s16
	s_cselect_b32 s17, s35, s9
	s_cselect_b32 s16, s34, s8
	s_cselect_b32 s19, s51, s53
	s_cselect_b32 s18, s50, s52
	s_cselect_b32 s62, s58, s3
	s_cselect_b32 s20, s10, s12
	s_cselect_b32 s21, s11, s13
	s_cselect_b32 s22, s30, s14
	s_cselect_b32 s23, s31, s15
	s_or_b32 s63, s64, 0x80
	s_mov_b32 m0, s45
	ds_read_b128 v[168:171], v162
	ds_read_b128 v[172:175], v162 offset:1024
	ds_read_b128 v[176:179], v162 offset:2048
	ds_read_b128 v[180:183], v162 offset:3072
	ds_read_b128 v[184:187], v162 offset:4096
	ds_read_b128 v[188:191], v162 offset:5120
	ds_read_b128 v[192:195], v162 offset:6144
	ds_read_b128 v[200:203], v162 offset:7168
	buffer_load_dwordx4 v0, s[12:15], s2 offen lds
	s_mov_b32 m0, s46
	s_nop 0
	buffer_load_dwordx4 v159, s[12:15], s2 offen lds
	s_waitcnt vmcnt(8)
	s_waitcnt lgkmcnt(0)
	s_cmp_eq_u32 s100, 0
	s_cbranch_scc1 .Lhb_72
	s_barrier

.Lhb_76:
	s_mov_b32 m0, s92
	ds_read_b128 v[168:171], v162 offset:16384
	ds_read_b128 v[172:175], v162 offset:17408
	ds_read_b128 v[176:179], v162 offset:18432
	ds_read_b128 v[180:183], v162 offset:19456
	ds_read_b128 v[184:187], v162 offset:20480
	ds_read_b128 v[188:191], v162 offset:21504
	ds_read_b128 v[192:195], v162 offset:22528
	ds_read_b128 v[200:203], v162 offset:23552
	buffer_load_dwordx4 v158, s[16:19], s62 offen lds
	s_mov_b32 m0, s93
	s_add_i32 s65, s62, 0xb0000
	buffer_load_dwordx4 v160, s[16:19], s62 offen lds
	s_mov_b32 m0, s94
	s_nop 0
	buffer_load_dwordx4 v158, s[16:19], s65 offen lds
	s_mov_b32 m0, s95
	s_nop 0
	buffer_load_dwordx4 v160, s[16:19], s65 offen lds
	s_mov_b32 m0, s44
	s_nop 0
	buffer_load_dwordx4 v0, s[20:23], s64 offen lds
	s_mov_b32 m0, s36
	s_nop 0
	buffer_load_dwordx4 v159, s[20:23], s64 offen lds
	s_waitcnt vmcnt(8)
	s_waitcnt lgkmcnt(0)
	s_cmp_eq_u32 s100, 0
	s_cbranch_scc1 .Lhb_73
	s_barrier

.Lhb_77:
	v_add_u32_e32 v142, 0x18000, v161
	v_add_u32_e32 v163, 0x1c000, v161
	ds_read_b128 v[130:133], v142
	ds_read_b128 v[134:137], v142 offset:1024
	ds_read_b128 v[138:141], v142 offset:2048
	ds_read_b128 v[142:145], v142 offset:3072
	ds_read_b128 v[146:149], v163
	ds_read_b128 v[150:153], v163 offset:1024
	ds_read_b128 v[154:157], v163 offset:2048
	ds_read_b128 v[164:167], v163 offset:3072
	s_add_i32 s64, s64, 0xc0000
	s_mov_b32 m0, s37
	ds_read_b128 v[168:171], v162 offset:32768
	ds_read_b128 v[172:175], v162 offset:33792
	ds_read_b128 v[176:179], v162 offset:34816
	ds_read_b128 v[180:183], v162 offset:35840
	ds_read_b128 v[184:187], v162 offset:36864
	ds_read_b128 v[188:191], v162 offset:37888
	ds_read_b128 v[192:195], v162 offset:38912
	ds_read_b128 v[200:203], v162 offset:39936
	buffer_load_dwordx4 v0, s[20:23], s64 offen lds
	s_mov_b32 m0, s38
	s_nop 0
	buffer_load_dwordx4 v159, s[20:23], s64 offen lds
	s_waitcnt vmcnt(8)
	s_waitcnt lgkmcnt(0)
	s_cmp_eq_u32 s100, 0
	s_cbranch_scc1 .Lhb_74
	s_barrier

.Lhb_78:
	s_mov_b32 m0, s39
	s_or_b32 s64, s62, 0x80
	ds_read_b128 v[168:171], v162 offset:49152
	ds_read_b128 v[172:175], v162 offset:50176
	ds_read_b128 v[176:179], v162 offset:51200
	ds_read_b128 v[180:183], v162 offset:52224
	ds_read_b128 v[184:187], v162 offset:53248
	ds_read_b128 v[188:191], v162 offset:54272
	ds_read_b128 v[192:195], v162 offset:55296
	ds_read_b128 v[200:203], v162 offset:56320
	buffer_load_dwordx4 v158, s[16:19], s64 offen lds
	s_mov_b32 m0, s40
	s_add_i32 s62, s62, 0xb0080
	buffer_load_dwordx4 v160, s[16:19], s64 offen lds
	s_mov_b32 m0, s43
	s_nop 0
	buffer_load_dwordx4 v158, s[16:19], s62 offen lds
	s_mov_b32 m0, s42
	s_nop 0
	buffer_load_dwordx4 v160, s[16:19], s62 offen lds
	s_mov_b32 m0, s41
	s_nop 0
	buffer_load_dwordx4 v0, s[20:23], s63 offen lds
	s_mov_b32 m0, s33
	s_nop 0
	buffer_load_dwordx4 v159, s[20:23], s63 offen lds
	s_waitcnt vmcnt(8)
	s_waitcnt lgkmcnt(0)
	s_cmp_eq_u32 s100, 0
	s_cbranch_scc1 .Lhb_75
	s_barrier

; #define PG8_STAGE(bufoff, gbase, voff) do { const Src _g = (gbase); _Pragma("unroll") for (int _i = 0; _i < 2; ++_i) \
;         __builtin_amdgcn_raw_ptr_buffer_load_lds(_g.r, (LAS unsigned*)(lds + (bufoff) + ldsw + _i * 8192), 16, (voff)[_i], _g.o, 0, 0); } while (0)
; #define PG8_WAIT_V(n) asm volatile("s_waitcnt vmcnt(" #n ")" ::: "memory")
; template <class Epi, bool ALIGN_EPI, bool SP2, class Hook>
; __device__ __forceinline__ void gemm_phase(LAS unsigned char* lds, const Gemm g, const StaticOrder& S, const Epi& E, Acc& acc, const bool fresh, const Hook& H, const int wave_id) {
;     ...
;         for (int t = t0; t < nt; t += 2) {
;             const bool last = (t == nt - 2);
;             const Src a1 = cA + (size_t)(t + 1) * kstep;
;             const Src a2 = last ? nA : cA + (size_t)(t + 2) * kstep, b2 = last ? nB : cB + (size_t)(t + 2) * kstep;
;             const Src a3 = a2 + kstep, b3 = b2 + kstep;
;             if (last && has_next) H(nxt);
;             if constexpr (SP2) {
;             PG8_TRIP_SP2(PG8_WAIT_V(8));
;             } else {
;             PG8_LDB(B0, 0, 0); PG8_SCHED; PG8_LDA(At, 0, 0); PG8_STAGE(PG8_SA(1, 1), a1 + hstepA, voffA);
;             PG8_WAIT_L(8); PG8_BAR; PG8_WAIT_L(0); PG8_MMA(0, 0, At, B0); PG8_BAR; PG8_SCHED;
;             PG8_LDB(B1, 0, 1); PG8_STAGE(PG8_SB(0, 0), b2, voffB);
;             PG8_BAR; PG8_WAIT_L(0); PG8_MMA(0, 1, At, B1); PG8_BAR;
;             PG8_LDA(At, 0, 1); PG8_STAGE(PG8_SA(0, 0), a2, voffA);
;             PG8_BAR; PG8_WAIT_L(0); PG8_MMA(1, 0, At, B0); PG8_BAR; PG8_SCHED;
;             PG8_STAGE(PG8_SB(0, 1), b2 + hstep, voffB);
;             PG8_WAIT_V(6); PG8_BAR; PG8_MMA(1, 1, At, B1); PG8_BAR;
;             PG8_LDB(B0, 1, 0); PG8_SCHED; PG8_LDA(At, 1, 0); PG8_STAGE(PG8_SA(0, 1), a2 + hstepA, voffA);
;             PG8_WAIT_L(8); PG8_BAR; PG8_WAIT_L(0); PG8_MMA(0, 0, At, B0); PG8_BAR; PG8_SCHED;
;             PG8_LDB(B1, 1, 1); PG8_STAGE(PG8_SB(1, 0), b3, voffB);
;             PG8_BAR; PG8_WAIT_L(0); PG8_MMA(0, 1, At, B1); PG8_BAR;
;             PG8_LDA(At, 1, 1); PG8_STAGE(PG8_SA(1, 0), a3, voffA);
;             PG8_BAR; PG8_WAIT_L(0); PG8_MMA(1, 0, At, B0); PG8_BAR; PG8_SCHED;
;             PG8_STAGE(PG8_SB(1, 1), b3 + hstep, voffB);
;             PG8_WAIT_V(6); PG8_BAR; PG8_MMA(1, 1, At, B1); PG8_BAR;
;             }
;         }
;         if constexpr (ALIGN_EPI) { if (wr == 0) PG8_BAR; }
.Lhb_79:
	s_add_i32 s61, s61, 2
	s_addk_i32 s2, 0x100
	s_addk_i32 s3, 0x100
	s_cmp_gt_u32 s61, 41
	s_cbranch_scc0 .LBB0_1572
	v_readlane_b32 s2, v251, 45
	v_readlane_b32 s3, v251, 46
	s_and_b64 vcc, exec, s[2:3]
	s_cbranch_vccz .LBB0_1575

; #define GAS __attribute__((address_space(1)))
; #define PG8_BAR __builtin_amdgcn_s_barrier()
; template <class Epi, bool ALIGN_EPI, bool SP2, class Hook>
; __device__ __forceinline__ void gemm_phase(LAS unsigned char* lds, const Gemm g, const StaticOrder& S, const Epi& E, Acc& acc, const bool fresh, const Hook& H, const int wave_id) {
;     const int tid = opaque_tid(wave_id), wid = wave_id, lane = tid & 63, wr = wid >> 2, wc = wid & 3, fr = lane & 15, fq = lane >> 4;
;     const int K = g.K, nt = K / BK, lda = g.lda ? g.lda : K;
;     unsigned voffA[2], voffB[2];
; #pragma unroll
;     for (int i = 0; i < 2; ++i) { int R, C; stage_rc(tid * 16 + i * 8192, R, C); const int Rb = (R & ~31) + perm32(R & 31);
;         voffA[i] = (unsigned)(R * lda + C) * 2u; voffB[i] = (unsigned)(Rb * K + C) * 2u; }
;     const size_t kstep = (size_t)(BK * 2);
;     const size_t hstep = (size_t)HALF * K * 2, hstepA = (size_t)HALF * lda * 2;
;     const size_t tstep = 2 * hstep, tstepA = 2 * hstepA;
;     const unsigned ldsw = (unsigned)wid * 1024u;
;     const int aoff = lds_byte(wr * 64 + fr, fq * 8), boff = lds_byte(wc * 32 + fr, fq * 8);
;     ...
;     Unit cur, nxt; int ui = 0, rs_pm = -1, t0 = 0;
;     if (!S.next(0, cur)) return;
;     if (fresh) {
; #pragma unroll
;         for (int a = 0; a < 2; ++a)
; #pragma unroll
;             for (int b = 0; b < 2; ++b)
; #pragma unroll
;                 for (int m = 0; m < 4; ++m)
; #pragma unroll
;                     for (int n = 0; n < 2; ++n) acc[a][b][m][n] = (f32x4){0.f, 0.f, 0.f, 0.f};
;     }
;     bf16x8 At[4][2], B0[2][2], B1[2][2];
;     Src cA = make_src(selA(g, cur.seg), (size_t)cur.pm * tstepA), cB = make_src(selB(g, cur.seg), (size_t)cur.pn * tstep);
;     if constexpr (SP2) {
;         f32x4 rpa = {0.f, 0.f, 0.f, 0.f}, rpb = rpa;
;         float rsum = 0.f;
;         if constexpr (Epi::NEEDS_RS) { const GAS f32x4* p = (const GAS f32x4*)(E.rowss + (size_t)(cur.pm * BM + (tid >> 1)) * 16) + (tid & 1) * 2; rpa = p[0]; rpb = p[1]; }
;         PG8_STAGE(PG8_SB(0, 0), cB, voffB); PG8_STAGE(PG8_SB(0, 1), cB + hstep, voffB); PG8_STAGE(PG8_SA(0, 0), cA, voffA); PG8_STAGE(PG8_SA(0, 1), cA + hstepA, voffA);
;         if (wr == 1) PG8_BAR;
;         PG8_WAIT_V(2); PG8_BAR;
;         if constexpr (Epi::NEEDS_RS) {
;             rsum = ((rpa[0] + rpa[1]) + (rpa[2] + rpa[3])) + ((rpb[0] + rpb[1]) + (rpb[2] + rpb[3]));
.LBB0_1596:
	s_andn2_b64 vcc, exec, s[0:1]
	s_cbranch_vccnz .LBB0_1716
	v_readlane_b32 s0, v251, 40
	v_readlane_b32 s1, v251, 41
	v_mov_b32_e32 v0, v1
	s_andn2_b64 vcc, exec, s[0:1]
	s_cbranch_vccnz .LBB0_1716
	v_mbcnt_lo_u32_b32 v0, -1, v0
	v_mbcnt_hi_u32_b32 v0, -1, v0
	v_readlane_b32 s0, v250, 8
	s_mov_b32 s1, 0xffffe0
	v_writelane_b32 v254, s24, 55
	v_lshl_add_u32 v2, v0, 4, s0
	v_ashrrev_i32_e32 v3, 31, v2
	v_lshrrev_b32_e32 v3, 22, v3
	v_add_u32_e32 v3, v2, v3
	v_ashrrev_i32_e32 v3, 10, v3
	v_mul_i32_i24_e32 v4, 0x400, v3
	v_sub_u32_e32 v4, v2, v4
	s_waitcnt lgkmcnt(0)
	v_lshrrev_b32_e32 v5, 4, v4
	v_bitop3_b32 v4, v5, v4, 32 bitop3:0x6c
	v_ashrrev_i32_e32 v6, 31, v4
	v_lshrrev_b32_e32 v6, 26, v6
	v_add_u32_e32 v6, v4, v6
	v_lshlrev_b32_e32 v5, 3, v3
	v_ashrrev_i32_e32 v7, 6, v6
	v_and_b32_e32 v6, 0xc0, v6
	v_and_b32_e32 v5, -16, v5
	v_lshlrev_b32_e32 v3, 5, v3
	v_sub_u32_e32 v4, v4, v6
	v_add_u32_e32 v5, v7, v5
	v_and_b32_e32 v3, 32, v3
	v_ashrrev_i16_sdwa v4, v226, sext(v4) dst_sel:DWORD dst_unused:UNUSED_PAD src0_sel:DWORD src1_sel:BYTE_0
	v_add_u32_sdwa v3, v3, sext(v4) dst_sel:DWORD dst_unused:UNUSED_PAD src0_sel:DWORD src1_sel:WORD_0
	v_lshlrev_b32_e32 v4, 1, v5
	v_lshrrev_b32_e32 v6, 2, v5
	v_and_b32_e32 v7, 3, v7
	v_and_b32_e32 v4, 24, v4
	v_and_b32_e32 v6, 4, v6
	v_and_or_b32 v7, v5, s1, v7
	v_or3_b32 v4, v7, v6, v4
	s_movk_i32 s0, 0xc00
	v_mul_lo_u32 v5, v5, s0
	v_mul_u32_u24_e32 v4, 0xb00, v4
	v_add_u32_e32 v2, 0x2000, v2
	v_add_lshl_u32 v168, v3, v5, 1
	v_add_lshl_u32 v169, v4, v3, 1
	v_ashrrev_i32_e32 v3, 31, v2
	v_lshrrev_b32_e32 v3, 22, v3
	v_add_u32_e32 v3, v2, v3
	v_ashrrev_i32_e32 v3, 10, v3
	v_mul_i32_i24_e32 v4, 0x400, v3
	v_sub_u32_e32 v2, v2, v4
	v_lshrrev_b32_e32 v4, 4, v2
	v_bitop3_b32 v2, v4, v2, 32 bitop3:0x6c
	v_ashrrev_i32_e32 v5, 31, v2
	v_lshrrev_b32_e32 v5, 26, v5
	v_add_u32_e32 v5, v2, v5
	v_ashrrev_i32_e32 v6, 6, v5
	v_and_b32_e32 v5, 0xffc0, v5
	v_sub_u32_e32 v2, v2, v5
	v_lshrrev_b16_e32 v5, 7, v2
	v_writelane_b32 v254, s25, 56
	v_lshlrev_b32_e32 v4, 3, v3
	v_and_b32_e32 v5, 1, v5
	v_and_b32_e32 v4, -16, v4
	v_lshlrev_b32_e32 v3, 5, v3
	v_add_u16_e32 v2, v2, v5
	v_readlane_b32 s2, v254, 57
	v_add_u32_e32 v4, v6, v4
	v_and_b32_e32 v3, 32, v3
	v_ashrrev_i16_sdwa v2, v226, sext(v2) dst_sel:DWORD dst_unused:UNUSED_PAD src0_sel:DWORD src1_sel:BYTE_0
	v_and_b32_e32 v6, 3, v6
	v_readlane_b32 s3, v254, 58
	v_add_u32_sdwa v2, v3, sext(v2) dst_sel:DWORD dst_unused:UNUSED_PAD src0_sel:DWORD src1_sel:WORD_0
	v_lshlrev_b32_e32 v3, 1, v4
	v_lshrrev_b32_e32 v5, 2, v4
	v_and_or_b32 v6, v4, s1, v6
	v_mul_lo_u32 v4, v4, s0
	s_mov_b64 s[8:9], s[2:3]
	s_mov_b64 s[0:1], s[2:3]
	v_and_b32_e32 v3, 24, v3
	v_and_b32_e32 v5, 4, v5
	s_mov_b64 s[76:77], s[28:29]
	s_mov_b64 s[0:1], s[28:29]
	s_mov_b64 s[2:3], s[28:29]
	v_or3_b32 v3, v6, v5, v3
	s_mov_b32 m0, s92
	v_mul_u32_u24_e32 v3, 0xb00, v3
	s_and_b32 s77, s77, 0xffff
	v_readlane_b32 s0, v254, 14
	v_add_lshl_u32 v171, v3, v2, 1
	s_and_b32 s9, s9, 0xffff
	s_mov_b32 s10, s78
	s_mov_b32 s11, s79
	v_add_lshl_u32 v170, v2, v4, 1
	buffer_load_dwordx4 v169, s[76:79], s0 offen lds
	s_mov_b32 m0, s93
	v_readlane_b32 s2, v250, 9
	buffer_load_dwordx4 v171, s[76:79], s0 offen lds
	s_mov_b32 m0, s94
	v_readlane_b32 s0, v254, 8
	v_readlane_b32 s3, v250, 10
	s_mov_b32 s25, s73
	s_andn2_b64 vcc, exec, s[2:3]
	v_cndmask_b32_e64 v2, 0, 1, s[2:3]
	s_nop 0
	buffer_load_dwordx4 v169, s[76:79], s0 offen lds
	s_mov_b32 m0, s95
	s_nop 0
	buffer_load_dwordx4 v171, s[76:79], s0 offen lds
	s_mov_b32 m0, s44
	v_readlane_b32 s0, v254, 12
	s_nop 4
	buffer_load_dwordx4 v168, s[8:11], s0 offen lds
	s_mov_b32 m0, s36
	s_nop 0
	buffer_load_dwordx4 v170, s[8:11], s0 offen lds
	s_mov_b32 m0, s37
	v_readlane_b32 s0, v254, 10
	s_nop 4
	buffer_load_dwordx4 v168, s[8:11], s0 offen lds
	s_mov_b32 m0, s38
	s_nop 0
	buffer_load_dwordx4 v170, s[8:11], s0 offen lds
	v_cmp_ne_u32_e64 s[0:1], 1, v2
	s_cbranch_vccnz .LBB0_1600
.LBB0_1600:
	s_mov_b32 m0, s39
	v_readlane_b32 s2, v254, 11
	s_waitcnt vmcnt(2)
	s_barrier
	s_mov_b32 s10, s78
	s_mov_b32 s11, s79
	v_and_b32_e32 v2, 15, v0
	s_nop 0
	buffer_load_dwordx4 v169, s[76:79], s2 offen lds
	s_mov_b32 m0, s40
	v_and_b32_e32 v4, 48, v0
	buffer_load_dwordx4 v171, s[76:79], s2 offen lds
	s_mov_b32 m0, s41
	v_readlane_b32 s2, v254, 13
	v_lshlrev_b32_e32 v0, 2, v0
	v_and_b32_e32 v0, 32, v0
	s_mov_b32 s52, 0
	v_readlane_b32 s58, v254, 7
	v_readlane_b32 s57, v254, 9
	buffer_load_dwordx4 v168, s[8:11], s2 offen lds
	s_mov_b32 m0, s33
	s_mov_b64 s[50:51], s[78:79]
	buffer_load_dwordx4 v170, s[8:11], s2 offen lds
	s_mov_b32 m0, s43
	v_readlane_b32 s2, v254, 15
	v_readlane_b32 s12, v254, 14
	s_mov_b64 s[10:11], s[78:79]
	v_readlane_b32 s13, v254, 12
	s_nop 1
	buffer_load_dwordx4 v169, s[76:79], s2 offen lds
	s_mov_b32 m0, s42
	s_nop 0
	buffer_load_dwordx4 v171, s[76:79], s2 offen lds
	v_readlane_b32 s2, v250, 1
	s_waitcnt vmcnt(6)
	s_barrier
	s_nop 0
	v_or_b32_e32 v3, s2, v2
	v_lshlrev_b32_e32 v5, 6, v3
	s_movk_i32 s2, 0x3c0
	v_lshlrev_b32_e32 v3, 2, v3
	v_and_or_b32 v5, v5, s2, v4
	v_and_b32_e32 v3, 32, v3
	v_readlane_b32 s2, v250, 2
	v_lshl_or_b32 v2, v2, 6, v4
	s_nop 0
	v_bitop3_b32 v3, v5, s2, v3 bitop3:0xde
	v_readlane_b32 s2, v250, 4
	v_add_u32_e32 v173, 0, v3
	s_nop 0
	v_bitop3_b32 v0, v2, s2, v0 bitop3:0xde
	v_add_u32_e32 v172, 0, v0
	s_branch .LBB0_1603

.LBB0_1614:
	v_add_u32_e32 v0, 0x10000, v172
	ds_read_b128 v[130:133], v0
	ds_read_b128 v[134:137], v0 offset:1024
	ds_read_b128 v[138:141], v0 offset:2048
	ds_read_b128 v[142:145], v0 offset:3072
	v_add_u32_e32 v0, 0x14000, v172
	ds_read_b128 v[146:149], v0
	ds_read_b128 v[150:153], v0 offset:1024
	ds_read_b128 v[154:157], v0 offset:2048
	ds_read_b128 v[158:161], v0 offset:3072
	s_add_i32 s12, s2, 0xfff40080
	s_cmp_eq_u32 s59, 40
	s_cselect_b32 s62, s55, s12
	s_cselect_b32 s13, s31, s77
	s_cselect_b32 s12, s30, s76
	s_cselect_b32 s15, s35, s51
	s_cselect_b32 s14, s34, s50
	s_cselect_b32 s60, s56, s3
	s_cselect_b32 s16, s20, s8
	s_cselect_b32 s17, s21, s9
	s_cselect_b32 s18, s22, s10
	s_cselect_b32 s19, s23, s11
	s_or_b32 s61, s62, 0x80
	s_mov_b32 m0, s45
	ds_read_b128 v[162:165], v173
	ds_read_b128 v[174:177], v173 offset:1024
	ds_read_b128 v[178:181], v173 offset:2048
	ds_read_b128 v[182:185], v173 offset:3072
	ds_read_b128 v[186:189], v173 offset:4096
	ds_read_b128 v[190:193], v173 offset:5120
	ds_read_b128 v[194:197], v173 offset:6144
	ds_read_b128 v[200:203], v173 offset:7168
	buffer_load_dwordx4 v168, s[8:11], s2 offen lds
	s_mov_b32 m0, s46
	s_nop 0
	buffer_load_dwordx4 v170, s[8:11], s2 offen lds
	s_waitcnt vmcnt(8)
	s_waitcnt lgkmcnt(0)
	s_cmp_eq_u32 s100, 0
	s_cbranch_scc1 .Lhb_80
	s_barrier
.Lhb_80:
	s_setprio 1
	s_waitcnt lgkmcnt(7)
	v_mfma_f32_16x16x32_bf16 v[126:129], v[130:133], v[162:165], v[126:129]
	v_mfma_f32_16x16x32_bf16 v[122:125], v[138:141], v[162:165], v[122:125]
	s_waitcnt lgkmcnt(5)
	v_mfma_f32_16x16x32_bf16 v[110:113], v[130:133], v[178:181], v[110:113]
	v_mfma_f32_16x16x32_bf16 v[106:109], v[138:141], v[178:181], v[106:109]
	s_waitcnt lgkmcnt(3)
	v_mfma_f32_16x16x32_bf16 v[94:97], v[130:133], v[186:189], v[94:97]
	v_mfma_f32_16x16x32_bf16 v[90:93], v[138:141], v[186:189], v[90:93]
	s_waitcnt lgkmcnt(1)
	v_mfma_f32_16x16x32_bf16 v[78:81], v[130:133], v[194:197], v[78:81]
	v_mfma_f32_16x16x32_bf16 v[74:77], v[138:141], v[194:197], v[74:77]
	v_mfma_f32_16x16x32_bf16 v[126:129], v[134:137], v[174:177], v[126:129]
	v_mfma_f32_16x16x32_bf16 v[122:125], v[142:145], v[174:177], v[122:125]
	v_mfma_f32_16x16x32_bf16 v[110:113], v[134:137], v[182:185], v[110:113]
	v_mfma_f32_16x16x32_bf16 v[106:109], v[142:145], v[182:185], v[106:109]
	v_mfma_f32_16x16x32_bf16 v[94:97], v[134:137], v[190:193], v[94:97]
	v_mfma_f32_16x16x32_bf16 v[90:93], v[142:145], v[190:193], v[90:93]
	s_waitcnt lgkmcnt(0)
	v_mfma_f32_16x16x32_bf16 v[78:81], v[134:137], v[200:203], v[78:81]
	v_mfma_f32_16x16x32_bf16 v[74:77], v[142:145], v[200:203], v[74:77]
	s_setprio 0
	s_setprio 1
	v_mfma_f32_16x16x32_bf16 v[118:121], v[146:149], v[162:165], v[118:121]
	v_mfma_f32_16x16x32_bf16 v[114:117], v[154:157], v[162:165], v[114:117]
	v_mfma_f32_16x16x32_bf16 v[102:105], v[146:149], v[178:181], v[102:105]
	v_mfma_f32_16x16x32_bf16 v[98:101], v[154:157], v[178:181], v[98:101]
	v_mfma_f32_16x16x32_bf16 v[86:89], v[146:149], v[186:189], v[86:89]
	v_mfma_f32_16x16x32_bf16 v[82:85], v[154:157], v[186:189], v[82:85]
	v_mfma_f32_16x16x32_bf16 v[70:73], v[146:149], v[194:197], v[70:73]
	v_mfma_f32_16x16x32_bf16 v[66:69], v[154:157], v[194:197], v[66:69]
	v_mfma_f32_16x16x32_bf16 v[118:121], v[150:153], v[174:177], v[118:121]
	v_mfma_f32_16x16x32_bf16 v[114:117], v[158:161], v[174:177], v[114:117]
	v_mfma_f32_16x16x32_bf16 v[102:105], v[150:153], v[182:185], v[102:105]
	v_mfma_f32_16x16x32_bf16 v[98:101], v[158:161], v[182:185], v[98:101]
	v_mfma_f32_16x16x32_bf16 v[86:89], v[150:153], v[190:193], v[86:89]
	v_mfma_f32_16x16x32_bf16 v[82:85], v[158:161], v[190:193], v[82:85]
	v_mfma_f32_16x16x32_bf16 v[70:73], v[150:153], v[200:203], v[70:73]
	v_mfma_f32_16x16x32_bf16 v[66:69], v[158:161], v[200:203], v[66:69]
	s_setprio 0
	s_cmp_lg_u32 s100, 0
	s_cbranch_scc1 .Lhb_84
	s_barrier
.Lhb_84:
	s_mov_b32 m0, s92
	ds_read_b128 v[162:165], v173 offset:16384
	ds_read_b128 v[174:177], v173 offset:17408
	ds_read_b128 v[178:181], v173 offset:18432
	ds_read_b128 v[182:185], v173 offset:19456
	ds_read_b128 v[186:189], v173 offset:20480
	ds_read_b128 v[190:193], v173 offset:21504
	ds_read_b128 v[194:197], v173 offset:22528
	ds_read_b128 v[200:203], v173 offset:23552
	buffer_load_dwordx4 v169, s[12:15], s60 offen lds
	s_mov_b32 m0, s93
	s_add_i32 s63, s60, 0xb0000
	buffer_load_dwordx4 v171, s[12:15], s60 offen lds
	s_mov_b32 m0, s94
	s_nop 0
	buffer_load_dwordx4 v169, s[12:15], s63 offen lds
	s_mov_b32 m0, s95
	s_nop 0
	buffer_load_dwordx4 v171, s[12:15], s63 offen lds
	s_mov_b32 m0, s44
	s_nop 0
	buffer_load_dwordx4 v168, s[16:19], s62 offen lds
	s_mov_b32 m0, s36
	s_nop 0
	buffer_load_dwordx4 v170, s[16:19], s62 offen lds
	s_waitcnt vmcnt(8)
	s_waitcnt lgkmcnt(0)
	s_cmp_eq_u32 s100, 0
	s_cbranch_scc1 .Lhb_81
	s_barrier
.Lhb_81:
	s_setprio 1
	s_waitcnt lgkmcnt(7)
	v_mfma_f32_16x16x32_bf16 v[62:65], v[130:133], v[162:165], v[62:65]
	v_mfma_f32_16x16x32_bf16 v[58:61], v[138:141], v[162:165], v[58:61]
	s_waitcnt lgkmcnt(5)
	v_mfma_f32_16x16x32_bf16 v[46:49], v[130:133], v[178:181], v[46:49]
	v_mfma_f32_16x16x32_bf16 v[42:45], v[138:141], v[178:181], v[42:45]
	s_waitcnt lgkmcnt(3)
	v_mfma_f32_16x16x32_bf16 v[30:33], v[130:133], v[186:189], v[30:33]
	v_mfma_f32_16x16x32_bf16 v[26:29], v[138:141], v[186:189], v[26:29]
	s_waitcnt lgkmcnt(1)
	v_mfma_f32_16x16x32_bf16 v[14:17], v[130:133], v[194:197], v[14:17]
	v_mfma_f32_16x16x32_bf16 v[10:13], v[138:141], v[194:197], v[10:13]
	v_mfma_f32_16x16x32_bf16 v[62:65], v[134:137], v[174:177], v[62:65]
	v_mfma_f32_16x16x32_bf16 v[58:61], v[142:145], v[174:177], v[58:61]
	v_mfma_f32_16x16x32_bf16 v[46:49], v[134:137], v[182:185], v[46:49]
	v_mfma_f32_16x16x32_bf16 v[42:45], v[142:145], v[182:185], v[42:45]
	v_mfma_f32_16x16x32_bf16 v[30:33], v[134:137], v[190:193], v[30:33]
	v_mfma_f32_16x16x32_bf16 v[26:29], v[142:145], v[190:193], v[26:29]
	s_waitcnt lgkmcnt(0)
	v_mfma_f32_16x16x32_bf16 v[14:17], v[134:137], v[200:203], v[14:17]
	v_mfma_f32_16x16x32_bf16 v[10:13], v[142:145], v[200:203], v[10:13]
	s_setprio 0
	s_setprio 1
	v_mfma_f32_16x16x32_bf16 v[54:57], v[146:149], v[162:165], v[54:57]
	v_mfma_f32_16x16x32_bf16 v[50:53], v[154:157], v[162:165], v[50:53]
	v_mfma_f32_16x16x32_bf16 v[38:41], v[146:149], v[178:181], v[38:41]
	v_mfma_f32_16x16x32_bf16 v[34:37], v[154:157], v[178:181], v[34:37]
	v_mfma_f32_16x16x32_bf16 v[22:25], v[146:149], v[186:189], v[22:25]
	v_mfma_f32_16x16x32_bf16 v[18:21], v[154:157], v[186:189], v[18:21]
	v_mfma_f32_16x16x32_bf16 v[6:9], v[146:149], v[194:197], v[6:9]
	v_mfma_f32_16x16x32_bf16 v[2:5], v[154:157], v[194:197], v[2:5]
	v_mfma_f32_16x16x32_bf16 v[54:57], v[150:153], v[174:177], v[54:57]
	v_mfma_f32_16x16x32_bf16 v[50:53], v[158:161], v[174:177], v[50:53]
	v_mfma_f32_16x16x32_bf16 v[38:41], v[150:153], v[182:185], v[38:41]
	v_mfma_f32_16x16x32_bf16 v[34:37], v[158:161], v[182:185], v[34:37]
	v_mfma_f32_16x16x32_bf16 v[22:25], v[150:153], v[190:193], v[22:25]
	v_mfma_f32_16x16x32_bf16 v[18:21], v[158:161], v[190:193], v[18:21]
	v_mfma_f32_16x16x32_bf16 v[6:9], v[150:153], v[200:203], v[6:9]
	v_mfma_f32_16x16x32_bf16 v[2:5], v[158:161], v[200:203], v[2:5]
	s_setprio 0
	s_cmp_lg_u32 s100, 0
	s_cbranch_scc1 .Lhb_85
	s_barrier
.Lhb_85:
	v_add_u32_e32 v0, 0x18000, v172
	ds_read_b128 v[130:133], v0
	ds_read_b128 v[134:137], v0 offset:1024
	ds_read_b128 v[138:141], v0 offset:2048
	ds_read_b128 v[142:145], v0 offset:3072
	v_add_u32_e32 v0, 0x1c000, v172
	ds_read_b128 v[146:149], v0
	ds_read_b128 v[150:153], v0 offset:1024
	ds_read_b128 v[154:157], v0 offset:2048
	ds_read_b128 v[158:161], v0 offset:3072
	s_add_i32 s62, s62, 0xc0000
	s_mov_b32 m0, s37
	ds_read_b128 v[162:165], v173 offset:32768
	ds_read_b128 v[174:177], v173 offset:33792
	ds_read_b128 v[178:181], v173 offset:34816
	ds_read_b128 v[182:185], v173 offset:35840
	ds_read_b128 v[186:189], v173 offset:36864
	ds_read_b128 v[190:193], v173 offset:37888
	ds_read_b128 v[194:197], v173 offset:38912
	ds_read_b128 v[200:203], v173 offset:39936
	buffer_load_dwordx4 v168, s[16:19], s62 offen lds
	s_mov_b32 m0, s38
	s_nop 0
	buffer_load_dwordx4 v170, s[16:19], s62 offen lds
	s_waitcnt vmcnt(8)
	s_waitcnt lgkmcnt(0)
	s_cmp_eq_u32 s100, 0
	s_cbranch_scc1 .Lhb_82
	s_barrier

.Lhb_86:
	s_mov_b32 m0, s39
	s_or_b32 s62, s60, 0x80
	ds_read_b128 v[162:165], v173 offset:49152
	ds_read_b128 v[174:177], v173 offset:50176
	ds_read_b128 v[178:181], v173 offset:51200
	ds_read_b128 v[182:185], v173 offset:52224
	ds_read_b128 v[186:189], v173 offset:53248
	ds_read_b128 v[190:193], v173 offset:54272
	ds_read_b128 v[194:197], v173 offset:55296
	ds_read_b128 v[200:203], v173 offset:56320
	buffer_load_dwordx4 v169, s[12:15], s62 offen lds
	s_mov_b32 m0, s40
	s_add_i32 s60, s60, 0xb0080
	buffer_load_dwordx4 v171, s[12:15], s62 offen lds
	s_mov_b32 m0, s43
	s_nop 0
	buffer_load_dwordx4 v169, s[12:15], s60 offen lds
	s_mov_b32 m0, s42
	s_nop 0
	buffer_load_dwordx4 v171, s[12:15], s60 offen lds
	s_mov_b32 m0, s41
	s_nop 0
	buffer_load_dwordx4 v168, s[16:19], s61 offen lds
	s_mov_b32 m0, s33
	s_nop 0
	buffer_load_dwordx4 v170, s[16:19], s61 offen lds
	s_waitcnt vmcnt(8)
	s_waitcnt lgkmcnt(0)
	s_cmp_eq_u32 s100, 0
	s_cbranch_scc1 .Lhb_83
	s_barrier

; #define PG8_STAGE(bufoff, gbase, voff) do { const Src _g = (gbase); _Pragma("unroll") for (int _i = 0; _i < 2; ++_i) \
;         __builtin_amdgcn_raw_ptr_buffer_load_lds(_g.r, (LAS unsigned*)(lds + (bufoff) + ldsw + _i * 8192), 16, (voff)[_i], _g.o, 0, 0); } while (0)
; #define PG8_WAIT_V(n) asm volatile("s_waitcnt vmcnt(" #n ")" ::: "memory")
; template <class Epi, bool ALIGN_EPI, bool SP2, class Hook>
; __device__ __forceinline__ void gemm_phase(LAS unsigned char* lds, const Gemm g, const StaticOrder& S, const Epi& E, Acc& acc, const bool fresh, const Hook& H, const int wave_id) {
;     ...
;         for (int t = t0; t < nt; t += 2) {
;             const bool last = (t == nt - 2);
;             const Src a1 = cA + (size_t)(t + 1) * kstep;
;             const Src a2 = last ? nA : cA + (size_t)(t + 2) * kstep, b2 = last ? nB : cB + (size_t)(t + 2) * kstep;
;             const Src a3 = a2 + kstep, b3 = b2 + kstep;
;             if (last && has_next) H(nxt);
;             if constexpr (SP2) {
;             PG8_TRIP_SP2(PG8_WAIT_V(8));
;             } else {
;             PG8_LDB(B0, 0, 0); PG8_SCHED; PG8_LDA(At, 0, 0); PG8_STAGE(PG8_SA(1, 1), a1 + hstepA, voffA);
;             PG8_WAIT_L(8); PG8_BAR; PG8_WAIT_L(0); PG8_MMA(0, 0, At, B0); PG8_BAR; PG8_SCHED;
;             PG8_LDB(B1, 0, 1); PG8_STAGE(PG8_SB(0, 0), b2, voffB);
;             PG8_BAR; PG8_WAIT_L(0); PG8_MMA(0, 1, At, B1); PG8_BAR;
;             PG8_LDA(At, 0, 1); PG8_STAGE(PG8_SA(0, 0), a2, voffA);
;             PG8_BAR; PG8_WAIT_L(0); PG8_MMA(1, 0, At, B0); PG8_BAR; PG8_SCHED;
;             PG8_STAGE(PG8_SB(0, 1), b2 + hstep, voffB);
;             PG8_WAIT_V(6); PG8_BAR; PG8_MMA(1, 1, At, B1); PG8_BAR;
;             PG8_LDB(B0, 1, 0); PG8_SCHED; PG8_LDA(At, 1, 0); PG8_STAGE(PG8_SA(0, 1), a2 + hstepA, voffA);
;             PG8_WAIT_L(8); PG8_BAR; PG8_WAIT_L(0); PG8_MMA(0, 0, At, B0); PG8_BAR; PG8_SCHED;
;             PG8_LDB(B1, 1, 1); PG8_STAGE(PG8_SB(1, 0), b3, voffB);
;             PG8_BAR; PG8_WAIT_L(0); PG8_MMA(0, 1, At, B1); PG8_BAR;
;             PG8_LDA(At, 1, 1); PG8_STAGE(PG8_SA(1, 0), a3, voffA);
;             PG8_BAR; PG8_WAIT_L(0); PG8_MMA(1, 0, At, B0); PG8_BAR; PG8_SCHED;
;             PG8_STAGE(PG8_SB(1, 1), b3 + hstep, voffB);
;             PG8_WAIT_V(6); PG8_BAR; PG8_MMA(1, 1, At, B1); PG8_BAR;
;             }
;         }
;         if constexpr (ALIGN_EPI) { if (wr == 0) PG8_BAR; }
.Lhb_87:
	s_add_i32 s59, s59, 2
	s_addk_i32 s2, 0x100
	s_addk_i32 s3, 0x100
	s_cmp_gt_u32 s59, 41
	s_cbranch_scc0 .LBB0_1614
	v_readlane_b32 s2, v251, 45
	v_readlane_b32 s3, v251, 46
	s_and_b64 vcc, exec, s[2:3]
	s_cbranch_vccz .LBB0_1617

; #define LAS __attribute__((address_space(3)))
; #define GAS __attribute__((address_space(1)))
;     __device__ __forceinline__ bool operator()(pg8::Acc& acc, const pg8::Unit& u, int wr, int wc, int fr, int fq, const LAS float* rstab) const {
;     ...
;         {
;             const int tid_ = ((wr * 4 + wc) * 64) + fq * 16 + fr;
;             const GAS f32x4* p = (const GAS f32x4*)(ss + (size_t)(u.pm * BM + (tid_ >> 1)) * 16) + (tid_ & 1) * 2; const f32x4 pa = p[0], pb = p[1];
;             float t = ((pa[0] + pa[1]) + (pa[2] + pa[3])) + ((pb[0] + pb[1]) + (pb[2] + pb[3]));
;             const float t2 = __shfl_xor(t, 1); t = (tid_ & 1) ? (t2 + t) : (t + t2);
;             if ((tid_ & 1) == 0) ((LAS float*)rstab)[tid_ >> 1] = __builtin_amdgcn_rsqf(t * (1.0f / DM) + NORM_EPS);
;             asm volatile("s_waitcnt lgkmcnt(0)" ::: "memory"); __builtin_amdgcn_s_barrier(); asm volatile("" ::: "memory");
;         }
;         float* op0 = OUT + (size_t)row0 * DM + col0;
; #pragma unroll
;         for (int bj = 0; bj < 2; ++bj) {
;             const f32x4 g0 = gld<f32x4>(gain + col0 + bj * HALF), g1 = gld<f32x4>(gain + col0 + bj * HALF + 4);
; #pragma unroll
;             for (int ai = 0; ai < 2; ++ai)
; #pragma unroll
;                 for (int m = 0; m < 4; ++m) {
;                     const float rs = rstab[ai * HALF + wr * 64 + m * 16 + fr];
;                     float* op = op0 + (size_t)(ai * HALF + m * 16) * DM + bj * HALF;
;                     __builtin_nontemporal_store(acc[ai][bj][m][0] * rs * g0, (GAS f32x4*)op); __builtin_nontemporal_store(acc[ai][bj][m][1] * rs * g1, (GAS f32x4*)(op + 4));
;                 }
;         }
.LBB0_1712:
	s_or_b64 exec, exec, s[2:3]
	v_readlane_b32 s60, v249, 3
	s_waitcnt lgkmcnt(0)
	v_lshlrev_b64 v[2:3], 10, v[156:157]
	v_readlane_b32 s72, v249, 15
	v_readlane_b32 s73, v249, 16
	v_readlane_b32 s74, v249, 17
	v_readlane_b32 s75, v249, 18
	v_lshlrev_b64 v[4:5], 2, v[154:155]
	s_waitcnt lgkmcnt(0)
	s_barrier
	v_lshl_add_u64 v[2:3], v[2:3], 2, s[74:75]
	v_lshl_add_u64 v[136:137], s[72:73], 0, v[4:5]
	v_lshl_add_u64 v[82:83], v[2:3], 0, v[4:5]
	global_load_dwordx4 v[2:5], v[136:137], off offset:16
	global_load_dwordx4 v[6:9], v[136:137], off
	v_readlane_b32 s2, v250, 11
	v_readlane_b32 s61, v249, 4
	v_readlane_b32 s62, v249, 5
	v_lshl_add_u32 v87, v174, 2, s2
	ds_read2_b32 v[84:85], v87 offset1:16
	s_mov_b32 s2, 0x10000
	ds_read2_b32 v[72:73], v87 offset0:32 offset1:48
	v_add_co_u32_e32 v88, vcc, s2, v82
	s_waitcnt lgkmcnt(1)
	v_pk_mul_f32 v[10:11], v[126:127], v[84:85] op_sel_hi:[1,0]
	v_pk_mul_f32 v[12:13], v[128:129], v[84:85] op_sel_hi:[1,0]
	v_mov_b32_e32 v86, v85
	v_addc_co_u32_e32 v89, vcc, 0, v83, vcc
	v_add_co_u32_e32 v80, vcc, s79, v82
	s_waitcnt lgkmcnt(0)
	v_mov_b32_e32 v0, v73
	v_addc_co_u32_e32 v81, vcc, 0, v83, vcc
	s_mov_b32 s2, 0x30000
	ds_read2_b32 v[66:67], v87 offset0:128 offset1:144
	v_add_co_u32_e32 v68, vcc, s2, v82
	s_mov_b32 s2, 0x80000
	s_nop 0
	v_addc_co_u32_e32 v69, vcc, 0, v83, vcc
	v_readlane_b32 s63, v249, 6
	v_readlane_b32 s64, v249, 7
	v_readlane_b32 s65, v249, 8
	v_readlane_b32 s66, v249, 9
	v_readlane_b32 s67, v249, 10
	v_readlane_b32 s68, v249, 11
	v_readlane_b32 s69, v249, 12
	v_readlane_b32 s70, v249, 13
	v_readlane_b32 s71, v249, 14
	s_waitcnt vmcnt(0)
	v_pk_mul_f32 v[12:13], v[8:9], v[12:13]
	v_pk_mul_f32 v[10:11], v[6:7], v[10:11]
	global_store_dwordx4 v[82:83], v[10:13], off nt
	s_nop 1
	v_pk_mul_f32 v[10:11], v[122:123], v[84:85] op_sel_hi:[1,0]
	v_pk_mul_f32 v[12:13], v[124:125], v[84:85] op_sel_hi:[1,0]
	v_pk_mul_f32 v[10:11], v[2:3], v[10:11]
	v_pk_mul_f32 v[12:13], v[4:5], v[12:13]
	global_store_dwordx4 v[82:83], v[10:13], off offset:16 nt
	v_add_co_u32_e32 v122, vcc, s2, v82
	s_nop 0
	v_pk_mul_f32 v[10:11], v[160:161], v[86:87] op_sel_hi:[1,0]
	v_pk_mul_f32 v[12:13], v[162:163], v[86:87] op_sel_hi:[1,0]
	v_pk_mul_f32 v[10:11], v[6:7], v[10:11]
	v_pk_mul_f32 v[12:13], v[8:9], v[12:13]
	global_store_dwordx4 v[88:89], v[10:13], off nt
	v_addc_co_u32_e32 v123, vcc, 0, v83, vcc
	s_nop 0
	v_pk_mul_f32 v[10:11], v[158:159], v[86:87] op_sel_hi:[1,0]
	v_pk_mul_f32 v[12:13], v[150:151], v[86:87] op_sel_hi:[1,0]
	v_pk_mul_f32 v[10:11], v[2:3], v[10:11]
	v_pk_mul_f32 v[12:13], v[4:5], v[12:13]
	global_store_dwordx4 v[88:89], v[10:13], off offset:16 nt
	s_mov_b32 s2, 0x90000
	s_nop 0
	v_pk_mul_f32 v[10:11], v[148:149], v[72:73] op_sel_hi:[1,0]
	v_pk_mul_f32 v[12:13], v[142:143], v[72:73] op_sel_hi:[1,0]
	v_pk_mul_f32 v[10:11], v[6:7], v[10:11]
	v_pk_mul_f32 v[12:13], v[8:9], v[12:13]
	global_store_dwordx4 v[80:81], v[10:13], off nt
	s_nop 1
	v_pk_mul_f32 v[10:11], v[146:147], v[72:73] op_sel_hi:[1,0]
	v_pk_mul_f32 v[12:13], v[144:145], v[72:73] op_sel_hi:[1,0]
	v_pk_mul_f32 v[10:11], v[2:3], v[10:11]
	v_pk_mul_f32 v[12:13], v[4:5], v[12:13]
	global_store_dwordx4 v[80:81], v[10:13], off offset:16 nt
	s_nop 1
	v_pk_mul_f32 v[10:11], v[140:141], v[0:1] op_sel_hi:[1,0]
	v_pk_mul_f32 v[12:13], v[152:153], v[0:1] op_sel_hi:[1,0]
	v_pk_mul_f32 v[10:11], v[6:7], v[10:11]
	v_pk_mul_f32 v[12:13], v[8:9], v[12:13]
	global_store_dwordx4 v[68:69], v[10:13], off nt
	s_nop 1
	v_pk_mul_f32 v[10:11], v[138:139], v[0:1] op_sel_hi:[1,0]
	v_pk_mul_f32 v[12:13], v[134:135], v[0:1] op_sel_hi:[1,0]
	v_pk_mul_f32 v[10:11], v[2:3], v[10:11]
	v_pk_mul_f32 v[12:13], v[4:5], v[12:13]
	global_store_dwordx4 v[68:69], v[10:13], off offset:16 nt
	s_waitcnt lgkmcnt(0)
	s_nop 0
	v_pk_mul_f32 v[10:11], v[130:131], v[66:67] op_sel_hi:[1,0]
	v_pk_mul_f32 v[12:13], v[132:133], v[66:67] op_sel_hi:[1,0]
	v_pk_mul_f32 v[10:11], v[6:7], v[10:11]
	v_pk_mul_f32 v[12:13], v[8:9], v[12:13]
	global_store_dwordx4 v[122:123], v[10:13], off nt
	s_nop 1
	v_pk_mul_f32 v[10:11], v[58:59], v[66:67] op_sel_hi:[1,0]
	v_pk_mul_f32 v[12:13], v[60:61], v[66:67] op_sel_hi:[1,0]
	v_pk_mul_f32 v[10:11], v[2:3], v[10:11]
	v_pk_mul_f32 v[12:13], v[4:5], v[12:13]
	global_store_dwordx4 v[122:123], v[10:13], off offset:16 nt
	s_nop 1
	v_mov_b32_e32 v10, v67
	v_pk_mul_f32 v[12:13], v[64:65], v[10:11] op_sel_hi:[1,0]
	v_pk_mul_f32 v[42:43], v[42:43], v[10:11] op_sel_hi:[1,0]
	v_pk_mul_f32 v[58:59], v[6:7], v[12:13]
	v_add_co_u32_e32 v12, vcc, s2, v82
	v_pk_mul_f32 v[44:45], v[44:45], v[10:11] op_sel_hi:[1,0]
	s_nop 0
	v_addc_co_u32_e32 v13, vcc, 0, v83, vcc
	v_pk_mul_f32 v[44:45], v[4:5], v[44:45]
	v_pk_mul_f32 v[42:43], v[2:3], v[42:43]
	global_store_dwordx4 v[12:13], v[42:45], off offset:16 nt
	ds_read2_b32 v[42:43], v87 offset0:160 offset1:176
	v_pk_mul_f32 v[46:47], v[46:47], v[10:11] op_sel_hi:[1,0]
	s_mov_b32 s2, 0xa0000
	v_pk_mul_f32 v[60:61], v[8:9], v[46:47]
	global_store_dwordx4 v[12:13], v[58:61], off nt
	s_waitcnt lgkmcnt(0)
; #define GAS __attribute__((address_space(1)))
; #define PG8_BAR __builtin_amdgcn_s_barrier()
; template <class Epi, bool ALIGN_EPI, bool SP2, class Hook>
; __device__ __forceinline__ void gemm_phase(LAS unsigned char* lds, const Gemm g, const StaticOrder& S, const Epi& E, Acc& acc, const bool fresh, const Hook& H, const int wave_id) {
;     ...
;         if (!has_next) break;
;         if (reset) {
; #pragma unroll
;             for (int a = 0; a < 2; ++a)
; #pragma unroll
;                 for (int b = 0; b < 2; ++b)
; #pragma unroll
;                     for (int m = 0; m < 4; ++m)
; #pragma unroll
;                         for (int n = 0; n < 2; ++n) acc[a][b][m][n] = (f32x4){0.f, 0.f, 0.f, 0.f};
;         }
;         cur = nxt; cA = nA; cB = nB; ++ui;
;         if constexpr (ALIGN_EPI) { if (wr == 1) PG8_BAR; }
;     __device__ __forceinline__ bool operator()(pg8::Acc& acc, const pg8::Unit& u, int wr, int wc, int fr, int fq, const LAS float* rstab) const {
;     ...
;         float* op0 = OUT + (size_t)row0 * DM + col0;
; #pragma unroll
;         for (int bj = 0; bj < 2; ++bj) {
;             const f32x4 g0 = gld<f32x4>(gain + col0 + bj * HALF), g1 = gld<f32x4>(gain + col0 + bj * HALF + 4);
; #pragma unroll
;             for (int ai = 0; ai < 2; ++ai)
; #pragma unroll
;                 for (int m = 0; m < 4; ++m) {
;                     const float rs = rstab[ai * HALF + wr * 64 + m * 16 + fr];
;                     float* op = op0 + (size_t)(ai * HALF + m * 16) * DM + bj * HALF;
;                     __builtin_nontemporal_store(acc[ai][bj][m][0] * rs * g0, (GAS f32x4*)op); __builtin_nontemporal_store(acc[ai][bj][m][1] * rs * g1, (GAS f32x4*)(op + 4));
;                 }
;         }
	v_pk_mul_f32 v[44:45], v[48:49], v[42:43] op_sel_hi:[1,0]
	v_pk_mul_f32 v[46:47], v[62:63], v[42:43] op_sel_hi:[1,0]
	v_pk_mul_f32 v[30:31], v[30:31], v[42:43] op_sel_hi:[1,0]
	v_pk_mul_f32 v[48:49], v[8:9], v[46:47]
	v_pk_mul_f32 v[46:47], v[6:7], v[44:45]
	v_add_co_u32_e32 v44, vcc, s2, v82
	v_pk_mul_f32 v[32:33], v[32:33], v[42:43] op_sel_hi:[1,0]
	s_nop 0
	v_addc_co_u32_e32 v45, vcc, 0, v83, vcc
	v_pk_mul_f32 v[32:33], v[4:5], v[32:33]
	v_pk_mul_f32 v[30:31], v[2:3], v[30:31]
	global_store_dwordx4 v[44:45], v[30:33], off offset:16 nt
	s_mov_b32 s2, 0xb0000
	global_store_dwordx4 v[44:45], v[46:49], off nt
	v_mov_b32_e32 v30, v43
	v_pk_mul_f32 v[32:33], v[76:77], v[30:31] op_sel_hi:[1,0]
	v_pk_mul_f32 v[46:47], v[78:79], v[30:31] op_sel_hi:[1,0]
	v_pk_mul_f32 v[6:7], v[6:7], v[32:33]
	v_add_co_u32_e32 v32, vcc, s2, v82
	v_pk_mul_f32 v[8:9], v[8:9], v[46:47]
	s_nop 0
	v_addc_co_u32_e32 v33, vcc, 0, v83, vcc
	global_store_dwordx4 v[32:33], v[6:9], off nt
	v_pk_mul_f32 v[46:47], v[118:119], v[84:85] op_sel_hi:[1,0]
	v_pk_mul_f32 v[48:49], v[120:121], v[84:85] op_sel_hi:[1,0]
	v_pk_mul_f32 v[6:7], v[74:75], v[30:31] op_sel_hi:[1,0]
	v_pk_mul_f32 v[8:9], v[70:71], v[30:31] op_sel_hi:[1,0]
	v_pk_mul_f32 v[2:3], v[2:3], v[6:7]
	v_pk_mul_f32 v[4:5], v[4:5], v[8:9]
	global_store_dwordx4 v[32:33], v[2:5], off offset:16 nt
	global_load_dwordx4 v[2:5], v[136:137], off offset:528
	s_nop 0
	global_load_dwordx4 v[6:9], v[136:137], off offset:512
	v_pk_mul_f32 v[38:39], v[38:39], v[10:11] op_sel_hi:[1,0]
	v_pk_mul_f32 v[40:41], v[40:41], v[10:11] op_sel_hi:[1,0]
	v_pk_mul_f32 v[34:35], v[34:35], v[10:11] op_sel_hi:[1,0]
	v_pk_mul_f32 v[10:11], v[36:37], v[10:11] op_sel_hi:[1,0]
	s_mov_b64 s[2:3], -1
	s_and_b64 vcc, exec, s[4:5]
	s_waitcnt vmcnt(1)
	v_pk_mul_f32 v[36:37], v[10:11], v[4:5]
	s_waitcnt vmcnt(0)
	v_pk_mul_f32 v[48:49], v[48:49], v[8:9]
	v_pk_mul_f32 v[46:47], v[46:47], v[6:7]
	global_store_dwordx4 v[82:83], v[46:49], off offset:512 nt
	v_pk_mul_f32 v[40:41], v[40:41], v[8:9]
	v_pk_mul_f32 v[38:39], v[38:39], v[6:7]
	v_pk_mul_f32 v[46:47], v[114:115], v[84:85] op_sel_hi:[1,0]
	v_pk_mul_f32 v[48:49], v[116:117], v[84:85] op_sel_hi:[1,0]
	v_pk_mul_f32 v[46:47], v[46:47], v[2:3]
	v_pk_mul_f32 v[48:49], v[48:49], v[4:5]
	global_store_dwordx4 v[82:83], v[46:49], off offset:528 nt
	v_pk_mul_f32 v[34:35], v[34:35], v[2:3]
	global_store_dwordx4 v[12:13], v[38:41], off offset:512 nt
	v_pk_mul_f32 v[46:47], v[102:103], v[86:87] op_sel_hi:[1,0]
	v_pk_mul_f32 v[48:49], v[104:105], v[86:87] op_sel_hi:[1,0]
	v_pk_mul_f32 v[46:47], v[46:47], v[6:7]
	v_pk_mul_f32 v[48:49], v[48:49], v[8:9]
	global_store_dwordx4 v[88:89], v[46:49], off offset:512 nt
	global_store_dwordx4 v[12:13], v[34:37], off offset:528 nt
	v_pk_mul_f32 v[10:11], v[22:23], v[42:43] op_sel_hi:[1,0]
	v_pk_mul_f32 v[46:47], v[98:99], v[86:87] op_sel_hi:[1,0]
	v_pk_mul_f32 v[48:49], v[100:101], v[86:87] op_sel_hi:[1,0]
	v_pk_mul_f32 v[46:47], v[46:47], v[2:3]
	v_pk_mul_f32 v[48:49], v[48:49], v[4:5]
	global_store_dwordx4 v[88:89], v[46:49], off offset:528 nt
	v_pk_mul_f32 v[12:13], v[24:25], v[42:43] op_sel_hi:[1,0]
	v_pk_mul_f32 v[10:11], v[10:11], v[6:7]
	v_pk_mul_f32 v[46:47], v[94:95], v[72:73] op_sel_hi:[1,0]
	v_pk_mul_f32 v[48:49], v[96:97], v[72:73] op_sel_hi:[1,0]
	v_pk_mul_f32 v[46:47], v[46:47], v[6:7]
	v_pk_mul_f32 v[48:49], v[48:49], v[8:9]
	global_store_dwordx4 v[80:81], v[46:49], off offset:512 nt
	v_pk_mul_f32 v[12:13], v[12:13], v[8:9]
	global_store_dwordx4 v[44:45], v[10:13], off offset:512 nt
	v_pk_mul_f32 v[46:47], v[90:91], v[72:73] op_sel_hi:[1,0]
	v_pk_mul_f32 v[48:49], v[92:93], v[72:73] op_sel_hi:[1,0]
	v_pk_mul_f32 v[46:47], v[46:47], v[2:3]
	v_pk_mul_f32 v[48:49], v[48:49], v[4:5]
	global_store_dwordx4 v[80:81], v[46:49], off offset:528 nt
	v_pk_mul_f32 v[10:11], v[18:19], v[42:43] op_sel_hi:[1,0]
	v_pk_mul_f32 v[12:13], v[20:21], v[42:43] op_sel_hi:[1,0]
	v_pk_mul_f32 v[46:47], v[110:111], v[0:1] op_sel_hi:[1,0]
	v_pk_mul_f32 v[48:49], v[112:113], v[0:1] op_sel_hi:[1,0]
	v_pk_mul_f32 v[46:47], v[46:47], v[6:7]
	v_pk_mul_f32 v[48:49], v[48:49], v[8:9]
	global_store_dwordx4 v[68:69], v[46:49], off offset:512 nt
	v_pk_mul_f32 v[12:13], v[12:13], v[4:5]
	v_pk_mul_f32 v[10:11], v[10:11], v[2:3]
	v_pk_mul_f32 v[46:47], v[106:107], v[0:1] op_sel_hi:[1,0]
	v_pk_mul_f32 v[48:49], v[108:109], v[0:1] op_sel_hi:[1,0]
	v_pk_mul_f32 v[46:47], v[46:47], v[2:3]
	v_pk_mul_f32 v[48:49], v[48:49], v[4:5]
	global_store_dwordx4 v[68:69], v[46:49], off offset:528 nt
	global_store_dwordx4 v[44:45], v[10:13], off offset:528 nt
	s_nop 0
	v_pk_mul_f32 v[46:47], v[54:55], v[66:67] op_sel_hi:[1,0]
	v_pk_mul_f32 v[48:49], v[56:57], v[66:67] op_sel_hi:[1,0]
	v_pk_mul_f32 v[10:11], v[16:17], v[30:31] op_sel_hi:[1,0]
	v_pk_mul_f32 v[12:13], v[28:29], v[30:31] op_sel_hi:[1,0]
	v_pk_mul_f32 v[48:49], v[48:49], v[8:9]
	v_pk_mul_f32 v[46:47], v[46:47], v[6:7]
	v_pk_mul_f32 v[8:9], v[8:9], v[12:13]
	v_pk_mul_f32 v[6:7], v[6:7], v[10:11]
	global_store_dwordx4 v[122:123], v[46:49], off offset:512 nt
	global_store_dwordx4 v[32:33], v[6:9], off offset:512 nt
	s_nop 0
	v_pk_mul_f32 v[46:47], v[50:51], v[66:67] op_sel_hi:[1,0]
	v_pk_mul_f32 v[48:49], v[52:53], v[66:67] op_sel_hi:[1,0]
	v_pk_mul_f32 v[6:7], v[14:15], v[30:31] op_sel_hi:[1,0]
	v_pk_mul_f32 v[8:9], v[26:27], v[30:31] op_sel_hi:[1,0]
	v_pk_mul_f32 v[48:49], v[48:49], v[4:5]
	v_pk_mul_f32 v[46:47], v[46:47], v[2:3]
	v_pk_mul_f32 v[4:5], v[8:9], v[4:5]
	v_pk_mul_f32 v[2:3], v[6:7], v[2:3]
	global_store_dwordx4 v[122:123], v[46:49], off offset:528 nt
	global_store_dwordx4 v[32:33], v[2:5], off offset:528 nt
	s_cbranch_vccnz .LBB0_1602
	s_and_b64 vcc, exec, s[0:1]
	s_cbranch_vccnz .LBB0_1601
	s_branch .LBB0_1601

; #define LAS __attribute__((address_space(3)))
; __global__ void __launch_bounds__(NTHREADS, 2) fwd_kernel(Args args) {
;     extern __shared__ __attribute__((aligned(16))) unsigned char lds[];
;     Frame F;
;     F.lds = (LAS unsigned char*)lds; F.tid = threadIdx.x; F.lane = F.tid & 63; F.wave = __builtin_amdgcn_readfirstlane(F.tid >> 6); F.G = gridDim.x; F.ws = args.ws;
	.amdhsa_kernel _Z10fwd_kernel4Args
		.amdhsa_group_segment_fixed_size 0
		.amdhsa_private_segment_fixed_size 0
		.amdhsa_kernarg_size 472
		.amdhsa_user_sgpr_count 2
		.amdhsa_user_sgpr_dispatch_ptr 0
		.amdhsa_user_sgpr_queue_ptr 0
		.amdhsa_user_sgpr_kernarg_segment_ptr 1
		.amdhsa_user_sgpr_dispatch_id 0
		.amdhsa_user_sgpr_kernarg_preload_length 0
		.amdhsa_user_sgpr_kernarg_preload_offset 0
		.amdhsa_user_sgpr_private_segment_size 0
		.amdhsa_uses_dynamic_stack 0
		.amdhsa_enable_private_segment 0
		.amdhsa_system_sgpr_workgroup_id_x 1
		.amdhsa_system_sgpr_workgroup_id_y 0
		.amdhsa_system_sgpr_workgroup_id_z 0
		.amdhsa_system_sgpr_workgroup_info 0
		.amdhsa_system_vgpr_workitem_id 0
		.amdhsa_next_free_vgpr 256
		.amdhsa_next_free_sgpr 102
		.amdhsa_accum_offset 256
		.amdhsa_reserve_vcc 1
		.amdhsa_float_round_mode_32 0
		.amdhsa_float_round_mode_16_64 0
		.amdhsa_float_denorm_mode_32 3
		.amdhsa_float_denorm_mode_16_64 3
		.amdhsa_dx10_clamp 1
		.amdhsa_ieee_mode 1
		.amdhsa_fp16_overflow 0
		.amdhsa_tg_split 0
		.amdhsa_exception_fp_ieee_invalid_op 0
		.amdhsa_exception_fp_denorm_src 0
		.amdhsa_exception_fp_ieee_div_zero 0
		.amdhsa_exception_fp_ieee_overflow 0
		.amdhsa_exception_fp_ieee_underflow 0
		.amdhsa_exception_fp_ieee_inexact 0
		.amdhsa_exception_int_div_zero 0
	.end_amdhsa_kernel

; #define LAS __attribute__((address_space(3)))
; __global__ void __launch_bounds__(NTHREADS, 2) fwd_kernel(Args args) {
;     extern __shared__ __attribute__((aligned(16))) unsigned char lds[];
;     Frame F;
;     F.lds = (LAS unsigned char*)lds; F.tid = threadIdx.x; F.lane = F.tid & 63; F.wave = __builtin_amdgcn_readfirstlane(F.tid >> 6); F.G = gridDim.x; F.ws = args.ws;
amdhsa.kernels:
  - .agpr_count:     0
    .args:
      - .offset:         0
        .size:           216
        .value_kind:     by_value
      - .offset:         216
        .size:           4
        .value_kind:     hidden_block_count_x
      - .offset:         220
        .size:           4
        .value_kind:     hidden_block_count_y
      - .offset:         224
        .size:           4
        .value_kind:     hidden_block_count_z
      - .offset:         228
        .size:           2
        .value_kind:     hidden_group_size_x
      - .offset:         230
        .size:           2
        .value_kind:     hidden_group_size_y
      - .offset:         232
        .size:           2
        .value_kind:     hidden_group_size_z
      - .offset:         234
        .size:           2
        .value_kind:     hidden_remainder_x
      - .offset:         236
        .size:           2
        .value_kind:     hidden_remainder_y
      - .offset:         238
        .size:           2
        .value_kind:     hidden_remainder_z
      - .offset:         256
        .size:           8
        .value_kind:     hidden_global_offset_x
      - .offset:         264
        .size:           8
        .value_kind:     hidden_global_offset_y
      - .offset:         272
        .size:           8
        .value_kind:     hidden_global_offset_z
      - .offset:         280
        .size:           2
        .value_kind:     hidden_grid_dims
      - .offset:         336
        .size:           4
        .value_kind:     hidden_dynamic_lds_size
    .group_segment_fixed_size: 0
    .kernarg_segment_align: 8
    .kernarg_segment_size: 472
    .language:       OpenCL C
    .language_version:
      - 2
      - 0
    .max_flat_workgroup_size: 512
    .name:           _Z10fwd_kernel4Args
    .private_segment_fixed_size: 0
    .sgpr_count:     108
    .sgpr_spill_count: 508
    .symbol:         _Z10fwd_kernel4Args.kd
    .uniform_work_group_size: 1
    .uses_dynamic_stack: false
    .vgpr_count:     256
    .vgpr_spill_count: 0
    .wavefront_size: 64
